# v46 + GEMM K-loops: merge the paired pre-barrier vmcnt(8) and lgkmcnt(0) waits into one s_waitcnt
# speedup vs baseline: 1.0048x; 1.0048x over previous
; #define PG8_STAGE(bufoff, gbase, voff) do { _Pragma("unroll") for (int _i = 0; _i < 2; ++_i) \
;         __builtin_amdgcn_global_load_lds((const unsigned*)((const char*)(gbase) + (voff)[_i]), (PG8_LAS unsigned*)(lds + (bufoff) + ldsw + _i * 8192), 16, 0, 0); } while (0)
; #define PG8_LDA(dst, b, h) do { _Pragma("unroll") for (int m = 0; m < 4; ++m) _Pragma("unroll") for (int k = 0; k < 2; ++k) dst[m][k] = *(const PG8_LAS bf16x8*)(lds + PG8_SA(b, h) + aoff + m * 2048 + k * 1024); } while (0)
; #define PG8_LDB(dst, b, h) do { _Pragma("unroll") for (int n = 0; n < 2; ++n) _Pragma("unroll") for (int k = 0; k < 2; ++k) dst[n][k] = *(const PG8_LAS bf16x8*)(lds + PG8_SB(b, h) + boff + n * 2048 + k * 1024); } while (0)
; #define PG8_MMA(ai, bj, At, Bt) do { __builtin_amdgcn_s_setprio(1); _Pragma("unroll") for (int m = 0; m < 4; ++m) _Pragma("unroll") for (int n = 0; n < 2; ++n) _Pragma("unroll") for (int k = 0; k < 2; ++k) \
;         acc[ai][bj][m][n] = __builtin_amdgcn_mfma_f32_16x16x32_bf16(Bt[n][k], At[m][k], acc[ai][bj][m][n], 0, 0, 0); __builtin_amdgcn_s_setprio(0); } while (0)
; #define PG8_WAIT_V(n) asm volatile("s_waitcnt vmcnt(" #n ")" ::: "memory")
; #define PG8_WAIT_L(n) asm volatile("s_waitcnt lgkmcnt(" #n ")" ::: "memory")
; #define PG8_BAR __builtin_amdgcn_s_barrier()
; #define PG8_SCHED __builtin_amdgcn_sched_barrier(0)
; template <class Epi, class Sched, bool ALIGN_EPI = false, bool SP2 = false>
; __device__ __forceinline__ void gemm_phase(PG8_LAS unsigned char* lds, const Gemm g, const Sched& S, const Epi& E) {
;     ...
;             const char* a2 = last ? nA : cA + (size_t)(t + 2) * kstep; const char* b2 = last ? nB : cB + (size_t)(t + 2) * kstep;
;             const char* a3 = a2 + kstep; const char* b3 = b2 + kstep;
;             if (last && has_next) S.a_ready(nxt);
;             if constexpr (SP2) {
;             PG8_LDB(B0, 0, 0); PG8_LDB(B1, 0, 1); PG8_SCHED; PG8_LDA(At, 0, 0); PG8_STAGE(PG8_SA(1, 1), a1 + hstepA, voffA);
;             PG8_WAIT_V(8); PG8_WAIT_L(0); PG8_BAR; PG8_MMA(0, 0, At, B0); PG8_MMA(0, 1, At, B1); PG8_BAR; PG8_SCHED;
;             PG8_LDA(At, 0, 1); PG8_STAGE(PG8_SB(0, 0), b2, voffB); PG8_STAGE(PG8_SB(0, 1), b2 + hstepB, voffB); PG8_STAGE(PG8_SA(0, 0), a2, voffA);
;             PG8_WAIT_V(8); PG8_WAIT_L(0); PG8_BAR; PG8_MMA(1, 0, At, B0); PG8_MMA(1, 1, At, B1); PG8_BAR; PG8_SCHED;
.LBB0_165:
	ds_read_b128 v[152:155], v146
	ds_read_b128 v[156:159], v146 offset:1024
	ds_read_b128 v[160:163], v146 offset:2048
	ds_read_b128 v[164:167], v146 offset:3072
	ds_read_b128 v[168:171], v147
	ds_read_b128 v[172:175], v147 offset:1024
	ds_read_b128 v[176:179], v147 offset:2048
	ds_read_b128 v[180:183], v147 offset:3072
	s_add_i32 s61, s40, 2
	s_add_u32 s41, s38, 0xffff0080
	s_addc_u32 s42, s39, -1
	s_cmp_eq_u32 s52, s40
	s_cselect_b32 s40, s58, s59
	s_cselect_b32 s43, s19, s42
	s_cselect_b32 s42, s23, s41
	s_cselect_b32 s41, s29, s60
	v_lshl_add_u64 v[142:143], s[38:39], 0, v[136:137]
	s_add_i32 m0, s33, 0xc000
	ds_read_b128 v[184:187], v148
	ds_read_b128 v[188:191], v148 offset:1024
	ds_read_b128 v[192:195], v148 offset:2048
	ds_read_b128 v[196:199], v148 offset:3072
	ds_read_b128 v[200:203], v148 offset:4096
	ds_read_b128 v[204:207], v148 offset:5120
	ds_read_b128 v[208:211], v148 offset:6144
	ds_read_b128 v[212:215], v148 offset:7168
	global_load_lds_dwordx4 v[142:143], off
	v_lshl_add_u64 v[142:143], s[38:39], 0, v[138:139]
	s_add_i32 m0, s33, 0xe000
	s_nop 0
	global_load_lds_dwordx4 v[142:143], off
	s_waitcnt vmcnt(8) lgkmcnt(0)
	s_barrier
	s_setprio 1
	v_mfma_f32_16x16x32_bf16 v[124:127], v[152:155], v[184:187], v[124:127]
	v_mfma_f32_16x16x32_bf16 v[120:123], v[160:163], v[184:187], v[120:123]
	v_mfma_f32_16x16x32_bf16 v[108:111], v[152:155], v[192:195], v[108:111]
	v_mfma_f32_16x16x32_bf16 v[104:107], v[160:163], v[192:195], v[104:107]
	v_mfma_f32_16x16x32_bf16 v[92:95], v[152:155], v[200:203], v[92:95]
	v_mfma_f32_16x16x32_bf16 v[88:91], v[160:163], v[200:203], v[88:91]
	v_mfma_f32_16x16x32_bf16 v[76:79], v[152:155], v[208:211], v[76:79]
	v_mfma_f32_16x16x32_bf16 v[72:75], v[160:163], v[208:211], v[72:75]
	v_mfma_f32_16x16x32_bf16 v[124:127], v[156:159], v[188:191], v[124:127]
	v_mfma_f32_16x16x32_bf16 v[120:123], v[164:167], v[188:191], v[120:123]
	v_mfma_f32_16x16x32_bf16 v[108:111], v[156:159], v[196:199], v[108:111]
	v_mfma_f32_16x16x32_bf16 v[104:107], v[164:167], v[196:199], v[104:107]
	v_mfma_f32_16x16x32_bf16 v[92:95], v[156:159], v[204:207], v[92:95]
	v_mfma_f32_16x16x32_bf16 v[88:91], v[164:167], v[204:207], v[88:91]
	v_mfma_f32_16x16x32_bf16 v[76:79], v[156:159], v[212:215], v[76:79]
	v_mfma_f32_16x16x32_bf16 v[72:75], v[164:167], v[212:215], v[72:75]
	v_mfma_f32_16x16x32_bf16 v[116:119], v[168:171], v[184:187], v[116:119]
	v_mfma_f32_16x16x32_bf16 v[112:115], v[176:179], v[184:187], v[112:115]
	v_mfma_f32_16x16x32_bf16 v[100:103], v[168:171], v[192:195], v[100:103]
	v_mfma_f32_16x16x32_bf16 v[96:99], v[176:179], v[192:195], v[96:99]
	v_mfma_f32_16x16x32_bf16 v[84:87], v[168:171], v[200:203], v[84:87]
	v_mfma_f32_16x16x32_bf16 v[80:83], v[176:179], v[200:203], v[80:83]
	v_mfma_f32_16x16x32_bf16 v[68:71], v[168:171], v[208:211], v[68:71]
	v_mfma_f32_16x16x32_bf16 v[64:67], v[176:179], v[208:211], v[64:67]
	v_mfma_f32_16x16x32_bf16 v[116:119], v[172:175], v[188:191], v[116:119]
	v_mfma_f32_16x16x32_bf16 v[112:115], v[180:183], v[188:191], v[112:115]
	v_mfma_f32_16x16x32_bf16 v[100:103], v[172:175], v[196:199], v[100:103]
	v_mfma_f32_16x16x32_bf16 v[96:99], v[180:183], v[196:199], v[96:99]
	v_mfma_f32_16x16x32_bf16 v[84:87], v[172:175], v[204:207], v[84:87]
	v_mfma_f32_16x16x32_bf16 v[80:83], v[180:183], v[204:207], v[80:83]
	v_mfma_f32_16x16x32_bf16 v[68:71], v[172:175], v[212:215], v[68:71]
	v_mfma_f32_16x16x32_bf16 v[64:67], v[180:183], v[212:215], v[64:67]
	s_setprio 0
	s_barrier
	s_add_i32 s62, s53, s17
	v_lshl_add_u64 v[142:143], s[40:41], 0, v[130:131]
	s_mov_b32 m0, s62
	ds_read_b128 v[184:187], v148 offset:16384
	ds_read_b128 v[188:191], v148 offset:17408
	ds_read_b128 v[192:195], v148 offset:18432
	ds_read_b128 v[196:199], v148 offset:19456
	ds_read_b128 v[200:203], v148 offset:20480
	ds_read_b128 v[204:207], v148 offset:21504
	ds_read_b128 v[208:211], v148 offset:22528
	ds_read_b128 v[212:215], v148 offset:23552
	global_load_lds_dwordx4 v[142:143], off
	s_add_i32 m0, s62, 0x2000
	s_add_u32 s62, s40, 0x10000
	v_lshl_add_u64 v[218:219], s[40:41], 0, v[134:135]
	s_addc_u32 s63, s41, 0
	s_add_i32 s64, s54, s17
	global_load_lds_dwordx4 v[218:219], off
	v_lshl_add_u64 v[220:221], s[62:63], 0, v[130:131]
	s_mov_b32 m0, s64
	v_lshl_add_u64 v[222:223], s[42:43], 0, v[132:133]
	global_load_lds_dwordx4 v[220:221], off
	v_lshl_add_u64 v[220:221], s[62:63], 0, v[134:135]
	s_add_i32 m0, s64, 0x2000
	s_nop 0
	global_load_lds_dwordx4 v[220:221], off
	v_lshl_add_u64 v[220:221], s[42:43], 0, v[128:129]
	s_mov_b32 m0, s33
	s_nop 0
	global_load_lds_dwordx4 v[220:221], off
	s_mov_b32 m0, s37
	s_nop 0
	global_load_lds_dwordx4 v[222:223], off
	s_waitcnt vmcnt(8) lgkmcnt(0)
	s_barrier
; #define PG8_STAGE(bufoff, gbase, voff) do { _Pragma("unroll") for (int _i = 0; _i < 2; ++_i) \
;         __builtin_amdgcn_global_load_lds((const unsigned*)((const char*)(gbase) + (voff)[_i]), (PG8_LAS unsigned*)(lds + (bufoff) + ldsw + _i * 8192), 16, 0, 0); } while (0)
; #define PG8_LDA(dst, b, h) do { _Pragma("unroll") for (int m = 0; m < 4; ++m) _Pragma("unroll") for (int k = 0; k < 2; ++k) dst[m][k] = *(const PG8_LAS bf16x8*)(lds + PG8_SA(b, h) + aoff + m * 2048 + k * 1024); } while (0)
; #define PG8_LDB(dst, b, h) do { _Pragma("unroll") for (int n = 0; n < 2; ++n) _Pragma("unroll") for (int k = 0; k < 2; ++k) dst[n][k] = *(const PG8_LAS bf16x8*)(lds + PG8_SB(b, h) + boff + n * 2048 + k * 1024); } while (0)
; #define PG8_MMA(ai, bj, At, Bt) do { __builtin_amdgcn_s_setprio(1); _Pragma("unroll") for (int m = 0; m < 4; ++m) _Pragma("unroll") for (int n = 0; n < 2; ++n) _Pragma("unroll") for (int k = 0; k < 2; ++k) \
;         acc[ai][bj][m][n] = __builtin_amdgcn_mfma_f32_16x16x32_bf16(Bt[n][k], At[m][k], acc[ai][bj][m][n], 0, 0, 0); __builtin_amdgcn_s_setprio(0); } while (0)
; #define PG8_WAIT_V(n) asm volatile("s_waitcnt vmcnt(" #n ")" ::: "memory")
; #define PG8_WAIT_L(n) asm volatile("s_waitcnt lgkmcnt(" #n ")" ::: "memory")
; #define PG8_BAR __builtin_amdgcn_s_barrier()
; #define PG8_SCHED __builtin_amdgcn_sched_barrier(0)
; template <class Epi, class Sched, bool ALIGN_EPI = false, bool SP2 = false>
; __device__ __forceinline__ void gemm_phase(PG8_LAS unsigned char* lds, const Gemm g, const Sched& S, const Epi& E) {
;     ...
;             PG8_WAIT_V(8); PG8_WAIT_L(0); PG8_BAR; PG8_MMA(1, 0, At, B0); PG8_MMA(1, 1, At, B1); PG8_BAR; PG8_SCHED;
;             PG8_LDB(B0, 1, 0); PG8_LDB(B1, 1, 1); PG8_SCHED; PG8_LDA(At, 1, 0); PG8_STAGE(PG8_SA(0, 1), a2 + hstepA, voffA);
;             PG8_WAIT_V(8); PG8_WAIT_L(0); PG8_BAR; PG8_MMA(0, 0, At, B0); PG8_MMA(0, 1, At, B1); PG8_BAR; PG8_SCHED;
	s_setprio 1
	v_mfma_f32_16x16x32_bf16 v[60:63], v[152:155], v[184:187], v[60:63]
	v_mfma_f32_16x16x32_bf16 v[56:59], v[160:163], v[184:187], v[56:59]
	v_mfma_f32_16x16x32_bf16 v[44:47], v[152:155], v[192:195], v[44:47]
	v_mfma_f32_16x16x32_bf16 v[40:43], v[160:163], v[192:195], v[40:43]
	v_mfma_f32_16x16x32_bf16 v[28:31], v[152:155], v[200:203], v[28:31]
	v_mfma_f32_16x16x32_bf16 v[24:27], v[160:163], v[200:203], v[24:27]
	v_mfma_f32_16x16x32_bf16 v[12:15], v[152:155], v[208:211], v[12:15]
	v_mfma_f32_16x16x32_bf16 v[8:11], v[160:163], v[208:211], v[8:11]
	v_mfma_f32_16x16x32_bf16 v[60:63], v[156:159], v[188:191], v[60:63]
	v_mfma_f32_16x16x32_bf16 v[56:59], v[164:167], v[188:191], v[56:59]
	v_mfma_f32_16x16x32_bf16 v[44:47], v[156:159], v[196:199], v[44:47]
	v_mfma_f32_16x16x32_bf16 v[40:43], v[164:167], v[196:199], v[40:43]
	v_mfma_f32_16x16x32_bf16 v[28:31], v[156:159], v[204:207], v[28:31]
	v_mfma_f32_16x16x32_bf16 v[24:27], v[164:167], v[204:207], v[24:27]
	v_mfma_f32_16x16x32_bf16 v[12:15], v[156:159], v[212:215], v[12:15]
	v_mfma_f32_16x16x32_bf16 v[8:11], v[164:167], v[212:215], v[8:11]
	v_mfma_f32_16x16x32_bf16 v[52:55], v[168:171], v[184:187], v[52:55]
	v_mfma_f32_16x16x32_bf16 v[48:51], v[176:179], v[184:187], v[48:51]
	v_mfma_f32_16x16x32_bf16 v[36:39], v[168:171], v[192:195], v[36:39]
	v_mfma_f32_16x16x32_bf16 v[32:35], v[176:179], v[192:195], v[32:35]
	v_mfma_f32_16x16x32_bf16 v[20:23], v[168:171], v[200:203], v[20:23]
	v_mfma_f32_16x16x32_bf16 v[16:19], v[176:179], v[200:203], v[16:19]
	v_mfma_f32_16x16x32_bf16 v[4:7], v[168:171], v[208:211], v[4:7]
	v_mfma_f32_16x16x32_bf16 v[0:3], v[176:179], v[208:211], v[0:3]
	v_mfma_f32_16x16x32_bf16 v[52:55], v[172:175], v[188:191], v[52:55]
	v_mfma_f32_16x16x32_bf16 v[48:51], v[180:183], v[188:191], v[48:51]
	v_mfma_f32_16x16x32_bf16 v[36:39], v[172:175], v[196:199], v[36:39]
	v_mfma_f32_16x16x32_bf16 v[32:35], v[180:183], v[196:199], v[32:35]
	v_mfma_f32_16x16x32_bf16 v[20:23], v[172:175], v[204:207], v[20:23]
	v_mfma_f32_16x16x32_bf16 v[16:19], v[180:183], v[204:207], v[16:19]
	v_mfma_f32_16x16x32_bf16 v[4:7], v[172:175], v[212:215], v[4:7]
	v_mfma_f32_16x16x32_bf16 v[0:3], v[180:183], v[212:215], v[0:3]
	s_setprio 0
	s_barrier
	s_add_i32 s62, 0, 0x18000
	v_add_u32_e32 v140, s62, v145
	s_add_i32 s63, 0, 0x1c000
	ds_read_b128 v[152:155], v140
	ds_read_b128 v[156:159], v140 offset:1024
	ds_read_b128 v[160:163], v140 offset:2048
	ds_read_b128 v[164:167], v140 offset:3072
	v_add_u32_e32 v140, s63, v145
	ds_read_b128 v[168:171], v140
	ds_read_b128 v[172:175], v140 offset:1024
	ds_read_b128 v[176:179], v140 offset:2048
	ds_read_b128 v[180:183], v140 offset:3072
	s_add_u32 s42, s42, 0x10000
	s_addc_u32 s43, s43, 0
	s_mov_b32 m0, s46
	v_lshl_add_u64 v[224:225], s[42:43], 0, v[128:129]
	ds_read_b128 v[184:187], v148 offset:32768
	ds_read_b128 v[188:191], v148 offset:33792
	ds_read_b128 v[192:195], v148 offset:34816
	ds_read_b128 v[196:199], v148 offset:35840
	ds_read_b128 v[200:203], v148 offset:36864
	ds_read_b128 v[204:207], v148 offset:37888
	ds_read_b128 v[208:211], v148 offset:38912
	ds_read_b128 v[212:215], v148 offset:39936
	global_load_lds_dwordx4 v[224:225], off
	v_lshl_add_u64 v[224:225], s[42:43], 0, v[132:133]
	s_mov_b32 m0, s47
	s_nop 0
	global_load_lds_dwordx4 v[224:225], off
	s_waitcnt vmcnt(8) lgkmcnt(0)
	s_barrier
	s_setprio 1
	v_mfma_f32_16x16x32_bf16 v[124:127], v[152:155], v[184:187], v[124:127]
	v_mfma_f32_16x16x32_bf16 v[120:123], v[160:163], v[184:187], v[120:123]
	v_mfma_f32_16x16x32_bf16 v[108:111], v[152:155], v[192:195], v[108:111]
	v_mfma_f32_16x16x32_bf16 v[104:107], v[160:163], v[192:195], v[104:107]
	v_mfma_f32_16x16x32_bf16 v[92:95], v[152:155], v[200:203], v[92:95]
	v_mfma_f32_16x16x32_bf16 v[88:91], v[160:163], v[200:203], v[88:91]
	v_mfma_f32_16x16x32_bf16 v[76:79], v[152:155], v[208:211], v[76:79]
	v_mfma_f32_16x16x32_bf16 v[72:75], v[160:163], v[208:211], v[72:75]
	v_mfma_f32_16x16x32_bf16 v[124:127], v[156:159], v[188:191], v[124:127]
	v_mfma_f32_16x16x32_bf16 v[120:123], v[164:167], v[188:191], v[120:123]
	v_mfma_f32_16x16x32_bf16 v[108:111], v[156:159], v[196:199], v[108:111]
	v_mfma_f32_16x16x32_bf16 v[104:107], v[164:167], v[196:199], v[104:107]
	v_mfma_f32_16x16x32_bf16 v[92:95], v[156:159], v[204:207], v[92:95]
	v_mfma_f32_16x16x32_bf16 v[88:91], v[164:167], v[204:207], v[88:91]
	v_mfma_f32_16x16x32_bf16 v[76:79], v[156:159], v[212:215], v[76:79]
	v_mfma_f32_16x16x32_bf16 v[72:75], v[164:167], v[212:215], v[72:75]
	v_mfma_f32_16x16x32_bf16 v[116:119], v[168:171], v[184:187], v[116:119]
	v_mfma_f32_16x16x32_bf16 v[112:115], v[176:179], v[184:187], v[112:115]
	v_mfma_f32_16x16x32_bf16 v[100:103], v[168:171], v[192:195], v[100:103]
	v_mfma_f32_16x16x32_bf16 v[96:99], v[176:179], v[192:195], v[96:99]
	v_mfma_f32_16x16x32_bf16 v[84:87], v[168:171], v[200:203], v[84:87]
	v_mfma_f32_16x16x32_bf16 v[80:83], v[176:179], v[200:203], v[80:83]
	v_mfma_f32_16x16x32_bf16 v[68:71], v[168:171], v[208:211], v[68:71]
	v_mfma_f32_16x16x32_bf16 v[64:67], v[176:179], v[208:211], v[64:67]
	v_mfma_f32_16x16x32_bf16 v[116:119], v[172:175], v[188:191], v[116:119]
	v_mfma_f32_16x16x32_bf16 v[112:115], v[180:183], v[188:191], v[112:115]
	v_mfma_f32_16x16x32_bf16 v[100:103], v[172:175], v[196:199], v[100:103]
	v_mfma_f32_16x16x32_bf16 v[96:99], v[180:183], v[196:199], v[96:99]
	v_mfma_f32_16x16x32_bf16 v[84:87], v[172:175], v[204:207], v[84:87]
	v_mfma_f32_16x16x32_bf16 v[80:83], v[180:183], v[204:207], v[80:83]
	v_mfma_f32_16x16x32_bf16 v[68:71], v[172:175], v[212:215], v[68:71]
	v_mfma_f32_16x16x32_bf16 v[64:67], v[180:183], v[212:215], v[64:67]
	s_setprio 0
	s_barrier
; #define PG8_STAGE(bufoff, gbase, voff) do { _Pragma("unroll") for (int _i = 0; _i < 2; ++_i) \
;         __builtin_amdgcn_global_load_lds((const unsigned*)((const char*)(gbase) + (voff)[_i]), (PG8_LAS unsigned*)(lds + (bufoff) + ldsw + _i * 8192), 16, 0, 0); } while (0)
; #define PG8_LDA(dst, b, h) do { _Pragma("unroll") for (int m = 0; m < 4; ++m) _Pragma("unroll") for (int k = 0; k < 2; ++k) dst[m][k] = *(const PG8_LAS bf16x8*)(lds + PG8_SA(b, h) + aoff + m * 2048 + k * 1024); } while (0)
; #define PG8_MMA(ai, bj, At, Bt) do { __builtin_amdgcn_s_setprio(1); _Pragma("unroll") for (int m = 0; m < 4; ++m) _Pragma("unroll") for (int n = 0; n < 2; ++n) _Pragma("unroll") for (int k = 0; k < 2; ++k) \
;         acc[ai][bj][m][n] = __builtin_amdgcn_mfma_f32_16x16x32_bf16(Bt[n][k], At[m][k], acc[ai][bj][m][n], 0, 0, 0); __builtin_amdgcn_s_setprio(0); } while (0)
; #define PG8_WAIT_V(n) asm volatile("s_waitcnt vmcnt(" #n ")" ::: "memory")
; #define PG8_WAIT_L(n) asm volatile("s_waitcnt lgkmcnt(" #n ")" ::: "memory")
; #define PG8_BAR __builtin_amdgcn_s_barrier()
; #define PG8_SCHED __builtin_amdgcn_sched_barrier(0)
; template <class Epi, class Sched, bool ALIGN_EPI = false, bool SP2 = false>
; __device__ __forceinline__ void gemm_phase(PG8_LAS unsigned char* lds, const Gemm g, const Sched& S, const Epi& E) {
;     ...
;             PG8_LDA(At, 1, 1); PG8_STAGE(PG8_SB(1, 0), b3, voffB); PG8_STAGE(PG8_SB(1, 1), b3 + hstepB, voffB); PG8_STAGE(PG8_SA(1, 0), a3, voffA);
;             PG8_WAIT_V(8); PG8_WAIT_L(0); PG8_BAR; PG8_MMA(1, 0, At, B0); PG8_MMA(1, 1, At, B1); PG8_BAR; PG8_SCHED;
	s_add_i32 s42, s62, s17
	v_lshl_add_u64 v[142:143], v[142:143], 0, s[8:9]
	s_mov_b32 m0, s42
	ds_read_b128 v[184:187], v148 offset:49152
	ds_read_b128 v[188:191], v148 offset:50176
	ds_read_b128 v[192:195], v148 offset:51200
	ds_read_b128 v[196:199], v148 offset:52224
	ds_read_b128 v[200:203], v148 offset:53248
	ds_read_b128 v[204:207], v148 offset:54272
	ds_read_b128 v[208:211], v148 offset:55296
	ds_read_b128 v[212:215], v148 offset:56320
	global_load_lds_dwordx4 v[142:143], off
	s_add_i32 m0, s42, 0x2000
	s_add_u32 s40, s40, 0x10080
	v_lshl_add_u64 v[142:143], v[218:219], 0, s[8:9]
	s_addc_u32 s41, s41, 0
	s_add_i32 s42, s63, s17
	global_load_lds_dwordx4 v[142:143], off
	v_lshl_add_u64 v[142:143], s[40:41], 0, v[130:131]
	s_mov_b32 m0, s42
	s_nop 0
	global_load_lds_dwordx4 v[142:143], off
	v_lshl_add_u64 v[142:143], s[40:41], 0, v[134:135]
	s_add_i32 m0, s42, 0x2000
	s_nop 0
	global_load_lds_dwordx4 v[142:143], off
	v_lshl_add_u64 v[142:143], v[220:221], 0, s[8:9]
	s_mov_b32 m0, s50
	s_nop 0
	global_load_lds_dwordx4 v[142:143], off
	v_lshl_add_u64 v[142:143], v[222:223], 0, s[8:9]
	s_mov_b32 m0, s51
	s_nop 0
	global_load_lds_dwordx4 v[142:143], off
	s_waitcnt vmcnt(8) lgkmcnt(0)
	s_barrier
	s_setprio 1
	v_mfma_f32_16x16x32_bf16 v[60:63], v[152:155], v[184:187], v[60:63]
	v_mfma_f32_16x16x32_bf16 v[56:59], v[160:163], v[184:187], v[56:59]
	v_mfma_f32_16x16x32_bf16 v[44:47], v[152:155], v[192:195], v[44:47]
	v_mfma_f32_16x16x32_bf16 v[40:43], v[160:163], v[192:195], v[40:43]
	v_mfma_f32_16x16x32_bf16 v[28:31], v[152:155], v[200:203], v[28:31]
	v_mfma_f32_16x16x32_bf16 v[24:27], v[160:163], v[200:203], v[24:27]
	v_mfma_f32_16x16x32_bf16 v[12:15], v[152:155], v[208:211], v[12:15]
	v_mfma_f32_16x16x32_bf16 v[8:11], v[160:163], v[208:211], v[8:11]
	v_mfma_f32_16x16x32_bf16 v[60:63], v[156:159], v[188:191], v[60:63]
	v_mfma_f32_16x16x32_bf16 v[56:59], v[164:167], v[188:191], v[56:59]
	v_mfma_f32_16x16x32_bf16 v[44:47], v[156:159], v[196:199], v[44:47]
	v_mfma_f32_16x16x32_bf16 v[40:43], v[164:167], v[196:199], v[40:43]
	v_mfma_f32_16x16x32_bf16 v[28:31], v[156:159], v[204:207], v[28:31]
	v_mfma_f32_16x16x32_bf16 v[24:27], v[164:167], v[204:207], v[24:27]
	v_mfma_f32_16x16x32_bf16 v[12:15], v[156:159], v[212:215], v[12:15]
	v_mfma_f32_16x16x32_bf16 v[8:11], v[164:167], v[212:215], v[8:11]
	v_mfma_f32_16x16x32_bf16 v[52:55], v[168:171], v[184:187], v[52:55]
	v_mfma_f32_16x16x32_bf16 v[48:51], v[176:179], v[184:187], v[48:51]
	v_mfma_f32_16x16x32_bf16 v[36:39], v[168:171], v[192:195], v[36:39]
	v_mfma_f32_16x16x32_bf16 v[32:35], v[176:179], v[192:195], v[32:35]
	v_mfma_f32_16x16x32_bf16 v[20:23], v[168:171], v[200:203], v[20:23]
	v_mfma_f32_16x16x32_bf16 v[16:19], v[176:179], v[200:203], v[16:19]
	v_mfma_f32_16x16x32_bf16 v[4:7], v[168:171], v[208:211], v[4:7]
	v_mfma_f32_16x16x32_bf16 v[0:3], v[176:179], v[208:211], v[0:3]
	v_mfma_f32_16x16x32_bf16 v[52:55], v[172:175], v[188:191], v[52:55]
	v_mfma_f32_16x16x32_bf16 v[48:51], v[180:183], v[188:191], v[48:51]
	v_mfma_f32_16x16x32_bf16 v[36:39], v[172:175], v[196:199], v[36:39]
	v_mfma_f32_16x16x32_bf16 v[32:35], v[180:183], v[196:199], v[32:35]
	v_mfma_f32_16x16x32_bf16 v[20:23], v[172:175], v[204:207], v[20:23]
	v_mfma_f32_16x16x32_bf16 v[16:19], v[180:183], v[204:207], v[16:19]
	v_mfma_f32_16x16x32_bf16 v[4:7], v[172:175], v[212:215], v[4:7]
	v_mfma_f32_16x16x32_bf16 v[0:3], v[180:183], v[212:215], v[0:3]
	s_setprio 0
	s_barrier
	s_add_u32 s38, s38, 0x100
	s_addc_u32 s39, s39, 0
	s_add_u32 s59, s59, 0x100
	s_addc_u32 s60, s60, 0
	s_cmp_ge_i32 s61, s48
	s_mov_b32 s40, s61
	s_cbranch_scc0 .LBB0_165

; #define PG8_STAGE(bufoff, gbase, voff) do { _Pragma("unroll") for (int _i = 0; _i < 2; ++_i) \
;         __builtin_amdgcn_global_load_lds((const unsigned*)((const char*)(gbase) + (voff)[_i]), (PG8_LAS unsigned*)(lds + (bufoff) + ldsw + _i * 8192), 16, 0, 0); } while (0)
; #define PG8_LDA(dst, b, h) do { _Pragma("unroll") for (int m = 0; m < 4; ++m) _Pragma("unroll") for (int k = 0; k < 2; ++k) dst[m][k] = *(const PG8_LAS bf16x8*)(lds + PG8_SA(b, h) + aoff + m * 2048 + k * 1024); } while (0)
; #define PG8_LDB(dst, b, h) do { _Pragma("unroll") for (int n = 0; n < 2; ++n) _Pragma("unroll") for (int k = 0; k < 2; ++k) dst[n][k] = *(const PG8_LAS bf16x8*)(lds + PG8_SB(b, h) + boff + n * 2048 + k * 1024); } while (0)
; #define PG8_MMA(ai, bj, At, Bt) do { __builtin_amdgcn_s_setprio(1); _Pragma("unroll") for (int m = 0; m < 4; ++m) _Pragma("unroll") for (int n = 0; n < 2; ++n) _Pragma("unroll") for (int k = 0; k < 2; ++k) \
;         acc[ai][bj][m][n] = __builtin_amdgcn_mfma_f32_16x16x32_bf16(Bt[n][k], At[m][k], acc[ai][bj][m][n], 0, 0, 0); __builtin_amdgcn_s_setprio(0); } while (0)
; #define PG8_WAIT_V(n) asm volatile("s_waitcnt vmcnt(" #n ")" ::: "memory")
; #define PG8_WAIT_L(n) asm volatile("s_waitcnt lgkmcnt(" #n ")" ::: "memory")
; #define PG8_BAR __builtin_amdgcn_s_barrier()
; #define PG8_SCHED __builtin_amdgcn_sched_barrier(0)
; template <class Epi, class Sched, bool ALIGN_EPI = false, bool SP2 = false>
; __device__ __forceinline__ void gemm_phase(PG8_LAS unsigned char* lds, const Gemm g, const Sched& S, const Epi& E) {
;     ...
;             const char* a2 = last ? nA : cA + (size_t)(t + 2) * kstep; const char* b2 = last ? nB : cB + (size_t)(t + 2) * kstep;
;             const char* a3 = a2 + kstep; const char* b3 = b2 + kstep;
;             if (last && has_next) S.a_ready(nxt);
;             if constexpr (SP2) {
;             PG8_LDB(B0, 0, 0); PG8_LDB(B1, 0, 1); PG8_SCHED; PG8_LDA(At, 0, 0); PG8_STAGE(PG8_SA(1, 1), a1 + hstepA, voffA);
;             PG8_WAIT_V(8); PG8_WAIT_L(0); PG8_BAR; PG8_MMA(0, 0, At, B0); PG8_MMA(0, 1, At, B1); PG8_BAR; PG8_SCHED;
;             PG8_LDA(At, 0, 1); PG8_STAGE(PG8_SB(0, 0), b2, voffB); PG8_STAGE(PG8_SB(0, 1), b2 + hstepB, voffB); PG8_STAGE(PG8_SA(0, 0), a2, voffA);
;             PG8_WAIT_V(8); PG8_WAIT_L(0); PG8_BAR; PG8_MMA(1, 0, At, B0); PG8_MMA(1, 1, At, B1); PG8_BAR; PG8_SCHED;
.LBB0_301:
	s_add_i32 s59, s48, 2
	s_add_u32 s46, s42, 0xfffc0080
	s_addc_u32 s47, s43, -1
	s_add_i32 s62, 0, 0x10000
	s_cmp_eq_u32 s16, s48
	s_cselect_b32 s49, s29, s47
	s_cselect_b32 s48, s33, s46
	s_cselect_b32 s47, s41, s58
	s_cselect_b32 s46, s45, s55
	s_add_i32 s64, 0, 0x14000
	v_add_u32_e32 v150, s62, v158
	v_add_u32_e32 v154, s64, v158
	ds_read_b128 v[138:141], v150
	ds_read_b128 v[142:145], v150 offset:1024
	ds_read_b128 v[146:149], v150 offset:2048
	ds_read_b128 v[150:153], v150 offset:3072
	ds_read_b128 v[160:163], v154
	ds_read_b128 v[164:167], v154 offset:1024
	ds_read_b128 v[168:171], v154 offset:2048
	ds_read_b128 v[172:175], v154 offset:3072
	v_lshl_add_u64 v[154:155], s[42:43], 0, v[134:135]
	s_add_i32 m0, s3, 0xc000
	ds_read_b128 v[176:179], v159
	ds_read_b128 v[180:183], v159 offset:1024
	ds_read_b128 v[184:187], v159 offset:2048
	ds_read_b128 v[188:191], v159 offset:3072
	ds_read_b128 v[200:203], v159 offset:4096
	ds_read_b128 v[204:207], v159 offset:5120
	ds_read_b128 v[208:211], v159 offset:6144
	ds_read_b128 v[212:215], v159 offset:7168
	global_load_lds_dwordx4 v[154:155], off
	v_lshl_add_u64 v[154:155], s[42:43], 0, v[136:137]
	s_add_i32 m0, s3, 0xe000
	s_nop 0
	global_load_lds_dwordx4 v[154:155], off
	s_waitcnt vmcnt(8) lgkmcnt(0)
	s_barrier
	s_setprio 1
	v_mfma_f32_16x16x32_bf16 v[124:127], v[138:141], v[176:179], v[124:127]
	v_mfma_f32_16x16x32_bf16 v[120:123], v[146:149], v[176:179], v[120:123]
	v_mfma_f32_16x16x32_bf16 v[108:111], v[138:141], v[184:187], v[108:111]
	v_mfma_f32_16x16x32_bf16 v[104:107], v[146:149], v[184:187], v[104:107]
	v_mfma_f32_16x16x32_bf16 v[92:95], v[138:141], v[200:203], v[92:95]
	v_mfma_f32_16x16x32_bf16 v[88:91], v[146:149], v[200:203], v[88:91]
	v_mfma_f32_16x16x32_bf16 v[76:79], v[138:141], v[208:211], v[76:79]
	v_mfma_f32_16x16x32_bf16 v[72:75], v[146:149], v[208:211], v[72:75]
	v_mfma_f32_16x16x32_bf16 v[124:127], v[142:145], v[180:183], v[124:127]
	v_mfma_f32_16x16x32_bf16 v[120:123], v[150:153], v[180:183], v[120:123]
	v_mfma_f32_16x16x32_bf16 v[108:111], v[142:145], v[188:191], v[108:111]
	v_mfma_f32_16x16x32_bf16 v[104:107], v[150:153], v[188:191], v[104:107]
	v_mfma_f32_16x16x32_bf16 v[92:95], v[142:145], v[204:207], v[92:95]
	v_mfma_f32_16x16x32_bf16 v[88:91], v[150:153], v[204:207], v[88:91]
	v_mfma_f32_16x16x32_bf16 v[76:79], v[142:145], v[212:215], v[76:79]
	v_mfma_f32_16x16x32_bf16 v[72:75], v[150:153], v[212:215], v[72:75]
	v_mfma_f32_16x16x32_bf16 v[112:115], v[160:163], v[176:179], v[112:115]
	v_mfma_f32_16x16x32_bf16 v[116:119], v[168:171], v[176:179], v[116:119]
	v_mfma_f32_16x16x32_bf16 v[100:103], v[160:163], v[184:187], v[100:103]
	v_mfma_f32_16x16x32_bf16 v[96:99], v[168:171], v[184:187], v[96:99]
	v_mfma_f32_16x16x32_bf16 v[84:87], v[160:163], v[200:203], v[84:87]
	v_mfma_f32_16x16x32_bf16 v[80:83], v[168:171], v[200:203], v[80:83]
	v_mfma_f32_16x16x32_bf16 v[68:71], v[160:163], v[208:211], v[68:71]
	v_mfma_f32_16x16x32_bf16 v[64:67], v[168:171], v[208:211], v[64:67]
	v_mfma_f32_16x16x32_bf16 v[112:115], v[164:167], v[180:183], v[112:115]
	v_mfma_f32_16x16x32_bf16 v[116:119], v[172:175], v[180:183], v[116:119]
	v_mfma_f32_16x16x32_bf16 v[100:103], v[164:167], v[188:191], v[100:103]
	v_mfma_f32_16x16x32_bf16 v[96:99], v[172:175], v[188:191], v[96:99]
	v_mfma_f32_16x16x32_bf16 v[84:87], v[164:167], v[204:207], v[84:87]
	v_mfma_f32_16x16x32_bf16 v[80:83], v[172:175], v[204:207], v[80:83]
	v_mfma_f32_16x16x32_bf16 v[68:71], v[164:167], v[212:215], v[68:71]
	v_mfma_f32_16x16x32_bf16 v[64:67], v[172:175], v[212:215], v[64:67]
	s_setprio 0
	s_barrier
	s_add_i32 s62, s62, s2
	v_lshl_add_u64 v[154:155], s[46:47], 0, v[194:195]
	s_mov_b32 m0, s62
	ds_read_b128 v[176:179], v159 offset:16384
	ds_read_b128 v[180:183], v159 offset:17408
	ds_read_b128 v[184:187], v159 offset:18432
	ds_read_b128 v[188:191], v159 offset:19456
	ds_read_b128 v[200:203], v159 offset:20480
	ds_read_b128 v[204:207], v159 offset:21504
	ds_read_b128 v[208:211], v159 offset:22528
	ds_read_b128 v[212:215], v159 offset:23552
	global_load_lds_dwordx4 v[154:155], off
	s_add_i32 m0, s62, 0x2000
	s_add_u32 s62, s46, 0x40000
	v_lshl_add_u64 v[192:193], s[46:47], 0, v[132:133]
	s_addc_u32 s63, s47, 0
	s_add_i32 s64, s64, s2
	global_load_lds_dwordx4 v[192:193], off
	v_lshl_add_u64 v[228:229], s[62:63], 0, v[194:195]
	s_mov_b32 m0, s64
	v_lshl_add_u64 v[230:231], s[48:49], 0, v[130:131]
	global_load_lds_dwordx4 v[228:229], off
	v_lshl_add_u64 v[228:229], s[62:63], 0, v[132:133]
	s_add_i32 m0, s64, 0x2000
	s_nop 0
	global_load_lds_dwordx4 v[228:229], off
	v_lshl_add_u64 v[228:229], s[48:49], 0, v[128:129]
	s_mov_b32 m0, s3
	s_nop 0
	global_load_lds_dwordx4 v[228:229], off
	s_mov_b32 m0, s8
	s_nop 0
	global_load_lds_dwordx4 v[230:231], off
	s_waitcnt vmcnt(8) lgkmcnt(0)
	s_barrier
; #define PG8_STAGE(bufoff, gbase, voff) do { _Pragma("unroll") for (int _i = 0; _i < 2; ++_i) \
;         __builtin_amdgcn_global_load_lds((const unsigned*)((const char*)(gbase) + (voff)[_i]), (PG8_LAS unsigned*)(lds + (bufoff) + ldsw + _i * 8192), 16, 0, 0); } while (0)
; #define PG8_LDA(dst, b, h) do { _Pragma("unroll") for (int m = 0; m < 4; ++m) _Pragma("unroll") for (int k = 0; k < 2; ++k) dst[m][k] = *(const PG8_LAS bf16x8*)(lds + PG8_SA(b, h) + aoff + m * 2048 + k * 1024); } while (0)
; #define PG8_LDB(dst, b, h) do { _Pragma("unroll") for (int n = 0; n < 2; ++n) _Pragma("unroll") for (int k = 0; k < 2; ++k) dst[n][k] = *(const PG8_LAS bf16x8*)(lds + PG8_SB(b, h) + boff + n * 2048 + k * 1024); } while (0)
; #define PG8_MMA(ai, bj, At, Bt) do { __builtin_amdgcn_s_setprio(1); _Pragma("unroll") for (int m = 0; m < 4; ++m) _Pragma("unroll") for (int n = 0; n < 2; ++n) _Pragma("unroll") for (int k = 0; k < 2; ++k) \
;         acc[ai][bj][m][n] = __builtin_amdgcn_mfma_f32_16x16x32_bf16(Bt[n][k], At[m][k], acc[ai][bj][m][n], 0, 0, 0); __builtin_amdgcn_s_setprio(0); } while (0)
; #define PG8_WAIT_V(n) asm volatile("s_waitcnt vmcnt(" #n ")" ::: "memory")
; #define PG8_WAIT_L(n) asm volatile("s_waitcnt lgkmcnt(" #n ")" ::: "memory")
; #define PG8_BAR __builtin_amdgcn_s_barrier()
; #define PG8_SCHED __builtin_amdgcn_sched_barrier(0)
; template <class Epi, class Sched, bool ALIGN_EPI = false, bool SP2 = false>
; __device__ __forceinline__ void gemm_phase(PG8_LAS unsigned char* lds, const Gemm g, const Sched& S, const Epi& E) {
;     ...
;             PG8_WAIT_V(8); PG8_WAIT_L(0); PG8_BAR; PG8_MMA(1, 0, At, B0); PG8_MMA(1, 1, At, B1); PG8_BAR; PG8_SCHED;
;             PG8_LDB(B0, 1, 0); PG8_LDB(B1, 1, 1); PG8_SCHED; PG8_LDA(At, 1, 0); PG8_STAGE(PG8_SA(0, 1), a2 + hstepA, voffA);
;             PG8_WAIT_V(8); PG8_WAIT_L(0); PG8_BAR; PG8_MMA(0, 0, At, B0); PG8_MMA(0, 1, At, B1); PG8_BAR; PG8_SCHED;
	s_setprio 1
	v_mfma_f32_16x16x32_bf16 v[60:63], v[138:141], v[176:179], v[60:63]
	v_mfma_f32_16x16x32_bf16 v[56:59], v[146:149], v[176:179], v[56:59]
	v_mfma_f32_16x16x32_bf16 v[44:47], v[138:141], v[184:187], v[44:47]
	v_mfma_f32_16x16x32_bf16 v[40:43], v[146:149], v[184:187], v[40:43]
	v_mfma_f32_16x16x32_bf16 v[28:31], v[138:141], v[200:203], v[28:31]
	v_mfma_f32_16x16x32_bf16 v[24:27], v[146:149], v[200:203], v[24:27]
	v_mfma_f32_16x16x32_bf16 v[12:15], v[138:141], v[208:211], v[12:15]
	v_mfma_f32_16x16x32_bf16 v[8:11], v[146:149], v[208:211], v[8:11]
	v_mfma_f32_16x16x32_bf16 v[60:63], v[142:145], v[180:183], v[60:63]
	v_mfma_f32_16x16x32_bf16 v[56:59], v[150:153], v[180:183], v[56:59]
	v_mfma_f32_16x16x32_bf16 v[44:47], v[142:145], v[188:191], v[44:47]
	v_mfma_f32_16x16x32_bf16 v[40:43], v[150:153], v[188:191], v[40:43]
	v_mfma_f32_16x16x32_bf16 v[28:31], v[142:145], v[204:207], v[28:31]
	v_mfma_f32_16x16x32_bf16 v[24:27], v[150:153], v[204:207], v[24:27]
	v_mfma_f32_16x16x32_bf16 v[12:15], v[142:145], v[212:215], v[12:15]
	v_mfma_f32_16x16x32_bf16 v[8:11], v[150:153], v[212:215], v[8:11]
	v_mfma_f32_16x16x32_bf16 v[52:55], v[160:163], v[176:179], v[52:55]
	v_mfma_f32_16x16x32_bf16 v[48:51], v[168:171], v[176:179], v[48:51]
	v_mfma_f32_16x16x32_bf16 v[36:39], v[160:163], v[184:187], v[36:39]
	v_mfma_f32_16x16x32_bf16 v[32:35], v[168:171], v[184:187], v[32:35]
	v_mfma_f32_16x16x32_bf16 v[20:23], v[160:163], v[200:203], v[20:23]
	v_mfma_f32_16x16x32_bf16 v[16:19], v[168:171], v[200:203], v[16:19]
	v_mfma_f32_16x16x32_bf16 v[4:7], v[160:163], v[208:211], v[4:7]
	v_mfma_f32_16x16x32_bf16 v[0:3], v[168:171], v[208:211], v[0:3]
	v_mfma_f32_16x16x32_bf16 v[52:55], v[164:167], v[180:183], v[52:55]
	v_mfma_f32_16x16x32_bf16 v[48:51], v[172:175], v[180:183], v[48:51]
	v_mfma_f32_16x16x32_bf16 v[36:39], v[164:167], v[188:191], v[36:39]
	v_mfma_f32_16x16x32_bf16 v[32:35], v[172:175], v[188:191], v[32:35]
	v_mfma_f32_16x16x32_bf16 v[20:23], v[164:167], v[204:207], v[20:23]
	v_mfma_f32_16x16x32_bf16 v[16:19], v[172:175], v[204:207], v[16:19]
	v_mfma_f32_16x16x32_bf16 v[4:7], v[164:167], v[212:215], v[4:7]
	v_mfma_f32_16x16x32_bf16 v[0:3], v[172:175], v[212:215], v[0:3]
	s_setprio 0
	s_barrier
	s_add_i32 s62, 0, 0x18000
	s_add_i32 s63, 0, 0x1c000
	v_add_u32_e32 v150, s62, v158
	v_add_u32_e32 v172, s63, v158
	ds_read_b128 v[138:141], v150
	ds_read_b128 v[142:145], v150 offset:1024
	ds_read_b128 v[146:149], v150 offset:2048
	ds_read_b128 v[150:153], v150 offset:3072
	ds_read_b128 v[160:163], v172
	ds_read_b128 v[164:167], v172 offset:1024
	ds_read_b128 v[168:171], v172 offset:2048
	ds_read_b128 v[172:175], v172 offset:3072
	s_add_u32 s48, s48, 0x40000
	s_addc_u32 s49, s49, 0
	s_mov_b32 m0, s9
	v_lshl_add_u64 v[232:233], s[48:49], 0, v[128:129]
	ds_read_b128 v[176:179], v159 offset:32768
	ds_read_b128 v[180:183], v159 offset:33792
	ds_read_b128 v[184:187], v159 offset:34816
	ds_read_b128 v[188:191], v159 offset:35840
	ds_read_b128 v[200:203], v159 offset:36864
	ds_read_b128 v[204:207], v159 offset:37888
	ds_read_b128 v[208:211], v159 offset:38912
	ds_read_b128 v[212:215], v159 offset:39936
	global_load_lds_dwordx4 v[232:233], off
	v_lshl_add_u64 v[232:233], s[48:49], 0, v[130:131]
	s_mov_b32 m0, s10
	s_nop 0
	global_load_lds_dwordx4 v[232:233], off
	s_waitcnt vmcnt(8) lgkmcnt(0)
	s_barrier
	s_setprio 1
	v_mfma_f32_16x16x32_bf16 v[124:127], v[138:141], v[176:179], v[124:127]
	v_mfma_f32_16x16x32_bf16 v[120:123], v[146:149], v[176:179], v[120:123]
	v_mfma_f32_16x16x32_bf16 v[108:111], v[138:141], v[184:187], v[108:111]
	v_mfma_f32_16x16x32_bf16 v[104:107], v[146:149], v[184:187], v[104:107]
	v_mfma_f32_16x16x32_bf16 v[92:95], v[138:141], v[200:203], v[92:95]
	v_mfma_f32_16x16x32_bf16 v[88:91], v[146:149], v[200:203], v[88:91]
	v_mfma_f32_16x16x32_bf16 v[76:79], v[138:141], v[208:211], v[76:79]
	v_mfma_f32_16x16x32_bf16 v[72:75], v[146:149], v[208:211], v[72:75]
	v_mfma_f32_16x16x32_bf16 v[124:127], v[142:145], v[180:183], v[124:127]
	v_mfma_f32_16x16x32_bf16 v[120:123], v[150:153], v[180:183], v[120:123]
	v_mfma_f32_16x16x32_bf16 v[108:111], v[142:145], v[188:191], v[108:111]
	v_mfma_f32_16x16x32_bf16 v[104:107], v[150:153], v[188:191], v[104:107]
	v_mfma_f32_16x16x32_bf16 v[92:95], v[142:145], v[204:207], v[92:95]
	v_mfma_f32_16x16x32_bf16 v[88:91], v[150:153], v[204:207], v[88:91]
	v_mfma_f32_16x16x32_bf16 v[76:79], v[142:145], v[212:215], v[76:79]
	v_mfma_f32_16x16x32_bf16 v[72:75], v[150:153], v[212:215], v[72:75]
	v_mfma_f32_16x16x32_bf16 v[112:115], v[160:163], v[176:179], v[112:115]
	v_mfma_f32_16x16x32_bf16 v[116:119], v[168:171], v[176:179], v[116:119]
	v_mfma_f32_16x16x32_bf16 v[100:103], v[160:163], v[184:187], v[100:103]
	v_mfma_f32_16x16x32_bf16 v[96:99], v[168:171], v[184:187], v[96:99]
	v_mfma_f32_16x16x32_bf16 v[84:87], v[160:163], v[200:203], v[84:87]
	v_mfma_f32_16x16x32_bf16 v[80:83], v[168:171], v[200:203], v[80:83]
	v_mfma_f32_16x16x32_bf16 v[68:71], v[160:163], v[208:211], v[68:71]
	v_mfma_f32_16x16x32_bf16 v[64:67], v[168:171], v[208:211], v[64:67]
	v_mfma_f32_16x16x32_bf16 v[112:115], v[164:167], v[180:183], v[112:115]
	v_mfma_f32_16x16x32_bf16 v[116:119], v[172:175], v[180:183], v[116:119]
	v_mfma_f32_16x16x32_bf16 v[100:103], v[164:167], v[188:191], v[100:103]
	v_mfma_f32_16x16x32_bf16 v[96:99], v[172:175], v[188:191], v[96:99]
	v_mfma_f32_16x16x32_bf16 v[84:87], v[164:167], v[204:207], v[84:87]
	v_mfma_f32_16x16x32_bf16 v[80:83], v[172:175], v[204:207], v[80:83]
	v_mfma_f32_16x16x32_bf16 v[68:71], v[164:167], v[212:215], v[68:71]
	v_mfma_f32_16x16x32_bf16 v[64:67], v[172:175], v[212:215], v[64:67]
	s_setprio 0
	s_barrier
; #define PG8_STAGE(bufoff, gbase, voff) do { _Pragma("unroll") for (int _i = 0; _i < 2; ++_i) \
;         __builtin_amdgcn_global_load_lds((const unsigned*)((const char*)(gbase) + (voff)[_i]), (PG8_LAS unsigned*)(lds + (bufoff) + ldsw + _i * 8192), 16, 0, 0); } while (0)
; #define PG8_LDA(dst, b, h) do { _Pragma("unroll") for (int m = 0; m < 4; ++m) _Pragma("unroll") for (int k = 0; k < 2; ++k) dst[m][k] = *(const PG8_LAS bf16x8*)(lds + PG8_SA(b, h) + aoff + m * 2048 + k * 1024); } while (0)
; #define PG8_MMA(ai, bj, At, Bt) do { __builtin_amdgcn_s_setprio(1); _Pragma("unroll") for (int m = 0; m < 4; ++m) _Pragma("unroll") for (int n = 0; n < 2; ++n) _Pragma("unroll") for (int k = 0; k < 2; ++k) \
;         acc[ai][bj][m][n] = __builtin_amdgcn_mfma_f32_16x16x32_bf16(Bt[n][k], At[m][k], acc[ai][bj][m][n], 0, 0, 0); __builtin_amdgcn_s_setprio(0); } while (0)
; #define PG8_WAIT_V(n) asm volatile("s_waitcnt vmcnt(" #n ")" ::: "memory")
; #define PG8_WAIT_L(n) asm volatile("s_waitcnt lgkmcnt(" #n ")" ::: "memory")
; #define PG8_BAR __builtin_amdgcn_s_barrier()
; #define PG8_SCHED __builtin_amdgcn_sched_barrier(0)
; template <class Epi, class Sched, bool ALIGN_EPI = false, bool SP2 = false>
; __device__ __forceinline__ void gemm_phase(PG8_LAS unsigned char* lds, const Gemm g, const Sched& S, const Epi& E) {
;     ...
;             PG8_LDA(At, 1, 1); PG8_STAGE(PG8_SB(1, 0), b3, voffB); PG8_STAGE(PG8_SB(1, 1), b3 + hstepB, voffB); PG8_STAGE(PG8_SA(1, 0), a3, voffA);
;             PG8_WAIT_V(8); PG8_WAIT_L(0); PG8_BAR; PG8_MMA(1, 0, At, B0); PG8_MMA(1, 1, At, B1); PG8_BAR; PG8_SCHED;
	s_add_i32 s48, s62, s2
	v_lshl_add_u64 v[154:155], v[154:155], 0, s[26:27]
	s_mov_b32 m0, s48
	ds_read_b128 v[176:179], v159 offset:49152
	ds_read_b128 v[180:183], v159 offset:50176
	ds_read_b128 v[184:187], v159 offset:51200
	ds_read_b128 v[188:191], v159 offset:52224
	ds_read_b128 v[200:203], v159 offset:53248
	ds_read_b128 v[204:207], v159 offset:54272
	ds_read_b128 v[208:211], v159 offset:55296
	ds_read_b128 v[212:215], v159 offset:56320
	global_load_lds_dwordx4 v[154:155], off
	s_add_i32 m0, s48, 0x2000
	s_add_u32 s46, s46, 0x40080
	v_lshl_add_u64 v[154:155], v[192:193], 0, s[26:27]
	s_addc_u32 s47, s47, 0
	s_add_i32 s48, s63, s2
	global_load_lds_dwordx4 v[154:155], off
	v_lshl_add_u64 v[154:155], s[46:47], 0, v[194:195]
	s_mov_b32 m0, s48
	s_nop 0
	global_load_lds_dwordx4 v[154:155], off
	v_lshl_add_u64 v[154:155], s[46:47], 0, v[132:133]
	s_add_i32 m0, s48, 0x2000
	s_nop 0
	global_load_lds_dwordx4 v[154:155], off
	v_lshl_add_u64 v[154:155], v[228:229], 0, s[26:27]
	s_mov_b32 m0, s14
	s_nop 0
	global_load_lds_dwordx4 v[154:155], off
	v_lshl_add_u64 v[154:155], v[230:231], 0, s[26:27]
	s_mov_b32 m0, s15
	s_nop 0
	global_load_lds_dwordx4 v[154:155], off
	s_waitcnt vmcnt(8) lgkmcnt(0)
	s_barrier
	s_setprio 1
	v_mfma_f32_16x16x32_bf16 v[60:63], v[138:141], v[176:179], v[60:63]
	v_mfma_f32_16x16x32_bf16 v[56:59], v[146:149], v[176:179], v[56:59]
	v_mfma_f32_16x16x32_bf16 v[44:47], v[138:141], v[184:187], v[44:47]
	v_mfma_f32_16x16x32_bf16 v[40:43], v[146:149], v[184:187], v[40:43]
	v_mfma_f32_16x16x32_bf16 v[28:31], v[138:141], v[200:203], v[28:31]
	v_mfma_f32_16x16x32_bf16 v[24:27], v[146:149], v[200:203], v[24:27]
	v_mfma_f32_16x16x32_bf16 v[12:15], v[138:141], v[208:211], v[12:15]
	v_mfma_f32_16x16x32_bf16 v[8:11], v[146:149], v[208:211], v[8:11]
	v_mfma_f32_16x16x32_bf16 v[60:63], v[142:145], v[180:183], v[60:63]
	v_mfma_f32_16x16x32_bf16 v[56:59], v[150:153], v[180:183], v[56:59]
	v_mfma_f32_16x16x32_bf16 v[44:47], v[142:145], v[188:191], v[44:47]
	v_mfma_f32_16x16x32_bf16 v[40:43], v[150:153], v[188:191], v[40:43]
	v_mfma_f32_16x16x32_bf16 v[28:31], v[142:145], v[204:207], v[28:31]
	v_mfma_f32_16x16x32_bf16 v[24:27], v[150:153], v[204:207], v[24:27]
	v_mfma_f32_16x16x32_bf16 v[12:15], v[142:145], v[212:215], v[12:15]
	v_mfma_f32_16x16x32_bf16 v[8:11], v[150:153], v[212:215], v[8:11]
	v_mfma_f32_16x16x32_bf16 v[52:55], v[160:163], v[176:179], v[52:55]
	v_mfma_f32_16x16x32_bf16 v[48:51], v[168:171], v[176:179], v[48:51]
	v_mfma_f32_16x16x32_bf16 v[36:39], v[160:163], v[184:187], v[36:39]
	v_mfma_f32_16x16x32_bf16 v[32:35], v[168:171], v[184:187], v[32:35]
	v_mfma_f32_16x16x32_bf16 v[20:23], v[160:163], v[200:203], v[20:23]
	v_mfma_f32_16x16x32_bf16 v[16:19], v[168:171], v[200:203], v[16:19]
	v_mfma_f32_16x16x32_bf16 v[4:7], v[160:163], v[208:211], v[4:7]
	v_mfma_f32_16x16x32_bf16 v[0:3], v[168:171], v[208:211], v[0:3]
	v_mfma_f32_16x16x32_bf16 v[52:55], v[164:167], v[180:183], v[52:55]
	v_mfma_f32_16x16x32_bf16 v[48:51], v[172:175], v[180:183], v[48:51]
	v_mfma_f32_16x16x32_bf16 v[36:39], v[164:167], v[188:191], v[36:39]
	v_mfma_f32_16x16x32_bf16 v[32:35], v[172:175], v[188:191], v[32:35]
	v_mfma_f32_16x16x32_bf16 v[20:23], v[164:167], v[204:207], v[20:23]
	v_mfma_f32_16x16x32_bf16 v[16:19], v[172:175], v[204:207], v[16:19]
	v_mfma_f32_16x16x32_bf16 v[4:7], v[164:167], v[212:215], v[4:7]
	v_mfma_f32_16x16x32_bf16 v[0:3], v[172:175], v[212:215], v[0:3]
	s_setprio 0
	s_barrier
	s_add_u32 s42, s42, 0x100
	s_addc_u32 s43, s43, 0
	s_add_u32 s55, s55, 0x100
	s_addc_u32 s58, s58, 0
	s_cmp_ge_i32 s59, s11
	s_mov_b32 s48, s59
	s_cbranch_scc0 .LBB0_301
	s_and_b64 vcc, exec, s[76:77]
	s_cbranch_vccz .LBB0_304

; #define PG8_STAGE(bufoff, gbase, voff) do { _Pragma("unroll") for (int _i = 0; _i < 2; ++_i) \
;         __builtin_amdgcn_global_load_lds((const unsigned*)((const char*)(gbase) + (voff)[_i]), (PG8_LAS unsigned*)(lds + (bufoff) + ldsw + _i * 8192), 16, 0, 0); } while (0)
; #define PG8_LDA(dst, b, h) do { _Pragma("unroll") for (int m = 0; m < 4; ++m) _Pragma("unroll") for (int k = 0; k < 2; ++k) dst[m][k] = *(const PG8_LAS bf16x8*)(lds + PG8_SA(b, h) + aoff + m * 2048 + k * 1024); } while (0)
; #define PG8_LDB(dst, b, h) do { _Pragma("unroll") for (int n = 0; n < 2; ++n) _Pragma("unroll") for (int k = 0; k < 2; ++k) dst[n][k] = *(const PG8_LAS bf16x8*)(lds + PG8_SB(b, h) + boff + n * 2048 + k * 1024); } while (0)
; #define PG8_MMA(ai, bj, At, Bt) do { __builtin_amdgcn_s_setprio(1); _Pragma("unroll") for (int m = 0; m < 4; ++m) _Pragma("unroll") for (int n = 0; n < 2; ++n) _Pragma("unroll") for (int k = 0; k < 2; ++k) \
;         acc[ai][bj][m][n] = __builtin_amdgcn_mfma_f32_16x16x32_bf16(Bt[n][k], At[m][k], acc[ai][bj][m][n], 0, 0, 0); __builtin_amdgcn_s_setprio(0); } while (0)
; #define PG8_WAIT_V(n) asm volatile("s_waitcnt vmcnt(" #n ")" ::: "memory")
; #define PG8_WAIT_L(n) asm volatile("s_waitcnt lgkmcnt(" #n ")" ::: "memory")
; #define PG8_BAR __builtin_amdgcn_s_barrier()
; #define PG8_SCHED __builtin_amdgcn_sched_barrier(0)
; template <class Epi, class Sched, bool ALIGN_EPI = false, bool SP2 = false>
; __device__ __forceinline__ void gemm_phase(PG8_LAS unsigned char* lds, const Gemm g, const Sched& S, const Epi& E) {
;     ...
;             const char* a2 = last ? nA : cA + (size_t)(t + 2) * kstep; const char* b2 = last ? nB : cB + (size_t)(t + 2) * kstep;
;             const char* a3 = a2 + kstep; const char* b3 = b2 + kstep;
;             if (last && has_next) S.a_ready(nxt);
;             if constexpr (SP2) {
;             PG8_LDB(B0, 0, 0); PG8_LDB(B1, 0, 1); PG8_SCHED; PG8_LDA(At, 0, 0); PG8_STAGE(PG8_SA(1, 1), a1 + hstepA, voffA);
;             PG8_WAIT_V(8); PG8_WAIT_L(0); PG8_BAR; PG8_MMA(0, 0, At, B0); PG8_MMA(0, 1, At, B1); PG8_BAR; PG8_SCHED;
;             PG8_LDA(At, 0, 1); PG8_STAGE(PG8_SB(0, 0), b2, voffB); PG8_STAGE(PG8_SB(0, 1), b2 + hstepB, voffB); PG8_STAGE(PG8_SA(0, 0), a2, voffA);
;             PG8_WAIT_V(8); PG8_WAIT_L(0); PG8_BAR; PG8_MMA(1, 0, At, B0); PG8_MMA(1, 1, At, B1); PG8_BAR; PG8_SCHED;
.LBB0_502:
	s_add_i32 s48, s44, 2
	s_add_u32 s45, s42, 0xfffe0080
	s_addc_u32 s46, s43, -1
	s_add_i32 s49, 0, 0x10000
	s_cmp_eq_u32 s58, s44
	s_cselect_b32 s47, s15, s46
	s_cselect_b32 s46, s16, s45
	v_add_u32_e32 v150, s49, v154
	s_cselect_b32 s45, s17, s41
	s_cselect_b32 s44, s33, s35
	s_add_i32 s62, 0, 0x14000
	ds_read_b128 v[138:141], v150
	ds_read_b128 v[142:145], v150 offset:1024
	ds_read_b128 v[146:149], v150 offset:2048
	ds_read_b128 v[156:159], v150 offset:3072
	v_add_u32_e32 v150, s62, v154
	ds_read_b128 v[160:163], v150
	ds_read_b128 v[164:167], v150 offset:1024
	ds_read_b128 v[168:171], v150 offset:2048
	ds_read_b128 v[172:175], v150 offset:3072
	v_lshl_add_u64 v[150:151], s[42:43], 0, v[134:135]
	s_add_i32 m0, s9, 0xc000
	ds_read_b128 v[176:179], v155
	ds_read_b128 v[180:183], v155 offset:1024
	ds_read_b128 v[184:187], v155 offset:2048
	ds_read_b128 v[188:191], v155 offset:3072
	ds_read_b128 v[200:203], v155 offset:4096
	ds_read_b128 v[204:207], v155 offset:5120
	ds_read_b128 v[208:211], v155 offset:6144
	ds_read_b128 v[212:215], v155 offset:7168
	global_load_lds_dwordx4 v[150:151], off
	v_lshl_add_u64 v[150:151], s[42:43], 0, v[136:137]
	s_add_i32 m0, s9, 0xe000
	s_nop 0
	global_load_lds_dwordx4 v[150:151], off
	s_waitcnt vmcnt(8) lgkmcnt(0)
	s_barrier
	s_setprio 1
	v_mfma_f32_16x16x32_bf16 v[120:123], v[138:141], v[176:179], v[120:123]
	v_mfma_f32_16x16x32_bf16 v[124:127], v[146:149], v[176:179], v[124:127]
	v_mfma_f32_16x16x32_bf16 v[108:111], v[138:141], v[184:187], v[108:111]
	v_mfma_f32_16x16x32_bf16 v[104:107], v[146:149], v[184:187], v[104:107]
	v_mfma_f32_16x16x32_bf16 v[92:95], v[138:141], v[200:203], v[92:95]
	v_mfma_f32_16x16x32_bf16 v[88:91], v[146:149], v[200:203], v[88:91]
	v_mfma_f32_16x16x32_bf16 v[76:79], v[138:141], v[208:211], v[76:79]
	v_mfma_f32_16x16x32_bf16 v[72:75], v[146:149], v[208:211], v[72:75]
	v_mfma_f32_16x16x32_bf16 v[120:123], v[142:145], v[180:183], v[120:123]
	v_mfma_f32_16x16x32_bf16 v[124:127], v[156:159], v[180:183], v[124:127]
	v_mfma_f32_16x16x32_bf16 v[108:111], v[142:145], v[188:191], v[108:111]
	v_mfma_f32_16x16x32_bf16 v[104:107], v[156:159], v[188:191], v[104:107]
	v_mfma_f32_16x16x32_bf16 v[92:95], v[142:145], v[204:207], v[92:95]
	v_mfma_f32_16x16x32_bf16 v[88:91], v[156:159], v[204:207], v[88:91]
	v_mfma_f32_16x16x32_bf16 v[76:79], v[142:145], v[212:215], v[76:79]
	v_mfma_f32_16x16x32_bf16 v[72:75], v[156:159], v[212:215], v[72:75]
	v_mfma_f32_16x16x32_bf16 v[116:119], v[160:163], v[176:179], v[116:119]
	v_mfma_f32_16x16x32_bf16 v[112:115], v[168:171], v[176:179], v[112:115]
	v_mfma_f32_16x16x32_bf16 v[100:103], v[160:163], v[184:187], v[100:103]
	v_mfma_f32_16x16x32_bf16 v[96:99], v[168:171], v[184:187], v[96:99]
	v_mfma_f32_16x16x32_bf16 v[84:87], v[160:163], v[200:203], v[84:87]
	v_mfma_f32_16x16x32_bf16 v[80:83], v[168:171], v[200:203], v[80:83]
	v_mfma_f32_16x16x32_bf16 v[68:71], v[160:163], v[208:211], v[68:71]
	v_mfma_f32_16x16x32_bf16 v[64:67], v[168:171], v[208:211], v[64:67]
	v_mfma_f32_16x16x32_bf16 v[116:119], v[164:167], v[180:183], v[116:119]
	v_mfma_f32_16x16x32_bf16 v[112:115], v[172:175], v[180:183], v[112:115]
	v_mfma_f32_16x16x32_bf16 v[100:103], v[164:167], v[188:191], v[100:103]
	v_mfma_f32_16x16x32_bf16 v[96:99], v[172:175], v[188:191], v[96:99]
	v_mfma_f32_16x16x32_bf16 v[84:87], v[164:167], v[204:207], v[84:87]
	v_mfma_f32_16x16x32_bf16 v[80:83], v[172:175], v[204:207], v[80:83]
	v_mfma_f32_16x16x32_bf16 v[68:71], v[164:167], v[212:215], v[68:71]
	v_mfma_f32_16x16x32_bf16 v[64:67], v[172:175], v[212:215], v[64:67]
	s_setprio 0
	s_barrier
	s_add_i32 s49, s49, s8
	v_lshl_add_u64 v[150:151], s[44:45], 0, v[194:195]
	s_mov_b32 m0, s49
	ds_read_b128 v[176:179], v155 offset:16384
	ds_read_b128 v[180:183], v155 offset:17408
	ds_read_b128 v[184:187], v155 offset:18432
	ds_read_b128 v[188:191], v155 offset:19456
	ds_read_b128 v[200:203], v155 offset:20480
	ds_read_b128 v[204:207], v155 offset:21504
	ds_read_b128 v[208:211], v155 offset:22528
	ds_read_b128 v[212:215], v155 offset:23552
	global_load_lds_dwordx4 v[150:151], off
	s_add_i32 m0, s49, 0x2000
	s_add_u32 s52, s44, 0x10000
	v_lshl_add_u64 v[192:193], s[44:45], 0, v[132:133]
	s_addc_u32 s53, s45, 0
	s_add_i32 s49, s62, s8
	global_load_lds_dwordx4 v[192:193], off
	v_lshl_add_u64 v[228:229], s[52:53], 0, v[194:195]
	s_mov_b32 m0, s49
	v_lshl_add_u64 v[230:231], s[46:47], 0, v[130:131]
	global_load_lds_dwordx4 v[228:229], off
	v_lshl_add_u64 v[228:229], s[52:53], 0, v[132:133]
	s_add_i32 m0, s49, 0x2000
	s_nop 0
	global_load_lds_dwordx4 v[228:229], off
	v_lshl_add_u64 v[228:229], s[46:47], 0, v[128:129]
	s_mov_b32 m0, s9
	s_nop 0
	global_load_lds_dwordx4 v[228:229], off
	s_mov_b32 m0, s28
	s_nop 0
	global_load_lds_dwordx4 v[230:231], off
	s_waitcnt vmcnt(8) lgkmcnt(0)
	s_barrier
; #define PG8_STAGE(bufoff, gbase, voff) do { _Pragma("unroll") for (int _i = 0; _i < 2; ++_i) \
;         __builtin_amdgcn_global_load_lds((const unsigned*)((const char*)(gbase) + (voff)[_i]), (PG8_LAS unsigned*)(lds + (bufoff) + ldsw + _i * 8192), 16, 0, 0); } while (0)
; #define PG8_LDA(dst, b, h) do { _Pragma("unroll") for (int m = 0; m < 4; ++m) _Pragma("unroll") for (int k = 0; k < 2; ++k) dst[m][k] = *(const PG8_LAS bf16x8*)(lds + PG8_SA(b, h) + aoff + m * 2048 + k * 1024); } while (0)
; #define PG8_LDB(dst, b, h) do { _Pragma("unroll") for (int n = 0; n < 2; ++n) _Pragma("unroll") for (int k = 0; k < 2; ++k) dst[n][k] = *(const PG8_LAS bf16x8*)(lds + PG8_SB(b, h) + boff + n * 2048 + k * 1024); } while (0)
; #define PG8_MMA(ai, bj, At, Bt) do { __builtin_amdgcn_s_setprio(1); _Pragma("unroll") for (int m = 0; m < 4; ++m) _Pragma("unroll") for (int n = 0; n < 2; ++n) _Pragma("unroll") for (int k = 0; k < 2; ++k) \
;         acc[ai][bj][m][n] = __builtin_amdgcn_mfma_f32_16x16x32_bf16(Bt[n][k], At[m][k], acc[ai][bj][m][n], 0, 0, 0); __builtin_amdgcn_s_setprio(0); } while (0)
; #define PG8_WAIT_V(n) asm volatile("s_waitcnt vmcnt(" #n ")" ::: "memory")
; #define PG8_WAIT_L(n) asm volatile("s_waitcnt lgkmcnt(" #n ")" ::: "memory")
; #define PG8_BAR __builtin_amdgcn_s_barrier()
; #define PG8_SCHED __builtin_amdgcn_sched_barrier(0)
; template <class Epi, class Sched, bool ALIGN_EPI = false, bool SP2 = false>
; __device__ __forceinline__ void gemm_phase(PG8_LAS unsigned char* lds, const Gemm g, const Sched& S, const Epi& E) {
;     ...
;             PG8_WAIT_V(8); PG8_WAIT_L(0); PG8_BAR; PG8_MMA(1, 0, At, B0); PG8_MMA(1, 1, At, B1); PG8_BAR; PG8_SCHED;
;             PG8_LDB(B0, 1, 0); PG8_LDB(B1, 1, 1); PG8_SCHED; PG8_LDA(At, 1, 0); PG8_STAGE(PG8_SA(0, 1), a2 + hstepA, voffA);
;             PG8_WAIT_V(8); PG8_WAIT_L(0); PG8_BAR; PG8_MMA(0, 0, At, B0); PG8_MMA(0, 1, At, B1); PG8_BAR; PG8_SCHED;
	s_setprio 1
	v_mfma_f32_16x16x32_bf16 v[60:63], v[138:141], v[176:179], v[60:63]
	v_mfma_f32_16x16x32_bf16 v[56:59], v[146:149], v[176:179], v[56:59]
	v_mfma_f32_16x16x32_bf16 v[44:47], v[138:141], v[184:187], v[44:47]
	v_mfma_f32_16x16x32_bf16 v[40:43], v[146:149], v[184:187], v[40:43]
	v_mfma_f32_16x16x32_bf16 v[28:31], v[138:141], v[200:203], v[28:31]
	v_mfma_f32_16x16x32_bf16 v[24:27], v[146:149], v[200:203], v[24:27]
	v_mfma_f32_16x16x32_bf16 v[12:15], v[138:141], v[208:211], v[12:15]
	v_mfma_f32_16x16x32_bf16 v[8:11], v[146:149], v[208:211], v[8:11]
	v_mfma_f32_16x16x32_bf16 v[60:63], v[142:145], v[180:183], v[60:63]
	v_mfma_f32_16x16x32_bf16 v[56:59], v[156:159], v[180:183], v[56:59]
	v_mfma_f32_16x16x32_bf16 v[44:47], v[142:145], v[188:191], v[44:47]
	v_mfma_f32_16x16x32_bf16 v[40:43], v[156:159], v[188:191], v[40:43]
	v_mfma_f32_16x16x32_bf16 v[28:31], v[142:145], v[204:207], v[28:31]
	v_mfma_f32_16x16x32_bf16 v[24:27], v[156:159], v[204:207], v[24:27]
	v_mfma_f32_16x16x32_bf16 v[12:15], v[142:145], v[212:215], v[12:15]
	v_mfma_f32_16x16x32_bf16 v[8:11], v[156:159], v[212:215], v[8:11]
	v_mfma_f32_16x16x32_bf16 v[52:55], v[160:163], v[176:179], v[52:55]
	v_mfma_f32_16x16x32_bf16 v[48:51], v[168:171], v[176:179], v[48:51]
	v_mfma_f32_16x16x32_bf16 v[36:39], v[160:163], v[184:187], v[36:39]
	v_mfma_f32_16x16x32_bf16 v[32:35], v[168:171], v[184:187], v[32:35]
	v_mfma_f32_16x16x32_bf16 v[20:23], v[160:163], v[200:203], v[20:23]
	v_mfma_f32_16x16x32_bf16 v[16:19], v[168:171], v[200:203], v[16:19]
	v_mfma_f32_16x16x32_bf16 v[4:7], v[160:163], v[208:211], v[4:7]
	v_mfma_f32_16x16x32_bf16 v[0:3], v[168:171], v[208:211], v[0:3]
	v_mfma_f32_16x16x32_bf16 v[52:55], v[164:167], v[180:183], v[52:55]
	v_mfma_f32_16x16x32_bf16 v[48:51], v[172:175], v[180:183], v[48:51]
	v_mfma_f32_16x16x32_bf16 v[36:39], v[164:167], v[188:191], v[36:39]
	v_mfma_f32_16x16x32_bf16 v[32:35], v[172:175], v[188:191], v[32:35]
	v_mfma_f32_16x16x32_bf16 v[20:23], v[164:167], v[204:207], v[20:23]
	v_mfma_f32_16x16x32_bf16 v[16:19], v[172:175], v[204:207], v[16:19]
	v_mfma_f32_16x16x32_bf16 v[4:7], v[164:167], v[212:215], v[4:7]
	v_mfma_f32_16x16x32_bf16 v[0:3], v[172:175], v[212:215], v[0:3]
	s_setprio 0
	s_barrier
	s_add_i32 s49, 0, 0x18000
	s_add_i32 s52, 0, 0x1c000
	v_add_u32_e32 v156, s49, v154
	v_add_u32_e32 v172, s52, v154
	ds_read_b128 v[138:141], v156
	ds_read_b128 v[142:145], v156 offset:1024
	ds_read_b128 v[146:149], v156 offset:2048
	ds_read_b128 v[156:159], v156 offset:3072
	ds_read_b128 v[160:163], v172
	ds_read_b128 v[164:167], v172 offset:1024
	ds_read_b128 v[168:171], v172 offset:2048
	ds_read_b128 v[172:175], v172 offset:3072
	s_add_u32 s46, s46, 0x20000
	s_addc_u32 s47, s47, 0
	s_mov_b32 m0, s10
	v_lshl_add_u64 v[232:233], s[46:47], 0, v[128:129]
	ds_read_b128 v[176:179], v155 offset:32768
	ds_read_b128 v[180:183], v155 offset:33792
	ds_read_b128 v[184:187], v155 offset:34816
	ds_read_b128 v[188:191], v155 offset:35840
	ds_read_b128 v[200:203], v155 offset:36864
	ds_read_b128 v[204:207], v155 offset:37888
	ds_read_b128 v[208:211], v155 offset:38912
	ds_read_b128 v[212:215], v155 offset:39936
	global_load_lds_dwordx4 v[232:233], off
	v_lshl_add_u64 v[232:233], s[46:47], 0, v[130:131]
	s_mov_b32 m0, s11
	s_nop 0
	global_load_lds_dwordx4 v[232:233], off
	s_waitcnt vmcnt(8) lgkmcnt(0)
	s_barrier
	s_setprio 1
	v_mfma_f32_16x16x32_bf16 v[120:123], v[138:141], v[176:179], v[120:123]
	v_mfma_f32_16x16x32_bf16 v[124:127], v[146:149], v[176:179], v[124:127]
	v_mfma_f32_16x16x32_bf16 v[108:111], v[138:141], v[184:187], v[108:111]
	v_mfma_f32_16x16x32_bf16 v[104:107], v[146:149], v[184:187], v[104:107]
	v_mfma_f32_16x16x32_bf16 v[92:95], v[138:141], v[200:203], v[92:95]
	v_mfma_f32_16x16x32_bf16 v[88:91], v[146:149], v[200:203], v[88:91]
	v_mfma_f32_16x16x32_bf16 v[76:79], v[138:141], v[208:211], v[76:79]
	v_mfma_f32_16x16x32_bf16 v[72:75], v[146:149], v[208:211], v[72:75]
	v_mfma_f32_16x16x32_bf16 v[120:123], v[142:145], v[180:183], v[120:123]
	v_mfma_f32_16x16x32_bf16 v[124:127], v[156:159], v[180:183], v[124:127]
	v_mfma_f32_16x16x32_bf16 v[108:111], v[142:145], v[188:191], v[108:111]
	v_mfma_f32_16x16x32_bf16 v[104:107], v[156:159], v[188:191], v[104:107]
	v_mfma_f32_16x16x32_bf16 v[92:95], v[142:145], v[204:207], v[92:95]
	v_mfma_f32_16x16x32_bf16 v[88:91], v[156:159], v[204:207], v[88:91]
	v_mfma_f32_16x16x32_bf16 v[76:79], v[142:145], v[212:215], v[76:79]
	v_mfma_f32_16x16x32_bf16 v[72:75], v[156:159], v[212:215], v[72:75]
	v_mfma_f32_16x16x32_bf16 v[116:119], v[160:163], v[176:179], v[116:119]
	v_mfma_f32_16x16x32_bf16 v[112:115], v[168:171], v[176:179], v[112:115]
	v_mfma_f32_16x16x32_bf16 v[100:103], v[160:163], v[184:187], v[100:103]
	v_mfma_f32_16x16x32_bf16 v[96:99], v[168:171], v[184:187], v[96:99]
	v_mfma_f32_16x16x32_bf16 v[84:87], v[160:163], v[200:203], v[84:87]
	v_mfma_f32_16x16x32_bf16 v[80:83], v[168:171], v[200:203], v[80:83]
	v_mfma_f32_16x16x32_bf16 v[68:71], v[160:163], v[208:211], v[68:71]
	v_mfma_f32_16x16x32_bf16 v[64:67], v[168:171], v[208:211], v[64:67]
	v_mfma_f32_16x16x32_bf16 v[116:119], v[164:167], v[180:183], v[116:119]
	v_mfma_f32_16x16x32_bf16 v[112:115], v[172:175], v[180:183], v[112:115]
	v_mfma_f32_16x16x32_bf16 v[100:103], v[164:167], v[188:191], v[100:103]
	v_mfma_f32_16x16x32_bf16 v[96:99], v[172:175], v[188:191], v[96:99]
	v_mfma_f32_16x16x32_bf16 v[84:87], v[164:167], v[204:207], v[84:87]
	v_mfma_f32_16x16x32_bf16 v[80:83], v[172:175], v[204:207], v[80:83]
	v_mfma_f32_16x16x32_bf16 v[68:71], v[164:167], v[212:215], v[68:71]
	v_mfma_f32_16x16x32_bf16 v[64:67], v[172:175], v[212:215], v[64:67]
	s_setprio 0
	s_barrier
; #define PG8_STAGE(bufoff, gbase, voff) do { _Pragma("unroll") for (int _i = 0; _i < 2; ++_i) \
;         __builtin_amdgcn_global_load_lds((const unsigned*)((const char*)(gbase) + (voff)[_i]), (PG8_LAS unsigned*)(lds + (bufoff) + ldsw + _i * 8192), 16, 0, 0); } while (0)
; #define PG8_LDA(dst, b, h) do { _Pragma("unroll") for (int m = 0; m < 4; ++m) _Pragma("unroll") for (int k = 0; k < 2; ++k) dst[m][k] = *(const PG8_LAS bf16x8*)(lds + PG8_SA(b, h) + aoff + m * 2048 + k * 1024); } while (0)
; #define PG8_MMA(ai, bj, At, Bt) do { __builtin_amdgcn_s_setprio(1); _Pragma("unroll") for (int m = 0; m < 4; ++m) _Pragma("unroll") for (int n = 0; n < 2; ++n) _Pragma("unroll") for (int k = 0; k < 2; ++k) \
;         acc[ai][bj][m][n] = __builtin_amdgcn_mfma_f32_16x16x32_bf16(Bt[n][k], At[m][k], acc[ai][bj][m][n], 0, 0, 0); __builtin_amdgcn_s_setprio(0); } while (0)
; #define PG8_WAIT_V(n) asm volatile("s_waitcnt vmcnt(" #n ")" ::: "memory")
; #define PG8_WAIT_L(n) asm volatile("s_waitcnt lgkmcnt(" #n ")" ::: "memory")
; #define PG8_BAR __builtin_amdgcn_s_barrier()
; #define PG8_SCHED __builtin_amdgcn_sched_barrier(0)
; template <class Epi, class Sched, bool ALIGN_EPI = false, bool SP2 = false>
; __device__ __forceinline__ void gemm_phase(PG8_LAS unsigned char* lds, const Gemm g, const Sched& S, const Epi& E) {
;     ...
;             PG8_LDA(At, 1, 1); PG8_STAGE(PG8_SB(1, 0), b3, voffB); PG8_STAGE(PG8_SB(1, 1), b3 + hstepB, voffB); PG8_STAGE(PG8_SA(1, 0), a3, voffA);
;             PG8_WAIT_V(8); PG8_WAIT_L(0); PG8_BAR; PG8_MMA(1, 0, At, B0); PG8_MMA(1, 1, At, B1); PG8_BAR; PG8_SCHED;
	s_add_i32 s46, s49, s8
	v_lshl_add_u64 v[150:151], v[150:151], 0, s[26:27]
	s_mov_b32 m0, s46
	ds_read_b128 v[176:179], v155 offset:49152
	ds_read_b128 v[180:183], v155 offset:50176
	ds_read_b128 v[184:187], v155 offset:51200
	ds_read_b128 v[188:191], v155 offset:52224
	ds_read_b128 v[200:203], v155 offset:53248
	ds_read_b128 v[204:207], v155 offset:54272
	ds_read_b128 v[208:211], v155 offset:55296
	ds_read_b128 v[212:215], v155 offset:56320
	global_load_lds_dwordx4 v[150:151], off
	s_add_i32 m0, s46, 0x2000
	s_add_u32 s44, s44, 0x10080
	v_lshl_add_u64 v[150:151], v[192:193], 0, s[26:27]
	s_addc_u32 s45, s45, 0
	s_add_i32 s46, s52, s8
	global_load_lds_dwordx4 v[150:151], off
	v_lshl_add_u64 v[150:151], s[44:45], 0, v[194:195]
	s_mov_b32 m0, s46
	s_nop 0
	global_load_lds_dwordx4 v[150:151], off
	v_lshl_add_u64 v[150:151], s[44:45], 0, v[132:133]
	s_add_i32 m0, s46, 0x2000
	s_nop 0
	global_load_lds_dwordx4 v[150:151], off
	v_lshl_add_u64 v[150:151], v[228:229], 0, s[26:27]
	s_mov_b32 m0, s3
	s_nop 0
	global_load_lds_dwordx4 v[150:151], off
	v_lshl_add_u64 v[150:151], v[230:231], 0, s[26:27]
	s_mov_b32 m0, s55
	s_nop 0
	global_load_lds_dwordx4 v[150:151], off
	s_waitcnt vmcnt(8) lgkmcnt(0)
	s_barrier
	s_setprio 1
	v_mfma_f32_16x16x32_bf16 v[60:63], v[138:141], v[176:179], v[60:63]
	v_mfma_f32_16x16x32_bf16 v[56:59], v[146:149], v[176:179], v[56:59]
	v_mfma_f32_16x16x32_bf16 v[44:47], v[138:141], v[184:187], v[44:47]
	v_mfma_f32_16x16x32_bf16 v[40:43], v[146:149], v[184:187], v[40:43]
	v_mfma_f32_16x16x32_bf16 v[28:31], v[138:141], v[200:203], v[28:31]
	v_mfma_f32_16x16x32_bf16 v[24:27], v[146:149], v[200:203], v[24:27]
	v_mfma_f32_16x16x32_bf16 v[12:15], v[138:141], v[208:211], v[12:15]
	v_mfma_f32_16x16x32_bf16 v[8:11], v[146:149], v[208:211], v[8:11]
	v_mfma_f32_16x16x32_bf16 v[60:63], v[142:145], v[180:183], v[60:63]
	v_mfma_f32_16x16x32_bf16 v[56:59], v[156:159], v[180:183], v[56:59]
	v_mfma_f32_16x16x32_bf16 v[44:47], v[142:145], v[188:191], v[44:47]
	v_mfma_f32_16x16x32_bf16 v[40:43], v[156:159], v[188:191], v[40:43]
	v_mfma_f32_16x16x32_bf16 v[28:31], v[142:145], v[204:207], v[28:31]
	v_mfma_f32_16x16x32_bf16 v[24:27], v[156:159], v[204:207], v[24:27]
	v_mfma_f32_16x16x32_bf16 v[12:15], v[142:145], v[212:215], v[12:15]
	v_mfma_f32_16x16x32_bf16 v[8:11], v[156:159], v[212:215], v[8:11]
	v_mfma_f32_16x16x32_bf16 v[52:55], v[160:163], v[176:179], v[52:55]
	v_mfma_f32_16x16x32_bf16 v[48:51], v[168:171], v[176:179], v[48:51]
	v_mfma_f32_16x16x32_bf16 v[36:39], v[160:163], v[184:187], v[36:39]
	v_mfma_f32_16x16x32_bf16 v[32:35], v[168:171], v[184:187], v[32:35]
	v_mfma_f32_16x16x32_bf16 v[20:23], v[160:163], v[200:203], v[20:23]
	v_mfma_f32_16x16x32_bf16 v[16:19], v[168:171], v[200:203], v[16:19]
	v_mfma_f32_16x16x32_bf16 v[4:7], v[160:163], v[208:211], v[4:7]
	v_mfma_f32_16x16x32_bf16 v[0:3], v[168:171], v[208:211], v[0:3]
	v_mfma_f32_16x16x32_bf16 v[52:55], v[164:167], v[180:183], v[52:55]
	v_mfma_f32_16x16x32_bf16 v[48:51], v[172:175], v[180:183], v[48:51]
	v_mfma_f32_16x16x32_bf16 v[36:39], v[164:167], v[188:191], v[36:39]
	v_mfma_f32_16x16x32_bf16 v[32:35], v[172:175], v[188:191], v[32:35]
	v_mfma_f32_16x16x32_bf16 v[20:23], v[164:167], v[204:207], v[20:23]
	v_mfma_f32_16x16x32_bf16 v[16:19], v[172:175], v[204:207], v[16:19]
	v_mfma_f32_16x16x32_bf16 v[4:7], v[164:167], v[212:215], v[4:7]
	v_mfma_f32_16x16x32_bf16 v[0:3], v[172:175], v[212:215], v[0:3]
	s_setprio 0
	s_barrier
	s_add_u32 s42, s42, 0x100
	s_addc_u32 s43, s43, 0
	s_add_u32 s35, s35, 0x100
	s_addc_u32 s41, s41, 0
	s_cmp_ge_i32 s48, s13
	s_mov_b32 s44, s48
	s_cbranch_scc0 .LBB0_502

; #define PG8_STAGE(bufoff, gbase, voff) do { _Pragma("unroll") for (int _i = 0; _i < 2; ++_i) \
;         __builtin_amdgcn_global_load_lds((const unsigned*)((const char*)(gbase) + (voff)[_i]), (PG8_LAS unsigned*)(lds + (bufoff) + ldsw + _i * 8192), 16, 0, 0); } while (0)
; #define PG8_LDA(dst, b, h) do { _Pragma("unroll") for (int m = 0; m < 4; ++m) _Pragma("unroll") for (int k = 0; k < 2; ++k) dst[m][k] = *(const PG8_LAS bf16x8*)(lds + PG8_SA(b, h) + aoff + m * 2048 + k * 1024); } while (0)
; #define PG8_LDB(dst, b, h) do { _Pragma("unroll") for (int n = 0; n < 2; ++n) _Pragma("unroll") for (int k = 0; k < 2; ++k) dst[n][k] = *(const PG8_LAS bf16x8*)(lds + PG8_SB(b, h) + boff + n * 2048 + k * 1024); } while (0)
; #define PG8_MMA(ai, bj, At, Bt) do { __builtin_amdgcn_s_setprio(1); _Pragma("unroll") for (int m = 0; m < 4; ++m) _Pragma("unroll") for (int n = 0; n < 2; ++n) _Pragma("unroll") for (int k = 0; k < 2; ++k) \
;         acc[ai][bj][m][n] = __builtin_amdgcn_mfma_f32_16x16x32_bf16(Bt[n][k], At[m][k], acc[ai][bj][m][n], 0, 0, 0); __builtin_amdgcn_s_setprio(0); } while (0)
; #define PG8_WAIT_V(n) asm volatile("s_waitcnt vmcnt(" #n ")" ::: "memory")
; #define PG8_WAIT_L(n) asm volatile("s_waitcnt lgkmcnt(" #n ")" ::: "memory")
; #define PG8_BAR __builtin_amdgcn_s_barrier()
; #define PG8_SCHED __builtin_amdgcn_sched_barrier(0)
; template <class Epi, class Sched, bool ALIGN_EPI = false, bool SP2 = false>
; __device__ __forceinline__ void gemm_phase(PG8_LAS unsigned char* lds, const Gemm g, const Sched& S, const Epi& E) {
;     ...
;             const char* a2 = last ? nA : cA + (size_t)(t + 2) * kstep; const char* b2 = last ? nB : cB + (size_t)(t + 2) * kstep;
;             const char* a3 = a2 + kstep; const char* b3 = b2 + kstep;
;             if (last && has_next) S.a_ready(nxt);
;             if constexpr (SP2) {
;             PG8_LDB(B0, 0, 0); PG8_LDB(B1, 0, 1); PG8_SCHED; PG8_LDA(At, 0, 0); PG8_STAGE(PG8_SA(1, 1), a1 + hstepA, voffA);
;             PG8_WAIT_V(8); PG8_WAIT_L(0); PG8_BAR; PG8_MMA(0, 0, At, B0); PG8_MMA(0, 1, At, B1); PG8_BAR; PG8_SCHED;
;             PG8_LDA(At, 0, 1); PG8_STAGE(PG8_SB(0, 0), b2, voffB); PG8_STAGE(PG8_SB(0, 1), b2 + hstepB, voffB); PG8_STAGE(PG8_SA(0, 0), a2, voffA);
;             PG8_WAIT_V(8); PG8_WAIT_L(0); PG8_BAR; PG8_MMA(1, 0, At, B0); PG8_MMA(1, 1, At, B1); PG8_BAR; PG8_SCHED;
.LBB0_569:
	s_add_i32 s58, s55, 2
	s_add_u32 s59, s84, 0xfffe0080
	s_addc_u32 s62, s85, -1
	s_add_i32 s64, 0, 0x10000
	s_cmp_eq_u32 s15, s55
	s_cselect_b32 s87, s28, s62
	s_cselect_b32 s86, s29, s59
	s_cselect_b32 s63, s33, s53
	s_cselect_b32 s62, s47, s49
	s_add_i32 s55, 0, 0x14000
	v_add_u32_e32 v154, s64, v148
	v_add_u32_e32 v170, s55, v148
	ds_read_b128 v[138:141], v154
	ds_read_b128 v[142:145], v154 offset:1024
	ds_read_b128 v[150:153], v154 offset:2048
	ds_read_b128 v[154:157], v154 offset:3072
	ds_read_b128 v[158:161], v170
	ds_read_b128 v[162:165], v170 offset:1024
	ds_read_b128 v[166:169], v170 offset:2048
	ds_read_b128 v[170:173], v170 offset:3072
	v_lshl_add_u64 v[212:213], s[84:85], 0, v[134:135]
	s_add_i32 m0, s3, 0xc000
	ds_read_b128 v[174:177], v149
	ds_read_b128 v[178:181], v149 offset:1024
	ds_read_b128 v[182:185], v149 offset:2048
	ds_read_b128 v[186:189], v149 offset:3072
	ds_read_b128 v[190:193], v149 offset:4096
	ds_read_b128 v[200:203], v149 offset:5120
	ds_read_b128 v[204:207], v149 offset:6144
	ds_read_b128 v[208:211], v149 offset:7168
	global_load_lds_dwordx4 v[212:213], off
	v_lshl_add_u64 v[212:213], s[84:85], 0, v[136:137]
	s_add_i32 m0, s3, 0xe000
	s_nop 0
	global_load_lds_dwordx4 v[212:213], off
	s_waitcnt vmcnt(8) lgkmcnt(0)
	s_barrier
	s_setprio 1
	v_mfma_f32_16x16x32_bf16 v[124:127], v[138:141], v[174:177], v[124:127]
	v_mfma_f32_16x16x32_bf16 v[120:123], v[150:153], v[174:177], v[120:123]
	v_mfma_f32_16x16x32_bf16 v[108:111], v[138:141], v[182:185], v[108:111]
	v_mfma_f32_16x16x32_bf16 v[104:107], v[150:153], v[182:185], v[104:107]
	v_mfma_f32_16x16x32_bf16 v[92:95], v[138:141], v[190:193], v[92:95]
	v_mfma_f32_16x16x32_bf16 v[88:91], v[150:153], v[190:193], v[88:91]
	v_mfma_f32_16x16x32_bf16 v[76:79], v[138:141], v[204:207], v[76:79]
	v_mfma_f32_16x16x32_bf16 v[72:75], v[150:153], v[204:207], v[72:75]
	v_mfma_f32_16x16x32_bf16 v[124:127], v[142:145], v[178:181], v[124:127]
	v_mfma_f32_16x16x32_bf16 v[120:123], v[154:157], v[178:181], v[120:123]
	v_mfma_f32_16x16x32_bf16 v[108:111], v[142:145], v[186:189], v[108:111]
	v_mfma_f32_16x16x32_bf16 v[104:107], v[154:157], v[186:189], v[104:107]
	v_mfma_f32_16x16x32_bf16 v[92:95], v[142:145], v[200:203], v[92:95]
	v_mfma_f32_16x16x32_bf16 v[88:91], v[154:157], v[200:203], v[88:91]
	v_mfma_f32_16x16x32_bf16 v[76:79], v[142:145], v[208:211], v[76:79]
	v_mfma_f32_16x16x32_bf16 v[72:75], v[154:157], v[208:211], v[72:75]
	v_mfma_f32_16x16x32_bf16 v[116:119], v[158:161], v[174:177], v[116:119]
	v_mfma_f32_16x16x32_bf16 v[112:115], v[166:169], v[174:177], v[112:115]
	v_mfma_f32_16x16x32_bf16 v[100:103], v[158:161], v[182:185], v[100:103]
	v_mfma_f32_16x16x32_bf16 v[96:99], v[166:169], v[182:185], v[96:99]
	v_mfma_f32_16x16x32_bf16 v[84:87], v[158:161], v[190:193], v[84:87]
	v_mfma_f32_16x16x32_bf16 v[80:83], v[166:169], v[190:193], v[80:83]
	v_mfma_f32_16x16x32_bf16 v[68:71], v[158:161], v[204:207], v[68:71]
	v_mfma_f32_16x16x32_bf16 v[64:67], v[166:169], v[204:207], v[64:67]
	v_mfma_f32_16x16x32_bf16 v[116:119], v[162:165], v[178:181], v[116:119]
	v_mfma_f32_16x16x32_bf16 v[112:115], v[170:173], v[178:181], v[112:115]
	v_mfma_f32_16x16x32_bf16 v[100:103], v[162:165], v[186:189], v[100:103]
	v_mfma_f32_16x16x32_bf16 v[96:99], v[170:173], v[186:189], v[96:99]
	v_mfma_f32_16x16x32_bf16 v[84:87], v[162:165], v[200:203], v[84:87]
	v_mfma_f32_16x16x32_bf16 v[80:83], v[170:173], v[200:203], v[80:83]
	v_mfma_f32_16x16x32_bf16 v[68:71], v[162:165], v[208:211], v[68:71]
	v_mfma_f32_16x16x32_bf16 v[64:67], v[170:173], v[208:211], v[64:67]
	s_setprio 0
	s_barrier
	s_add_i32 s59, s64, s2
	v_lshl_add_u64 v[212:213], s[62:63], 0, v[194:195]
	s_mov_b32 m0, s59
	ds_read_b128 v[174:177], v149 offset:16384
	ds_read_b128 v[178:181], v149 offset:17408
	ds_read_b128 v[182:185], v149 offset:18432
	ds_read_b128 v[186:189], v149 offset:19456
	ds_read_b128 v[190:193], v149 offset:20480
	ds_read_b128 v[200:203], v149 offset:21504
	ds_read_b128 v[204:207], v149 offset:22528
	ds_read_b128 v[208:211], v149 offset:23552
	global_load_lds_dwordx4 v[212:213], off
	s_add_i32 m0, s59, 0x2000
	s_add_u32 s78, s62, 0x8000
	v_lshl_add_u64 v[214:215], s[62:63], 0, v[132:133]
	s_addc_u32 s79, s63, 0
	s_add_i32 s55, s55, s2
	global_load_lds_dwordx4 v[214:215], off
	v_lshl_add_u64 v[228:229], s[78:79], 0, v[194:195]
	s_mov_b32 m0, s55
	v_lshl_add_u64 v[230:231], s[86:87], 0, v[130:131]
	global_load_lds_dwordx4 v[228:229], off
	v_lshl_add_u64 v[228:229], s[78:79], 0, v[132:133]
	s_add_i32 m0, s55, 0x2000
	s_nop 0
	global_load_lds_dwordx4 v[228:229], off
	v_lshl_add_u64 v[228:229], s[86:87], 0, v[128:129]
	s_mov_b32 m0, s3
	s_nop 0
	global_load_lds_dwordx4 v[228:229], off
	s_mov_b32 m0, s8
	s_nop 0
	global_load_lds_dwordx4 v[230:231], off
	s_waitcnt vmcnt(8) lgkmcnt(0)
	s_barrier
; #define PG8_STAGE(bufoff, gbase, voff) do { _Pragma("unroll") for (int _i = 0; _i < 2; ++_i) \
;         __builtin_amdgcn_global_load_lds((const unsigned*)((const char*)(gbase) + (voff)[_i]), (PG8_LAS unsigned*)(lds + (bufoff) + ldsw + _i * 8192), 16, 0, 0); } while (0)
; #define PG8_LDA(dst, b, h) do { _Pragma("unroll") for (int m = 0; m < 4; ++m) _Pragma("unroll") for (int k = 0; k < 2; ++k) dst[m][k] = *(const PG8_LAS bf16x8*)(lds + PG8_SA(b, h) + aoff + m * 2048 + k * 1024); } while (0)
; #define PG8_LDB(dst, b, h) do { _Pragma("unroll") for (int n = 0; n < 2; ++n) _Pragma("unroll") for (int k = 0; k < 2; ++k) dst[n][k] = *(const PG8_LAS bf16x8*)(lds + PG8_SB(b, h) + boff + n * 2048 + k * 1024); } while (0)
; #define PG8_MMA(ai, bj, At, Bt) do { __builtin_amdgcn_s_setprio(1); _Pragma("unroll") for (int m = 0; m < 4; ++m) _Pragma("unroll") for (int n = 0; n < 2; ++n) _Pragma("unroll") for (int k = 0; k < 2; ++k) \
;         acc[ai][bj][m][n] = __builtin_amdgcn_mfma_f32_16x16x32_bf16(Bt[n][k], At[m][k], acc[ai][bj][m][n], 0, 0, 0); __builtin_amdgcn_s_setprio(0); } while (0)
; #define PG8_WAIT_V(n) asm volatile("s_waitcnt vmcnt(" #n ")" ::: "memory")
; #define PG8_WAIT_L(n) asm volatile("s_waitcnt lgkmcnt(" #n ")" ::: "memory")
; #define PG8_BAR __builtin_amdgcn_s_barrier()
; #define PG8_SCHED __builtin_amdgcn_sched_barrier(0)
; template <class Epi, class Sched, bool ALIGN_EPI = false, bool SP2 = false>
; __device__ __forceinline__ void gemm_phase(PG8_LAS unsigned char* lds, const Gemm g, const Sched& S, const Epi& E) {
;     ...
;             PG8_WAIT_V(8); PG8_WAIT_L(0); PG8_BAR; PG8_MMA(1, 0, At, B0); PG8_MMA(1, 1, At, B1); PG8_BAR; PG8_SCHED;
;             PG8_LDB(B0, 1, 0); PG8_LDB(B1, 1, 1); PG8_SCHED; PG8_LDA(At, 1, 0); PG8_STAGE(PG8_SA(0, 1), a2 + hstepA, voffA);
;             PG8_WAIT_V(8); PG8_WAIT_L(0); PG8_BAR; PG8_MMA(0, 0, At, B0); PG8_MMA(0, 1, At, B1); PG8_BAR; PG8_SCHED;
	s_setprio 1
	v_mfma_f32_16x16x32_bf16 v[60:63], v[138:141], v[174:177], v[60:63]
	v_mfma_f32_16x16x32_bf16 v[56:59], v[150:153], v[174:177], v[56:59]
	v_mfma_f32_16x16x32_bf16 v[44:47], v[138:141], v[182:185], v[44:47]
	v_mfma_f32_16x16x32_bf16 v[40:43], v[150:153], v[182:185], v[40:43]
	v_mfma_f32_16x16x32_bf16 v[28:31], v[138:141], v[190:193], v[28:31]
	v_mfma_f32_16x16x32_bf16 v[24:27], v[150:153], v[190:193], v[24:27]
	v_mfma_f32_16x16x32_bf16 v[12:15], v[138:141], v[204:207], v[12:15]
	v_mfma_f32_16x16x32_bf16 v[8:11], v[150:153], v[204:207], v[8:11]
	v_mfma_f32_16x16x32_bf16 v[60:63], v[142:145], v[178:181], v[60:63]
	v_mfma_f32_16x16x32_bf16 v[56:59], v[154:157], v[178:181], v[56:59]
	v_mfma_f32_16x16x32_bf16 v[44:47], v[142:145], v[186:189], v[44:47]
	v_mfma_f32_16x16x32_bf16 v[40:43], v[154:157], v[186:189], v[40:43]
	v_mfma_f32_16x16x32_bf16 v[28:31], v[142:145], v[200:203], v[28:31]
	v_mfma_f32_16x16x32_bf16 v[24:27], v[154:157], v[200:203], v[24:27]
	v_mfma_f32_16x16x32_bf16 v[12:15], v[142:145], v[208:211], v[12:15]
	v_mfma_f32_16x16x32_bf16 v[8:11], v[154:157], v[208:211], v[8:11]
	v_mfma_f32_16x16x32_bf16 v[52:55], v[158:161], v[174:177], v[52:55]
	v_mfma_f32_16x16x32_bf16 v[48:51], v[166:169], v[174:177], v[48:51]
	v_mfma_f32_16x16x32_bf16 v[36:39], v[158:161], v[182:185], v[36:39]
	v_mfma_f32_16x16x32_bf16 v[32:35], v[166:169], v[182:185], v[32:35]
	v_mfma_f32_16x16x32_bf16 v[20:23], v[158:161], v[190:193], v[20:23]
	v_mfma_f32_16x16x32_bf16 v[16:19], v[166:169], v[190:193], v[16:19]
	v_mfma_f32_16x16x32_bf16 v[4:7], v[158:161], v[204:207], v[4:7]
	v_mfma_f32_16x16x32_bf16 v[0:3], v[166:169], v[204:207], v[0:3]
	v_mfma_f32_16x16x32_bf16 v[52:55], v[162:165], v[178:181], v[52:55]
	v_mfma_f32_16x16x32_bf16 v[48:51], v[170:173], v[178:181], v[48:51]
	v_mfma_f32_16x16x32_bf16 v[36:39], v[162:165], v[186:189], v[36:39]
	v_mfma_f32_16x16x32_bf16 v[32:35], v[170:173], v[186:189], v[32:35]
	v_mfma_f32_16x16x32_bf16 v[20:23], v[162:165], v[200:203], v[20:23]
	v_mfma_f32_16x16x32_bf16 v[16:19], v[170:173], v[200:203], v[16:19]
	v_mfma_f32_16x16x32_bf16 v[4:7], v[162:165], v[208:211], v[4:7]
	v_mfma_f32_16x16x32_bf16 v[0:3], v[170:173], v[208:211], v[0:3]
	s_setprio 0
	s_barrier
	s_add_i32 s55, 0, 0x18000
	s_add_i32 s59, 0, 0x1c000
	v_add_u32_e32 v154, s55, v148
	v_add_u32_e32 v170, s59, v148
	ds_read_b128 v[138:141], v154
	ds_read_b128 v[142:145], v154 offset:1024
	ds_read_b128 v[150:153], v154 offset:2048
	ds_read_b128 v[154:157], v154 offset:3072
	ds_read_b128 v[158:161], v170
	ds_read_b128 v[162:165], v170 offset:1024
	ds_read_b128 v[166:169], v170 offset:2048
	ds_read_b128 v[170:173], v170 offset:3072
	s_add_u32 s78, s86, 0x20000
	s_addc_u32 s79, s87, 0
	s_mov_b32 m0, s9
	v_lshl_add_u64 v[232:233], s[78:79], 0, v[128:129]
	ds_read_b128 v[174:177], v149 offset:32768
	ds_read_b128 v[178:181], v149 offset:33792
	ds_read_b128 v[182:185], v149 offset:34816
	ds_read_b128 v[186:189], v149 offset:35840
	ds_read_b128 v[190:193], v149 offset:36864
	ds_read_b128 v[200:203], v149 offset:37888
	ds_read_b128 v[204:207], v149 offset:38912
	ds_read_b128 v[208:211], v149 offset:39936
	global_load_lds_dwordx4 v[232:233], off
	v_lshl_add_u64 v[232:233], s[78:79], 0, v[130:131]
	s_mov_b32 m0, s10
	s_nop 0
	global_load_lds_dwordx4 v[232:233], off
	s_waitcnt vmcnt(8) lgkmcnt(0)
	s_barrier
	s_setprio 1
	v_mfma_f32_16x16x32_bf16 v[124:127], v[138:141], v[174:177], v[124:127]
	v_mfma_f32_16x16x32_bf16 v[120:123], v[150:153], v[174:177], v[120:123]
	v_mfma_f32_16x16x32_bf16 v[108:111], v[138:141], v[182:185], v[108:111]
	v_mfma_f32_16x16x32_bf16 v[104:107], v[150:153], v[182:185], v[104:107]
	v_mfma_f32_16x16x32_bf16 v[92:95], v[138:141], v[190:193], v[92:95]
	v_mfma_f32_16x16x32_bf16 v[88:91], v[150:153], v[190:193], v[88:91]
	v_mfma_f32_16x16x32_bf16 v[76:79], v[138:141], v[204:207], v[76:79]
	v_mfma_f32_16x16x32_bf16 v[72:75], v[150:153], v[204:207], v[72:75]
	v_mfma_f32_16x16x32_bf16 v[124:127], v[142:145], v[178:181], v[124:127]
	v_mfma_f32_16x16x32_bf16 v[120:123], v[154:157], v[178:181], v[120:123]
	v_mfma_f32_16x16x32_bf16 v[108:111], v[142:145], v[186:189], v[108:111]
	v_mfma_f32_16x16x32_bf16 v[104:107], v[154:157], v[186:189], v[104:107]
	v_mfma_f32_16x16x32_bf16 v[92:95], v[142:145], v[200:203], v[92:95]
	v_mfma_f32_16x16x32_bf16 v[88:91], v[154:157], v[200:203], v[88:91]
	v_mfma_f32_16x16x32_bf16 v[76:79], v[142:145], v[208:211], v[76:79]
	v_mfma_f32_16x16x32_bf16 v[72:75], v[154:157], v[208:211], v[72:75]
	v_mfma_f32_16x16x32_bf16 v[116:119], v[158:161], v[174:177], v[116:119]
	v_mfma_f32_16x16x32_bf16 v[112:115], v[166:169], v[174:177], v[112:115]
	v_mfma_f32_16x16x32_bf16 v[100:103], v[158:161], v[182:185], v[100:103]
	v_mfma_f32_16x16x32_bf16 v[96:99], v[166:169], v[182:185], v[96:99]
	v_mfma_f32_16x16x32_bf16 v[84:87], v[158:161], v[190:193], v[84:87]
	v_mfma_f32_16x16x32_bf16 v[80:83], v[166:169], v[190:193], v[80:83]
	v_mfma_f32_16x16x32_bf16 v[68:71], v[158:161], v[204:207], v[68:71]
	v_mfma_f32_16x16x32_bf16 v[64:67], v[166:169], v[204:207], v[64:67]
	v_mfma_f32_16x16x32_bf16 v[116:119], v[162:165], v[178:181], v[116:119]
	v_mfma_f32_16x16x32_bf16 v[112:115], v[170:173], v[178:181], v[112:115]
	v_mfma_f32_16x16x32_bf16 v[100:103], v[162:165], v[186:189], v[100:103]
	v_mfma_f32_16x16x32_bf16 v[96:99], v[170:173], v[186:189], v[96:99]
	v_mfma_f32_16x16x32_bf16 v[84:87], v[162:165], v[200:203], v[84:87]
	v_mfma_f32_16x16x32_bf16 v[80:83], v[170:173], v[200:203], v[80:83]
	v_mfma_f32_16x16x32_bf16 v[68:71], v[162:165], v[208:211], v[68:71]
	v_mfma_f32_16x16x32_bf16 v[64:67], v[170:173], v[208:211], v[64:67]
	s_setprio 0
	s_barrier
; #define PG8_STAGE(bufoff, gbase, voff) do { _Pragma("unroll") for (int _i = 0; _i < 2; ++_i) \
;         __builtin_amdgcn_global_load_lds((const unsigned*)((const char*)(gbase) + (voff)[_i]), (PG8_LAS unsigned*)(lds + (bufoff) + ldsw + _i * 8192), 16, 0, 0); } while (0)
; #define PG8_LDA(dst, b, h) do { _Pragma("unroll") for (int m = 0; m < 4; ++m) _Pragma("unroll") for (int k = 0; k < 2; ++k) dst[m][k] = *(const PG8_LAS bf16x8*)(lds + PG8_SA(b, h) + aoff + m * 2048 + k * 1024); } while (0)
; #define PG8_MMA(ai, bj, At, Bt) do { __builtin_amdgcn_s_setprio(1); _Pragma("unroll") for (int m = 0; m < 4; ++m) _Pragma("unroll") for (int n = 0; n < 2; ++n) _Pragma("unroll") for (int k = 0; k < 2; ++k) \
;         acc[ai][bj][m][n] = __builtin_amdgcn_mfma_f32_16x16x32_bf16(Bt[n][k], At[m][k], acc[ai][bj][m][n], 0, 0, 0); __builtin_amdgcn_s_setprio(0); } while (0)
; #define PG8_WAIT_V(n) asm volatile("s_waitcnt vmcnt(" #n ")" ::: "memory")
; #define PG8_WAIT_L(n) asm volatile("s_waitcnt lgkmcnt(" #n ")" ::: "memory")
; #define PG8_BAR __builtin_amdgcn_s_barrier()
; #define PG8_SCHED __builtin_amdgcn_sched_barrier(0)
; template <class Epi, class Sched, bool ALIGN_EPI = false, bool SP2 = false>
; __device__ __forceinline__ void gemm_phase(PG8_LAS unsigned char* lds, const Gemm g, const Sched& S, const Epi& E) {
;     ...
;             PG8_LDA(At, 1, 1); PG8_STAGE(PG8_SB(1, 0), b3, voffB); PG8_STAGE(PG8_SB(1, 1), b3 + hstepB, voffB); PG8_STAGE(PG8_SA(1, 0), a3, voffA);
;             PG8_WAIT_V(8); PG8_WAIT_L(0); PG8_BAR; PG8_MMA(1, 0, At, B0); PG8_MMA(1, 1, At, B1); PG8_BAR; PG8_SCHED;
	s_add_i32 s55, s55, s2
	v_lshl_add_u64 v[212:213], v[212:213], 0, s[26:27]
	s_mov_b32 m0, s55
	ds_read_b128 v[174:177], v149 offset:49152
	ds_read_b128 v[178:181], v149 offset:50176
	ds_read_b128 v[182:185], v149 offset:51200
	ds_read_b128 v[186:189], v149 offset:52224
	ds_read_b128 v[190:193], v149 offset:53248
	ds_read_b128 v[200:203], v149 offset:54272
	ds_read_b128 v[204:207], v149 offset:55296
	ds_read_b128 v[208:211], v149 offset:56320
	global_load_lds_dwordx4 v[212:213], off
	s_add_i32 m0, s55, 0x2000
	s_add_u32 s62, s62, 0x8080
	v_lshl_add_u64 v[212:213], v[214:215], 0, s[26:27]
	s_addc_u32 s63, s63, 0
	s_add_i32 s55, s59, s2
	global_load_lds_dwordx4 v[212:213], off
	v_lshl_add_u64 v[212:213], s[62:63], 0, v[194:195]
	s_mov_b32 m0, s55
	s_nop 0
	global_load_lds_dwordx4 v[212:213], off
	v_lshl_add_u64 v[212:213], s[62:63], 0, v[132:133]
	s_add_i32 m0, s55, 0x2000
	s_nop 0
	global_load_lds_dwordx4 v[212:213], off
	v_lshl_add_u64 v[212:213], v[228:229], 0, s[26:27]
	s_mov_b32 m0, s13
	s_nop 0
	global_load_lds_dwordx4 v[212:213], off
	v_lshl_add_u64 v[212:213], v[230:231], 0, s[26:27]
	s_mov_b32 m0, s14
	s_nop 0
	global_load_lds_dwordx4 v[212:213], off
	s_waitcnt vmcnt(8) lgkmcnt(0)
	s_barrier
	s_setprio 1
	v_mfma_f32_16x16x32_bf16 v[60:63], v[138:141], v[174:177], v[60:63]
	v_mfma_f32_16x16x32_bf16 v[56:59], v[150:153], v[174:177], v[56:59]
	v_mfma_f32_16x16x32_bf16 v[44:47], v[138:141], v[182:185], v[44:47]
	v_mfma_f32_16x16x32_bf16 v[40:43], v[150:153], v[182:185], v[40:43]
	v_mfma_f32_16x16x32_bf16 v[28:31], v[138:141], v[190:193], v[28:31]
	v_mfma_f32_16x16x32_bf16 v[24:27], v[150:153], v[190:193], v[24:27]
	v_mfma_f32_16x16x32_bf16 v[12:15], v[138:141], v[204:207], v[12:15]
	v_mfma_f32_16x16x32_bf16 v[8:11], v[150:153], v[204:207], v[8:11]
	v_mfma_f32_16x16x32_bf16 v[60:63], v[142:145], v[178:181], v[60:63]
	v_mfma_f32_16x16x32_bf16 v[56:59], v[154:157], v[178:181], v[56:59]
	v_mfma_f32_16x16x32_bf16 v[44:47], v[142:145], v[186:189], v[44:47]
	v_mfma_f32_16x16x32_bf16 v[40:43], v[154:157], v[186:189], v[40:43]
	v_mfma_f32_16x16x32_bf16 v[28:31], v[142:145], v[200:203], v[28:31]
	v_mfma_f32_16x16x32_bf16 v[24:27], v[154:157], v[200:203], v[24:27]
	v_mfma_f32_16x16x32_bf16 v[12:15], v[142:145], v[208:211], v[12:15]
	v_mfma_f32_16x16x32_bf16 v[8:11], v[154:157], v[208:211], v[8:11]
	v_mfma_f32_16x16x32_bf16 v[52:55], v[158:161], v[174:177], v[52:55]
	v_mfma_f32_16x16x32_bf16 v[48:51], v[166:169], v[174:177], v[48:51]
	v_mfma_f32_16x16x32_bf16 v[36:39], v[158:161], v[182:185], v[36:39]
	v_mfma_f32_16x16x32_bf16 v[32:35], v[166:169], v[182:185], v[32:35]
	v_mfma_f32_16x16x32_bf16 v[20:23], v[158:161], v[190:193], v[20:23]
	v_mfma_f32_16x16x32_bf16 v[16:19], v[166:169], v[190:193], v[16:19]
	v_mfma_f32_16x16x32_bf16 v[4:7], v[158:161], v[204:207], v[4:7]
	v_mfma_f32_16x16x32_bf16 v[0:3], v[166:169], v[204:207], v[0:3]
	v_mfma_f32_16x16x32_bf16 v[52:55], v[162:165], v[178:181], v[52:55]
	v_mfma_f32_16x16x32_bf16 v[48:51], v[170:173], v[178:181], v[48:51]
	v_mfma_f32_16x16x32_bf16 v[36:39], v[162:165], v[186:189], v[36:39]
	v_mfma_f32_16x16x32_bf16 v[32:35], v[170:173], v[186:189], v[32:35]
	v_mfma_f32_16x16x32_bf16 v[20:23], v[162:165], v[200:203], v[20:23]
	v_mfma_f32_16x16x32_bf16 v[16:19], v[170:173], v[200:203], v[16:19]
	v_mfma_f32_16x16x32_bf16 v[4:7], v[162:165], v[208:211], v[4:7]
	v_mfma_f32_16x16x32_bf16 v[0:3], v[170:173], v[208:211], v[0:3]
	s_setprio 0
	s_barrier
	s_add_u32 s84, s84, 0x100
	s_addc_u32 s85, s85, 0
	s_add_u32 s49, s49, 0x100
	s_addc_u32 s53, s53, 0
	s_cmp_ge_i32 s58, s11
	s_mov_b32 s55, s58
	s_cbranch_scc0 .LBB0_569

; #define PG8_STAGE(bufoff, gbase, voff) do { _Pragma("unroll") for (int _i = 0; _i < 2; ++_i) \
;         __builtin_amdgcn_global_load_lds((const unsigned*)((const char*)(gbase) + (voff)[_i]), (PG8_LAS unsigned*)(lds + (bufoff) + ldsw + _i * 8192), 16, 0, 0); } while (0)
; #define PG8_LDA(dst, b, h) do { _Pragma("unroll") for (int m = 0; m < 4; ++m) _Pragma("unroll") for (int k = 0; k < 2; ++k) dst[m][k] = *(const PG8_LAS bf16x8*)(lds + PG8_SA(b, h) + aoff + m * 2048 + k * 1024); } while (0)
; #define PG8_LDB(dst, b, h) do { _Pragma("unroll") for (int n = 0; n < 2; ++n) _Pragma("unroll") for (int k = 0; k < 2; ++k) dst[n][k] = *(const PG8_LAS bf16x8*)(lds + PG8_SB(b, h) + boff + n * 2048 + k * 1024); } while (0)
; #define PG8_MMA(ai, bj, At, Bt) do { __builtin_amdgcn_s_setprio(1); _Pragma("unroll") for (int m = 0; m < 4; ++m) _Pragma("unroll") for (int n = 0; n < 2; ++n) _Pragma("unroll") for (int k = 0; k < 2; ++k) \
;         acc[ai][bj][m][n] = __builtin_amdgcn_mfma_f32_16x16x32_bf16(Bt[n][k], At[m][k], acc[ai][bj][m][n], 0, 0, 0); __builtin_amdgcn_s_setprio(0); } while (0)
; #define PG8_WAIT_V(n) asm volatile("s_waitcnt vmcnt(" #n ")" ::: "memory")
; #define PG8_WAIT_L(n) asm volatile("s_waitcnt lgkmcnt(" #n ")" ::: "memory")
; #define PG8_BAR __builtin_amdgcn_s_barrier()
; #define PG8_SCHED __builtin_amdgcn_sched_barrier(0)
; template <class Epi, class Sched, bool ALIGN_EPI = false, bool SP2 = false>
; __device__ __forceinline__ void gemm_phase(PG8_LAS unsigned char* lds, const Gemm g, const Sched& S, const Epi& E) {
;     ...
;             const char* a2 = last ? nA : cA + (size_t)(t + 2) * kstep; const char* b2 = last ? nB : cB + (size_t)(t + 2) * kstep;
;             const char* a3 = a2 + kstep; const char* b3 = b2 + kstep;
;             if (last && has_next) S.a_ready(nxt);
;             if constexpr (SP2) {
;             PG8_LDB(B0, 0, 0); PG8_LDB(B1, 0, 1); PG8_SCHED; PG8_LDA(At, 0, 0); PG8_STAGE(PG8_SA(1, 1), a1 + hstepA, voffA);
;             PG8_WAIT_V(8); PG8_WAIT_L(0); PG8_BAR; PG8_MMA(0, 0, At, B0); PG8_MMA(0, 1, At, B1); PG8_BAR; PG8_SCHED;
;             PG8_LDA(At, 0, 1); PG8_STAGE(PG8_SB(0, 0), b2, voffB); PG8_STAGE(PG8_SB(0, 1), b2 + hstepB, voffB); PG8_STAGE(PG8_SA(0, 0), a2, voffA);
;             PG8_WAIT_V(8); PG8_WAIT_L(0); PG8_BAR; PG8_MMA(1, 0, At, B0); PG8_MMA(1, 1, At, B1); PG8_BAR; PG8_SCHED;
.LBB0_618:
	s_add_i32 s79, s62, 2
	s_add_u32 s63, s42, 0xffff8080
	s_addc_u32 s74, s43, -1
	s_add_i32 s75, 0, 0x10000
	s_cmp_eq_u32 s55, s62
	s_cselect_b32 s85, s41, s74
	s_cselect_b32 s84, s53, s63
	s_cselect_b32 s63, s59, s78
	s_cselect_b32 s62, s64, s69
	s_add_i32 s74, 0, 0x14000
	v_add_u32_e32 v156, s75, v154
	v_add_u32_e32 v172, s74, v154
	ds_read_b128 v[128:131], v156
	ds_read_b128 v[144:147], v156 offset:1024
	ds_read_b128 v[148:151], v156 offset:2048
	ds_read_b128 v[156:159], v156 offset:3072
	ds_read_b128 v[160:163], v172
	ds_read_b128 v[164:167], v172 offset:1024
	ds_read_b128 v[168:171], v172 offset:2048
	ds_read_b128 v[172:175], v172 offset:3072
	v_lshl_add_u64 v[192:193], s[42:43], 0, v[140:141]
	s_add_i32 m0, s12, 0xc000
	ds_read_b128 v[176:179], v155
	ds_read_b128 v[180:183], v155 offset:1024
	ds_read_b128 v[184:187], v155 offset:2048
	ds_read_b128 v[188:191], v155 offset:3072
	ds_read_b128 v[200:203], v155 offset:4096
	ds_read_b128 v[204:207], v155 offset:5120
	ds_read_b128 v[208:211], v155 offset:6144
	ds_read_b128 v[212:215], v155 offset:7168
	global_load_lds_dwordx4 v[192:193], off
	v_lshl_add_u64 v[192:193], s[42:43], 0, v[142:143]
	s_add_i32 m0, s12, 0xe000
	s_nop 0
	global_load_lds_dwordx4 v[192:193], off
	s_waitcnt vmcnt(8) lgkmcnt(0)
	s_barrier
	s_setprio 1
	v_mfma_f32_16x16x32_bf16 v[124:127], v[128:131], v[176:179], v[124:127]
	v_mfma_f32_16x16x32_bf16 v[120:123], v[148:151], v[176:179], v[120:123]
	v_mfma_f32_16x16x32_bf16 v[116:119], v[128:131], v[184:187], v[116:119]
	v_mfma_f32_16x16x32_bf16 v[112:115], v[148:151], v[184:187], v[112:115]
	v_mfma_f32_16x16x32_bf16 v[108:111], v[128:131], v[200:203], v[108:111]
	v_mfma_f32_16x16x32_bf16 v[104:107], v[148:151], v[200:203], v[104:107]
	v_mfma_f32_16x16x32_bf16 v[100:103], v[128:131], v[208:211], v[100:103]
	v_mfma_f32_16x16x32_bf16 v[96:99], v[148:151], v[208:211], v[96:99]
	v_mfma_f32_16x16x32_bf16 v[124:127], v[144:147], v[180:183], v[124:127]
	v_mfma_f32_16x16x32_bf16 v[120:123], v[156:159], v[180:183], v[120:123]
	v_mfma_f32_16x16x32_bf16 v[116:119], v[144:147], v[188:191], v[116:119]
	v_mfma_f32_16x16x32_bf16 v[112:115], v[156:159], v[188:191], v[112:115]
	v_mfma_f32_16x16x32_bf16 v[108:111], v[144:147], v[204:207], v[108:111]
	v_mfma_f32_16x16x32_bf16 v[104:107], v[156:159], v[204:207], v[104:107]
	v_mfma_f32_16x16x32_bf16 v[100:103], v[144:147], v[212:215], v[100:103]
	v_mfma_f32_16x16x32_bf16 v[96:99], v[156:159], v[212:215], v[96:99]
	v_mfma_f32_16x16x32_bf16 v[60:63], v[160:163], v[176:179], v[60:63]
	v_mfma_f32_16x16x32_bf16 v[56:59], v[168:171], v[176:179], v[56:59]
	v_mfma_f32_16x16x32_bf16 v[52:55], v[160:163], v[184:187], v[52:55]
	v_mfma_f32_16x16x32_bf16 v[48:51], v[168:171], v[184:187], v[48:51]
	v_mfma_f32_16x16x32_bf16 v[44:47], v[160:163], v[200:203], v[44:47]
	v_mfma_f32_16x16x32_bf16 v[40:43], v[168:171], v[200:203], v[40:43]
	v_mfma_f32_16x16x32_bf16 v[36:39], v[160:163], v[208:211], v[36:39]
	v_mfma_f32_16x16x32_bf16 v[32:35], v[168:171], v[208:211], v[32:35]
	v_mfma_f32_16x16x32_bf16 v[60:63], v[164:167], v[180:183], v[60:63]
	v_mfma_f32_16x16x32_bf16 v[56:59], v[172:175], v[180:183], v[56:59]
	v_mfma_f32_16x16x32_bf16 v[52:55], v[164:167], v[188:191], v[52:55]
	v_mfma_f32_16x16x32_bf16 v[48:51], v[172:175], v[188:191], v[48:51]
	v_mfma_f32_16x16x32_bf16 v[44:47], v[164:167], v[204:207], v[44:47]
	v_mfma_f32_16x16x32_bf16 v[40:43], v[172:175], v[204:207], v[40:43]
	v_mfma_f32_16x16x32_bf16 v[36:39], v[164:167], v[212:215], v[36:39]
	v_mfma_f32_16x16x32_bf16 v[32:35], v[172:175], v[212:215], v[32:35]
	s_setprio 0
	s_barrier
	s_add_i32 s75, s75, s2
	v_lshl_add_u64 v[192:193], s[62:63], 0, v[136:137]
	s_mov_b32 m0, s75
	ds_read_b128 v[176:179], v155 offset:16384
	ds_read_b128 v[180:183], v155 offset:17408
	ds_read_b128 v[184:187], v155 offset:18432
	ds_read_b128 v[188:191], v155 offset:19456
	ds_read_b128 v[200:203], v155 offset:20480
	ds_read_b128 v[204:207], v155 offset:21504
	ds_read_b128 v[208:211], v155 offset:22528
	ds_read_b128 v[212:215], v155 offset:23552
	global_load_lds_dwordx4 v[192:193], off
	s_add_i32 m0, s75, 0x2000
	s_add_u32 s86, s62, 0x20000
	v_lshl_add_u64 v[228:229], s[62:63], 0, v[132:133]
	s_addc_u32 s87, s63, 0
	s_add_i32 s74, s74, s2
	global_load_lds_dwordx4 v[228:229], off
	v_lshl_add_u64 v[230:231], s[86:87], 0, v[136:137]
	s_mov_b32 m0, s74
	v_lshl_add_u64 v[232:233], s[84:85], 0, v[134:135]
	global_load_lds_dwordx4 v[230:231], off
	v_lshl_add_u64 v[230:231], s[86:87], 0, v[132:133]
	s_add_i32 m0, s74, 0x2000
	s_nop 0
	global_load_lds_dwordx4 v[230:231], off
	v_lshl_add_u64 v[230:231], s[84:85], 0, v[138:139]
	s_mov_b32 m0, s12
	s_nop 0
	global_load_lds_dwordx4 v[230:231], off
	s_mov_b32 m0, s13
	s_nop 0
	global_load_lds_dwordx4 v[232:233], off
	s_waitcnt vmcnt(8) lgkmcnt(0)
	s_barrier
; #define PG8_STAGE(bufoff, gbase, voff) do { _Pragma("unroll") for (int _i = 0; _i < 2; ++_i) \
;         __builtin_amdgcn_global_load_lds((const unsigned*)((const char*)(gbase) + (voff)[_i]), (PG8_LAS unsigned*)(lds + (bufoff) + ldsw + _i * 8192), 16, 0, 0); } while (0)
; #define PG8_LDA(dst, b, h) do { _Pragma("unroll") for (int m = 0; m < 4; ++m) _Pragma("unroll") for (int k = 0; k < 2; ++k) dst[m][k] = *(const PG8_LAS bf16x8*)(lds + PG8_SA(b, h) + aoff + m * 2048 + k * 1024); } while (0)
; #define PG8_LDB(dst, b, h) do { _Pragma("unroll") for (int n = 0; n < 2; ++n) _Pragma("unroll") for (int k = 0; k < 2; ++k) dst[n][k] = *(const PG8_LAS bf16x8*)(lds + PG8_SB(b, h) + boff + n * 2048 + k * 1024); } while (0)
; #define PG8_MMA(ai, bj, At, Bt) do { __builtin_amdgcn_s_setprio(1); _Pragma("unroll") for (int m = 0; m < 4; ++m) _Pragma("unroll") for (int n = 0; n < 2; ++n) _Pragma("unroll") for (int k = 0; k < 2; ++k) \
;         acc[ai][bj][m][n] = __builtin_amdgcn_mfma_f32_16x16x32_bf16(Bt[n][k], At[m][k], acc[ai][bj][m][n], 0, 0, 0); __builtin_amdgcn_s_setprio(0); } while (0)
; #define PG8_WAIT_V(n) asm volatile("s_waitcnt vmcnt(" #n ")" ::: "memory")
; #define PG8_WAIT_L(n) asm volatile("s_waitcnt lgkmcnt(" #n ")" ::: "memory")
; #define PG8_BAR __builtin_amdgcn_s_barrier()
; #define PG8_SCHED __builtin_amdgcn_sched_barrier(0)
; template <class Epi, class Sched, bool ALIGN_EPI = false, bool SP2 = false>
; __device__ __forceinline__ void gemm_phase(PG8_LAS unsigned char* lds, const Gemm g, const Sched& S, const Epi& E) {
;     ...
;             PG8_WAIT_V(8); PG8_WAIT_L(0); PG8_BAR; PG8_MMA(1, 0, At, B0); PG8_MMA(1, 1, At, B1); PG8_BAR; PG8_SCHED;
;             PG8_LDB(B0, 1, 0); PG8_LDB(B1, 1, 1); PG8_SCHED; PG8_LDA(At, 1, 0); PG8_STAGE(PG8_SA(0, 1), a2 + hstepA, voffA);
;             PG8_WAIT_V(8); PG8_WAIT_L(0); PG8_BAR; PG8_MMA(0, 0, At, B0); PG8_MMA(0, 1, At, B1); PG8_BAR; PG8_SCHED;
	s_setprio 1
	v_mfma_f32_16x16x32_bf16 v[92:95], v[128:131], v[176:179], v[92:95]
	v_mfma_f32_16x16x32_bf16 v[88:91], v[148:151], v[176:179], v[88:91]
	v_mfma_f32_16x16x32_bf16 v[84:87], v[128:131], v[184:187], v[84:87]
	v_mfma_f32_16x16x32_bf16 v[80:83], v[148:151], v[184:187], v[80:83]
	v_mfma_f32_16x16x32_bf16 v[76:79], v[128:131], v[200:203], v[76:79]
	v_mfma_f32_16x16x32_bf16 v[72:75], v[148:151], v[200:203], v[72:75]
	v_mfma_f32_16x16x32_bf16 v[68:71], v[128:131], v[208:211], v[68:71]
	v_mfma_f32_16x16x32_bf16 v[64:67], v[148:151], v[208:211], v[64:67]
	v_mfma_f32_16x16x32_bf16 v[92:95], v[144:147], v[180:183], v[92:95]
	v_mfma_f32_16x16x32_bf16 v[88:91], v[156:159], v[180:183], v[88:91]
	v_mfma_f32_16x16x32_bf16 v[84:87], v[144:147], v[188:191], v[84:87]
	v_mfma_f32_16x16x32_bf16 v[80:83], v[156:159], v[188:191], v[80:83]
	v_mfma_f32_16x16x32_bf16 v[76:79], v[144:147], v[204:207], v[76:79]
	v_mfma_f32_16x16x32_bf16 v[72:75], v[156:159], v[204:207], v[72:75]
	v_mfma_f32_16x16x32_bf16 v[68:71], v[144:147], v[212:215], v[68:71]
	v_mfma_f32_16x16x32_bf16 v[64:67], v[156:159], v[212:215], v[64:67]
	v_mfma_f32_16x16x32_bf16 v[28:31], v[160:163], v[176:179], v[28:31]
	v_mfma_f32_16x16x32_bf16 v[24:27], v[168:171], v[176:179], v[24:27]
	v_mfma_f32_16x16x32_bf16 v[20:23], v[160:163], v[184:187], v[20:23]
	v_mfma_f32_16x16x32_bf16 v[16:19], v[168:171], v[184:187], v[16:19]
	v_mfma_f32_16x16x32_bf16 v[12:15], v[160:163], v[200:203], v[12:15]
	v_mfma_f32_16x16x32_bf16 v[8:11], v[168:171], v[200:203], v[8:11]
	v_mfma_f32_16x16x32_bf16 v[4:7], v[160:163], v[208:211], v[4:7]
	v_mfma_f32_16x16x32_bf16 v[0:3], v[168:171], v[208:211], v[0:3]
	v_mfma_f32_16x16x32_bf16 v[28:31], v[164:167], v[180:183], v[28:31]
	v_mfma_f32_16x16x32_bf16 v[24:27], v[172:175], v[180:183], v[24:27]
	v_mfma_f32_16x16x32_bf16 v[20:23], v[164:167], v[188:191], v[20:23]
	v_mfma_f32_16x16x32_bf16 v[16:19], v[172:175], v[188:191], v[16:19]
	v_mfma_f32_16x16x32_bf16 v[12:15], v[164:167], v[204:207], v[12:15]
	v_mfma_f32_16x16x32_bf16 v[8:11], v[172:175], v[204:207], v[8:11]
	v_mfma_f32_16x16x32_bf16 v[4:7], v[164:167], v[212:215], v[4:7]
	v_mfma_f32_16x16x32_bf16 v[0:3], v[172:175], v[212:215], v[0:3]
	s_setprio 0
	s_barrier
	s_add_i32 s74, 0, 0x18000
	s_add_i32 s75, 0, 0x1c000
	v_add_u32_e32 v156, s74, v154
	v_add_u32_e32 v172, s75, v154
	ds_read_b128 v[128:131], v156
	ds_read_b128 v[144:147], v156 offset:1024
	ds_read_b128 v[148:151], v156 offset:2048
	ds_read_b128 v[156:159], v156 offset:3072
	ds_read_b128 v[160:163], v172
	ds_read_b128 v[164:167], v172 offset:1024
	ds_read_b128 v[168:171], v172 offset:2048
	ds_read_b128 v[172:175], v172 offset:3072
	s_add_u32 s84, s84, 0x8000
	s_addc_u32 s85, s85, 0
	s_mov_b32 m0, s14
	v_lshl_add_u64 v[234:235], s[84:85], 0, v[138:139]
	ds_read_b128 v[176:179], v155 offset:32768
	ds_read_b128 v[180:183], v155 offset:33792
	ds_read_b128 v[184:187], v155 offset:34816
	ds_read_b128 v[188:191], v155 offset:35840
	ds_read_b128 v[200:203], v155 offset:36864
	ds_read_b128 v[204:207], v155 offset:37888
	ds_read_b128 v[208:211], v155 offset:38912
	ds_read_b128 v[212:215], v155 offset:39936
	global_load_lds_dwordx4 v[234:235], off
	v_lshl_add_u64 v[234:235], s[84:85], 0, v[134:135]
	s_mov_b32 m0, s15
	s_nop 0
	global_load_lds_dwordx4 v[234:235], off
	s_waitcnt vmcnt(8) lgkmcnt(0)
	s_barrier
	s_setprio 1
	v_mfma_f32_16x16x32_bf16 v[124:127], v[128:131], v[176:179], v[124:127]
	v_mfma_f32_16x16x32_bf16 v[120:123], v[148:151], v[176:179], v[120:123]
	v_mfma_f32_16x16x32_bf16 v[116:119], v[128:131], v[184:187], v[116:119]
	v_mfma_f32_16x16x32_bf16 v[112:115], v[148:151], v[184:187], v[112:115]
	v_mfma_f32_16x16x32_bf16 v[108:111], v[128:131], v[200:203], v[108:111]
	v_mfma_f32_16x16x32_bf16 v[104:107], v[148:151], v[200:203], v[104:107]
	v_mfma_f32_16x16x32_bf16 v[100:103], v[128:131], v[208:211], v[100:103]
	v_mfma_f32_16x16x32_bf16 v[96:99], v[148:151], v[208:211], v[96:99]
	v_mfma_f32_16x16x32_bf16 v[124:127], v[144:147], v[180:183], v[124:127]
	v_mfma_f32_16x16x32_bf16 v[120:123], v[156:159], v[180:183], v[120:123]
	v_mfma_f32_16x16x32_bf16 v[116:119], v[144:147], v[188:191], v[116:119]
	v_mfma_f32_16x16x32_bf16 v[112:115], v[156:159], v[188:191], v[112:115]
	v_mfma_f32_16x16x32_bf16 v[108:111], v[144:147], v[204:207], v[108:111]
	v_mfma_f32_16x16x32_bf16 v[104:107], v[156:159], v[204:207], v[104:107]
	v_mfma_f32_16x16x32_bf16 v[100:103], v[144:147], v[212:215], v[100:103]
	v_mfma_f32_16x16x32_bf16 v[96:99], v[156:159], v[212:215], v[96:99]
	v_mfma_f32_16x16x32_bf16 v[60:63], v[160:163], v[176:179], v[60:63]
	v_mfma_f32_16x16x32_bf16 v[56:59], v[168:171], v[176:179], v[56:59]
	v_mfma_f32_16x16x32_bf16 v[52:55], v[160:163], v[184:187], v[52:55]
	v_mfma_f32_16x16x32_bf16 v[48:51], v[168:171], v[184:187], v[48:51]
	v_mfma_f32_16x16x32_bf16 v[44:47], v[160:163], v[200:203], v[44:47]
	v_mfma_f32_16x16x32_bf16 v[40:43], v[168:171], v[200:203], v[40:43]
	v_mfma_f32_16x16x32_bf16 v[36:39], v[160:163], v[208:211], v[36:39]
	v_mfma_f32_16x16x32_bf16 v[32:35], v[168:171], v[208:211], v[32:35]
	v_mfma_f32_16x16x32_bf16 v[60:63], v[164:167], v[180:183], v[60:63]
	v_mfma_f32_16x16x32_bf16 v[56:59], v[172:175], v[180:183], v[56:59]
	v_mfma_f32_16x16x32_bf16 v[52:55], v[164:167], v[188:191], v[52:55]
	v_mfma_f32_16x16x32_bf16 v[48:51], v[172:175], v[188:191], v[48:51]
	v_mfma_f32_16x16x32_bf16 v[44:47], v[164:167], v[204:207], v[44:47]
	v_mfma_f32_16x16x32_bf16 v[40:43], v[172:175], v[204:207], v[40:43]
	v_mfma_f32_16x16x32_bf16 v[36:39], v[164:167], v[212:215], v[36:39]
	v_mfma_f32_16x16x32_bf16 v[32:35], v[172:175], v[212:215], v[32:35]
	s_setprio 0
	s_barrier
; #define PG8_STAGE(bufoff, gbase, voff) do { _Pragma("unroll") for (int _i = 0; _i < 2; ++_i) \
;         __builtin_amdgcn_global_load_lds((const unsigned*)((const char*)(gbase) + (voff)[_i]), (PG8_LAS unsigned*)(lds + (bufoff) + ldsw + _i * 8192), 16, 0, 0); } while (0)
; #define PG8_LDA(dst, b, h) do { _Pragma("unroll") for (int m = 0; m < 4; ++m) _Pragma("unroll") for (int k = 0; k < 2; ++k) dst[m][k] = *(const PG8_LAS bf16x8*)(lds + PG8_SA(b, h) + aoff + m * 2048 + k * 1024); } while (0)
; #define PG8_MMA(ai, bj, At, Bt) do { __builtin_amdgcn_s_setprio(1); _Pragma("unroll") for (int m = 0; m < 4; ++m) _Pragma("unroll") for (int n = 0; n < 2; ++n) _Pragma("unroll") for (int k = 0; k < 2; ++k) \
;         acc[ai][bj][m][n] = __builtin_amdgcn_mfma_f32_16x16x32_bf16(Bt[n][k], At[m][k], acc[ai][bj][m][n], 0, 0, 0); __builtin_amdgcn_s_setprio(0); } while (0)
; #define PG8_WAIT_V(n) asm volatile("s_waitcnt vmcnt(" #n ")" ::: "memory")
; #define PG8_WAIT_L(n) asm volatile("s_waitcnt lgkmcnt(" #n ")" ::: "memory")
; #define PG8_BAR __builtin_amdgcn_s_barrier()
; #define PG8_SCHED __builtin_amdgcn_sched_barrier(0)
; template <class Epi, class Sched, bool ALIGN_EPI = false, bool SP2 = false>
; __device__ __forceinline__ void gemm_phase(PG8_LAS unsigned char* lds, const Gemm g, const Sched& S, const Epi& E) {
;     ...
;             PG8_LDA(At, 1, 1); PG8_STAGE(PG8_SB(1, 0), b3, voffB); PG8_STAGE(PG8_SB(1, 1), b3 + hstepB, voffB); PG8_STAGE(PG8_SA(1, 0), a3, voffA);
;             PG8_WAIT_V(8); PG8_WAIT_L(0); PG8_BAR; PG8_MMA(1, 0, At, B0); PG8_MMA(1, 1, At, B1); PG8_BAR; PG8_SCHED;
	s_add_i32 s74, s74, s2
	v_lshl_add_u64 v[192:193], v[192:193], 0, s[26:27]
	s_mov_b32 m0, s74
	ds_read_b128 v[176:179], v155 offset:49152
	ds_read_b128 v[180:183], v155 offset:50176
	ds_read_b128 v[184:187], v155 offset:51200
	ds_read_b128 v[188:191], v155 offset:52224
	ds_read_b128 v[200:203], v155 offset:53248
	ds_read_b128 v[204:207], v155 offset:54272
	ds_read_b128 v[208:211], v155 offset:55296
	ds_read_b128 v[212:215], v155 offset:56320
	global_load_lds_dwordx4 v[192:193], off
	s_add_i32 m0, s74, 0x2000
	s_add_u32 s62, s62, 0x20080
	v_lshl_add_u64 v[192:193], v[228:229], 0, s[26:27]
	s_addc_u32 s63, s63, 0
	s_add_i32 s74, s75, s2
	global_load_lds_dwordx4 v[192:193], off
	v_lshl_add_u64 v[192:193], s[62:63], 0, v[136:137]
	s_mov_b32 m0, s74
	s_nop 0
	global_load_lds_dwordx4 v[192:193], off
	v_lshl_add_u64 v[192:193], s[62:63], 0, v[132:133]
	s_add_i32 m0, s74, 0x2000
	s_nop 0
	global_load_lds_dwordx4 v[192:193], off
	v_lshl_add_u64 v[192:193], v[230:231], 0, s[26:27]
	s_mov_b32 m0, s29
	s_nop 0
	global_load_lds_dwordx4 v[192:193], off
	v_lshl_add_u64 v[192:193], v[232:233], 0, s[26:27]
	s_mov_b32 m0, s33
	s_nop 0
	global_load_lds_dwordx4 v[192:193], off
	s_waitcnt vmcnt(8) lgkmcnt(0)
	s_barrier
	s_setprio 1
	v_mfma_f32_16x16x32_bf16 v[92:95], v[128:131], v[176:179], v[92:95]
	v_mfma_f32_16x16x32_bf16 v[88:91], v[148:151], v[176:179], v[88:91]
	v_mfma_f32_16x16x32_bf16 v[84:87], v[128:131], v[184:187], v[84:87]
	v_mfma_f32_16x16x32_bf16 v[80:83], v[148:151], v[184:187], v[80:83]
	v_mfma_f32_16x16x32_bf16 v[76:79], v[128:131], v[200:203], v[76:79]
	v_mfma_f32_16x16x32_bf16 v[72:75], v[148:151], v[200:203], v[72:75]
	v_mfma_f32_16x16x32_bf16 v[68:71], v[128:131], v[208:211], v[68:71]
	v_mfma_f32_16x16x32_bf16 v[64:67], v[148:151], v[208:211], v[64:67]
	v_mfma_f32_16x16x32_bf16 v[92:95], v[144:147], v[180:183], v[92:95]
	v_mfma_f32_16x16x32_bf16 v[88:91], v[156:159], v[180:183], v[88:91]
	v_mfma_f32_16x16x32_bf16 v[84:87], v[144:147], v[188:191], v[84:87]
	v_mfma_f32_16x16x32_bf16 v[80:83], v[156:159], v[188:191], v[80:83]
	v_mfma_f32_16x16x32_bf16 v[76:79], v[144:147], v[204:207], v[76:79]
	v_mfma_f32_16x16x32_bf16 v[72:75], v[156:159], v[204:207], v[72:75]
	v_mfma_f32_16x16x32_bf16 v[68:71], v[144:147], v[212:215], v[68:71]
	v_mfma_f32_16x16x32_bf16 v[64:67], v[156:159], v[212:215], v[64:67]
	v_mfma_f32_16x16x32_bf16 v[28:31], v[160:163], v[176:179], v[28:31]
	v_mfma_f32_16x16x32_bf16 v[24:27], v[168:171], v[176:179], v[24:27]
	v_mfma_f32_16x16x32_bf16 v[20:23], v[160:163], v[184:187], v[20:23]
	v_mfma_f32_16x16x32_bf16 v[16:19], v[168:171], v[184:187], v[16:19]
	v_mfma_f32_16x16x32_bf16 v[12:15], v[160:163], v[200:203], v[12:15]
	v_mfma_f32_16x16x32_bf16 v[8:11], v[168:171], v[200:203], v[8:11]
	v_mfma_f32_16x16x32_bf16 v[4:7], v[160:163], v[208:211], v[4:7]
	v_mfma_f32_16x16x32_bf16 v[0:3], v[168:171], v[208:211], v[0:3]
	v_mfma_f32_16x16x32_bf16 v[28:31], v[164:167], v[180:183], v[28:31]
	v_mfma_f32_16x16x32_bf16 v[24:27], v[172:175], v[180:183], v[24:27]
	v_mfma_f32_16x16x32_bf16 v[20:23], v[164:167], v[188:191], v[20:23]
	v_mfma_f32_16x16x32_bf16 v[16:19], v[172:175], v[188:191], v[16:19]
	v_mfma_f32_16x16x32_bf16 v[12:15], v[164:167], v[204:207], v[12:15]
	v_mfma_f32_16x16x32_bf16 v[8:11], v[172:175], v[204:207], v[8:11]
	v_mfma_f32_16x16x32_bf16 v[4:7], v[164:167], v[212:215], v[4:7]
	v_mfma_f32_16x16x32_bf16 v[0:3], v[172:175], v[212:215], v[0:3]
	s_setprio 0
	s_barrier
	s_add_u32 s42, s42, 0x100
	s_addc_u32 s43, s43, 0
	s_add_u32 s69, s69, 0x100
	s_addc_u32 s78, s78, 0
	s_cmp_ge_i32 s79, s16
	s_mov_b32 s62, s79
	s_cbranch_scc0 .LBB0_618

; #define PG8_STAGE(bufoff, gbase, voff) do { _Pragma("unroll") for (int _i = 0; _i < 2; ++_i) \
;         __builtin_amdgcn_global_load_lds((const unsigned*)((const char*)(gbase) + (voff)[_i]), (PG8_LAS unsigned*)(lds + (bufoff) + ldsw + _i * 8192), 16, 0, 0); } while (0)
; #define PG8_LDA(dst, b, h) do { _Pragma("unroll") for (int m = 0; m < 4; ++m) _Pragma("unroll") for (int k = 0; k < 2; ++k) dst[m][k] = *(const PG8_LAS bf16x8*)(lds + PG8_SA(b, h) + aoff + m * 2048 + k * 1024); } while (0)
; #define PG8_LDB(dst, b, h) do { _Pragma("unroll") for (int n = 0; n < 2; ++n) _Pragma("unroll") for (int k = 0; k < 2; ++k) dst[n][k] = *(const PG8_LAS bf16x8*)(lds + PG8_SB(b, h) + boff + n * 2048 + k * 1024); } while (0)
; #define PG8_MMA(ai, bj, At, Bt) do { __builtin_amdgcn_s_setprio(1); _Pragma("unroll") for (int m = 0; m < 4; ++m) _Pragma("unroll") for (int n = 0; n < 2; ++n) _Pragma("unroll") for (int k = 0; k < 2; ++k) \
;         acc[ai][bj][m][n] = __builtin_amdgcn_mfma_f32_16x16x32_bf16(Bt[n][k], At[m][k], acc[ai][bj][m][n], 0, 0, 0); __builtin_amdgcn_s_setprio(0); } while (0)
; #define PG8_WAIT_V(n) asm volatile("s_waitcnt vmcnt(" #n ")" ::: "memory")
; #define PG8_WAIT_L(n) asm volatile("s_waitcnt lgkmcnt(" #n ")" ::: "memory")
; #define PG8_BAR __builtin_amdgcn_s_barrier()
; #define PG8_SCHED __builtin_amdgcn_sched_barrier(0)
; template <class Epi, class Sched, bool ALIGN_EPI = false, bool SP2 = false>
; __device__ __forceinline__ void gemm_phase(PG8_LAS unsigned char* lds, const Gemm g, const Sched& S, const Epi& E) {
;     ...
;             const char* a2 = last ? nA : cA + (size_t)(t + 2) * kstep; const char* b2 = last ? nB : cB + (size_t)(t + 2) * kstep;
;             const char* a3 = a2 + kstep; const char* b3 = b2 + kstep;
;             if (last && has_next) S.a_ready(nxt);
;             if constexpr (SP2) {
;             PG8_LDB(B0, 0, 0); PG8_LDB(B1, 0, 1); PG8_SCHED; PG8_LDA(At, 0, 0); PG8_STAGE(PG8_SA(1, 1), a1 + hstepA, voffA);
;             PG8_WAIT_V(8); PG8_WAIT_L(0); PG8_BAR; PG8_MMA(0, 0, At, B0); PG8_MMA(0, 1, At, B1); PG8_BAR; PG8_SCHED;
;             PG8_LDA(At, 0, 1); PG8_STAGE(PG8_SB(0, 0), b2, voffB); PG8_STAGE(PG8_SB(0, 1), b2 + hstepB, voffB); PG8_STAGE(PG8_SA(0, 0), a2, voffA);
;             PG8_WAIT_V(8); PG8_WAIT_L(0); PG8_BAR; PG8_MMA(1, 0, At, B0); PG8_MMA(1, 1, At, B1); PG8_BAR; PG8_SCHED;
.LBB0_929:
	s_add_i32 s59, s58, 2
	s_add_u32 s62, s84, 0xfffc0080
	s_addc_u32 s63, s85, -1
	s_add_i32 s64, 0, 0x10000
	s_cmp_eq_u32 s16, s58
	s_cselect_b32 s87, s28, s63
	s_cselect_b32 s86, s29, s62
	v_add_u32_e32 v136, s64, v170
	s_cselect_b32 s63, s33, s55
	s_cselect_b32 s62, s43, s45
	s_add_i32 s58, 0, 0x14000
	ds_read_b128 v[128:131], v136
	ds_read_b128 v[132:135], v136 offset:1024
	ds_read_b128 v[150:153], v136 offset:2048
	ds_read_b128 v[154:157], v136 offset:3072
	v_add_u32_e32 v136, s58, v170
	ds_read_b128 v[158:161], v136
	ds_read_b128 v[162:165], v136 offset:1024
	ds_read_b128 v[172:175], v136 offset:2048
	ds_read_b128 v[176:179], v136 offset:3072
	v_lshl_add_u64 v[136:137], s[84:85], 0, v[146:147]
	s_add_i32 m0, s3, 0xc000
	ds_read_b128 v[180:183], v171
	ds_read_b128 v[184:187], v171 offset:1024
	ds_read_b128 v[188:191], v171 offset:2048
	ds_read_b128 v[200:203], v171 offset:3072
	ds_read_b128 v[204:207], v171 offset:4096
	ds_read_b128 v[208:211], v171 offset:5120
	ds_read_b128 v[212:215], v171 offset:6144
	ds_read_b128 v[228:231], v171 offset:7168
	global_load_lds_dwordx4 v[136:137], off
	v_lshl_add_u64 v[136:137], s[84:85], 0, v[148:149]
	s_add_i32 m0, s3, 0xe000
	s_nop 0
	global_load_lds_dwordx4 v[136:137], off
	s_waitcnt vmcnt(8) lgkmcnt(0)
	s_barrier
	s_setprio 1
	v_mfma_f32_16x16x32_bf16 v[124:127], v[128:131], v[180:183], v[124:127]
	v_mfma_f32_16x16x32_bf16 v[120:123], v[150:153], v[180:183], v[120:123]
	v_mfma_f32_16x16x32_bf16 v[108:111], v[128:131], v[188:191], v[108:111]
	v_mfma_f32_16x16x32_bf16 v[104:107], v[150:153], v[188:191], v[104:107]
	v_mfma_f32_16x16x32_bf16 v[92:95], v[128:131], v[204:207], v[92:95]
	v_mfma_f32_16x16x32_bf16 v[88:91], v[150:153], v[204:207], v[88:91]
	v_mfma_f32_16x16x32_bf16 v[76:79], v[128:131], v[212:215], v[76:79]
	v_mfma_f32_16x16x32_bf16 v[72:75], v[150:153], v[212:215], v[72:75]
	v_mfma_f32_16x16x32_bf16 v[124:127], v[132:135], v[184:187], v[124:127]
	v_mfma_f32_16x16x32_bf16 v[120:123], v[154:157], v[184:187], v[120:123]
	v_mfma_f32_16x16x32_bf16 v[108:111], v[132:135], v[200:203], v[108:111]
	v_mfma_f32_16x16x32_bf16 v[104:107], v[154:157], v[200:203], v[104:107]
	v_mfma_f32_16x16x32_bf16 v[92:95], v[132:135], v[208:211], v[92:95]
	v_mfma_f32_16x16x32_bf16 v[88:91], v[154:157], v[208:211], v[88:91]
	v_mfma_f32_16x16x32_bf16 v[76:79], v[132:135], v[228:231], v[76:79]
	v_mfma_f32_16x16x32_bf16 v[72:75], v[154:157], v[228:231], v[72:75]
	v_mfma_f32_16x16x32_bf16 v[116:119], v[158:161], v[180:183], v[116:119]
	v_mfma_f32_16x16x32_bf16 v[112:115], v[172:175], v[180:183], v[112:115]
	v_mfma_f32_16x16x32_bf16 v[100:103], v[158:161], v[188:191], v[100:103]
	v_mfma_f32_16x16x32_bf16 v[96:99], v[172:175], v[188:191], v[96:99]
	v_mfma_f32_16x16x32_bf16 v[84:87], v[158:161], v[204:207], v[84:87]
	v_mfma_f32_16x16x32_bf16 v[80:83], v[172:175], v[204:207], v[80:83]
	v_mfma_f32_16x16x32_bf16 v[68:71], v[158:161], v[212:215], v[68:71]
	v_mfma_f32_16x16x32_bf16 v[64:67], v[172:175], v[212:215], v[64:67]
	v_mfma_f32_16x16x32_bf16 v[116:119], v[162:165], v[184:187], v[116:119]
	v_mfma_f32_16x16x32_bf16 v[112:115], v[176:179], v[184:187], v[112:115]
	v_mfma_f32_16x16x32_bf16 v[100:103], v[162:165], v[200:203], v[100:103]
	v_mfma_f32_16x16x32_bf16 v[96:99], v[176:179], v[200:203], v[96:99]
	v_mfma_f32_16x16x32_bf16 v[84:87], v[162:165], v[208:211], v[84:87]
	v_mfma_f32_16x16x32_bf16 v[80:83], v[176:179], v[208:211], v[80:83]
	v_mfma_f32_16x16x32_bf16 v[68:71], v[162:165], v[228:231], v[68:71]
	v_mfma_f32_16x16x32_bf16 v[64:67], v[176:179], v[228:231], v[64:67]
	s_setprio 0
	s_barrier
	s_add_i32 s64, s64, s2
	v_lshl_add_u64 v[136:137], s[62:63], 0, v[140:141]
	s_mov_b32 m0, s64
	ds_read_b128 v[180:183], v171 offset:16384
	ds_read_b128 v[184:187], v171 offset:17408
	ds_read_b128 v[188:191], v171 offset:18432
	ds_read_b128 v[200:203], v171 offset:19456
	ds_read_b128 v[204:207], v171 offset:20480
	ds_read_b128 v[208:211], v171 offset:21504
	ds_read_b128 v[212:215], v171 offset:22528
	ds_read_b128 v[228:231], v171 offset:23552
	global_load_lds_dwordx4 v[136:137], off
	s_add_i32 m0, s64, 0x2000
	s_add_u32 s78, s62, 0x40000
	v_lshl_add_u64 v[166:167], s[62:63], 0, v[144:145]
	s_addc_u32 s79, s63, 0
	s_add_i32 s58, s58, s2
	global_load_lds_dwordx4 v[166:167], off
	v_lshl_add_u64 v[192:193], s[78:79], 0, v[140:141]
	s_mov_b32 m0, s58
	v_lshl_add_u64 v[232:233], s[86:87], 0, v[142:143]
	global_load_lds_dwordx4 v[192:193], off
	v_lshl_add_u64 v[192:193], s[78:79], 0, v[144:145]
	s_add_i32 m0, s58, 0x2000
	s_nop 0
	global_load_lds_dwordx4 v[192:193], off
	v_lshl_add_u64 v[192:193], s[86:87], 0, v[138:139]
	s_mov_b32 m0, s3
	s_nop 0
	global_load_lds_dwordx4 v[192:193], off
	s_mov_b32 m0, s8
	s_nop 0
	global_load_lds_dwordx4 v[232:233], off
	s_waitcnt vmcnt(8) lgkmcnt(0)
	s_barrier
; #define PG8_STAGE(bufoff, gbase, voff) do { _Pragma("unroll") for (int _i = 0; _i < 2; ++_i) \
;         __builtin_amdgcn_global_load_lds((const unsigned*)((const char*)(gbase) + (voff)[_i]), (PG8_LAS unsigned*)(lds + (bufoff) + ldsw + _i * 8192), 16, 0, 0); } while (0)
; #define PG8_LDA(dst, b, h) do { _Pragma("unroll") for (int m = 0; m < 4; ++m) _Pragma("unroll") for (int k = 0; k < 2; ++k) dst[m][k] = *(const PG8_LAS bf16x8*)(lds + PG8_SA(b, h) + aoff + m * 2048 + k * 1024); } while (0)
; #define PG8_LDB(dst, b, h) do { _Pragma("unroll") for (int n = 0; n < 2; ++n) _Pragma("unroll") for (int k = 0; k < 2; ++k) dst[n][k] = *(const PG8_LAS bf16x8*)(lds + PG8_SB(b, h) + boff + n * 2048 + k * 1024); } while (0)
; #define PG8_MMA(ai, bj, At, Bt) do { __builtin_amdgcn_s_setprio(1); _Pragma("unroll") for (int m = 0; m < 4; ++m) _Pragma("unroll") for (int n = 0; n < 2; ++n) _Pragma("unroll") for (int k = 0; k < 2; ++k) \
;         acc[ai][bj][m][n] = __builtin_amdgcn_mfma_f32_16x16x32_bf16(Bt[n][k], At[m][k], acc[ai][bj][m][n], 0, 0, 0); __builtin_amdgcn_s_setprio(0); } while (0)
; #define PG8_WAIT_V(n) asm volatile("s_waitcnt vmcnt(" #n ")" ::: "memory")
; #define PG8_WAIT_L(n) asm volatile("s_waitcnt lgkmcnt(" #n ")" ::: "memory")
; #define PG8_BAR __builtin_amdgcn_s_barrier()
; #define PG8_SCHED __builtin_amdgcn_sched_barrier(0)
; template <class Epi, class Sched, bool ALIGN_EPI = false, bool SP2 = false>
; __device__ __forceinline__ void gemm_phase(PG8_LAS unsigned char* lds, const Gemm g, const Sched& S, const Epi& E) {
;     ...
;             PG8_WAIT_V(8); PG8_WAIT_L(0); PG8_BAR; PG8_MMA(1, 0, At, B0); PG8_MMA(1, 1, At, B1); PG8_BAR; PG8_SCHED;
;             PG8_LDB(B0, 1, 0); PG8_LDB(B1, 1, 1); PG8_SCHED; PG8_LDA(At, 1, 0); PG8_STAGE(PG8_SA(0, 1), a2 + hstepA, voffA);
;             PG8_WAIT_V(8); PG8_WAIT_L(0); PG8_BAR; PG8_MMA(0, 0, At, B0); PG8_MMA(0, 1, At, B1); PG8_BAR; PG8_SCHED;
	s_setprio 1
	v_mfma_f32_16x16x32_bf16 v[60:63], v[128:131], v[180:183], v[60:63]
	v_mfma_f32_16x16x32_bf16 v[56:59], v[150:153], v[180:183], v[56:59]
	v_mfma_f32_16x16x32_bf16 v[44:47], v[128:131], v[188:191], v[44:47]
	v_mfma_f32_16x16x32_bf16 v[40:43], v[150:153], v[188:191], v[40:43]
	v_mfma_f32_16x16x32_bf16 v[28:31], v[128:131], v[204:207], v[28:31]
	v_mfma_f32_16x16x32_bf16 v[24:27], v[150:153], v[204:207], v[24:27]
	v_mfma_f32_16x16x32_bf16 v[12:15], v[128:131], v[212:215], v[12:15]
	v_mfma_f32_16x16x32_bf16 v[8:11], v[150:153], v[212:215], v[8:11]
	v_mfma_f32_16x16x32_bf16 v[60:63], v[132:135], v[184:187], v[60:63]
	v_mfma_f32_16x16x32_bf16 v[56:59], v[154:157], v[184:187], v[56:59]
	v_mfma_f32_16x16x32_bf16 v[44:47], v[132:135], v[200:203], v[44:47]
	v_mfma_f32_16x16x32_bf16 v[40:43], v[154:157], v[200:203], v[40:43]
	v_mfma_f32_16x16x32_bf16 v[28:31], v[132:135], v[208:211], v[28:31]
	v_mfma_f32_16x16x32_bf16 v[24:27], v[154:157], v[208:211], v[24:27]
	v_mfma_f32_16x16x32_bf16 v[12:15], v[132:135], v[228:231], v[12:15]
	v_mfma_f32_16x16x32_bf16 v[8:11], v[154:157], v[228:231], v[8:11]
	v_mfma_f32_16x16x32_bf16 v[52:55], v[158:161], v[180:183], v[52:55]
	v_mfma_f32_16x16x32_bf16 v[48:51], v[172:175], v[180:183], v[48:51]
	v_mfma_f32_16x16x32_bf16 v[36:39], v[158:161], v[188:191], v[36:39]
	v_mfma_f32_16x16x32_bf16 v[32:35], v[172:175], v[188:191], v[32:35]
	v_mfma_f32_16x16x32_bf16 v[20:23], v[158:161], v[204:207], v[20:23]
	v_mfma_f32_16x16x32_bf16 v[16:19], v[172:175], v[204:207], v[16:19]
	v_mfma_f32_16x16x32_bf16 v[4:7], v[158:161], v[212:215], v[4:7]
	v_mfma_f32_16x16x32_bf16 v[0:3], v[172:175], v[212:215], v[0:3]
	v_mfma_f32_16x16x32_bf16 v[52:55], v[162:165], v[184:187], v[52:55]
	v_mfma_f32_16x16x32_bf16 v[48:51], v[176:179], v[184:187], v[48:51]
	v_mfma_f32_16x16x32_bf16 v[36:39], v[162:165], v[200:203], v[36:39]
	v_mfma_f32_16x16x32_bf16 v[32:35], v[176:179], v[200:203], v[32:35]
	v_mfma_f32_16x16x32_bf16 v[20:23], v[162:165], v[208:211], v[20:23]
	v_mfma_f32_16x16x32_bf16 v[16:19], v[176:179], v[208:211], v[16:19]
	v_mfma_f32_16x16x32_bf16 v[4:7], v[162:165], v[228:231], v[4:7]
	v_mfma_f32_16x16x32_bf16 v[0:3], v[176:179], v[228:231], v[0:3]
	s_setprio 0
	s_barrier
	s_add_i32 s58, 0, 0x18000
	s_add_i32 s64, 0, 0x1c000
	v_add_u32_e32 v154, s58, v170
	v_add_u32_e32 v176, s64, v170
	ds_read_b128 v[128:131], v154
	ds_read_b128 v[132:135], v154 offset:1024
	ds_read_b128 v[150:153], v154 offset:2048
	ds_read_b128 v[154:157], v154 offset:3072
	ds_read_b128 v[158:161], v176
	ds_read_b128 v[162:165], v176 offset:1024
	ds_read_b128 v[172:175], v176 offset:2048
	ds_read_b128 v[176:179], v176 offset:3072
	s_add_u32 s78, s86, 0x40000
	s_addc_u32 s79, s87, 0
	s_mov_b32 m0, s9
	v_lshl_add_u64 v[234:235], s[78:79], 0, v[138:139]
	ds_read_b128 v[180:183], v171 offset:32768
	ds_read_b128 v[184:187], v171 offset:33792
	ds_read_b128 v[188:191], v171 offset:34816
	ds_read_b128 v[200:203], v171 offset:35840
	ds_read_b128 v[204:207], v171 offset:36864
	ds_read_b128 v[208:211], v171 offset:37888
	ds_read_b128 v[212:215], v171 offset:38912
	ds_read_b128 v[228:231], v171 offset:39936
	global_load_lds_dwordx4 v[234:235], off
	v_lshl_add_u64 v[234:235], s[78:79], 0, v[142:143]
	s_mov_b32 m0, s10
	s_nop 0
	global_load_lds_dwordx4 v[234:235], off
	s_waitcnt vmcnt(8) lgkmcnt(0)
	s_barrier
	s_setprio 1
	v_mfma_f32_16x16x32_bf16 v[124:127], v[128:131], v[180:183], v[124:127]
	v_mfma_f32_16x16x32_bf16 v[120:123], v[150:153], v[180:183], v[120:123]
	v_mfma_f32_16x16x32_bf16 v[108:111], v[128:131], v[188:191], v[108:111]
	v_mfma_f32_16x16x32_bf16 v[104:107], v[150:153], v[188:191], v[104:107]
	v_mfma_f32_16x16x32_bf16 v[92:95], v[128:131], v[204:207], v[92:95]
	v_mfma_f32_16x16x32_bf16 v[88:91], v[150:153], v[204:207], v[88:91]
	v_mfma_f32_16x16x32_bf16 v[76:79], v[128:131], v[212:215], v[76:79]
	v_mfma_f32_16x16x32_bf16 v[72:75], v[150:153], v[212:215], v[72:75]
	v_mfma_f32_16x16x32_bf16 v[124:127], v[132:135], v[184:187], v[124:127]
	v_mfma_f32_16x16x32_bf16 v[120:123], v[154:157], v[184:187], v[120:123]
	v_mfma_f32_16x16x32_bf16 v[108:111], v[132:135], v[200:203], v[108:111]
	v_mfma_f32_16x16x32_bf16 v[104:107], v[154:157], v[200:203], v[104:107]
	v_mfma_f32_16x16x32_bf16 v[92:95], v[132:135], v[208:211], v[92:95]
	v_mfma_f32_16x16x32_bf16 v[88:91], v[154:157], v[208:211], v[88:91]
	v_mfma_f32_16x16x32_bf16 v[76:79], v[132:135], v[228:231], v[76:79]
	v_mfma_f32_16x16x32_bf16 v[72:75], v[154:157], v[228:231], v[72:75]
	v_mfma_f32_16x16x32_bf16 v[116:119], v[158:161], v[180:183], v[116:119]
	v_mfma_f32_16x16x32_bf16 v[112:115], v[172:175], v[180:183], v[112:115]
	v_mfma_f32_16x16x32_bf16 v[100:103], v[158:161], v[188:191], v[100:103]
	v_mfma_f32_16x16x32_bf16 v[96:99], v[172:175], v[188:191], v[96:99]
	v_mfma_f32_16x16x32_bf16 v[84:87], v[158:161], v[204:207], v[84:87]
	v_mfma_f32_16x16x32_bf16 v[80:83], v[172:175], v[204:207], v[80:83]
	v_mfma_f32_16x16x32_bf16 v[68:71], v[158:161], v[212:215], v[68:71]
	v_mfma_f32_16x16x32_bf16 v[64:67], v[172:175], v[212:215], v[64:67]
	v_mfma_f32_16x16x32_bf16 v[116:119], v[162:165], v[184:187], v[116:119]
	v_mfma_f32_16x16x32_bf16 v[112:115], v[176:179], v[184:187], v[112:115]
	v_mfma_f32_16x16x32_bf16 v[100:103], v[162:165], v[200:203], v[100:103]
	v_mfma_f32_16x16x32_bf16 v[96:99], v[176:179], v[200:203], v[96:99]
	v_mfma_f32_16x16x32_bf16 v[84:87], v[162:165], v[208:211], v[84:87]
	v_mfma_f32_16x16x32_bf16 v[80:83], v[176:179], v[208:211], v[80:83]
	v_mfma_f32_16x16x32_bf16 v[68:71], v[162:165], v[228:231], v[68:71]
	v_mfma_f32_16x16x32_bf16 v[64:67], v[176:179], v[228:231], v[64:67]
	s_setprio 0
	s_barrier
; #define PG8_STAGE(bufoff, gbase, voff) do { _Pragma("unroll") for (int _i = 0; _i < 2; ++_i) \
;         __builtin_amdgcn_global_load_lds((const unsigned*)((const char*)(gbase) + (voff)[_i]), (PG8_LAS unsigned*)(lds + (bufoff) + ldsw + _i * 8192), 16, 0, 0); } while (0)
; #define PG8_LDA(dst, b, h) do { _Pragma("unroll") for (int m = 0; m < 4; ++m) _Pragma("unroll") for (int k = 0; k < 2; ++k) dst[m][k] = *(const PG8_LAS bf16x8*)(lds + PG8_SA(b, h) + aoff + m * 2048 + k * 1024); } while (0)
; #define PG8_MMA(ai, bj, At, Bt) do { __builtin_amdgcn_s_setprio(1); _Pragma("unroll") for (int m = 0; m < 4; ++m) _Pragma("unroll") for (int n = 0; n < 2; ++n) _Pragma("unroll") for (int k = 0; k < 2; ++k) \
;         acc[ai][bj][m][n] = __builtin_amdgcn_mfma_f32_16x16x32_bf16(Bt[n][k], At[m][k], acc[ai][bj][m][n], 0, 0, 0); __builtin_amdgcn_s_setprio(0); } while (0)
; #define PG8_WAIT_V(n) asm volatile("s_waitcnt vmcnt(" #n ")" ::: "memory")
; #define PG8_WAIT_L(n) asm volatile("s_waitcnt lgkmcnt(" #n ")" ::: "memory")
; #define PG8_BAR __builtin_amdgcn_s_barrier()
; #define PG8_SCHED __builtin_amdgcn_sched_barrier(0)
; template <class Epi, class Sched, bool ALIGN_EPI = false, bool SP2 = false>
; __device__ __forceinline__ void gemm_phase(PG8_LAS unsigned char* lds, const Gemm g, const Sched& S, const Epi& E) {
;     ...
;             PG8_LDA(At, 1, 1); PG8_STAGE(PG8_SB(1, 0), b3, voffB); PG8_STAGE(PG8_SB(1, 1), b3 + hstepB, voffB); PG8_STAGE(PG8_SA(1, 0), a3, voffA);
;             PG8_WAIT_V(8); PG8_WAIT_L(0); PG8_BAR; PG8_MMA(1, 0, At, B0); PG8_MMA(1, 1, At, B1); PG8_BAR; PG8_SCHED;
	s_add_i32 s58, s58, s2
	v_lshl_add_u64 v[136:137], v[136:137], 0, s[26:27]
	s_mov_b32 m0, s58
	ds_read_b128 v[180:183], v171 offset:49152
	ds_read_b128 v[184:187], v171 offset:50176
	ds_read_b128 v[188:191], v171 offset:51200
	ds_read_b128 v[200:203], v171 offset:52224
	ds_read_b128 v[204:207], v171 offset:53248
	ds_read_b128 v[208:211], v171 offset:54272
	ds_read_b128 v[212:215], v171 offset:55296
	ds_read_b128 v[228:231], v171 offset:56320
	global_load_lds_dwordx4 v[136:137], off
	s_add_i32 m0, s58, 0x2000
	s_add_u32 s62, s62, 0x40080
	v_lshl_add_u64 v[136:137], v[166:167], 0, s[26:27]
	s_addc_u32 s63, s63, 0
	s_add_i32 s58, s64, s2
	global_load_lds_dwordx4 v[136:137], off
	v_lshl_add_u64 v[136:137], s[62:63], 0, v[140:141]
	s_mov_b32 m0, s58
	s_nop 0
	global_load_lds_dwordx4 v[136:137], off
	v_lshl_add_u64 v[136:137], s[62:63], 0, v[144:145]
	s_add_i32 m0, s58, 0x2000
	s_nop 0
	global_load_lds_dwordx4 v[136:137], off
	v_lshl_add_u64 v[136:137], v[192:193], 0, s[26:27]
	s_mov_b32 m0, s14
	s_nop 0
	global_load_lds_dwordx4 v[136:137], off
	v_lshl_add_u64 v[136:137], v[232:233], 0, s[26:27]
	s_mov_b32 m0, s15
	s_nop 0
	global_load_lds_dwordx4 v[136:137], off
	s_waitcnt vmcnt(8) lgkmcnt(0)
	s_barrier
	s_setprio 1
	v_mfma_f32_16x16x32_bf16 v[60:63], v[128:131], v[180:183], v[60:63]
	v_mfma_f32_16x16x32_bf16 v[56:59], v[150:153], v[180:183], v[56:59]
	v_mfma_f32_16x16x32_bf16 v[44:47], v[128:131], v[188:191], v[44:47]
	v_mfma_f32_16x16x32_bf16 v[40:43], v[150:153], v[188:191], v[40:43]
	v_mfma_f32_16x16x32_bf16 v[28:31], v[128:131], v[204:207], v[28:31]
	v_mfma_f32_16x16x32_bf16 v[24:27], v[150:153], v[204:207], v[24:27]
	v_mfma_f32_16x16x32_bf16 v[12:15], v[128:131], v[212:215], v[12:15]
	v_mfma_f32_16x16x32_bf16 v[8:11], v[150:153], v[212:215], v[8:11]
	v_mfma_f32_16x16x32_bf16 v[60:63], v[132:135], v[184:187], v[60:63]
	v_mfma_f32_16x16x32_bf16 v[56:59], v[154:157], v[184:187], v[56:59]
	v_mfma_f32_16x16x32_bf16 v[44:47], v[132:135], v[200:203], v[44:47]
	v_mfma_f32_16x16x32_bf16 v[40:43], v[154:157], v[200:203], v[40:43]
	v_mfma_f32_16x16x32_bf16 v[28:31], v[132:135], v[208:211], v[28:31]
	v_mfma_f32_16x16x32_bf16 v[24:27], v[154:157], v[208:211], v[24:27]
	v_mfma_f32_16x16x32_bf16 v[12:15], v[132:135], v[228:231], v[12:15]
	v_mfma_f32_16x16x32_bf16 v[8:11], v[154:157], v[228:231], v[8:11]
	v_mfma_f32_16x16x32_bf16 v[52:55], v[158:161], v[180:183], v[52:55]
	v_mfma_f32_16x16x32_bf16 v[48:51], v[172:175], v[180:183], v[48:51]
	v_mfma_f32_16x16x32_bf16 v[36:39], v[158:161], v[188:191], v[36:39]
	v_mfma_f32_16x16x32_bf16 v[32:35], v[172:175], v[188:191], v[32:35]
	v_mfma_f32_16x16x32_bf16 v[20:23], v[158:161], v[204:207], v[20:23]
	v_mfma_f32_16x16x32_bf16 v[16:19], v[172:175], v[204:207], v[16:19]
	v_mfma_f32_16x16x32_bf16 v[4:7], v[158:161], v[212:215], v[4:7]
	v_mfma_f32_16x16x32_bf16 v[0:3], v[172:175], v[212:215], v[0:3]
	v_mfma_f32_16x16x32_bf16 v[52:55], v[162:165], v[184:187], v[52:55]
	v_mfma_f32_16x16x32_bf16 v[48:51], v[176:179], v[184:187], v[48:51]
	v_mfma_f32_16x16x32_bf16 v[36:39], v[162:165], v[200:203], v[36:39]
	v_mfma_f32_16x16x32_bf16 v[32:35], v[176:179], v[200:203], v[32:35]
	v_mfma_f32_16x16x32_bf16 v[20:23], v[162:165], v[208:211], v[20:23]
	v_mfma_f32_16x16x32_bf16 v[16:19], v[176:179], v[208:211], v[16:19]
	v_mfma_f32_16x16x32_bf16 v[4:7], v[162:165], v[228:231], v[4:7]
	v_mfma_f32_16x16x32_bf16 v[0:3], v[176:179], v[228:231], v[0:3]
	s_setprio 0
	s_barrier
	s_add_u32 s84, s84, 0x100
	s_addc_u32 s85, s85, 0
	s_add_u32 s45, s45, 0x100
	s_addc_u32 s55, s55, 0
	s_cmp_ge_i32 s59, s11
	s_mov_b32 s58, s59
	s_cbranch_scc0 .LBB0_929

; #define PG8_STAGE(bufoff, gbase, voff) do { _Pragma("unroll") for (int _i = 0; _i < 2; ++_i) \
;         __builtin_amdgcn_global_load_lds((const unsigned*)((const char*)(gbase) + (voff)[_i]), (PG8_LAS unsigned*)(lds + (bufoff) + ldsw + _i * 8192), 16, 0, 0); } while (0)
; #define PG8_LDA(dst, b, h) do { _Pragma("unroll") for (int m = 0; m < 4; ++m) _Pragma("unroll") for (int k = 0; k < 2; ++k) dst[m][k] = *(const PG8_LAS bf16x8*)(lds + PG8_SA(b, h) + aoff + m * 2048 + k * 1024); } while (0)
; #define PG8_LDB(dst, b, h) do { _Pragma("unroll") for (int n = 0; n < 2; ++n) _Pragma("unroll") for (int k = 0; k < 2; ++k) dst[n][k] = *(const PG8_LAS bf16x8*)(lds + PG8_SB(b, h) + boff + n * 2048 + k * 1024); } while (0)
; #define PG8_MMA(ai, bj, At, Bt) do { __builtin_amdgcn_s_setprio(1); _Pragma("unroll") for (int m = 0; m < 4; ++m) _Pragma("unroll") for (int n = 0; n < 2; ++n) _Pragma("unroll") for (int k = 0; k < 2; ++k) \
;         acc[ai][bj][m][n] = __builtin_amdgcn_mfma_f32_16x16x32_bf16(Bt[n][k], At[m][k], acc[ai][bj][m][n], 0, 0, 0); __builtin_amdgcn_s_setprio(0); } while (0)
; #define PG8_WAIT_V(n) asm volatile("s_waitcnt vmcnt(" #n ")" ::: "memory")
; #define PG8_WAIT_L(n) asm volatile("s_waitcnt lgkmcnt(" #n ")" ::: "memory")
; #define PG8_BAR __builtin_amdgcn_s_barrier()
; #define PG8_SCHED __builtin_amdgcn_sched_barrier(0)
; template <class Epi, class Sched, bool ALIGN_EPI = false, bool SP2 = false>
; __device__ __forceinline__ void gemm_phase(PG8_LAS unsigned char* lds, const Gemm g, const Sched& S, const Epi& E) {
;     ...
;             const char* a2 = last ? nA : cA + (size_t)(t + 2) * kstep; const char* b2 = last ? nB : cB + (size_t)(t + 2) * kstep;
;             const char* a3 = a2 + kstep; const char* b3 = b2 + kstep;
;             if (last && has_next) S.a_ready(nxt);
;             if constexpr (SP2) {
;             PG8_LDB(B0, 0, 0); PG8_LDB(B1, 0, 1); PG8_SCHED; PG8_LDA(At, 0, 0); PG8_STAGE(PG8_SA(1, 1), a1 + hstepA, voffA);
;             PG8_WAIT_V(8); PG8_WAIT_L(0); PG8_BAR; PG8_MMA(0, 0, At, B0); PG8_MMA(0, 1, At, B1); PG8_BAR; PG8_SCHED;
;             PG8_LDA(At, 0, 1); PG8_STAGE(PG8_SB(0, 0), b2, voffB); PG8_STAGE(PG8_SB(0, 1), b2 + hstepB, voffB); PG8_STAGE(PG8_SA(0, 0), a2, voffA);
;             PG8_WAIT_V(8); PG8_WAIT_L(0); PG8_BAR; PG8_MMA(1, 0, At, B0); PG8_MMA(1, 1, At, B1); PG8_BAR; PG8_SCHED;
.LBB0_1019:
	s_add_i32 s64, s62, 2
	s_add_u32 s63, s84, 0xfffc0080
	s_addc_u32 s69, s85, -1
	s_add_i32 s74, 0, 0x10000
	s_cmp_eq_u32 s33, s62
	s_cselect_b32 s87, s49, s69
	s_cselect_b32 s86, s53, s63
	s_cselect_b32 s63, s55, s61
	s_cselect_b32 s62, s58, s59
	s_add_i32 s69, 0, 0x14000
	v_add_u32_e32 v156, s74, v142
	v_add_u32_e32 v172, s69, v142
	ds_read_b128 v[144:147], v156
	ds_read_b128 v[148:151], v156 offset:1024
	ds_read_b128 v[152:155], v156 offset:2048
	ds_read_b128 v[156:159], v156 offset:3072
	ds_read_b128 v[160:163], v172
	ds_read_b128 v[164:167], v172 offset:1024
	ds_read_b128 v[168:171], v172 offset:2048
	ds_read_b128 v[172:175], v172 offset:3072
	v_lshl_add_u64 v[192:193], s[84:85], 0, v[136:137]
	s_add_i32 m0, s11, 0xc000
	ds_read_b128 v[176:179], v143
	ds_read_b128 v[180:183], v143 offset:1024
	ds_read_b128 v[184:187], v143 offset:2048
	ds_read_b128 v[188:191], v143 offset:3072
	ds_read_b128 v[200:203], v143 offset:4096
	ds_read_b128 v[204:207], v143 offset:5120
	ds_read_b128 v[208:211], v143 offset:6144
	ds_read_b128 v[212:215], v143 offset:7168
	global_load_lds_dwordx4 v[192:193], off
	v_lshl_add_u64 v[192:193], s[84:85], 0, v[138:139]
	s_add_i32 m0, s11, 0xe000
	s_nop 0
	global_load_lds_dwordx4 v[192:193], off
	s_waitcnt vmcnt(8) lgkmcnt(0)
	s_barrier
	s_setprio 1
	v_mfma_f32_16x16x32_bf16 v[120:123], v[144:147], v[176:179], v[120:123]
	v_mfma_f32_16x16x32_bf16 v[124:127], v[152:155], v[176:179], v[124:127]
	v_mfma_f32_16x16x32_bf16 v[116:119], v[144:147], v[184:187], v[116:119]
	v_mfma_f32_16x16x32_bf16 v[112:115], v[152:155], v[184:187], v[112:115]
	v_mfma_f32_16x16x32_bf16 v[108:111], v[144:147], v[200:203], v[108:111]
	v_mfma_f32_16x16x32_bf16 v[104:107], v[152:155], v[200:203], v[104:107]
	v_mfma_f32_16x16x32_bf16 v[100:103], v[144:147], v[208:211], v[100:103]
	v_mfma_f32_16x16x32_bf16 v[96:99], v[152:155], v[208:211], v[96:99]
	v_mfma_f32_16x16x32_bf16 v[120:123], v[148:151], v[180:183], v[120:123]
	v_mfma_f32_16x16x32_bf16 v[124:127], v[156:159], v[180:183], v[124:127]
	v_mfma_f32_16x16x32_bf16 v[116:119], v[148:151], v[188:191], v[116:119]
	v_mfma_f32_16x16x32_bf16 v[112:115], v[156:159], v[188:191], v[112:115]
	v_mfma_f32_16x16x32_bf16 v[108:111], v[148:151], v[204:207], v[108:111]
	v_mfma_f32_16x16x32_bf16 v[104:107], v[156:159], v[204:207], v[104:107]
	v_mfma_f32_16x16x32_bf16 v[100:103], v[148:151], v[212:215], v[100:103]
	v_mfma_f32_16x16x32_bf16 v[96:99], v[156:159], v[212:215], v[96:99]
	v_mfma_f32_16x16x32_bf16 v[60:63], v[160:163], v[176:179], v[60:63]
	v_mfma_f32_16x16x32_bf16 v[56:59], v[168:171], v[176:179], v[56:59]
	v_mfma_f32_16x16x32_bf16 v[52:55], v[160:163], v[184:187], v[52:55]
	v_mfma_f32_16x16x32_bf16 v[48:51], v[168:171], v[184:187], v[48:51]
	v_mfma_f32_16x16x32_bf16 v[44:47], v[160:163], v[200:203], v[44:47]
	v_mfma_f32_16x16x32_bf16 v[40:43], v[168:171], v[200:203], v[40:43]
	v_mfma_f32_16x16x32_bf16 v[36:39], v[160:163], v[208:211], v[36:39]
	v_mfma_f32_16x16x32_bf16 v[32:35], v[168:171], v[208:211], v[32:35]
	v_mfma_f32_16x16x32_bf16 v[60:63], v[164:167], v[180:183], v[60:63]
	v_mfma_f32_16x16x32_bf16 v[56:59], v[172:175], v[180:183], v[56:59]
	v_mfma_f32_16x16x32_bf16 v[52:55], v[164:167], v[188:191], v[52:55]
	v_mfma_f32_16x16x32_bf16 v[48:51], v[172:175], v[188:191], v[48:51]
	v_mfma_f32_16x16x32_bf16 v[44:47], v[164:167], v[204:207], v[44:47]
	v_mfma_f32_16x16x32_bf16 v[40:43], v[172:175], v[204:207], v[40:43]
	v_mfma_f32_16x16x32_bf16 v[36:39], v[164:167], v[212:215], v[36:39]
	v_mfma_f32_16x16x32_bf16 v[32:35], v[172:175], v[212:215], v[32:35]
	s_setprio 0
	s_barrier
	s_add_i32 s74, s74, s2
	v_lshl_add_u64 v[192:193], s[62:63], 0, v[132:133]
	s_mov_b32 m0, s74
	ds_read_b128 v[176:179], v143 offset:16384
	ds_read_b128 v[180:183], v143 offset:17408
	ds_read_b128 v[184:187], v143 offset:18432
	ds_read_b128 v[188:191], v143 offset:19456
	ds_read_b128 v[200:203], v143 offset:20480
	ds_read_b128 v[204:207], v143 offset:21504
	ds_read_b128 v[208:211], v143 offset:22528
	ds_read_b128 v[212:215], v143 offset:23552
	global_load_lds_dwordx4 v[192:193], off
	s_add_i32 m0, s74, 0x2000
	s_add_u32 s78, s62, 0x40000
	v_lshl_add_u64 v[228:229], s[62:63], 0, v[128:129]
	s_addc_u32 s79, s63, 0
	s_add_i32 s69, s69, s2
	global_load_lds_dwordx4 v[228:229], off
	v_lshl_add_u64 v[230:231], s[78:79], 0, v[132:133]
	s_mov_b32 m0, s69
	v_lshl_add_u64 v[232:233], s[86:87], 0, v[130:131]
	global_load_lds_dwordx4 v[230:231], off
	v_lshl_add_u64 v[230:231], s[78:79], 0, v[128:129]
	s_add_i32 m0, s69, 0x2000
	s_nop 0
	global_load_lds_dwordx4 v[230:231], off
	v_lshl_add_u64 v[230:231], s[86:87], 0, v[134:135]
	s_mov_b32 m0, s11
	s_nop 0
	global_load_lds_dwordx4 v[230:231], off
	s_mov_b32 m0, s12
	s_nop 0
	global_load_lds_dwordx4 v[232:233], off
	s_waitcnt vmcnt(8) lgkmcnt(0)
	s_barrier
; #define PG8_STAGE(bufoff, gbase, voff) do { _Pragma("unroll") for (int _i = 0; _i < 2; ++_i) \
;         __builtin_amdgcn_global_load_lds((const unsigned*)((const char*)(gbase) + (voff)[_i]), (PG8_LAS unsigned*)(lds + (bufoff) + ldsw + _i * 8192), 16, 0, 0); } while (0)
; #define PG8_LDA(dst, b, h) do { _Pragma("unroll") for (int m = 0; m < 4; ++m) _Pragma("unroll") for (int k = 0; k < 2; ++k) dst[m][k] = *(const PG8_LAS bf16x8*)(lds + PG8_SA(b, h) + aoff + m * 2048 + k * 1024); } while (0)
; #define PG8_LDB(dst, b, h) do { _Pragma("unroll") for (int n = 0; n < 2; ++n) _Pragma("unroll") for (int k = 0; k < 2; ++k) dst[n][k] = *(const PG8_LAS bf16x8*)(lds + PG8_SB(b, h) + boff + n * 2048 + k * 1024); } while (0)
; #define PG8_MMA(ai, bj, At, Bt) do { __builtin_amdgcn_s_setprio(1); _Pragma("unroll") for (int m = 0; m < 4; ++m) _Pragma("unroll") for (int n = 0; n < 2; ++n) _Pragma("unroll") for (int k = 0; k < 2; ++k) \
;         acc[ai][bj][m][n] = __builtin_amdgcn_mfma_f32_16x16x32_bf16(Bt[n][k], At[m][k], acc[ai][bj][m][n], 0, 0, 0); __builtin_amdgcn_s_setprio(0); } while (0)
; #define PG8_WAIT_V(n) asm volatile("s_waitcnt vmcnt(" #n ")" ::: "memory")
; #define PG8_WAIT_L(n) asm volatile("s_waitcnt lgkmcnt(" #n ")" ::: "memory")
; #define PG8_BAR __builtin_amdgcn_s_barrier()
; #define PG8_SCHED __builtin_amdgcn_sched_barrier(0)
; template <class Epi, class Sched, bool ALIGN_EPI = false, bool SP2 = false>
; __device__ __forceinline__ void gemm_phase(PG8_LAS unsigned char* lds, const Gemm g, const Sched& S, const Epi& E) {
;     ...
;             PG8_WAIT_V(8); PG8_WAIT_L(0); PG8_BAR; PG8_MMA(1, 0, At, B0); PG8_MMA(1, 1, At, B1); PG8_BAR; PG8_SCHED;
;             PG8_LDB(B0, 1, 0); PG8_LDB(B1, 1, 1); PG8_SCHED; PG8_LDA(At, 1, 0); PG8_STAGE(PG8_SA(0, 1), a2 + hstepA, voffA);
;             PG8_WAIT_V(8); PG8_WAIT_L(0); PG8_BAR; PG8_MMA(0, 0, At, B0); PG8_MMA(0, 1, At, B1); PG8_BAR; PG8_SCHED;
	s_setprio 1
	v_mfma_f32_16x16x32_bf16 v[92:95], v[144:147], v[176:179], v[92:95]
	v_mfma_f32_16x16x32_bf16 v[88:91], v[152:155], v[176:179], v[88:91]
	v_mfma_f32_16x16x32_bf16 v[84:87], v[144:147], v[184:187], v[84:87]
	v_mfma_f32_16x16x32_bf16 v[80:83], v[152:155], v[184:187], v[80:83]
	v_mfma_f32_16x16x32_bf16 v[76:79], v[144:147], v[200:203], v[76:79]
	v_mfma_f32_16x16x32_bf16 v[72:75], v[152:155], v[200:203], v[72:75]
	v_mfma_f32_16x16x32_bf16 v[68:71], v[144:147], v[208:211], v[68:71]
	v_mfma_f32_16x16x32_bf16 v[64:67], v[152:155], v[208:211], v[64:67]
	v_mfma_f32_16x16x32_bf16 v[92:95], v[148:151], v[180:183], v[92:95]
	v_mfma_f32_16x16x32_bf16 v[88:91], v[156:159], v[180:183], v[88:91]
	v_mfma_f32_16x16x32_bf16 v[84:87], v[148:151], v[188:191], v[84:87]
	v_mfma_f32_16x16x32_bf16 v[80:83], v[156:159], v[188:191], v[80:83]
	v_mfma_f32_16x16x32_bf16 v[76:79], v[148:151], v[204:207], v[76:79]
	v_mfma_f32_16x16x32_bf16 v[72:75], v[156:159], v[204:207], v[72:75]
	v_mfma_f32_16x16x32_bf16 v[68:71], v[148:151], v[212:215], v[68:71]
	v_mfma_f32_16x16x32_bf16 v[64:67], v[156:159], v[212:215], v[64:67]
	v_mfma_f32_16x16x32_bf16 v[28:31], v[160:163], v[176:179], v[28:31]
	v_mfma_f32_16x16x32_bf16 v[24:27], v[168:171], v[176:179], v[24:27]
	v_mfma_f32_16x16x32_bf16 v[20:23], v[160:163], v[184:187], v[20:23]
	v_mfma_f32_16x16x32_bf16 v[16:19], v[168:171], v[184:187], v[16:19]
	v_mfma_f32_16x16x32_bf16 v[12:15], v[160:163], v[200:203], v[12:15]
	v_mfma_f32_16x16x32_bf16 v[8:11], v[168:171], v[200:203], v[8:11]
	v_mfma_f32_16x16x32_bf16 v[4:7], v[160:163], v[208:211], v[4:7]
	v_mfma_f32_16x16x32_bf16 v[0:3], v[168:171], v[208:211], v[0:3]
	v_mfma_f32_16x16x32_bf16 v[28:31], v[164:167], v[180:183], v[28:31]
	v_mfma_f32_16x16x32_bf16 v[24:27], v[172:175], v[180:183], v[24:27]
	v_mfma_f32_16x16x32_bf16 v[20:23], v[164:167], v[188:191], v[20:23]
	v_mfma_f32_16x16x32_bf16 v[16:19], v[172:175], v[188:191], v[16:19]
	v_mfma_f32_16x16x32_bf16 v[12:15], v[164:167], v[204:207], v[12:15]
	v_mfma_f32_16x16x32_bf16 v[8:11], v[172:175], v[204:207], v[8:11]
	v_mfma_f32_16x16x32_bf16 v[4:7], v[164:167], v[212:215], v[4:7]
	v_mfma_f32_16x16x32_bf16 v[0:3], v[172:175], v[212:215], v[0:3]
	s_setprio 0
	s_barrier
	s_add_i32 s69, 0, 0x18000
	s_add_i32 s74, 0, 0x1c000
	v_add_u32_e32 v156, s69, v142
	v_add_u32_e32 v172, s74, v142
	ds_read_b128 v[144:147], v156
	ds_read_b128 v[148:151], v156 offset:1024
	ds_read_b128 v[152:155], v156 offset:2048
	ds_read_b128 v[156:159], v156 offset:3072
	ds_read_b128 v[160:163], v172
	ds_read_b128 v[164:167], v172 offset:1024
	ds_read_b128 v[168:171], v172 offset:2048
	ds_read_b128 v[172:175], v172 offset:3072
	s_add_u32 s78, s86, 0x40000
	s_addc_u32 s79, s87, 0
	s_mov_b32 m0, s13
	v_lshl_add_u64 v[234:235], s[78:79], 0, v[134:135]
	ds_read_b128 v[176:179], v143 offset:32768
	ds_read_b128 v[180:183], v143 offset:33792
	ds_read_b128 v[184:187], v143 offset:34816
	ds_read_b128 v[188:191], v143 offset:35840
	ds_read_b128 v[200:203], v143 offset:36864
	ds_read_b128 v[204:207], v143 offset:37888
	ds_read_b128 v[208:211], v143 offset:38912
	ds_read_b128 v[212:215], v143 offset:39936
	global_load_lds_dwordx4 v[234:235], off
	v_lshl_add_u64 v[234:235], s[78:79], 0, v[130:131]
	s_mov_b32 m0, s14
	s_nop 0
	global_load_lds_dwordx4 v[234:235], off
	s_waitcnt vmcnt(8) lgkmcnt(0)
	s_barrier
	s_setprio 1
	v_mfma_f32_16x16x32_bf16 v[120:123], v[144:147], v[176:179], v[120:123]
	v_mfma_f32_16x16x32_bf16 v[124:127], v[152:155], v[176:179], v[124:127]
	v_mfma_f32_16x16x32_bf16 v[116:119], v[144:147], v[184:187], v[116:119]
	v_mfma_f32_16x16x32_bf16 v[112:115], v[152:155], v[184:187], v[112:115]
	v_mfma_f32_16x16x32_bf16 v[108:111], v[144:147], v[200:203], v[108:111]
	v_mfma_f32_16x16x32_bf16 v[104:107], v[152:155], v[200:203], v[104:107]
	v_mfma_f32_16x16x32_bf16 v[100:103], v[144:147], v[208:211], v[100:103]
	v_mfma_f32_16x16x32_bf16 v[96:99], v[152:155], v[208:211], v[96:99]
	v_mfma_f32_16x16x32_bf16 v[120:123], v[148:151], v[180:183], v[120:123]
	v_mfma_f32_16x16x32_bf16 v[124:127], v[156:159], v[180:183], v[124:127]
	v_mfma_f32_16x16x32_bf16 v[116:119], v[148:151], v[188:191], v[116:119]
	v_mfma_f32_16x16x32_bf16 v[112:115], v[156:159], v[188:191], v[112:115]
	v_mfma_f32_16x16x32_bf16 v[108:111], v[148:151], v[204:207], v[108:111]
	v_mfma_f32_16x16x32_bf16 v[104:107], v[156:159], v[204:207], v[104:107]
	v_mfma_f32_16x16x32_bf16 v[100:103], v[148:151], v[212:215], v[100:103]
	v_mfma_f32_16x16x32_bf16 v[96:99], v[156:159], v[212:215], v[96:99]
	v_mfma_f32_16x16x32_bf16 v[60:63], v[160:163], v[176:179], v[60:63]
	v_mfma_f32_16x16x32_bf16 v[56:59], v[168:171], v[176:179], v[56:59]
	v_mfma_f32_16x16x32_bf16 v[52:55], v[160:163], v[184:187], v[52:55]
	v_mfma_f32_16x16x32_bf16 v[48:51], v[168:171], v[184:187], v[48:51]
	v_mfma_f32_16x16x32_bf16 v[44:47], v[160:163], v[200:203], v[44:47]
	v_mfma_f32_16x16x32_bf16 v[40:43], v[168:171], v[200:203], v[40:43]
	v_mfma_f32_16x16x32_bf16 v[36:39], v[160:163], v[208:211], v[36:39]
	v_mfma_f32_16x16x32_bf16 v[32:35], v[168:171], v[208:211], v[32:35]
	v_mfma_f32_16x16x32_bf16 v[60:63], v[164:167], v[180:183], v[60:63]
	v_mfma_f32_16x16x32_bf16 v[56:59], v[172:175], v[180:183], v[56:59]
	v_mfma_f32_16x16x32_bf16 v[52:55], v[164:167], v[188:191], v[52:55]
	v_mfma_f32_16x16x32_bf16 v[48:51], v[172:175], v[188:191], v[48:51]
	v_mfma_f32_16x16x32_bf16 v[44:47], v[164:167], v[204:207], v[44:47]
	v_mfma_f32_16x16x32_bf16 v[40:43], v[172:175], v[204:207], v[40:43]
	v_mfma_f32_16x16x32_bf16 v[36:39], v[164:167], v[212:215], v[36:39]
	v_mfma_f32_16x16x32_bf16 v[32:35], v[172:175], v[212:215], v[32:35]
	s_setprio 0
	s_barrier
; #define PG8_STAGE(bufoff, gbase, voff) do { _Pragma("unroll") for (int _i = 0; _i < 2; ++_i) \
;         __builtin_amdgcn_global_load_lds((const unsigned*)((const char*)(gbase) + (voff)[_i]), (PG8_LAS unsigned*)(lds + (bufoff) + ldsw + _i * 8192), 16, 0, 0); } while (0)
; #define PG8_LDA(dst, b, h) do { _Pragma("unroll") for (int m = 0; m < 4; ++m) _Pragma("unroll") for (int k = 0; k < 2; ++k) dst[m][k] = *(const PG8_LAS bf16x8*)(lds + PG8_SA(b, h) + aoff + m * 2048 + k * 1024); } while (0)
; #define PG8_MMA(ai, bj, At, Bt) do { __builtin_amdgcn_s_setprio(1); _Pragma("unroll") for (int m = 0; m < 4; ++m) _Pragma("unroll") for (int n = 0; n < 2; ++n) _Pragma("unroll") for (int k = 0; k < 2; ++k) \
;         acc[ai][bj][m][n] = __builtin_amdgcn_mfma_f32_16x16x32_bf16(Bt[n][k], At[m][k], acc[ai][bj][m][n], 0, 0, 0); __builtin_amdgcn_s_setprio(0); } while (0)
; #define PG8_WAIT_V(n) asm volatile("s_waitcnt vmcnt(" #n ")" ::: "memory")
; #define PG8_WAIT_L(n) asm volatile("s_waitcnt lgkmcnt(" #n ")" ::: "memory")
; #define PG8_BAR __builtin_amdgcn_s_barrier()
; #define PG8_SCHED __builtin_amdgcn_sched_barrier(0)
; template <class Epi, class Sched, bool ALIGN_EPI = false, bool SP2 = false>
; __device__ __forceinline__ void gemm_phase(PG8_LAS unsigned char* lds, const Gemm g, const Sched& S, const Epi& E) {
;     ...
;             PG8_LDA(At, 1, 1); PG8_STAGE(PG8_SB(1, 0), b3, voffB); PG8_STAGE(PG8_SB(1, 1), b3 + hstepB, voffB); PG8_STAGE(PG8_SA(1, 0), a3, voffA);
;             PG8_WAIT_V(8); PG8_WAIT_L(0); PG8_BAR; PG8_MMA(1, 0, At, B0); PG8_MMA(1, 1, At, B1); PG8_BAR; PG8_SCHED;
	s_add_i32 s69, s69, s2
	v_lshl_add_u64 v[192:193], v[192:193], 0, s[26:27]
	s_mov_b32 m0, s69
	ds_read_b128 v[176:179], v143 offset:49152
	ds_read_b128 v[180:183], v143 offset:50176
	ds_read_b128 v[184:187], v143 offset:51200
	ds_read_b128 v[188:191], v143 offset:52224
	ds_read_b128 v[200:203], v143 offset:53248
	ds_read_b128 v[204:207], v143 offset:54272
	ds_read_b128 v[208:211], v143 offset:55296
	ds_read_b128 v[212:215], v143 offset:56320
	global_load_lds_dwordx4 v[192:193], off
	s_add_i32 m0, s69, 0x2000
	s_add_u32 s62, s62, 0x40080
	v_lshl_add_u64 v[192:193], v[228:229], 0, s[26:27]
	s_addc_u32 s63, s63, 0
	s_add_i32 s69, s74, s2
	global_load_lds_dwordx4 v[192:193], off
	v_lshl_add_u64 v[192:193], s[62:63], 0, v[132:133]
	s_mov_b32 m0, s69
	s_nop 0
	global_load_lds_dwordx4 v[192:193], off
	v_lshl_add_u64 v[192:193], s[62:63], 0, v[128:129]
	s_add_i32 m0, s69, 0x2000
	s_nop 0
	global_load_lds_dwordx4 v[192:193], off
	v_lshl_add_u64 v[192:193], v[230:231], 0, s[26:27]
	s_mov_b32 m0, s28
	s_nop 0
	global_load_lds_dwordx4 v[192:193], off
	v_lshl_add_u64 v[192:193], v[232:233], 0, s[26:27]
	s_mov_b32 m0, s29
	s_nop 0
	global_load_lds_dwordx4 v[192:193], off
	s_waitcnt vmcnt(8) lgkmcnt(0)
	s_barrier
	s_setprio 1
	v_mfma_f32_16x16x32_bf16 v[92:95], v[144:147], v[176:179], v[92:95]
	v_mfma_f32_16x16x32_bf16 v[88:91], v[152:155], v[176:179], v[88:91]
	v_mfma_f32_16x16x32_bf16 v[84:87], v[144:147], v[184:187], v[84:87]
	v_mfma_f32_16x16x32_bf16 v[80:83], v[152:155], v[184:187], v[80:83]
	v_mfma_f32_16x16x32_bf16 v[76:79], v[144:147], v[200:203], v[76:79]
	v_mfma_f32_16x16x32_bf16 v[72:75], v[152:155], v[200:203], v[72:75]
	v_mfma_f32_16x16x32_bf16 v[68:71], v[144:147], v[208:211], v[68:71]
	v_mfma_f32_16x16x32_bf16 v[64:67], v[152:155], v[208:211], v[64:67]
	v_mfma_f32_16x16x32_bf16 v[92:95], v[148:151], v[180:183], v[92:95]
	v_mfma_f32_16x16x32_bf16 v[88:91], v[156:159], v[180:183], v[88:91]
	v_mfma_f32_16x16x32_bf16 v[84:87], v[148:151], v[188:191], v[84:87]
	v_mfma_f32_16x16x32_bf16 v[80:83], v[156:159], v[188:191], v[80:83]
	v_mfma_f32_16x16x32_bf16 v[76:79], v[148:151], v[204:207], v[76:79]
	v_mfma_f32_16x16x32_bf16 v[72:75], v[156:159], v[204:207], v[72:75]
	v_mfma_f32_16x16x32_bf16 v[68:71], v[148:151], v[212:215], v[68:71]
	v_mfma_f32_16x16x32_bf16 v[64:67], v[156:159], v[212:215], v[64:67]
	v_mfma_f32_16x16x32_bf16 v[28:31], v[160:163], v[176:179], v[28:31]
	v_mfma_f32_16x16x32_bf16 v[24:27], v[168:171], v[176:179], v[24:27]
	v_mfma_f32_16x16x32_bf16 v[20:23], v[160:163], v[184:187], v[20:23]
	v_mfma_f32_16x16x32_bf16 v[16:19], v[168:171], v[184:187], v[16:19]
	v_mfma_f32_16x16x32_bf16 v[12:15], v[160:163], v[200:203], v[12:15]
	v_mfma_f32_16x16x32_bf16 v[8:11], v[168:171], v[200:203], v[8:11]
	v_mfma_f32_16x16x32_bf16 v[4:7], v[160:163], v[208:211], v[4:7]
	v_mfma_f32_16x16x32_bf16 v[0:3], v[168:171], v[208:211], v[0:3]
	v_mfma_f32_16x16x32_bf16 v[28:31], v[164:167], v[180:183], v[28:31]
	v_mfma_f32_16x16x32_bf16 v[24:27], v[172:175], v[180:183], v[24:27]
	v_mfma_f32_16x16x32_bf16 v[20:23], v[164:167], v[188:191], v[20:23]
	v_mfma_f32_16x16x32_bf16 v[16:19], v[172:175], v[188:191], v[16:19]
	v_mfma_f32_16x16x32_bf16 v[12:15], v[164:167], v[204:207], v[12:15]
	v_mfma_f32_16x16x32_bf16 v[8:11], v[172:175], v[204:207], v[8:11]
	v_mfma_f32_16x16x32_bf16 v[4:7], v[164:167], v[212:215], v[4:7]
	v_mfma_f32_16x16x32_bf16 v[0:3], v[172:175], v[212:215], v[0:3]
	s_setprio 0
	s_barrier
	s_add_u32 s84, s84, 0x100
	s_addc_u32 s85, s85, 0
	s_add_u32 s59, s59, 0x100
	s_addc_u32 s61, s61, 0
	s_cmp_ge_i32 s64, s15
	s_mov_b32 s62, s64
	s_cbranch_scc0 .LBB0_1019

; #define PG8_STAGE(bufoff, gbase, voff) do { _Pragma("unroll") for (int _i = 0; _i < 2; ++_i) \
;         __builtin_amdgcn_global_load_lds((const unsigned*)((const char*)(gbase) + (voff)[_i]), (PG8_LAS unsigned*)(lds + (bufoff) + ldsw + _i * 8192), 16, 0, 0); } while (0)
; #define PG8_LDA(dst, b, h) do { _Pragma("unroll") for (int m = 0; m < 4; ++m) _Pragma("unroll") for (int k = 0; k < 2; ++k) dst[m][k] = *(const PG8_LAS bf16x8*)(lds + PG8_SA(b, h) + aoff + m * 2048 + k * 1024); } while (0)
; #define PG8_LDB(dst, b, h) do { _Pragma("unroll") for (int n = 0; n < 2; ++n) _Pragma("unroll") for (int k = 0; k < 2; ++k) dst[n][k] = *(const PG8_LAS bf16x8*)(lds + PG8_SB(b, h) + boff + n * 2048 + k * 1024); } while (0)
; #define PG8_MMA(ai, bj, At, Bt) do { __builtin_amdgcn_s_setprio(1); _Pragma("unroll") for (int m = 0; m < 4; ++m) _Pragma("unroll") for (int n = 0; n < 2; ++n) _Pragma("unroll") for (int k = 0; k < 2; ++k) \
;         acc[ai][bj][m][n] = __builtin_amdgcn_mfma_f32_16x16x32_bf16(Bt[n][k], At[m][k], acc[ai][bj][m][n], 0, 0, 0); __builtin_amdgcn_s_setprio(0); } while (0)
; #define PG8_WAIT_V(n) asm volatile("s_waitcnt vmcnt(" #n ")" ::: "memory")
; #define PG8_WAIT_L(n) asm volatile("s_waitcnt lgkmcnt(" #n ")" ::: "memory")
; template <class Epi, class Sched, bool ALIGN_EPI = false, bool SP2 = false>
; __device__ __forceinline__ void gemm_phase(PG8_LAS unsigned char* lds, const Gemm g, const Sched& S, const Epi& E) {
;     ...
;             const bool last = (t == nt - 2);
;             const char* a1 = cA + (size_t)(t + 1) * kstep;
;             const char* a2 = last ? nA : cA + (size_t)(t + 2) * kstep; const char* b2 = last ? nB : cB + (size_t)(t + 2) * kstep;
;             const char* a3 = a2 + kstep; const char* b3 = b2 + kstep;
;             if (last && has_next) S.a_ready(nxt);
;             if constexpr (SP2) {
;             PG8_LDB(B0, 0, 0); PG8_LDB(B1, 0, 1); PG8_SCHED; PG8_LDA(At, 0, 0); PG8_STAGE(PG8_SA(1, 1), a1 + hstepA, voffA);
;             PG8_WAIT_V(8); PG8_WAIT_L(0); PG8_BAR; PG8_MMA(0, 0, At, B0); PG8_MMA(0, 1, At, B1); PG8_BAR; PG8_SCHED;
;             PG8_LDA(At, 0, 1); PG8_STAGE(PG8_SB(0, 0), b2, voffB); PG8_STAGE(PG8_SB(0, 1), b2 + hstepB, voffB); PG8_STAGE(PG8_SA(0, 0), a2, voffA);
;             PG8_WAIT_V(8); PG8_WAIT_L(0); PG8_BAR; PG8_MMA(1, 0, At, B0); PG8_MMA(1, 1, At, B1); PG8_BAR; PG8_SCHED;
.LBB0_1218:
	s_add_i32 s79, s44, 2
	s_add_u32 s83, s42, 0x80
	s_addc_u32 s45, s43, 0
	s_add_i32 s74, 0, 0x10000
	s_cmp_eq_u32 s15, s44
	s_cselect_b32 s45, s35, s45
	s_cselect_b32 s44, s41, s83
	s_cselect_b32 vcc_hi, s61, s69
	s_cselect_b32 vcc_lo, s62, s63
	s_add_i32 s75, 0, 0x14000
	v_add_u32_e32 v150, s74, v178
	v_add_u32_e32 v166, s75, v178
	ds_read_b128 v[128:131], v150
	ds_read_b128 v[132:135], v150 offset:1024
	ds_read_b128 v[146:149], v150 offset:2048
	ds_read_b128 v[150:153], v150 offset:3072
	ds_read_b128 v[154:157], v166
	ds_read_b128 v[158:161], v166 offset:1024
	ds_read_b128 v[162:165], v166 offset:2048
	ds_read_b128 v[166:169], v166 offset:3072
	v_lshl_add_u64 v[174:175], s[42:43], 0, v[142:143]
	s_add_i32 m0, s85, 0xc000
	ds_read_b128 v[170:173], v179
	ds_read_b128 v[180:183], v179 offset:1024
	ds_read_b128 v[184:187], v179 offset:2048
	ds_read_b128 v[188:191], v179 offset:3072
	ds_read_b128 v[200:203], v179 offset:4096
	ds_read_b128 v[204:207], v179 offset:5120
	ds_read_b128 v[208:211], v179 offset:6144
	ds_read_b128 v[212:215], v179 offset:7168
	global_load_lds_dwordx4 v[174:175], off
	v_lshl_add_u64 v[174:175], s[42:43], 0, v[144:145]
	s_add_i32 m0, s85, 0xe000
	s_nop 0
	global_load_lds_dwordx4 v[174:175], off
	s_waitcnt vmcnt(8) lgkmcnt(0)
	s_barrier
	s_setprio 1
	v_mfma_f32_16x16x32_bf16 v[120:123], v[128:131], v[170:173], v[120:123]
	v_mfma_f32_16x16x32_bf16 v[124:127], v[146:149], v[170:173], v[124:127]
	v_mfma_f32_16x16x32_bf16 v[108:111], v[128:131], v[184:187], v[108:111]
	v_mfma_f32_16x16x32_bf16 v[104:107], v[146:149], v[184:187], v[104:107]
	v_mfma_f32_16x16x32_bf16 v[92:95], v[128:131], v[200:203], v[92:95]
	v_mfma_f32_16x16x32_bf16 v[88:91], v[146:149], v[200:203], v[88:91]
	v_mfma_f32_16x16x32_bf16 v[76:79], v[128:131], v[208:211], v[76:79]
	v_mfma_f32_16x16x32_bf16 v[72:75], v[146:149], v[208:211], v[72:75]
	v_mfma_f32_16x16x32_bf16 v[120:123], v[132:135], v[180:183], v[120:123]
	v_mfma_f32_16x16x32_bf16 v[124:127], v[150:153], v[180:183], v[124:127]
	v_mfma_f32_16x16x32_bf16 v[108:111], v[132:135], v[188:191], v[108:111]
	v_mfma_f32_16x16x32_bf16 v[104:107], v[150:153], v[188:191], v[104:107]
	v_mfma_f32_16x16x32_bf16 v[92:95], v[132:135], v[204:207], v[92:95]
	v_mfma_f32_16x16x32_bf16 v[88:91], v[150:153], v[204:207], v[88:91]
	v_mfma_f32_16x16x32_bf16 v[76:79], v[132:135], v[212:215], v[76:79]
	v_mfma_f32_16x16x32_bf16 v[72:75], v[150:153], v[212:215], v[72:75]
	v_mfma_f32_16x16x32_bf16 v[116:119], v[154:157], v[170:173], v[116:119]
	v_mfma_f32_16x16x32_bf16 v[112:115], v[162:165], v[170:173], v[112:115]
	v_mfma_f32_16x16x32_bf16 v[100:103], v[154:157], v[184:187], v[100:103]
	v_mfma_f32_16x16x32_bf16 v[96:99], v[162:165], v[184:187], v[96:99]
	v_mfma_f32_16x16x32_bf16 v[84:87], v[154:157], v[200:203], v[84:87]
	v_mfma_f32_16x16x32_bf16 v[80:83], v[162:165], v[200:203], v[80:83]
	v_mfma_f32_16x16x32_bf16 v[68:71], v[154:157], v[208:211], v[68:71]
	v_mfma_f32_16x16x32_bf16 v[64:67], v[162:165], v[208:211], v[64:67]
	v_mfma_f32_16x16x32_bf16 v[116:119], v[158:161], v[180:183], v[116:119]
	v_mfma_f32_16x16x32_bf16 v[112:115], v[166:169], v[180:183], v[112:115]
	v_mfma_f32_16x16x32_bf16 v[100:103], v[158:161], v[188:191], v[100:103]
	v_mfma_f32_16x16x32_bf16 v[96:99], v[166:169], v[188:191], v[96:99]
	v_mfma_f32_16x16x32_bf16 v[84:87], v[158:161], v[204:207], v[84:87]
	v_mfma_f32_16x16x32_bf16 v[80:83], v[166:169], v[204:207], v[80:83]
	v_mfma_f32_16x16x32_bf16 v[68:71], v[158:161], v[212:215], v[68:71]
	v_mfma_f32_16x16x32_bf16 v[64:67], v[166:169], v[212:215], v[64:67]
	s_setprio 0
	s_barrier
	s_add_i32 s74, s74, s8
	v_lshl_add_u64 v[174:175], vcc, 0, v[194:195]
	s_mov_b32 m0, s74
	ds_read_b128 v[170:173], v179 offset:16384
	ds_read_b128 v[180:183], v179 offset:17408
	ds_read_b128 v[184:187], v179 offset:18432
	ds_read_b128 v[188:191], v179 offset:19456
	ds_read_b128 v[200:203], v179 offset:20480
	ds_read_b128 v[204:207], v179 offset:21504
	ds_read_b128 v[208:211], v179 offset:22528
	ds_read_b128 v[212:215], v179 offset:23552
	global_load_lds_dwordx4 v[174:175], off
	s_add_i32 m0, s74, 0x2000
	v_lshl_add_u64 v[192:193], vcc, 0, v[140:141]
	s_add_u32 vcc_lo, vcc_lo, s82
	s_addc_u32 vcc_hi, vcc_hi, 0
	s_add_i32 s74, s75, s8
	global_load_lds_dwordx4 v[192:193], off
	v_lshl_add_u64 v[228:229], vcc, 0, v[194:195]
	s_mov_b32 m0, s74
	v_lshl_add_u64 v[230:231], vcc, 0, v[140:141]
	global_load_lds_dwordx4 v[228:229], off
	s_add_i32 m0, s74, 0x2000
	v_lshl_add_u64 v[232:233], s[44:45], 0, v[136:137]
	global_load_lds_dwordx4 v[230:231], off
	s_mov_b32 m0, s85
	v_lshl_add_u64 v[234:235], s[44:45], 0, v[138:139]
	global_load_lds_dwordx4 v[232:233], off
	s_mov_b32 m0, s10
	s_nop 0
	global_load_lds_dwordx4 v[234:235], off
	s_waitcnt vmcnt(8) lgkmcnt(0)
	s_barrier
; #define PG8_STAGE(bufoff, gbase, voff) do { _Pragma("unroll") for (int _i = 0; _i < 2; ++_i) \
;         __builtin_amdgcn_global_load_lds((const unsigned*)((const char*)(gbase) + (voff)[_i]), (PG8_LAS unsigned*)(lds + (bufoff) + ldsw + _i * 8192), 16, 0, 0); } while (0)
; #define PG8_LDA(dst, b, h) do { _Pragma("unroll") for (int m = 0; m < 4; ++m) _Pragma("unroll") for (int k = 0; k < 2; ++k) dst[m][k] = *(const PG8_LAS bf16x8*)(lds + PG8_SA(b, h) + aoff + m * 2048 + k * 1024); } while (0)
; #define PG8_LDB(dst, b, h) do { _Pragma("unroll") for (int n = 0; n < 2; ++n) _Pragma("unroll") for (int k = 0; k < 2; ++k) dst[n][k] = *(const PG8_LAS bf16x8*)(lds + PG8_SB(b, h) + boff + n * 2048 + k * 1024); } while (0)
; #define PG8_MMA(ai, bj, At, Bt) do { __builtin_amdgcn_s_setprio(1); _Pragma("unroll") for (int m = 0; m < 4; ++m) _Pragma("unroll") for (int n = 0; n < 2; ++n) _Pragma("unroll") for (int k = 0; k < 2; ++k) \
;         acc[ai][bj][m][n] = __builtin_amdgcn_mfma_f32_16x16x32_bf16(Bt[n][k], At[m][k], acc[ai][bj][m][n], 0, 0, 0); __builtin_amdgcn_s_setprio(0); } while (0)
; #define PG8_WAIT_V(n) asm volatile("s_waitcnt vmcnt(" #n ")" ::: "memory")
; #define PG8_WAIT_L(n) asm volatile("s_waitcnt lgkmcnt(" #n ")" ::: "memory")
; #define PG8_BAR __builtin_amdgcn_s_barrier()
; #define PG8_SCHED __builtin_amdgcn_sched_barrier(0)
; template <class Epi, class Sched, bool ALIGN_EPI = false, bool SP2 = false>
; __device__ __forceinline__ void gemm_phase(PG8_LAS unsigned char* lds, const Gemm g, const Sched& S, const Epi& E) {
;     ...
;             PG8_WAIT_V(8); PG8_WAIT_L(0); PG8_BAR; PG8_MMA(1, 0, At, B0); PG8_MMA(1, 1, At, B1); PG8_BAR; PG8_SCHED;
;             PG8_LDB(B0, 1, 0); PG8_LDB(B1, 1, 1); PG8_SCHED; PG8_LDA(At, 1, 0); PG8_STAGE(PG8_SA(0, 1), a2 + hstepA, voffA);
;             PG8_WAIT_V(8); PG8_WAIT_L(0); PG8_BAR; PG8_MMA(0, 0, At, B0); PG8_MMA(0, 1, At, B1); PG8_BAR; PG8_SCHED;
	s_setprio 1
	v_mfma_f32_16x16x32_bf16 v[60:63], v[128:131], v[170:173], v[60:63]
	v_mfma_f32_16x16x32_bf16 v[56:59], v[146:149], v[170:173], v[56:59]
	v_mfma_f32_16x16x32_bf16 v[44:47], v[128:131], v[184:187], v[44:47]
	v_mfma_f32_16x16x32_bf16 v[40:43], v[146:149], v[184:187], v[40:43]
	v_mfma_f32_16x16x32_bf16 v[28:31], v[128:131], v[200:203], v[28:31]
	v_mfma_f32_16x16x32_bf16 v[24:27], v[146:149], v[200:203], v[24:27]
	v_mfma_f32_16x16x32_bf16 v[12:15], v[128:131], v[208:211], v[12:15]
	v_mfma_f32_16x16x32_bf16 v[8:11], v[146:149], v[208:211], v[8:11]
	v_mfma_f32_16x16x32_bf16 v[60:63], v[132:135], v[180:183], v[60:63]
	v_mfma_f32_16x16x32_bf16 v[56:59], v[150:153], v[180:183], v[56:59]
	v_mfma_f32_16x16x32_bf16 v[44:47], v[132:135], v[188:191], v[44:47]
	v_mfma_f32_16x16x32_bf16 v[40:43], v[150:153], v[188:191], v[40:43]
	v_mfma_f32_16x16x32_bf16 v[28:31], v[132:135], v[204:207], v[28:31]
	v_mfma_f32_16x16x32_bf16 v[24:27], v[150:153], v[204:207], v[24:27]
	v_mfma_f32_16x16x32_bf16 v[12:15], v[132:135], v[212:215], v[12:15]
	v_mfma_f32_16x16x32_bf16 v[8:11], v[150:153], v[212:215], v[8:11]
	v_mfma_f32_16x16x32_bf16 v[52:55], v[154:157], v[170:173], v[52:55]
	v_mfma_f32_16x16x32_bf16 v[48:51], v[162:165], v[170:173], v[48:51]
	v_mfma_f32_16x16x32_bf16 v[36:39], v[154:157], v[184:187], v[36:39]
	v_mfma_f32_16x16x32_bf16 v[32:35], v[162:165], v[184:187], v[32:35]
	v_mfma_f32_16x16x32_bf16 v[20:23], v[154:157], v[200:203], v[20:23]
	v_mfma_f32_16x16x32_bf16 v[16:19], v[162:165], v[200:203], v[16:19]
	v_mfma_f32_16x16x32_bf16 v[4:7], v[154:157], v[208:211], v[4:7]
	v_mfma_f32_16x16x32_bf16 v[0:3], v[162:165], v[208:211], v[0:3]
	v_mfma_f32_16x16x32_bf16 v[52:55], v[158:161], v[180:183], v[52:55]
	v_mfma_f32_16x16x32_bf16 v[48:51], v[166:169], v[180:183], v[48:51]
	v_mfma_f32_16x16x32_bf16 v[36:39], v[158:161], v[188:191], v[36:39]
	v_mfma_f32_16x16x32_bf16 v[32:35], v[166:169], v[188:191], v[32:35]
	v_mfma_f32_16x16x32_bf16 v[20:23], v[158:161], v[204:207], v[20:23]
	v_mfma_f32_16x16x32_bf16 v[16:19], v[166:169], v[204:207], v[16:19]
	v_mfma_f32_16x16x32_bf16 v[4:7], v[158:161], v[212:215], v[4:7]
	v_mfma_f32_16x16x32_bf16 v[0:3], v[166:169], v[212:215], v[0:3]
	s_setprio 0
	s_barrier
	s_add_i32 s74, 0, 0x18000
	s_add_i32 s75, 0, 0x1c000
	v_add_u32_e32 v150, s74, v178
	v_add_u32_e32 v166, s75, v178
	ds_read_b128 v[128:131], v150
	ds_read_b128 v[132:135], v150 offset:1024
	ds_read_b128 v[146:149], v150 offset:2048
	ds_read_b128 v[150:153], v150 offset:3072
	ds_read_b128 v[154:157], v166
	ds_read_b128 v[158:161], v166 offset:1024
	ds_read_b128 v[162:165], v166 offset:2048
	ds_read_b128 v[166:169], v166 offset:3072
	s_add_u32 s44, s44, s82
	s_addc_u32 s45, s45, 0
	s_mov_b32 m0, s11
	v_lshl_add_u64 v[236:237], s[44:45], 0, v[136:137]
	ds_read_b128 v[170:173], v179 offset:32768
	ds_read_b128 v[180:183], v179 offset:33792
	ds_read_b128 v[184:187], v179 offset:34816
	ds_read_b128 v[188:191], v179 offset:35840
	ds_read_b128 v[200:203], v179 offset:36864
	ds_read_b128 v[204:207], v179 offset:37888
	ds_read_b128 v[208:211], v179 offset:38912
	ds_read_b128 v[212:215], v179 offset:39936
	global_load_lds_dwordx4 v[236:237], off
	v_lshl_add_u64 v[236:237], s[44:45], 0, v[138:139]
	s_mov_b32 m0, s12
	s_nop 0
	global_load_lds_dwordx4 v[236:237], off
	s_waitcnt vmcnt(8) lgkmcnt(0)
	s_barrier
	s_setprio 1
	v_mfma_f32_16x16x32_bf16 v[120:123], v[128:131], v[170:173], v[120:123]
	v_mfma_f32_16x16x32_bf16 v[124:127], v[146:149], v[170:173], v[124:127]
	v_mfma_f32_16x16x32_bf16 v[108:111], v[128:131], v[184:187], v[108:111]
	v_mfma_f32_16x16x32_bf16 v[104:107], v[146:149], v[184:187], v[104:107]
	v_mfma_f32_16x16x32_bf16 v[92:95], v[128:131], v[200:203], v[92:95]
	v_mfma_f32_16x16x32_bf16 v[88:91], v[146:149], v[200:203], v[88:91]
	v_mfma_f32_16x16x32_bf16 v[76:79], v[128:131], v[208:211], v[76:79]
	v_mfma_f32_16x16x32_bf16 v[72:75], v[146:149], v[208:211], v[72:75]
	v_mfma_f32_16x16x32_bf16 v[120:123], v[132:135], v[180:183], v[120:123]
	v_mfma_f32_16x16x32_bf16 v[124:127], v[150:153], v[180:183], v[124:127]
	v_mfma_f32_16x16x32_bf16 v[108:111], v[132:135], v[188:191], v[108:111]
	v_mfma_f32_16x16x32_bf16 v[104:107], v[150:153], v[188:191], v[104:107]
	v_mfma_f32_16x16x32_bf16 v[92:95], v[132:135], v[204:207], v[92:95]
	v_mfma_f32_16x16x32_bf16 v[88:91], v[150:153], v[204:207], v[88:91]
	v_mfma_f32_16x16x32_bf16 v[76:79], v[132:135], v[212:215], v[76:79]
	v_mfma_f32_16x16x32_bf16 v[72:75], v[150:153], v[212:215], v[72:75]
	v_mfma_f32_16x16x32_bf16 v[116:119], v[154:157], v[170:173], v[116:119]
	v_mfma_f32_16x16x32_bf16 v[112:115], v[162:165], v[170:173], v[112:115]
	v_mfma_f32_16x16x32_bf16 v[100:103], v[154:157], v[184:187], v[100:103]
	v_mfma_f32_16x16x32_bf16 v[96:99], v[162:165], v[184:187], v[96:99]
	v_mfma_f32_16x16x32_bf16 v[84:87], v[154:157], v[200:203], v[84:87]
	v_mfma_f32_16x16x32_bf16 v[80:83], v[162:165], v[200:203], v[80:83]
	v_mfma_f32_16x16x32_bf16 v[68:71], v[154:157], v[208:211], v[68:71]
	v_mfma_f32_16x16x32_bf16 v[64:67], v[162:165], v[208:211], v[64:67]
	v_mfma_f32_16x16x32_bf16 v[116:119], v[158:161], v[180:183], v[116:119]
	v_mfma_f32_16x16x32_bf16 v[112:115], v[166:169], v[180:183], v[112:115]
	v_mfma_f32_16x16x32_bf16 v[100:103], v[158:161], v[188:191], v[100:103]
	v_mfma_f32_16x16x32_bf16 v[96:99], v[166:169], v[188:191], v[96:99]
	v_mfma_f32_16x16x32_bf16 v[84:87], v[158:161], v[204:207], v[84:87]
	v_mfma_f32_16x16x32_bf16 v[80:83], v[166:169], v[204:207], v[80:83]
	v_mfma_f32_16x16x32_bf16 v[68:71], v[158:161], v[212:215], v[68:71]
	v_mfma_f32_16x16x32_bf16 v[64:67], v[166:169], v[212:215], v[64:67]
	s_setprio 0
	s_barrier
; #define PG8_STAGE(bufoff, gbase, voff) do { _Pragma("unroll") for (int _i = 0; _i < 2; ++_i) \
;         __builtin_amdgcn_global_load_lds((const unsigned*)((const char*)(gbase) + (voff)[_i]), (PG8_LAS unsigned*)(lds + (bufoff) + ldsw + _i * 8192), 16, 0, 0); } while (0)
; #define PG8_LDA(dst, b, h) do { _Pragma("unroll") for (int m = 0; m < 4; ++m) _Pragma("unroll") for (int k = 0; k < 2; ++k) dst[m][k] = *(const PG8_LAS bf16x8*)(lds + PG8_SA(b, h) + aoff + m * 2048 + k * 1024); } while (0)
; #define PG8_MMA(ai, bj, At, Bt) do { __builtin_amdgcn_s_setprio(1); _Pragma("unroll") for (int m = 0; m < 4; ++m) _Pragma("unroll") for (int n = 0; n < 2; ++n) _Pragma("unroll") for (int k = 0; k < 2; ++k) \
;         acc[ai][bj][m][n] = __builtin_amdgcn_mfma_f32_16x16x32_bf16(Bt[n][k], At[m][k], acc[ai][bj][m][n], 0, 0, 0); __builtin_amdgcn_s_setprio(0); } while (0)
; #define PG8_WAIT_V(n) asm volatile("s_waitcnt vmcnt(" #n ")" ::: "memory")
; #define PG8_WAIT_L(n) asm volatile("s_waitcnt lgkmcnt(" #n ")" ::: "memory")
; #define PG8_BAR __builtin_amdgcn_s_barrier()
; #define PG8_SCHED __builtin_amdgcn_sched_barrier(0)
; template <class Epi, class Sched, bool ALIGN_EPI = false, bool SP2 = false>
; __device__ __forceinline__ void gemm_phase(PG8_LAS unsigned char* lds, const Gemm g, const Sched& S, const Epi& E) {
;     ...
;         for (int t = 0; t < nt; t += 2) {
;     ...
;             PG8_LDA(At, 1, 1); PG8_STAGE(PG8_SB(1, 0), b3, voffB); PG8_STAGE(PG8_SB(1, 1), b3 + hstepB, voffB); PG8_STAGE(PG8_SA(1, 0), a3, voffA);
;             PG8_WAIT_V(8); PG8_WAIT_L(0); PG8_BAR; PG8_MMA(1, 0, At, B0); PG8_MMA(1, 1, At, B1); PG8_BAR; PG8_SCHED;
	s_add_i32 s44, s74, s8
	v_lshl_add_u64 v[174:175], v[174:175], 0, s[26:27]
	s_mov_b32 m0, s44
	ds_read_b128 v[170:173], v179 offset:49152
	ds_read_b128 v[180:183], v179 offset:50176
	ds_read_b128 v[184:187], v179 offset:51200
	ds_read_b128 v[188:191], v179 offset:52224
	ds_read_b128 v[200:203], v179 offset:53248
	ds_read_b128 v[204:207], v179 offset:54272
	ds_read_b128 v[208:211], v179 offset:55296
	ds_read_b128 v[212:215], v179 offset:56320
	global_load_lds_dwordx4 v[174:175], off
	v_lshl_add_u64 v[174:175], v[192:193], 0, s[26:27]
	s_add_i32 m0, s44, 0x2000
	s_add_i32 s44, s75, s8
	global_load_lds_dwordx4 v[174:175], off
	v_lshl_add_u64 v[174:175], v[228:229], 0, s[26:27]
	s_mov_b32 m0, s44
	s_nop 0
	global_load_lds_dwordx4 v[174:175], off
	v_lshl_add_u64 v[174:175], v[230:231], 0, s[26:27]
	s_add_i32 m0, s44, 0x2000
	s_nop 0
	global_load_lds_dwordx4 v[174:175], off
	v_lshl_add_u64 v[174:175], v[232:233], 0, s[26:27]
	s_mov_b32 m0, s64
	s_nop 0
	global_load_lds_dwordx4 v[174:175], off
	v_lshl_add_u64 v[174:175], v[234:235], 0, s[26:27]
	s_mov_b32 m0, s14
	s_nop 0
	global_load_lds_dwordx4 v[174:175], off
	s_waitcnt vmcnt(8) lgkmcnt(0)
	s_barrier
	s_setprio 1
	v_mfma_f32_16x16x32_bf16 v[60:63], v[128:131], v[170:173], v[60:63]
	v_mfma_f32_16x16x32_bf16 v[56:59], v[146:149], v[170:173], v[56:59]
	v_mfma_f32_16x16x32_bf16 v[44:47], v[128:131], v[184:187], v[44:47]
	v_mfma_f32_16x16x32_bf16 v[40:43], v[146:149], v[184:187], v[40:43]
	v_mfma_f32_16x16x32_bf16 v[28:31], v[128:131], v[200:203], v[28:31]
	v_mfma_f32_16x16x32_bf16 v[24:27], v[146:149], v[200:203], v[24:27]
	v_mfma_f32_16x16x32_bf16 v[12:15], v[128:131], v[208:211], v[12:15]
	v_mfma_f32_16x16x32_bf16 v[8:11], v[146:149], v[208:211], v[8:11]
	v_mfma_f32_16x16x32_bf16 v[60:63], v[132:135], v[180:183], v[60:63]
	v_mfma_f32_16x16x32_bf16 v[56:59], v[150:153], v[180:183], v[56:59]
	v_mfma_f32_16x16x32_bf16 v[44:47], v[132:135], v[188:191], v[44:47]
	v_mfma_f32_16x16x32_bf16 v[40:43], v[150:153], v[188:191], v[40:43]
	v_mfma_f32_16x16x32_bf16 v[28:31], v[132:135], v[204:207], v[28:31]
	v_mfma_f32_16x16x32_bf16 v[24:27], v[150:153], v[204:207], v[24:27]
	v_mfma_f32_16x16x32_bf16 v[12:15], v[132:135], v[212:215], v[12:15]
	v_mfma_f32_16x16x32_bf16 v[8:11], v[150:153], v[212:215], v[8:11]
	v_mfma_f32_16x16x32_bf16 v[52:55], v[154:157], v[170:173], v[52:55]
	v_mfma_f32_16x16x32_bf16 v[48:51], v[162:165], v[170:173], v[48:51]
	v_mfma_f32_16x16x32_bf16 v[36:39], v[154:157], v[184:187], v[36:39]
	v_mfma_f32_16x16x32_bf16 v[32:35], v[162:165], v[184:187], v[32:35]
	v_mfma_f32_16x16x32_bf16 v[20:23], v[154:157], v[200:203], v[20:23]
	v_mfma_f32_16x16x32_bf16 v[16:19], v[162:165], v[200:203], v[16:19]
	v_mfma_f32_16x16x32_bf16 v[4:7], v[154:157], v[208:211], v[4:7]
	v_mfma_f32_16x16x32_bf16 v[0:3], v[162:165], v[208:211], v[0:3]
	v_mfma_f32_16x16x32_bf16 v[52:55], v[158:161], v[180:183], v[52:55]
	v_mfma_f32_16x16x32_bf16 v[48:51], v[166:169], v[180:183], v[48:51]
	v_mfma_f32_16x16x32_bf16 v[36:39], v[158:161], v[188:191], v[36:39]
	v_mfma_f32_16x16x32_bf16 v[32:35], v[166:169], v[188:191], v[32:35]
	v_mfma_f32_16x16x32_bf16 v[20:23], v[158:161], v[204:207], v[20:23]
	v_mfma_f32_16x16x32_bf16 v[16:19], v[166:169], v[204:207], v[16:19]
	v_mfma_f32_16x16x32_bf16 v[4:7], v[158:161], v[212:215], v[4:7]
	v_mfma_f32_16x16x32_bf16 v[0:3], v[166:169], v[212:215], v[0:3]
	s_setprio 0
	s_barrier
	s_add_u32 s42, s42, 0x100
	s_addc_u32 s43, s43, 0
	s_add_u32 s63, s63, 0x100
	s_addc_u32 s69, s69, 0
	s_cmp_ge_i32 s79, s13
	s_mov_b32 s44, s79
	s_cbranch_scc0 .LBB0_1218

; #define PG8_STAGE(bufoff, gbase, voff) do { _Pragma("unroll") for (int _i = 0; _i < 2; ++_i) \
;         __builtin_amdgcn_global_load_lds((const unsigned*)((const char*)(gbase) + (voff)[_i]), (PG8_LAS unsigned*)(lds + (bufoff) + ldsw + _i * 8192), 16, 0, 0); } while (0)
; #define PG8_LDA(dst, b, h) do { _Pragma("unroll") for (int m = 0; m < 4; ++m) _Pragma("unroll") for (int k = 0; k < 2; ++k) dst[m][k] = *(const PG8_LAS bf16x8*)(lds + PG8_SA(b, h) + aoff + m * 2048 + k * 1024); } while (0)
; #define PG8_LDB(dst, b, h) do { _Pragma("unroll") for (int n = 0; n < 2; ++n) _Pragma("unroll") for (int k = 0; k < 2; ++k) dst[n][k] = *(const PG8_LAS bf16x8*)(lds + PG8_SB(b, h) + boff + n * 2048 + k * 1024); } while (0)
; #define PG8_MMA(ai, bj, At, Bt) do { __builtin_amdgcn_s_setprio(1); _Pragma("unroll") for (int m = 0; m < 4; ++m) _Pragma("unroll") for (int n = 0; n < 2; ++n) _Pragma("unroll") for (int k = 0; k < 2; ++k) \
;         acc[ai][bj][m][n] = __builtin_amdgcn_mfma_f32_16x16x32_bf16(Bt[n][k], At[m][k], acc[ai][bj][m][n], 0, 0, 0); __builtin_amdgcn_s_setprio(0); } while (0)
; #define PG8_WAIT_V(n) asm volatile("s_waitcnt vmcnt(" #n ")" ::: "memory")
; #define PG8_WAIT_L(n) asm volatile("s_waitcnt lgkmcnt(" #n ")" ::: "memory")
; template <class Epi, class Sched, bool ALIGN_EPI = false, bool SP2 = false>
; __device__ __forceinline__ void gemm_phase(PG8_LAS unsigned char* lds, const Gemm g, const Sched& S, const Epi& E) {
;     ...
;             const bool last = (t == nt - 2);
;             const char* a1 = cA + (size_t)(t + 1) * kstep;
;             const char* a2 = last ? nA : cA + (size_t)(t + 2) * kstep; const char* b2 = last ? nB : cB + (size_t)(t + 2) * kstep;
;             const char* a3 = a2 + kstep; const char* b3 = b2 + kstep;
;             if (last && has_next) S.a_ready(nxt);
;             if constexpr (SP2) {
;             PG8_LDB(B0, 0, 0); PG8_LDB(B1, 0, 1); PG8_SCHED; PG8_LDA(At, 0, 0); PG8_STAGE(PG8_SA(1, 1), a1 + hstepA, voffA);
;             PG8_WAIT_V(8); PG8_WAIT_L(0); PG8_BAR; PG8_MMA(0, 0, At, B0); PG8_MMA(0, 1, At, B1); PG8_BAR; PG8_SCHED;
;             PG8_LDA(At, 0, 1); PG8_STAGE(PG8_SB(0, 0), b2, voffB); PG8_STAGE(PG8_SB(0, 1), b2 + hstepB, voffB); PG8_STAGE(PG8_SA(0, 0), a2, voffA);
;             PG8_WAIT_V(8); PG8_WAIT_L(0); PG8_BAR; PG8_MMA(1, 0, At, B0); PG8_MMA(1, 1, At, B1); PG8_BAR; PG8_SCHED;
.LBB0_1463:
	s_add_i32 s86, s84, 2
	s_add_u32 s74, s40, 0x80
	s_addc_u32 s75, s41, 0
	s_add_i32 s87, 0, 0x10000
	s_cmp_eq_u32 s29, s84
	s_cselect_b32 s85, s77, s75
	s_cselect_b32 s84, s76, s74
	s_cselect_b32 s89, s83, s79
	s_cselect_b32 s88, s82, s78
	s_add_i32 s74, 0, 0x14000
	v_add_u32_e32 v140, s87, v166
	v_add_u32_e32 v144, s74, v166
	ds_read_b128 v[128:131], v140
	ds_read_b128 v[132:135], v140 offset:1024
	ds_read_b128 v[136:139], v140 offset:2048
	ds_read_b128 v[140:143], v140 offset:3072
	ds_read_b128 v[156:159], v144
	ds_read_b128 v[160:163], v144 offset:1024
	ds_read_b128 v[168:171], v144 offset:2048
	ds_read_b128 v[172:175], v144 offset:3072
	v_lshl_add_u64 v[144:145], s[40:41], 0, v[152:153]
	s_add_i32 m0, s8, 0xc000
	ds_read_b128 v[176:179], v167
	ds_read_b128 v[180:183], v167 offset:1024
	ds_read_b128 v[184:187], v167 offset:2048
	ds_read_b128 v[188:191], v167 offset:3072
	ds_read_b128 v[200:203], v167 offset:4096
	ds_read_b128 v[204:207], v167 offset:5120
	ds_read_b128 v[208:211], v167 offset:6144
	ds_read_b128 v[212:215], v167 offset:7168
	global_load_lds_dwordx4 v[144:145], off
	v_lshl_add_u64 v[144:145], s[40:41], 0, v[154:155]
	s_add_i32 m0, s8, 0xe000
	s_nop 0
	global_load_lds_dwordx4 v[144:145], off
	s_waitcnt vmcnt(8) lgkmcnt(0)
	s_barrier
	s_setprio 1
	v_mfma_f32_16x16x32_bf16 v[124:127], v[128:131], v[176:179], v[124:127]
	v_mfma_f32_16x16x32_bf16 v[120:123], v[136:139], v[176:179], v[120:123]
	v_mfma_f32_16x16x32_bf16 v[116:119], v[128:131], v[184:187], v[116:119]
	v_mfma_f32_16x16x32_bf16 v[112:115], v[136:139], v[184:187], v[112:115]
	v_mfma_f32_16x16x32_bf16 v[108:111], v[128:131], v[200:203], v[108:111]
	v_mfma_f32_16x16x32_bf16 v[104:107], v[136:139], v[200:203], v[104:107]
	v_mfma_f32_16x16x32_bf16 v[100:103], v[128:131], v[208:211], v[100:103]
	v_mfma_f32_16x16x32_bf16 v[96:99], v[136:139], v[208:211], v[96:99]
	v_mfma_f32_16x16x32_bf16 v[124:127], v[132:135], v[180:183], v[124:127]
	v_mfma_f32_16x16x32_bf16 v[120:123], v[140:143], v[180:183], v[120:123]
	v_mfma_f32_16x16x32_bf16 v[116:119], v[132:135], v[188:191], v[116:119]
	v_mfma_f32_16x16x32_bf16 v[112:115], v[140:143], v[188:191], v[112:115]
	v_mfma_f32_16x16x32_bf16 v[108:111], v[132:135], v[204:207], v[108:111]
	v_mfma_f32_16x16x32_bf16 v[104:107], v[140:143], v[204:207], v[104:107]
	v_mfma_f32_16x16x32_bf16 v[100:103], v[132:135], v[212:215], v[100:103]
	v_mfma_f32_16x16x32_bf16 v[96:99], v[140:143], v[212:215], v[96:99]
	v_mfma_f32_16x16x32_bf16 v[60:63], v[156:159], v[176:179], v[60:63]
	v_mfma_f32_16x16x32_bf16 v[56:59], v[168:171], v[176:179], v[56:59]
	v_mfma_f32_16x16x32_bf16 v[52:55], v[156:159], v[184:187], v[52:55]
	v_mfma_f32_16x16x32_bf16 v[48:51], v[168:171], v[184:187], v[48:51]
	v_mfma_f32_16x16x32_bf16 v[44:47], v[156:159], v[200:203], v[44:47]
	v_mfma_f32_16x16x32_bf16 v[40:43], v[168:171], v[200:203], v[40:43]
	v_mfma_f32_16x16x32_bf16 v[36:39], v[156:159], v[208:211], v[36:39]
	v_mfma_f32_16x16x32_bf16 v[32:35], v[168:171], v[208:211], v[32:35]
	v_mfma_f32_16x16x32_bf16 v[60:63], v[160:163], v[180:183], v[60:63]
	v_mfma_f32_16x16x32_bf16 v[56:59], v[172:175], v[180:183], v[56:59]
	v_mfma_f32_16x16x32_bf16 v[52:55], v[160:163], v[188:191], v[52:55]
	v_mfma_f32_16x16x32_bf16 v[48:51], v[172:175], v[188:191], v[48:51]
	v_mfma_f32_16x16x32_bf16 v[44:47], v[160:163], v[204:207], v[44:47]
	v_mfma_f32_16x16x32_bf16 v[40:43], v[172:175], v[204:207], v[40:43]
	v_mfma_f32_16x16x32_bf16 v[36:39], v[160:163], v[212:215], v[36:39]
	v_mfma_f32_16x16x32_bf16 v[32:35], v[172:175], v[212:215], v[32:35]
	s_setprio 0
	s_barrier
	s_add_i32 s75, s87, s3
	v_lshl_add_u64 v[144:145], s[88:89], 0, v[194:195]
	s_mov_b32 m0, s75
	ds_read_b128 v[176:179], v167 offset:16384
	ds_read_b128 v[180:183], v167 offset:17408
	ds_read_b128 v[184:187], v167 offset:18432
	ds_read_b128 v[188:191], v167 offset:19456
	ds_read_b128 v[200:203], v167 offset:20480
	ds_read_b128 v[204:207], v167 offset:21504
	ds_read_b128 v[208:211], v167 offset:22528
	ds_read_b128 v[212:215], v167 offset:23552
	global_load_lds_dwordx4 v[144:145], off
	s_add_i32 m0, s75, 0x2000
	v_lshl_add_u64 v[192:193], s[88:89], 0, v[146:147]
	s_add_u32 s88, s88, s80
	s_addc_u32 s89, s89, 0
	s_add_i32 s74, s74, s3
	global_load_lds_dwordx4 v[192:193], off
	v_lshl_add_u64 v[228:229], s[88:89], 0, v[194:195]
	s_mov_b32 m0, s74
	v_lshl_add_u64 v[230:231], s[88:89], 0, v[146:147]
	global_load_lds_dwordx4 v[228:229], off
	s_add_i32 m0, s74, 0x2000
	v_lshl_add_u64 v[232:233], s[84:85], 0, v[150:151]
	global_load_lds_dwordx4 v[230:231], off
	s_mov_b32 m0, s8
	v_lshl_add_u64 v[234:235], s[84:85], 0, v[148:149]
	global_load_lds_dwordx4 v[232:233], off
	s_mov_b32 m0, s9
	s_nop 0
	global_load_lds_dwordx4 v[234:235], off
	s_waitcnt vmcnt(8) lgkmcnt(0)
	s_barrier
; #define PG8_STAGE(bufoff, gbase, voff) do { _Pragma("unroll") for (int _i = 0; _i < 2; ++_i) \
;         __builtin_amdgcn_global_load_lds((const unsigned*)((const char*)(gbase) + (voff)[_i]), (PG8_LAS unsigned*)(lds + (bufoff) + ldsw + _i * 8192), 16, 0, 0); } while (0)
; #define PG8_LDA(dst, b, h) do { _Pragma("unroll") for (int m = 0; m < 4; ++m) _Pragma("unroll") for (int k = 0; k < 2; ++k) dst[m][k] = *(const PG8_LAS bf16x8*)(lds + PG8_SA(b, h) + aoff + m * 2048 + k * 1024); } while (0)
; #define PG8_LDB(dst, b, h) do { _Pragma("unroll") for (int n = 0; n < 2; ++n) _Pragma("unroll") for (int k = 0; k < 2; ++k) dst[n][k] = *(const PG8_LAS bf16x8*)(lds + PG8_SB(b, h) + boff + n * 2048 + k * 1024); } while (0)
; #define PG8_MMA(ai, bj, At, Bt) do { __builtin_amdgcn_s_setprio(1); _Pragma("unroll") for (int m = 0; m < 4; ++m) _Pragma("unroll") for (int n = 0; n < 2; ++n) _Pragma("unroll") for (int k = 0; k < 2; ++k) \
;         acc[ai][bj][m][n] = __builtin_amdgcn_mfma_f32_16x16x32_bf16(Bt[n][k], At[m][k], acc[ai][bj][m][n], 0, 0, 0); __builtin_amdgcn_s_setprio(0); } while (0)
; #define PG8_WAIT_V(n) asm volatile("s_waitcnt vmcnt(" #n ")" ::: "memory")
; #define PG8_WAIT_L(n) asm volatile("s_waitcnt lgkmcnt(" #n ")" ::: "memory")
; #define PG8_BAR __builtin_amdgcn_s_barrier()
; #define PG8_SCHED __builtin_amdgcn_sched_barrier(0)
; template <class Epi, class Sched, bool ALIGN_EPI = false, bool SP2 = false>
; __device__ __forceinline__ void gemm_phase(PG8_LAS unsigned char* lds, const Gemm g, const Sched& S, const Epi& E) {
;     ...
;             PG8_WAIT_V(8); PG8_WAIT_L(0); PG8_BAR; PG8_MMA(1, 0, At, B0); PG8_MMA(1, 1, At, B1); PG8_BAR; PG8_SCHED;
;             PG8_LDB(B0, 1, 0); PG8_LDB(B1, 1, 1); PG8_SCHED; PG8_LDA(At, 1, 0); PG8_STAGE(PG8_SA(0, 1), a2 + hstepA, voffA);
;             PG8_WAIT_V(8); PG8_WAIT_L(0); PG8_BAR; PG8_MMA(0, 0, At, B0); PG8_MMA(0, 1, At, B1); PG8_BAR; PG8_SCHED;
	s_setprio 1
	v_mfma_f32_16x16x32_bf16 v[92:95], v[128:131], v[176:179], v[92:95]
	v_mfma_f32_16x16x32_bf16 v[88:91], v[136:139], v[176:179], v[88:91]
	v_mfma_f32_16x16x32_bf16 v[84:87], v[128:131], v[184:187], v[84:87]
	v_mfma_f32_16x16x32_bf16 v[80:83], v[136:139], v[184:187], v[80:83]
	v_mfma_f32_16x16x32_bf16 v[76:79], v[128:131], v[200:203], v[76:79]
	v_mfma_f32_16x16x32_bf16 v[72:75], v[136:139], v[200:203], v[72:75]
	v_mfma_f32_16x16x32_bf16 v[68:71], v[128:131], v[208:211], v[68:71]
	v_mfma_f32_16x16x32_bf16 v[64:67], v[136:139], v[208:211], v[64:67]
	v_mfma_f32_16x16x32_bf16 v[92:95], v[132:135], v[180:183], v[92:95]
	v_mfma_f32_16x16x32_bf16 v[88:91], v[140:143], v[180:183], v[88:91]
	v_mfma_f32_16x16x32_bf16 v[84:87], v[132:135], v[188:191], v[84:87]
	v_mfma_f32_16x16x32_bf16 v[80:83], v[140:143], v[188:191], v[80:83]
	v_mfma_f32_16x16x32_bf16 v[76:79], v[132:135], v[204:207], v[76:79]
	v_mfma_f32_16x16x32_bf16 v[72:75], v[140:143], v[204:207], v[72:75]
	v_mfma_f32_16x16x32_bf16 v[68:71], v[132:135], v[212:215], v[68:71]
	v_mfma_f32_16x16x32_bf16 v[64:67], v[140:143], v[212:215], v[64:67]
	v_mfma_f32_16x16x32_bf16 v[28:31], v[156:159], v[176:179], v[28:31]
	v_mfma_f32_16x16x32_bf16 v[24:27], v[168:171], v[176:179], v[24:27]
	v_mfma_f32_16x16x32_bf16 v[20:23], v[156:159], v[184:187], v[20:23]
	v_mfma_f32_16x16x32_bf16 v[16:19], v[168:171], v[184:187], v[16:19]
	v_mfma_f32_16x16x32_bf16 v[12:15], v[156:159], v[200:203], v[12:15]
	v_mfma_f32_16x16x32_bf16 v[8:11], v[168:171], v[200:203], v[8:11]
	v_mfma_f32_16x16x32_bf16 v[4:7], v[156:159], v[208:211], v[4:7]
	v_mfma_f32_16x16x32_bf16 v[0:3], v[168:171], v[208:211], v[0:3]
	v_mfma_f32_16x16x32_bf16 v[28:31], v[160:163], v[180:183], v[28:31]
	v_mfma_f32_16x16x32_bf16 v[24:27], v[172:175], v[180:183], v[24:27]
	v_mfma_f32_16x16x32_bf16 v[20:23], v[160:163], v[188:191], v[20:23]
	v_mfma_f32_16x16x32_bf16 v[16:19], v[172:175], v[188:191], v[16:19]
	v_mfma_f32_16x16x32_bf16 v[12:15], v[160:163], v[204:207], v[12:15]
	v_mfma_f32_16x16x32_bf16 v[8:11], v[172:175], v[204:207], v[8:11]
	v_mfma_f32_16x16x32_bf16 v[4:7], v[160:163], v[212:215], v[4:7]
	v_mfma_f32_16x16x32_bf16 v[0:3], v[172:175], v[212:215], v[0:3]
	s_setprio 0
	s_barrier
	s_add_i32 s74, 0, 0x18000
	s_add_i32 s75, 0, 0x1c000
	v_add_u32_e32 v140, s74, v166
	v_add_u32_e32 v172, s75, v166
	ds_read_b128 v[128:131], v140
	ds_read_b128 v[132:135], v140 offset:1024
	ds_read_b128 v[136:139], v140 offset:2048
	ds_read_b128 v[140:143], v140 offset:3072
	ds_read_b128 v[156:159], v172
	ds_read_b128 v[160:163], v172 offset:1024
	ds_read_b128 v[168:171], v172 offset:2048
	ds_read_b128 v[172:175], v172 offset:3072
	s_add_u32 s84, s84, s80
	s_addc_u32 s85, s85, 0
	s_mov_b32 m0, s10
	v_lshl_add_u64 v[236:237], s[84:85], 0, v[150:151]
	ds_read_b128 v[176:179], v167 offset:32768
	ds_read_b128 v[180:183], v167 offset:33792
	ds_read_b128 v[184:187], v167 offset:34816
	ds_read_b128 v[188:191], v167 offset:35840
	ds_read_b128 v[200:203], v167 offset:36864
	ds_read_b128 v[204:207], v167 offset:37888
	ds_read_b128 v[208:211], v167 offset:38912
	ds_read_b128 v[212:215], v167 offset:39936
	global_load_lds_dwordx4 v[236:237], off
	v_lshl_add_u64 v[236:237], s[84:85], 0, v[148:149]
	s_mov_b32 m0, s11
	s_nop 0
	global_load_lds_dwordx4 v[236:237], off
	s_waitcnt vmcnt(8) lgkmcnt(0)
	s_barrier
	s_setprio 1
	v_mfma_f32_16x16x32_bf16 v[124:127], v[128:131], v[176:179], v[124:127]
	v_mfma_f32_16x16x32_bf16 v[120:123], v[136:139], v[176:179], v[120:123]
	v_mfma_f32_16x16x32_bf16 v[116:119], v[128:131], v[184:187], v[116:119]
	v_mfma_f32_16x16x32_bf16 v[112:115], v[136:139], v[184:187], v[112:115]
	v_mfma_f32_16x16x32_bf16 v[108:111], v[128:131], v[200:203], v[108:111]
	v_mfma_f32_16x16x32_bf16 v[104:107], v[136:139], v[200:203], v[104:107]
	v_mfma_f32_16x16x32_bf16 v[100:103], v[128:131], v[208:211], v[100:103]
	v_mfma_f32_16x16x32_bf16 v[96:99], v[136:139], v[208:211], v[96:99]
	v_mfma_f32_16x16x32_bf16 v[124:127], v[132:135], v[180:183], v[124:127]
	v_mfma_f32_16x16x32_bf16 v[120:123], v[140:143], v[180:183], v[120:123]
	v_mfma_f32_16x16x32_bf16 v[116:119], v[132:135], v[188:191], v[116:119]
	v_mfma_f32_16x16x32_bf16 v[112:115], v[140:143], v[188:191], v[112:115]
	v_mfma_f32_16x16x32_bf16 v[108:111], v[132:135], v[204:207], v[108:111]
	v_mfma_f32_16x16x32_bf16 v[104:107], v[140:143], v[204:207], v[104:107]
	v_mfma_f32_16x16x32_bf16 v[100:103], v[132:135], v[212:215], v[100:103]
	v_mfma_f32_16x16x32_bf16 v[96:99], v[140:143], v[212:215], v[96:99]
	v_mfma_f32_16x16x32_bf16 v[60:63], v[156:159], v[176:179], v[60:63]
	v_mfma_f32_16x16x32_bf16 v[56:59], v[168:171], v[176:179], v[56:59]
	v_mfma_f32_16x16x32_bf16 v[52:55], v[156:159], v[184:187], v[52:55]
	v_mfma_f32_16x16x32_bf16 v[48:51], v[168:171], v[184:187], v[48:51]
	v_mfma_f32_16x16x32_bf16 v[44:47], v[156:159], v[200:203], v[44:47]
	v_mfma_f32_16x16x32_bf16 v[40:43], v[168:171], v[200:203], v[40:43]
	v_mfma_f32_16x16x32_bf16 v[36:39], v[156:159], v[208:211], v[36:39]
	v_mfma_f32_16x16x32_bf16 v[32:35], v[168:171], v[208:211], v[32:35]
	v_mfma_f32_16x16x32_bf16 v[60:63], v[160:163], v[180:183], v[60:63]
	v_mfma_f32_16x16x32_bf16 v[56:59], v[172:175], v[180:183], v[56:59]
	v_mfma_f32_16x16x32_bf16 v[52:55], v[160:163], v[188:191], v[52:55]
	v_mfma_f32_16x16x32_bf16 v[48:51], v[172:175], v[188:191], v[48:51]
	v_mfma_f32_16x16x32_bf16 v[44:47], v[160:163], v[204:207], v[44:47]
	v_mfma_f32_16x16x32_bf16 v[40:43], v[172:175], v[204:207], v[40:43]
	v_mfma_f32_16x16x32_bf16 v[36:39], v[160:163], v[212:215], v[36:39]
	v_mfma_f32_16x16x32_bf16 v[32:35], v[172:175], v[212:215], v[32:35]
	s_setprio 0
	s_barrier
; #define PG8_STAGE(bufoff, gbase, voff) do { _Pragma("unroll") for (int _i = 0; _i < 2; ++_i) \
;         __builtin_amdgcn_global_load_lds((const unsigned*)((const char*)(gbase) + (voff)[_i]), (PG8_LAS unsigned*)(lds + (bufoff) + ldsw + _i * 8192), 16, 0, 0); } while (0)
; #define PG8_LDA(dst, b, h) do { _Pragma("unroll") for (int m = 0; m < 4; ++m) _Pragma("unroll") for (int k = 0; k < 2; ++k) dst[m][k] = *(const PG8_LAS bf16x8*)(lds + PG8_SA(b, h) + aoff + m * 2048 + k * 1024); } while (0)
; #define PG8_MMA(ai, bj, At, Bt) do { __builtin_amdgcn_s_setprio(1); _Pragma("unroll") for (int m = 0; m < 4; ++m) _Pragma("unroll") for (int n = 0; n < 2; ++n) _Pragma("unroll") for (int k = 0; k < 2; ++k) \
;         acc[ai][bj][m][n] = __builtin_amdgcn_mfma_f32_16x16x32_bf16(Bt[n][k], At[m][k], acc[ai][bj][m][n], 0, 0, 0); __builtin_amdgcn_s_setprio(0); } while (0)
; #define PG8_WAIT_V(n) asm volatile("s_waitcnt vmcnt(" #n ")" ::: "memory")
; #define PG8_WAIT_L(n) asm volatile("s_waitcnt lgkmcnt(" #n ")" ::: "memory")
; #define PG8_BAR __builtin_amdgcn_s_barrier()
; #define PG8_SCHED __builtin_amdgcn_sched_barrier(0)
; template <class Epi, class Sched, bool ALIGN_EPI = false, bool SP2 = false>
; __device__ __forceinline__ void gemm_phase(PG8_LAS unsigned char* lds, const Gemm g, const Sched& S, const Epi& E) {
;     ...
;         for (int t = 0; t < nt; t += 2) {
;     ...
;             PG8_LDA(At, 1, 1); PG8_STAGE(PG8_SB(1, 0), b3, voffB); PG8_STAGE(PG8_SB(1, 1), b3 + hstepB, voffB); PG8_STAGE(PG8_SA(1, 0), a3, voffA);
;             PG8_WAIT_V(8); PG8_WAIT_L(0); PG8_BAR; PG8_MMA(1, 0, At, B0); PG8_MMA(1, 1, At, B1); PG8_BAR; PG8_SCHED;
	s_add_i32 s74, s74, s3
	v_lshl_add_u64 v[144:145], v[144:145], 0, s[26:27]
	s_mov_b32 m0, s74
	ds_read_b128 v[176:179], v167 offset:49152
	ds_read_b128 v[180:183], v167 offset:50176
	ds_read_b128 v[184:187], v167 offset:51200
	ds_read_b128 v[188:191], v167 offset:52224
	ds_read_b128 v[200:203], v167 offset:53248
	ds_read_b128 v[204:207], v167 offset:54272
	ds_read_b128 v[208:211], v167 offset:55296
	ds_read_b128 v[212:215], v167 offset:56320
	global_load_lds_dwordx4 v[144:145], off
	v_lshl_add_u64 v[144:145], v[192:193], 0, s[26:27]
	s_add_i32 m0, s74, 0x2000
	s_add_i32 s74, s75, s3
	global_load_lds_dwordx4 v[144:145], off
	v_lshl_add_u64 v[144:145], v[228:229], 0, s[26:27]
	s_mov_b32 m0, s74
	s_nop 0
	global_load_lds_dwordx4 v[144:145], off
	v_lshl_add_u64 v[144:145], v[230:231], 0, s[26:27]
	s_add_i32 m0, s74, 0x2000
	s_nop 0
	global_load_lds_dwordx4 v[144:145], off
	v_lshl_add_u64 v[144:145], v[232:233], 0, s[26:27]
	s_mov_b32 m0, s17
	s_nop 0
	global_load_lds_dwordx4 v[144:145], off
	v_lshl_add_u64 v[144:145], v[234:235], 0, s[26:27]
	s_mov_b32 m0, s28
	s_nop 0
	global_load_lds_dwordx4 v[144:145], off
	s_waitcnt vmcnt(8) lgkmcnt(0)
	s_barrier
	s_setprio 1
	v_mfma_f32_16x16x32_bf16 v[92:95], v[128:131], v[176:179], v[92:95]
	v_mfma_f32_16x16x32_bf16 v[88:91], v[136:139], v[176:179], v[88:91]
	v_mfma_f32_16x16x32_bf16 v[84:87], v[128:131], v[184:187], v[84:87]
	v_mfma_f32_16x16x32_bf16 v[80:83], v[136:139], v[184:187], v[80:83]
	v_mfma_f32_16x16x32_bf16 v[76:79], v[128:131], v[200:203], v[76:79]
	v_mfma_f32_16x16x32_bf16 v[72:75], v[136:139], v[200:203], v[72:75]
	v_mfma_f32_16x16x32_bf16 v[68:71], v[128:131], v[208:211], v[68:71]
	v_mfma_f32_16x16x32_bf16 v[64:67], v[136:139], v[208:211], v[64:67]
	v_mfma_f32_16x16x32_bf16 v[92:95], v[132:135], v[180:183], v[92:95]
	v_mfma_f32_16x16x32_bf16 v[88:91], v[140:143], v[180:183], v[88:91]
	v_mfma_f32_16x16x32_bf16 v[84:87], v[132:135], v[188:191], v[84:87]
	v_mfma_f32_16x16x32_bf16 v[80:83], v[140:143], v[188:191], v[80:83]
	v_mfma_f32_16x16x32_bf16 v[76:79], v[132:135], v[204:207], v[76:79]
	v_mfma_f32_16x16x32_bf16 v[72:75], v[140:143], v[204:207], v[72:75]
	v_mfma_f32_16x16x32_bf16 v[68:71], v[132:135], v[212:215], v[68:71]
	v_mfma_f32_16x16x32_bf16 v[64:67], v[140:143], v[212:215], v[64:67]
	v_mfma_f32_16x16x32_bf16 v[28:31], v[156:159], v[176:179], v[28:31]
	v_mfma_f32_16x16x32_bf16 v[24:27], v[168:171], v[176:179], v[24:27]
	v_mfma_f32_16x16x32_bf16 v[20:23], v[156:159], v[184:187], v[20:23]
	v_mfma_f32_16x16x32_bf16 v[16:19], v[168:171], v[184:187], v[16:19]
	v_mfma_f32_16x16x32_bf16 v[12:15], v[156:159], v[200:203], v[12:15]
	v_mfma_f32_16x16x32_bf16 v[8:11], v[168:171], v[200:203], v[8:11]
	v_mfma_f32_16x16x32_bf16 v[4:7], v[156:159], v[208:211], v[4:7]
	v_mfma_f32_16x16x32_bf16 v[0:3], v[168:171], v[208:211], v[0:3]
	v_mfma_f32_16x16x32_bf16 v[28:31], v[160:163], v[180:183], v[28:31]
	v_mfma_f32_16x16x32_bf16 v[24:27], v[172:175], v[180:183], v[24:27]
	v_mfma_f32_16x16x32_bf16 v[20:23], v[160:163], v[188:191], v[20:23]
	v_mfma_f32_16x16x32_bf16 v[16:19], v[172:175], v[188:191], v[16:19]
	v_mfma_f32_16x16x32_bf16 v[12:15], v[160:163], v[204:207], v[12:15]
	v_mfma_f32_16x16x32_bf16 v[8:11], v[172:175], v[204:207], v[8:11]
	v_mfma_f32_16x16x32_bf16 v[4:7], v[160:163], v[212:215], v[4:7]
	v_mfma_f32_16x16x32_bf16 v[0:3], v[172:175], v[212:215], v[0:3]
	s_setprio 0
	s_barrier
	s_add_u32 s40, s40, 0x100
	s_addc_u32 s41, s41, 0
	s_add_u32 s78, s78, 0x100
	s_addc_u32 s79, s79, 0
	s_cmp_ge_i32 s86, s14
	s_mov_b32 s84, s86
	s_cbranch_scc0 .LBB0_1463

; #define PG8_STAGE(bufoff, gbase, voff) do { _Pragma("unroll") for (int _i = 0; _i < 2; ++_i) \
;         __builtin_amdgcn_global_load_lds((const unsigned*)((const char*)(gbase) + (voff)[_i]), (PG8_LAS unsigned*)(lds + (bufoff) + ldsw + _i * 8192), 16, 0, 0); } while (0)
; #define PG8_LDA(dst, b, h) do { _Pragma("unroll") for (int m = 0; m < 4; ++m) _Pragma("unroll") for (int k = 0; k < 2; ++k) dst[m][k] = *(const PG8_LAS bf16x8*)(lds + PG8_SA(b, h) + aoff + m * 2048 + k * 1024); } while (0)
; #define PG8_LDB(dst, b, h) do { _Pragma("unroll") for (int n = 0; n < 2; ++n) _Pragma("unroll") for (int k = 0; k < 2; ++k) dst[n][k] = *(const PG8_LAS bf16x8*)(lds + PG8_SB(b, h) + boff + n * 2048 + k * 1024); } while (0)
; #define PG8_MMA(ai, bj, At, Bt) do { __builtin_amdgcn_s_setprio(1); _Pragma("unroll") for (int m = 0; m < 4; ++m) _Pragma("unroll") for (int n = 0; n < 2; ++n) _Pragma("unroll") for (int k = 0; k < 2; ++k) \
;         acc[ai][bj][m][n] = __builtin_amdgcn_mfma_f32_16x16x32_bf16(Bt[n][k], At[m][k], acc[ai][bj][m][n], 0, 0, 0); __builtin_amdgcn_s_setprio(0); } while (0)
; #define PG8_WAIT_V(n) asm volatile("s_waitcnt vmcnt(" #n ")" ::: "memory")
; #define PG8_WAIT_L(n) asm volatile("s_waitcnt lgkmcnt(" #n ")" ::: "memory")
; template <class Epi, class Sched, bool ALIGN_EPI = false, bool SP2 = false>
; __device__ __forceinline__ void gemm_phase(PG8_LAS unsigned char* lds, const Gemm g, const Sched& S, const Epi& E) {
;     ...
;             const bool last = (t == nt - 2);
;             const char* a1 = cA + (size_t)(t + 1) * kstep;
;             const char* a2 = last ? nA : cA + (size_t)(t + 2) * kstep; const char* b2 = last ? nB : cB + (size_t)(t + 2) * kstep;
;             const char* a3 = a2 + kstep; const char* b3 = b2 + kstep;
;             if (last && has_next) S.a_ready(nxt);
;             if constexpr (SP2) {
;             PG8_LDB(B0, 0, 0); PG8_LDB(B1, 0, 1); PG8_SCHED; PG8_LDA(At, 0, 0); PG8_STAGE(PG8_SA(1, 1), a1 + hstepA, voffA);
;             PG8_WAIT_V(8); PG8_WAIT_L(0); PG8_BAR; PG8_MMA(0, 0, At, B0); PG8_MMA(0, 1, At, B1); PG8_BAR; PG8_SCHED;
;             PG8_LDA(At, 0, 1); PG8_STAGE(PG8_SB(0, 0), b2, voffB); PG8_STAGE(PG8_SB(0, 1), b2 + hstepB, voffB); PG8_STAGE(PG8_SA(0, 0), a2, voffA);
;             PG8_WAIT_V(8); PG8_WAIT_L(0); PG8_BAR; PG8_MMA(1, 0, At, B0); PG8_MMA(1, 1, At, B1); PG8_BAR; PG8_SCHED;
.LBB0_1493:
	s_add_i32 s81, s79, 2
	s_add_u32 s74, s84, 0x80
	s_addc_u32 s75, s85, 0
	s_add_i32 s90, 0, 0x10000
	s_cmp_eq_u32 s28, s79
	s_cselect_b32 s87, s47, s75
	s_cselect_b32 s86, s46, s74
	s_cselect_b32 s89, s83, s78
	s_cselect_b32 s88, s82, s64
	s_add_i32 s74, 0, 0x14000
	v_add_u32_e32 v140, s90, v164
	v_add_u32_e32 v144, s74, v164
	ds_read_b128 v[128:131], v140
	ds_read_b128 v[132:135], v140 offset:1024
	ds_read_b128 v[136:139], v140 offset:2048
	ds_read_b128 v[140:143], v140 offset:3072
	ds_read_b128 v[156:159], v144
	ds_read_b128 v[166:169], v144 offset:1024
	ds_read_b128 v[170:173], v144 offset:2048
	ds_read_b128 v[174:177], v144 offset:3072
	v_lshl_add_u64 v[144:145], s[84:85], 0, v[152:153]
	s_add_i32 m0, s2, 0xc000
	ds_read_b128 v[178:181], v165
	ds_read_b128 v[182:185], v165 offset:1024
	ds_read_b128 v[186:189], v165 offset:2048
	ds_read_b128 v[190:193], v165 offset:3072
	ds_read_b128 v[200:203], v165 offset:4096
	ds_read_b128 v[204:207], v165 offset:5120
	ds_read_b128 v[208:211], v165 offset:6144
	ds_read_b128 v[212:215], v165 offset:7168
	global_load_lds_dwordx4 v[144:145], off
	v_lshl_add_u64 v[144:145], s[84:85], 0, v[154:155]
	s_add_i32 m0, s2, 0xe000
	s_nop 0
	global_load_lds_dwordx4 v[144:145], off
	s_waitcnt vmcnt(8) lgkmcnt(0)
	s_barrier
	s_setprio 1
	v_mfma_f32_16x16x32_bf16 v[124:127], v[128:131], v[178:181], v[124:127]
	v_mfma_f32_16x16x32_bf16 v[120:123], v[136:139], v[178:181], v[120:123]
	v_mfma_f32_16x16x32_bf16 v[116:119], v[128:131], v[186:189], v[116:119]
	v_mfma_f32_16x16x32_bf16 v[112:115], v[136:139], v[186:189], v[112:115]
	v_mfma_f32_16x16x32_bf16 v[108:111], v[128:131], v[200:203], v[108:111]
	v_mfma_f32_16x16x32_bf16 v[104:107], v[136:139], v[200:203], v[104:107]
	v_mfma_f32_16x16x32_bf16 v[100:103], v[128:131], v[208:211], v[100:103]
	v_mfma_f32_16x16x32_bf16 v[96:99], v[136:139], v[208:211], v[96:99]
	v_mfma_f32_16x16x32_bf16 v[124:127], v[132:135], v[182:185], v[124:127]
	v_mfma_f32_16x16x32_bf16 v[120:123], v[140:143], v[182:185], v[120:123]
	v_mfma_f32_16x16x32_bf16 v[116:119], v[132:135], v[190:193], v[116:119]
	v_mfma_f32_16x16x32_bf16 v[112:115], v[140:143], v[190:193], v[112:115]
	v_mfma_f32_16x16x32_bf16 v[108:111], v[132:135], v[204:207], v[108:111]
	v_mfma_f32_16x16x32_bf16 v[104:107], v[140:143], v[204:207], v[104:107]
	v_mfma_f32_16x16x32_bf16 v[100:103], v[132:135], v[212:215], v[100:103]
	v_mfma_f32_16x16x32_bf16 v[96:99], v[140:143], v[212:215], v[96:99]
	v_mfma_f32_16x16x32_bf16 v[60:63], v[156:159], v[178:181], v[60:63]
	v_mfma_f32_16x16x32_bf16 v[56:59], v[170:173], v[178:181], v[56:59]
	v_mfma_f32_16x16x32_bf16 v[52:55], v[156:159], v[186:189], v[52:55]
	v_mfma_f32_16x16x32_bf16 v[48:51], v[170:173], v[186:189], v[48:51]
	v_mfma_f32_16x16x32_bf16 v[44:47], v[156:159], v[200:203], v[44:47]
	v_mfma_f32_16x16x32_bf16 v[40:43], v[170:173], v[200:203], v[40:43]
	v_mfma_f32_16x16x32_bf16 v[36:39], v[156:159], v[208:211], v[36:39]
	v_mfma_f32_16x16x32_bf16 v[32:35], v[170:173], v[208:211], v[32:35]
	v_mfma_f32_16x16x32_bf16 v[60:63], v[166:169], v[182:185], v[60:63]
	v_mfma_f32_16x16x32_bf16 v[56:59], v[174:177], v[182:185], v[56:59]
	v_mfma_f32_16x16x32_bf16 v[52:55], v[166:169], v[190:193], v[52:55]
	v_mfma_f32_16x16x32_bf16 v[48:51], v[174:177], v[190:193], v[48:51]
	v_mfma_f32_16x16x32_bf16 v[44:47], v[166:169], v[204:207], v[44:47]
	v_mfma_f32_16x16x32_bf16 v[40:43], v[174:177], v[204:207], v[40:43]
	v_mfma_f32_16x16x32_bf16 v[36:39], v[166:169], v[212:215], v[36:39]
	v_mfma_f32_16x16x32_bf16 v[32:35], v[174:177], v[212:215], v[32:35]
	s_setprio 0
	s_barrier
	s_add_i32 s75, s90, s9
	v_lshl_add_u64 v[144:145], s[88:89], 0, v[194:195]
	s_mov_b32 m0, s75
	ds_read_b128 v[178:181], v165 offset:16384
	ds_read_b128 v[182:185], v165 offset:17408
	ds_read_b128 v[186:189], v165 offset:18432
	ds_read_b128 v[190:193], v165 offset:19456
	ds_read_b128 v[200:203], v165 offset:20480
	ds_read_b128 v[204:207], v165 offset:21504
	ds_read_b128 v[208:211], v165 offset:22528
	ds_read_b128 v[212:215], v165 offset:23552
	global_load_lds_dwordx4 v[144:145], off
	s_add_i32 m0, s75, 0x2000
	v_lshl_add_u64 v[160:161], s[88:89], 0, v[146:147]
	s_add_u32 s88, s88, s80
	s_addc_u32 s89, s89, 0
	s_add_i32 s74, s74, s9
	global_load_lds_dwordx4 v[160:161], off
	v_lshl_add_u64 v[228:229], s[88:89], 0, v[194:195]
	s_mov_b32 m0, s74
	v_lshl_add_u64 v[230:231], s[88:89], 0, v[146:147]
	global_load_lds_dwordx4 v[228:229], off
	s_add_i32 m0, s74, 0x2000
	v_lshl_add_u64 v[232:233], s[86:87], 0, v[150:151]
	global_load_lds_dwordx4 v[230:231], off
	s_mov_b32 m0, s2
	v_lshl_add_u64 v[234:235], s[86:87], 0, v[148:149]
	global_load_lds_dwordx4 v[232:233], off
	s_mov_b32 m0, s10
	s_nop 0
	global_load_lds_dwordx4 v[234:235], off
	s_waitcnt vmcnt(8) lgkmcnt(0)
	s_barrier
; #define PG8_STAGE(bufoff, gbase, voff) do { _Pragma("unroll") for (int _i = 0; _i < 2; ++_i) \
;         __builtin_amdgcn_global_load_lds((const unsigned*)((const char*)(gbase) + (voff)[_i]), (PG8_LAS unsigned*)(lds + (bufoff) + ldsw + _i * 8192), 16, 0, 0); } while (0)
; #define PG8_LDA(dst, b, h) do { _Pragma("unroll") for (int m = 0; m < 4; ++m) _Pragma("unroll") for (int k = 0; k < 2; ++k) dst[m][k] = *(const PG8_LAS bf16x8*)(lds + PG8_SA(b, h) + aoff + m * 2048 + k * 1024); } while (0)
; #define PG8_LDB(dst, b, h) do { _Pragma("unroll") for (int n = 0; n < 2; ++n) _Pragma("unroll") for (int k = 0; k < 2; ++k) dst[n][k] = *(const PG8_LAS bf16x8*)(lds + PG8_SB(b, h) + boff + n * 2048 + k * 1024); } while (0)
; #define PG8_MMA(ai, bj, At, Bt) do { __builtin_amdgcn_s_setprio(1); _Pragma("unroll") for (int m = 0; m < 4; ++m) _Pragma("unroll") for (int n = 0; n < 2; ++n) _Pragma("unroll") for (int k = 0; k < 2; ++k) \
;         acc[ai][bj][m][n] = __builtin_amdgcn_mfma_f32_16x16x32_bf16(Bt[n][k], At[m][k], acc[ai][bj][m][n], 0, 0, 0); __builtin_amdgcn_s_setprio(0); } while (0)
; #define PG8_WAIT_V(n) asm volatile("s_waitcnt vmcnt(" #n ")" ::: "memory")
; #define PG8_WAIT_L(n) asm volatile("s_waitcnt lgkmcnt(" #n ")" ::: "memory")
; #define PG8_BAR __builtin_amdgcn_s_barrier()
; #define PG8_SCHED __builtin_amdgcn_sched_barrier(0)
; template <class Epi, class Sched, bool ALIGN_EPI = false, bool SP2 = false>
; __device__ __forceinline__ void gemm_phase(PG8_LAS unsigned char* lds, const Gemm g, const Sched& S, const Epi& E) {
;     ...
;             PG8_WAIT_V(8); PG8_WAIT_L(0); PG8_BAR; PG8_MMA(1, 0, At, B0); PG8_MMA(1, 1, At, B1); PG8_BAR; PG8_SCHED;
;             PG8_LDB(B0, 1, 0); PG8_LDB(B1, 1, 1); PG8_SCHED; PG8_LDA(At, 1, 0); PG8_STAGE(PG8_SA(0, 1), a2 + hstepA, voffA);
;             PG8_WAIT_V(8); PG8_WAIT_L(0); PG8_BAR; PG8_MMA(0, 0, At, B0); PG8_MMA(0, 1, At, B1); PG8_BAR; PG8_SCHED;
	s_setprio 1
	v_mfma_f32_16x16x32_bf16 v[92:95], v[128:131], v[178:181], v[92:95]
	v_mfma_f32_16x16x32_bf16 v[88:91], v[136:139], v[178:181], v[88:91]
	v_mfma_f32_16x16x32_bf16 v[84:87], v[128:131], v[186:189], v[84:87]
	v_mfma_f32_16x16x32_bf16 v[80:83], v[136:139], v[186:189], v[80:83]
	v_mfma_f32_16x16x32_bf16 v[76:79], v[128:131], v[200:203], v[76:79]
	v_mfma_f32_16x16x32_bf16 v[72:75], v[136:139], v[200:203], v[72:75]
	v_mfma_f32_16x16x32_bf16 v[68:71], v[128:131], v[208:211], v[68:71]
	v_mfma_f32_16x16x32_bf16 v[64:67], v[136:139], v[208:211], v[64:67]
	v_mfma_f32_16x16x32_bf16 v[92:95], v[132:135], v[182:185], v[92:95]
	v_mfma_f32_16x16x32_bf16 v[88:91], v[140:143], v[182:185], v[88:91]
	v_mfma_f32_16x16x32_bf16 v[84:87], v[132:135], v[190:193], v[84:87]
	v_mfma_f32_16x16x32_bf16 v[80:83], v[140:143], v[190:193], v[80:83]
	v_mfma_f32_16x16x32_bf16 v[76:79], v[132:135], v[204:207], v[76:79]
	v_mfma_f32_16x16x32_bf16 v[72:75], v[140:143], v[204:207], v[72:75]
	v_mfma_f32_16x16x32_bf16 v[68:71], v[132:135], v[212:215], v[68:71]
	v_mfma_f32_16x16x32_bf16 v[64:67], v[140:143], v[212:215], v[64:67]
	v_mfma_f32_16x16x32_bf16 v[28:31], v[156:159], v[178:181], v[28:31]
	v_mfma_f32_16x16x32_bf16 v[24:27], v[170:173], v[178:181], v[24:27]
	v_mfma_f32_16x16x32_bf16 v[20:23], v[156:159], v[186:189], v[20:23]
	v_mfma_f32_16x16x32_bf16 v[16:19], v[170:173], v[186:189], v[16:19]
	v_mfma_f32_16x16x32_bf16 v[12:15], v[156:159], v[200:203], v[12:15]
	v_mfma_f32_16x16x32_bf16 v[8:11], v[170:173], v[200:203], v[8:11]
	v_mfma_f32_16x16x32_bf16 v[4:7], v[156:159], v[208:211], v[4:7]
	v_mfma_f32_16x16x32_bf16 v[0:3], v[170:173], v[208:211], v[0:3]
	v_mfma_f32_16x16x32_bf16 v[28:31], v[166:169], v[182:185], v[28:31]
	v_mfma_f32_16x16x32_bf16 v[24:27], v[174:177], v[182:185], v[24:27]
	v_mfma_f32_16x16x32_bf16 v[20:23], v[166:169], v[190:193], v[20:23]
	v_mfma_f32_16x16x32_bf16 v[16:19], v[174:177], v[190:193], v[16:19]
	v_mfma_f32_16x16x32_bf16 v[12:15], v[166:169], v[204:207], v[12:15]
	v_mfma_f32_16x16x32_bf16 v[8:11], v[174:177], v[204:207], v[8:11]
	v_mfma_f32_16x16x32_bf16 v[4:7], v[166:169], v[212:215], v[4:7]
	v_mfma_f32_16x16x32_bf16 v[0:3], v[174:177], v[212:215], v[0:3]
	s_setprio 0
	s_barrier
	s_add_i32 s74, 0, 0x18000
	s_add_i32 s75, 0, 0x1c000
	v_add_u32_e32 v140, s74, v164
	v_add_u32_e32 v174, s75, v164
	ds_read_b128 v[128:131], v140
	ds_read_b128 v[132:135], v140 offset:1024
	ds_read_b128 v[136:139], v140 offset:2048
	ds_read_b128 v[140:143], v140 offset:3072
	ds_read_b128 v[156:159], v174
	ds_read_b128 v[166:169], v174 offset:1024
	ds_read_b128 v[170:173], v174 offset:2048
	ds_read_b128 v[174:177], v174 offset:3072
	s_add_u32 s86, s86, s80
	s_addc_u32 s87, s87, 0
	s_mov_b32 m0, s11
	v_lshl_add_u64 v[236:237], s[86:87], 0, v[150:151]
	ds_read_b128 v[178:181], v165 offset:32768
	ds_read_b128 v[182:185], v165 offset:33792
	ds_read_b128 v[186:189], v165 offset:34816
	ds_read_b128 v[190:193], v165 offset:35840
	ds_read_b128 v[200:203], v165 offset:36864
	ds_read_b128 v[204:207], v165 offset:37888
	ds_read_b128 v[208:211], v165 offset:38912
	ds_read_b128 v[212:215], v165 offset:39936
	global_load_lds_dwordx4 v[236:237], off
	v_lshl_add_u64 v[236:237], s[86:87], 0, v[148:149]
	s_mov_b32 m0, s12
	s_nop 0
	global_load_lds_dwordx4 v[236:237], off
	s_waitcnt vmcnt(8) lgkmcnt(0)
	s_barrier
	s_setprio 1
	v_mfma_f32_16x16x32_bf16 v[124:127], v[128:131], v[178:181], v[124:127]
	v_mfma_f32_16x16x32_bf16 v[120:123], v[136:139], v[178:181], v[120:123]
	v_mfma_f32_16x16x32_bf16 v[116:119], v[128:131], v[186:189], v[116:119]
	v_mfma_f32_16x16x32_bf16 v[112:115], v[136:139], v[186:189], v[112:115]
	v_mfma_f32_16x16x32_bf16 v[108:111], v[128:131], v[200:203], v[108:111]
	v_mfma_f32_16x16x32_bf16 v[104:107], v[136:139], v[200:203], v[104:107]
	v_mfma_f32_16x16x32_bf16 v[100:103], v[128:131], v[208:211], v[100:103]
	v_mfma_f32_16x16x32_bf16 v[96:99], v[136:139], v[208:211], v[96:99]
	v_mfma_f32_16x16x32_bf16 v[124:127], v[132:135], v[182:185], v[124:127]
	v_mfma_f32_16x16x32_bf16 v[120:123], v[140:143], v[182:185], v[120:123]
	v_mfma_f32_16x16x32_bf16 v[116:119], v[132:135], v[190:193], v[116:119]
	v_mfma_f32_16x16x32_bf16 v[112:115], v[140:143], v[190:193], v[112:115]
	v_mfma_f32_16x16x32_bf16 v[108:111], v[132:135], v[204:207], v[108:111]
	v_mfma_f32_16x16x32_bf16 v[104:107], v[140:143], v[204:207], v[104:107]
	v_mfma_f32_16x16x32_bf16 v[100:103], v[132:135], v[212:215], v[100:103]
	v_mfma_f32_16x16x32_bf16 v[96:99], v[140:143], v[212:215], v[96:99]
	v_mfma_f32_16x16x32_bf16 v[60:63], v[156:159], v[178:181], v[60:63]
	v_mfma_f32_16x16x32_bf16 v[56:59], v[170:173], v[178:181], v[56:59]
	v_mfma_f32_16x16x32_bf16 v[52:55], v[156:159], v[186:189], v[52:55]
	v_mfma_f32_16x16x32_bf16 v[48:51], v[170:173], v[186:189], v[48:51]
	v_mfma_f32_16x16x32_bf16 v[44:47], v[156:159], v[200:203], v[44:47]
	v_mfma_f32_16x16x32_bf16 v[40:43], v[170:173], v[200:203], v[40:43]
	v_mfma_f32_16x16x32_bf16 v[36:39], v[156:159], v[208:211], v[36:39]
	v_mfma_f32_16x16x32_bf16 v[32:35], v[170:173], v[208:211], v[32:35]
	v_mfma_f32_16x16x32_bf16 v[60:63], v[166:169], v[182:185], v[60:63]
	v_mfma_f32_16x16x32_bf16 v[56:59], v[174:177], v[182:185], v[56:59]
	v_mfma_f32_16x16x32_bf16 v[52:55], v[166:169], v[190:193], v[52:55]
	v_mfma_f32_16x16x32_bf16 v[48:51], v[174:177], v[190:193], v[48:51]
	v_mfma_f32_16x16x32_bf16 v[44:47], v[166:169], v[204:207], v[44:47]
	v_mfma_f32_16x16x32_bf16 v[40:43], v[174:177], v[204:207], v[40:43]
	v_mfma_f32_16x16x32_bf16 v[36:39], v[166:169], v[212:215], v[36:39]
	v_mfma_f32_16x16x32_bf16 v[32:35], v[174:177], v[212:215], v[32:35]
	s_setprio 0
	s_barrier
; #define PG8_STAGE(bufoff, gbase, voff) do { _Pragma("unroll") for (int _i = 0; _i < 2; ++_i) \
;         __builtin_amdgcn_global_load_lds((const unsigned*)((const char*)(gbase) + (voff)[_i]), (PG8_LAS unsigned*)(lds + (bufoff) + ldsw + _i * 8192), 16, 0, 0); } while (0)
; #define PG8_LDA(dst, b, h) do { _Pragma("unroll") for (int m = 0; m < 4; ++m) _Pragma("unroll") for (int k = 0; k < 2; ++k) dst[m][k] = *(const PG8_LAS bf16x8*)(lds + PG8_SA(b, h) + aoff + m * 2048 + k * 1024); } while (0)
; #define PG8_MMA(ai, bj, At, Bt) do { __builtin_amdgcn_s_setprio(1); _Pragma("unroll") for (int m = 0; m < 4; ++m) _Pragma("unroll") for (int n = 0; n < 2; ++n) _Pragma("unroll") for (int k = 0; k < 2; ++k) \
;         acc[ai][bj][m][n] = __builtin_amdgcn_mfma_f32_16x16x32_bf16(Bt[n][k], At[m][k], acc[ai][bj][m][n], 0, 0, 0); __builtin_amdgcn_s_setprio(0); } while (0)
; #define PG8_WAIT_V(n) asm volatile("s_waitcnt vmcnt(" #n ")" ::: "memory")
; #define PG8_WAIT_L(n) asm volatile("s_waitcnt lgkmcnt(" #n ")" ::: "memory")
; #define PG8_BAR __builtin_amdgcn_s_barrier()
; #define PG8_SCHED __builtin_amdgcn_sched_barrier(0)
; template <class Epi, class Sched, bool ALIGN_EPI = false, bool SP2 = false>
; __device__ __forceinline__ void gemm_phase(PG8_LAS unsigned char* lds, const Gemm g, const Sched& S, const Epi& E) {
;     ...
;         for (int t = 0; t < nt; t += 2) {
;     ...
;             PG8_LDA(At, 1, 1); PG8_STAGE(PG8_SB(1, 0), b3, voffB); PG8_STAGE(PG8_SB(1, 1), b3 + hstepB, voffB); PG8_STAGE(PG8_SA(1, 0), a3, voffA);
;             PG8_WAIT_V(8); PG8_WAIT_L(0); PG8_BAR; PG8_MMA(1, 0, At, B0); PG8_MMA(1, 1, At, B1); PG8_BAR; PG8_SCHED;
	s_add_i32 s74, s74, s9
	v_lshl_add_u64 v[144:145], v[144:145], 0, s[26:27]
	s_mov_b32 m0, s74
	ds_read_b128 v[178:181], v165 offset:49152
	ds_read_b128 v[182:185], v165 offset:50176
	ds_read_b128 v[186:189], v165 offset:51200
	ds_read_b128 v[190:193], v165 offset:52224
	ds_read_b128 v[200:203], v165 offset:53248
	ds_read_b128 v[204:207], v165 offset:54272
	ds_read_b128 v[208:211], v165 offset:55296
	ds_read_b128 v[212:215], v165 offset:56320
	global_load_lds_dwordx4 v[144:145], off
	v_lshl_add_u64 v[144:145], v[160:161], 0, s[26:27]
	s_add_i32 m0, s74, 0x2000
	s_add_i32 s74, s75, s9
	global_load_lds_dwordx4 v[144:145], off
	v_lshl_add_u64 v[144:145], v[228:229], 0, s[26:27]
	s_mov_b32 m0, s74
	s_nop 0
	global_load_lds_dwordx4 v[144:145], off
	v_lshl_add_u64 v[144:145], v[230:231], 0, s[26:27]
	s_add_i32 m0, s74, 0x2000
	s_nop 0
	global_load_lds_dwordx4 v[144:145], off
	v_lshl_add_u64 v[144:145], v[232:233], 0, s[26:27]
	s_mov_b32 m0, s16
	s_nop 0
	global_load_lds_dwordx4 v[144:145], off
	v_lshl_add_u64 v[144:145], v[234:235], 0, s[26:27]
	s_mov_b32 m0, s17
	s_nop 0
	global_load_lds_dwordx4 v[144:145], off
	s_waitcnt vmcnt(8) lgkmcnt(0)
	s_barrier
	s_setprio 1
	v_mfma_f32_16x16x32_bf16 v[92:95], v[128:131], v[178:181], v[92:95]
	v_mfma_f32_16x16x32_bf16 v[88:91], v[136:139], v[178:181], v[88:91]
	v_mfma_f32_16x16x32_bf16 v[84:87], v[128:131], v[186:189], v[84:87]
	v_mfma_f32_16x16x32_bf16 v[80:83], v[136:139], v[186:189], v[80:83]
	v_mfma_f32_16x16x32_bf16 v[76:79], v[128:131], v[200:203], v[76:79]
	v_mfma_f32_16x16x32_bf16 v[72:75], v[136:139], v[200:203], v[72:75]
	v_mfma_f32_16x16x32_bf16 v[68:71], v[128:131], v[208:211], v[68:71]
	v_mfma_f32_16x16x32_bf16 v[64:67], v[136:139], v[208:211], v[64:67]
	v_mfma_f32_16x16x32_bf16 v[92:95], v[132:135], v[182:185], v[92:95]
	v_mfma_f32_16x16x32_bf16 v[88:91], v[140:143], v[182:185], v[88:91]
	v_mfma_f32_16x16x32_bf16 v[84:87], v[132:135], v[190:193], v[84:87]
	v_mfma_f32_16x16x32_bf16 v[80:83], v[140:143], v[190:193], v[80:83]
	v_mfma_f32_16x16x32_bf16 v[76:79], v[132:135], v[204:207], v[76:79]
	v_mfma_f32_16x16x32_bf16 v[72:75], v[140:143], v[204:207], v[72:75]
	v_mfma_f32_16x16x32_bf16 v[68:71], v[132:135], v[212:215], v[68:71]
	v_mfma_f32_16x16x32_bf16 v[64:67], v[140:143], v[212:215], v[64:67]
	v_mfma_f32_16x16x32_bf16 v[28:31], v[156:159], v[178:181], v[28:31]
	v_mfma_f32_16x16x32_bf16 v[24:27], v[170:173], v[178:181], v[24:27]
	v_mfma_f32_16x16x32_bf16 v[20:23], v[156:159], v[186:189], v[20:23]
	v_mfma_f32_16x16x32_bf16 v[16:19], v[170:173], v[186:189], v[16:19]
	v_mfma_f32_16x16x32_bf16 v[12:15], v[156:159], v[200:203], v[12:15]
	v_mfma_f32_16x16x32_bf16 v[8:11], v[170:173], v[200:203], v[8:11]
	v_mfma_f32_16x16x32_bf16 v[4:7], v[156:159], v[208:211], v[4:7]
	v_mfma_f32_16x16x32_bf16 v[0:3], v[170:173], v[208:211], v[0:3]
	v_mfma_f32_16x16x32_bf16 v[28:31], v[166:169], v[182:185], v[28:31]
	v_mfma_f32_16x16x32_bf16 v[24:27], v[174:177], v[182:185], v[24:27]
	v_mfma_f32_16x16x32_bf16 v[20:23], v[166:169], v[190:193], v[20:23]
	v_mfma_f32_16x16x32_bf16 v[16:19], v[174:177], v[190:193], v[16:19]
	v_mfma_f32_16x16x32_bf16 v[12:15], v[166:169], v[204:207], v[12:15]
	v_mfma_f32_16x16x32_bf16 v[8:11], v[174:177], v[204:207], v[8:11]
	v_mfma_f32_16x16x32_bf16 v[4:7], v[166:169], v[212:215], v[4:7]
	v_mfma_f32_16x16x32_bf16 v[0:3], v[174:177], v[212:215], v[0:3]
	s_setprio 0
	s_barrier
	s_add_u32 s84, s84, 0x100
	s_addc_u32 s85, s85, 0
	s_add_u32 s64, s64, 0x100
	s_addc_u32 s78, s78, 0
	s_cmp_ge_i32 s81, s13
	s_mov_b32 s79, s81
	s_cbranch_scc0 .LBB0_1493

; #define PG8_STAGE(bufoff, gbase, voff) do { _Pragma("unroll") for (int _i = 0; _i < 2; ++_i) \
;         __builtin_amdgcn_global_load_lds((const unsigned*)((const char*)(gbase) + (voff)[_i]), (PG8_LAS unsigned*)(lds + (bufoff) + ldsw + _i * 8192), 16, 0, 0); } while (0)
; #define PG8_LDA(dst, b, h) do { _Pragma("unroll") for (int m = 0; m < 4; ++m) _Pragma("unroll") for (int k = 0; k < 2; ++k) dst[m][k] = *(const PG8_LAS bf16x8*)(lds + PG8_SA(b, h) + aoff + m * 2048 + k * 1024); } while (0)
; #define PG8_LDB(dst, b, h) do { _Pragma("unroll") for (int n = 0; n < 2; ++n) _Pragma("unroll") for (int k = 0; k < 2; ++k) dst[n][k] = *(const PG8_LAS bf16x8*)(lds + PG8_SB(b, h) + boff + n * 2048 + k * 1024); } while (0)
; #define PG8_MMA(ai, bj, At, Bt) do { __builtin_amdgcn_s_setprio(1); _Pragma("unroll") for (int m = 0; m < 4; ++m) _Pragma("unroll") for (int n = 0; n < 2; ++n) _Pragma("unroll") for (int k = 0; k < 2; ++k) \
;         acc[ai][bj][m][n] = __builtin_amdgcn_mfma_f32_16x16x32_bf16(Bt[n][k], At[m][k], acc[ai][bj][m][n], 0, 0, 0); __builtin_amdgcn_s_setprio(0); } while (0)
; #define PG8_WAIT_V(n) asm volatile("s_waitcnt vmcnt(" #n ")" ::: "memory")
; #define PG8_WAIT_L(n) asm volatile("s_waitcnt lgkmcnt(" #n ")" ::: "memory")
; template <class Epi, class Sched, bool ALIGN_EPI = false, bool SP2 = false>
; __device__ __forceinline__ void gemm_phase(PG8_LAS unsigned char* lds, const Gemm g, const Sched& S, const Epi& E) {
;     ...
;             const bool last = (t == nt - 2);
;             const char* a1 = cA + (size_t)(t + 1) * kstep;
;             const char* a2 = last ? nA : cA + (size_t)(t + 2) * kstep; const char* b2 = last ? nB : cB + (size_t)(t + 2) * kstep;
;             const char* a3 = a2 + kstep; const char* b3 = b2 + kstep;
;             if (last && has_next) S.a_ready(nxt);
;             if constexpr (SP2) {
;             PG8_LDB(B0, 0, 0); PG8_LDB(B1, 0, 1); PG8_SCHED; PG8_LDA(At, 0, 0); PG8_STAGE(PG8_SA(1, 1), a1 + hstepA, voffA);
;             PG8_WAIT_V(8); PG8_WAIT_L(0); PG8_BAR; PG8_MMA(0, 0, At, B0); PG8_MMA(0, 1, At, B1); PG8_BAR; PG8_SCHED;
;             PG8_LDA(At, 0, 1); PG8_STAGE(PG8_SB(0, 0), b2, voffB); PG8_STAGE(PG8_SB(0, 1), b2 + hstepB, voffB); PG8_STAGE(PG8_SA(0, 0), a2, voffA);
;             PG8_WAIT_V(8); PG8_WAIT_L(0); PG8_BAR; PG8_MMA(1, 0, At, B0); PG8_MMA(1, 1, At, B1); PG8_BAR; PG8_SCHED;
.LBB0_1626:
	s_add_i32 s78, s69, 2
	s_add_u32 s74, s86, 0xfffc0080
	s_addc_u32 s75, s87, -1
	s_add_i32 s79, 0, 0x10000
	s_cmp_eq_u32 s33, s69
	s_cselect_b32 s91, s53, s75
	s_cselect_b32 s90, s58, s74
	v_add_u32_e32 v138, s79, v142
	s_cselect_b32 s89, s59, s64
	s_cselect_b32 s88, s61, s63
	s_add_i32 s69, 0, 0x14000
	ds_read_b128 v[144:147], v138
	ds_read_b128 v[148:151], v138 offset:1024
	ds_read_b128 v[152:155], v138 offset:2048
	ds_read_b128 v[156:159], v138 offset:3072
	v_add_u32_e32 v138, s69, v142
	ds_read_b128 v[160:163], v138
	ds_read_b128 v[164:167], v138 offset:1024
	ds_read_b128 v[168:171], v138 offset:2048
	ds_read_b128 v[172:175], v138 offset:3072
	v_lshl_add_u64 v[138:139], s[86:87], 0, v[134:135]
	s_add_i32 m0, s12, 0xc000
	ds_read_b128 v[176:179], v143
	ds_read_b128 v[180:183], v143 offset:1024
	ds_read_b128 v[184:187], v143 offset:2048
	ds_read_b128 v[188:191], v143 offset:3072
	ds_read_b128 v[200:203], v143 offset:4096
	ds_read_b128 v[204:207], v143 offset:5120
	ds_read_b128 v[208:211], v143 offset:6144
	ds_read_b128 v[212:215], v143 offset:7168
	global_load_lds_dwordx4 v[138:139], off
	v_lshl_add_u64 v[138:139], s[86:87], 0, v[136:137]
	s_add_i32 m0, s12, 0xe000
	s_nop 0
	global_load_lds_dwordx4 v[138:139], off
	s_waitcnt vmcnt(8) lgkmcnt(0)
	s_barrier
	s_setprio 1
	v_mfma_f32_16x16x32_bf16 v[120:123], v[144:147], v[176:179], v[120:123]
	v_mfma_f32_16x16x32_bf16 v[124:127], v[152:155], v[176:179], v[124:127]
	v_mfma_f32_16x16x32_bf16 v[108:111], v[144:147], v[184:187], v[108:111]
	v_mfma_f32_16x16x32_bf16 v[104:107], v[152:155], v[184:187], v[104:107]
	v_mfma_f32_16x16x32_bf16 v[92:95], v[144:147], v[200:203], v[92:95]
	v_mfma_f32_16x16x32_bf16 v[88:91], v[152:155], v[200:203], v[88:91]
	v_mfma_f32_16x16x32_bf16 v[76:79], v[144:147], v[208:211], v[76:79]
	v_mfma_f32_16x16x32_bf16 v[72:75], v[152:155], v[208:211], v[72:75]
	v_mfma_f32_16x16x32_bf16 v[120:123], v[148:151], v[180:183], v[120:123]
	v_mfma_f32_16x16x32_bf16 v[124:127], v[156:159], v[180:183], v[124:127]
	v_mfma_f32_16x16x32_bf16 v[108:111], v[148:151], v[188:191], v[108:111]
	v_mfma_f32_16x16x32_bf16 v[104:107], v[156:159], v[188:191], v[104:107]
	v_mfma_f32_16x16x32_bf16 v[92:95], v[148:151], v[204:207], v[92:95]
	v_mfma_f32_16x16x32_bf16 v[88:91], v[156:159], v[204:207], v[88:91]
	v_mfma_f32_16x16x32_bf16 v[76:79], v[148:151], v[212:215], v[76:79]
	v_mfma_f32_16x16x32_bf16 v[72:75], v[156:159], v[212:215], v[72:75]
	v_mfma_f32_16x16x32_bf16 v[116:119], v[160:163], v[176:179], v[116:119]
	v_mfma_f32_16x16x32_bf16 v[112:115], v[168:171], v[176:179], v[112:115]
	v_mfma_f32_16x16x32_bf16 v[100:103], v[160:163], v[184:187], v[100:103]
	v_mfma_f32_16x16x32_bf16 v[96:99], v[168:171], v[184:187], v[96:99]
	v_mfma_f32_16x16x32_bf16 v[84:87], v[160:163], v[200:203], v[84:87]
	v_mfma_f32_16x16x32_bf16 v[80:83], v[168:171], v[200:203], v[80:83]
	v_mfma_f32_16x16x32_bf16 v[68:71], v[160:163], v[208:211], v[68:71]
	v_mfma_f32_16x16x32_bf16 v[64:67], v[168:171], v[208:211], v[64:67]
	v_mfma_f32_16x16x32_bf16 v[116:119], v[164:167], v[180:183], v[116:119]
	v_mfma_f32_16x16x32_bf16 v[112:115], v[172:175], v[180:183], v[112:115]
	v_mfma_f32_16x16x32_bf16 v[100:103], v[164:167], v[188:191], v[100:103]
	v_mfma_f32_16x16x32_bf16 v[96:99], v[172:175], v[188:191], v[96:99]
	v_mfma_f32_16x16x32_bf16 v[84:87], v[164:167], v[204:207], v[84:87]
	v_mfma_f32_16x16x32_bf16 v[80:83], v[172:175], v[204:207], v[80:83]
	v_mfma_f32_16x16x32_bf16 v[68:71], v[164:167], v[212:215], v[68:71]
	v_mfma_f32_16x16x32_bf16 v[64:67], v[172:175], v[212:215], v[64:67]
	s_setprio 0
	s_barrier
	s_add_i32 s74, s79, s9
	v_lshl_add_u64 v[138:139], s[88:89], 0, v[194:195]
	s_mov_b32 m0, s74
	ds_read_b128 v[176:179], v143 offset:16384
	ds_read_b128 v[180:183], v143 offset:17408
	ds_read_b128 v[184:187], v143 offset:18432
	ds_read_b128 v[188:191], v143 offset:19456
	ds_read_b128 v[200:203], v143 offset:20480
	ds_read_b128 v[204:207], v143 offset:21504
	ds_read_b128 v[208:211], v143 offset:22528
	ds_read_b128 v[212:215], v143 offset:23552
	global_load_lds_dwordx4 v[138:139], off
	s_add_i32 m0, s74, 0x2000
	s_add_u32 s92, s88, 0x40000
	v_lshl_add_u64 v[192:193], s[88:89], 0, v[128:129]
	s_addc_u32 s93, s89, 0
	s_add_i32 s69, s69, s9
	global_load_lds_dwordx4 v[192:193], off
	v_lshl_add_u64 v[228:229], s[92:93], 0, v[194:195]
	s_mov_b32 m0, s69
	v_lshl_add_u64 v[230:231], s[90:91], 0, v[130:131]
	global_load_lds_dwordx4 v[228:229], off
	v_lshl_add_u64 v[228:229], s[92:93], 0, v[128:129]
	s_add_i32 m0, s69, 0x2000
	s_nop 0
	global_load_lds_dwordx4 v[228:229], off
	v_lshl_add_u64 v[228:229], s[90:91], 0, v[132:133]
	s_mov_b32 m0, s12
	s_nop 0
	global_load_lds_dwordx4 v[228:229], off
	s_mov_b32 m0, s13
	s_nop 0
	global_load_lds_dwordx4 v[230:231], off
	s_waitcnt vmcnt(8) lgkmcnt(0)
	s_barrier
; #define PG8_STAGE(bufoff, gbase, voff) do { _Pragma("unroll") for (int _i = 0; _i < 2; ++_i) \
;         __builtin_amdgcn_global_load_lds((const unsigned*)((const char*)(gbase) + (voff)[_i]), (PG8_LAS unsigned*)(lds + (bufoff) + ldsw + _i * 8192), 16, 0, 0); } while (0)
; #define PG8_LDA(dst, b, h) do { _Pragma("unroll") for (int m = 0; m < 4; ++m) _Pragma("unroll") for (int k = 0; k < 2; ++k) dst[m][k] = *(const PG8_LAS bf16x8*)(lds + PG8_SA(b, h) + aoff + m * 2048 + k * 1024); } while (0)
; #define PG8_LDB(dst, b, h) do { _Pragma("unroll") for (int n = 0; n < 2; ++n) _Pragma("unroll") for (int k = 0; k < 2; ++k) dst[n][k] = *(const PG8_LAS bf16x8*)(lds + PG8_SB(b, h) + boff + n * 2048 + k * 1024); } while (0)
; #define PG8_MMA(ai, bj, At, Bt) do { __builtin_amdgcn_s_setprio(1); _Pragma("unroll") for (int m = 0; m < 4; ++m) _Pragma("unroll") for (int n = 0; n < 2; ++n) _Pragma("unroll") for (int k = 0; k < 2; ++k) \
;         acc[ai][bj][m][n] = __builtin_amdgcn_mfma_f32_16x16x32_bf16(Bt[n][k], At[m][k], acc[ai][bj][m][n], 0, 0, 0); __builtin_amdgcn_s_setprio(0); } while (0)
; #define PG8_WAIT_V(n) asm volatile("s_waitcnt vmcnt(" #n ")" ::: "memory")
; #define PG8_WAIT_L(n) asm volatile("s_waitcnt lgkmcnt(" #n ")" ::: "memory")
; #define PG8_BAR __builtin_amdgcn_s_barrier()
; #define PG8_SCHED __builtin_amdgcn_sched_barrier(0)
; template <class Epi, class Sched, bool ALIGN_EPI = false, bool SP2 = false>
; __device__ __forceinline__ void gemm_phase(PG8_LAS unsigned char* lds, const Gemm g, const Sched& S, const Epi& E) {
;     ...
;             PG8_WAIT_V(8); PG8_WAIT_L(0); PG8_BAR; PG8_MMA(1, 0, At, B0); PG8_MMA(1, 1, At, B1); PG8_BAR; PG8_SCHED;
;             PG8_LDB(B0, 1, 0); PG8_LDB(B1, 1, 1); PG8_SCHED; PG8_LDA(At, 1, 0); PG8_STAGE(PG8_SA(0, 1), a2 + hstepA, voffA);
;             PG8_WAIT_V(8); PG8_WAIT_L(0); PG8_BAR; PG8_MMA(0, 0, At, B0); PG8_MMA(0, 1, At, B1); PG8_BAR; PG8_SCHED;
	s_setprio 1
	v_mfma_f32_16x16x32_bf16 v[60:63], v[144:147], v[176:179], v[60:63]
	v_mfma_f32_16x16x32_bf16 v[56:59], v[152:155], v[176:179], v[56:59]
	v_mfma_f32_16x16x32_bf16 v[44:47], v[144:147], v[184:187], v[44:47]
	v_mfma_f32_16x16x32_bf16 v[40:43], v[152:155], v[184:187], v[40:43]
	v_mfma_f32_16x16x32_bf16 v[28:31], v[144:147], v[200:203], v[28:31]
	v_mfma_f32_16x16x32_bf16 v[24:27], v[152:155], v[200:203], v[24:27]
	v_mfma_f32_16x16x32_bf16 v[12:15], v[144:147], v[208:211], v[12:15]
	v_mfma_f32_16x16x32_bf16 v[8:11], v[152:155], v[208:211], v[8:11]
	v_mfma_f32_16x16x32_bf16 v[60:63], v[148:151], v[180:183], v[60:63]
	v_mfma_f32_16x16x32_bf16 v[56:59], v[156:159], v[180:183], v[56:59]
	v_mfma_f32_16x16x32_bf16 v[44:47], v[148:151], v[188:191], v[44:47]
	v_mfma_f32_16x16x32_bf16 v[40:43], v[156:159], v[188:191], v[40:43]
	v_mfma_f32_16x16x32_bf16 v[28:31], v[148:151], v[204:207], v[28:31]
	v_mfma_f32_16x16x32_bf16 v[24:27], v[156:159], v[204:207], v[24:27]
	v_mfma_f32_16x16x32_bf16 v[12:15], v[148:151], v[212:215], v[12:15]
	v_mfma_f32_16x16x32_bf16 v[8:11], v[156:159], v[212:215], v[8:11]
	v_mfma_f32_16x16x32_bf16 v[52:55], v[160:163], v[176:179], v[52:55]
	v_mfma_f32_16x16x32_bf16 v[48:51], v[168:171], v[176:179], v[48:51]
	v_mfma_f32_16x16x32_bf16 v[36:39], v[160:163], v[184:187], v[36:39]
	v_mfma_f32_16x16x32_bf16 v[32:35], v[168:171], v[184:187], v[32:35]
	v_mfma_f32_16x16x32_bf16 v[20:23], v[160:163], v[200:203], v[20:23]
	v_mfma_f32_16x16x32_bf16 v[16:19], v[168:171], v[200:203], v[16:19]
	v_mfma_f32_16x16x32_bf16 v[4:7], v[160:163], v[208:211], v[4:7]
	v_mfma_f32_16x16x32_bf16 v[0:3], v[168:171], v[208:211], v[0:3]
	v_mfma_f32_16x16x32_bf16 v[52:55], v[164:167], v[180:183], v[52:55]
	v_mfma_f32_16x16x32_bf16 v[48:51], v[172:175], v[180:183], v[48:51]
	v_mfma_f32_16x16x32_bf16 v[36:39], v[164:167], v[188:191], v[36:39]
	v_mfma_f32_16x16x32_bf16 v[32:35], v[172:175], v[188:191], v[32:35]
	v_mfma_f32_16x16x32_bf16 v[20:23], v[164:167], v[204:207], v[20:23]
	v_mfma_f32_16x16x32_bf16 v[16:19], v[172:175], v[204:207], v[16:19]
	v_mfma_f32_16x16x32_bf16 v[4:7], v[164:167], v[212:215], v[4:7]
	v_mfma_f32_16x16x32_bf16 v[0:3], v[172:175], v[212:215], v[0:3]
	s_setprio 0
	s_barrier
	s_add_i32 s69, 0, 0x18000
	s_add_i32 s74, 0, 0x1c000
	v_add_u32_e32 v156, s69, v142
	v_add_u32_e32 v172, s74, v142
	ds_read_b128 v[144:147], v156
	ds_read_b128 v[148:151], v156 offset:1024
	ds_read_b128 v[152:155], v156 offset:2048
	ds_read_b128 v[156:159], v156 offset:3072
	ds_read_b128 v[160:163], v172
	ds_read_b128 v[164:167], v172 offset:1024
	ds_read_b128 v[168:171], v172 offset:2048
	ds_read_b128 v[172:175], v172 offset:3072
	s_add_u32 s90, s90, 0x40000
	s_addc_u32 s91, s91, 0
	s_mov_b32 m0, s14
	v_lshl_add_u64 v[232:233], s[90:91], 0, v[132:133]
	ds_read_b128 v[176:179], v143 offset:32768
	ds_read_b128 v[180:183], v143 offset:33792
	ds_read_b128 v[184:187], v143 offset:34816
	ds_read_b128 v[188:191], v143 offset:35840
	ds_read_b128 v[200:203], v143 offset:36864
	ds_read_b128 v[204:207], v143 offset:37888
	ds_read_b128 v[208:211], v143 offset:38912
	ds_read_b128 v[212:215], v143 offset:39936
	global_load_lds_dwordx4 v[232:233], off
	v_lshl_add_u64 v[232:233], s[90:91], 0, v[130:131]
	s_mov_b32 m0, s15
	s_nop 0
	global_load_lds_dwordx4 v[232:233], off
	s_waitcnt vmcnt(8) lgkmcnt(0)
	s_barrier
	s_setprio 1
	v_mfma_f32_16x16x32_bf16 v[120:123], v[144:147], v[176:179], v[120:123]
	v_mfma_f32_16x16x32_bf16 v[124:127], v[152:155], v[176:179], v[124:127]
	v_mfma_f32_16x16x32_bf16 v[108:111], v[144:147], v[184:187], v[108:111]
	v_mfma_f32_16x16x32_bf16 v[104:107], v[152:155], v[184:187], v[104:107]
	v_mfma_f32_16x16x32_bf16 v[92:95], v[144:147], v[200:203], v[92:95]
	v_mfma_f32_16x16x32_bf16 v[88:91], v[152:155], v[200:203], v[88:91]
	v_mfma_f32_16x16x32_bf16 v[76:79], v[144:147], v[208:211], v[76:79]
	v_mfma_f32_16x16x32_bf16 v[72:75], v[152:155], v[208:211], v[72:75]
	v_mfma_f32_16x16x32_bf16 v[120:123], v[148:151], v[180:183], v[120:123]
	v_mfma_f32_16x16x32_bf16 v[124:127], v[156:159], v[180:183], v[124:127]
	v_mfma_f32_16x16x32_bf16 v[108:111], v[148:151], v[188:191], v[108:111]
	v_mfma_f32_16x16x32_bf16 v[104:107], v[156:159], v[188:191], v[104:107]
	v_mfma_f32_16x16x32_bf16 v[92:95], v[148:151], v[204:207], v[92:95]
	v_mfma_f32_16x16x32_bf16 v[88:91], v[156:159], v[204:207], v[88:91]
	v_mfma_f32_16x16x32_bf16 v[76:79], v[148:151], v[212:215], v[76:79]
	v_mfma_f32_16x16x32_bf16 v[72:75], v[156:159], v[212:215], v[72:75]
	v_mfma_f32_16x16x32_bf16 v[116:119], v[160:163], v[176:179], v[116:119]
	v_mfma_f32_16x16x32_bf16 v[112:115], v[168:171], v[176:179], v[112:115]
	v_mfma_f32_16x16x32_bf16 v[100:103], v[160:163], v[184:187], v[100:103]
	v_mfma_f32_16x16x32_bf16 v[96:99], v[168:171], v[184:187], v[96:99]
	v_mfma_f32_16x16x32_bf16 v[84:87], v[160:163], v[200:203], v[84:87]
	v_mfma_f32_16x16x32_bf16 v[80:83], v[168:171], v[200:203], v[80:83]
	v_mfma_f32_16x16x32_bf16 v[68:71], v[160:163], v[208:211], v[68:71]
	v_mfma_f32_16x16x32_bf16 v[64:67], v[168:171], v[208:211], v[64:67]
	v_mfma_f32_16x16x32_bf16 v[116:119], v[164:167], v[180:183], v[116:119]
	v_mfma_f32_16x16x32_bf16 v[112:115], v[172:175], v[180:183], v[112:115]
	v_mfma_f32_16x16x32_bf16 v[100:103], v[164:167], v[188:191], v[100:103]
	v_mfma_f32_16x16x32_bf16 v[96:99], v[172:175], v[188:191], v[96:99]
	v_mfma_f32_16x16x32_bf16 v[84:87], v[164:167], v[204:207], v[84:87]
	v_mfma_f32_16x16x32_bf16 v[80:83], v[172:175], v[204:207], v[80:83]
	v_mfma_f32_16x16x32_bf16 v[68:71], v[164:167], v[212:215], v[68:71]
	v_mfma_f32_16x16x32_bf16 v[64:67], v[172:175], v[212:215], v[64:67]
	s_setprio 0
	s_barrier
; #define PG8_STAGE(bufoff, gbase, voff) do { _Pragma("unroll") for (int _i = 0; _i < 2; ++_i) \
;         __builtin_amdgcn_global_load_lds((const unsigned*)((const char*)(gbase) + (voff)[_i]), (PG8_LAS unsigned*)(lds + (bufoff) + ldsw + _i * 8192), 16, 0, 0); } while (0)
; #define PG8_LDA(dst, b, h) do { _Pragma("unroll") for (int m = 0; m < 4; ++m) _Pragma("unroll") for (int k = 0; k < 2; ++k) dst[m][k] = *(const PG8_LAS bf16x8*)(lds + PG8_SA(b, h) + aoff + m * 2048 + k * 1024); } while (0)
; #define PG8_MMA(ai, bj, At, Bt) do { __builtin_amdgcn_s_setprio(1); _Pragma("unroll") for (int m = 0; m < 4; ++m) _Pragma("unroll") for (int n = 0; n < 2; ++n) _Pragma("unroll") for (int k = 0; k < 2; ++k) \
;         acc[ai][bj][m][n] = __builtin_amdgcn_mfma_f32_16x16x32_bf16(Bt[n][k], At[m][k], acc[ai][bj][m][n], 0, 0, 0); __builtin_amdgcn_s_setprio(0); } while (0)
; #define PG8_WAIT_V(n) asm volatile("s_waitcnt vmcnt(" #n ")" ::: "memory")
; #define PG8_WAIT_L(n) asm volatile("s_waitcnt lgkmcnt(" #n ")" ::: "memory")
; #define PG8_BAR __builtin_amdgcn_s_barrier()
; #define PG8_SCHED __builtin_amdgcn_sched_barrier(0)
; template <class Epi, class Sched, bool ALIGN_EPI = false, bool SP2 = false>
; __device__ __forceinline__ void gemm_phase(PG8_LAS unsigned char* lds, const Gemm g, const Sched& S, const Epi& E) {
;     ...
;         for (int t = 0; t < nt; t += 2) {
;     ...
;             PG8_LDA(At, 1, 1); PG8_STAGE(PG8_SB(1, 0), b3, voffB); PG8_STAGE(PG8_SB(1, 1), b3 + hstepB, voffB); PG8_STAGE(PG8_SA(1, 0), a3, voffA);
;             PG8_WAIT_V(8); PG8_WAIT_L(0); PG8_BAR; PG8_MMA(1, 0, At, B0); PG8_MMA(1, 1, At, B1); PG8_BAR; PG8_SCHED;
	s_add_i32 s69, s69, s9
	v_lshl_add_u64 v[138:139], v[138:139], 0, s[26:27]
	s_mov_b32 m0, s69
	ds_read_b128 v[176:179], v143 offset:49152
	ds_read_b128 v[180:183], v143 offset:50176
	ds_read_b128 v[184:187], v143 offset:51200
	ds_read_b128 v[188:191], v143 offset:52224
	ds_read_b128 v[200:203], v143 offset:53248
	ds_read_b128 v[204:207], v143 offset:54272
	ds_read_b128 v[208:211], v143 offset:55296
	ds_read_b128 v[212:215], v143 offset:56320
	global_load_lds_dwordx4 v[138:139], off
	s_add_i32 m0, s69, 0x2000
	s_add_u32 s88, s88, 0x40080
	v_lshl_add_u64 v[138:139], v[192:193], 0, s[26:27]
	s_addc_u32 s89, s89, 0
	s_add_i32 s69, s74, s9
	global_load_lds_dwordx4 v[138:139], off
	v_lshl_add_u64 v[138:139], s[88:89], 0, v[194:195]
	s_mov_b32 m0, s69
	s_nop 0
	global_load_lds_dwordx4 v[138:139], off
	v_lshl_add_u64 v[138:139], s[88:89], 0, v[128:129]
	s_add_i32 m0, s69, 0x2000
	s_nop 0
	global_load_lds_dwordx4 v[138:139], off
	v_lshl_add_u64 v[138:139], v[228:229], 0, s[26:27]
	s_mov_b32 m0, s28
	s_nop 0
	global_load_lds_dwordx4 v[138:139], off
	v_lshl_add_u64 v[138:139], v[230:231], 0, s[26:27]
	s_mov_b32 m0, s29
	s_nop 0
	global_load_lds_dwordx4 v[138:139], off
	s_waitcnt vmcnt(8) lgkmcnt(0)
	s_barrier
	s_setprio 1
	v_mfma_f32_16x16x32_bf16 v[60:63], v[144:147], v[176:179], v[60:63]
	v_mfma_f32_16x16x32_bf16 v[56:59], v[152:155], v[176:179], v[56:59]
	v_mfma_f32_16x16x32_bf16 v[44:47], v[144:147], v[184:187], v[44:47]
	v_mfma_f32_16x16x32_bf16 v[40:43], v[152:155], v[184:187], v[40:43]
	v_mfma_f32_16x16x32_bf16 v[28:31], v[144:147], v[200:203], v[28:31]
	v_mfma_f32_16x16x32_bf16 v[24:27], v[152:155], v[200:203], v[24:27]
	v_mfma_f32_16x16x32_bf16 v[12:15], v[144:147], v[208:211], v[12:15]
	v_mfma_f32_16x16x32_bf16 v[8:11], v[152:155], v[208:211], v[8:11]
	v_mfma_f32_16x16x32_bf16 v[60:63], v[148:151], v[180:183], v[60:63]
	v_mfma_f32_16x16x32_bf16 v[56:59], v[156:159], v[180:183], v[56:59]
	v_mfma_f32_16x16x32_bf16 v[44:47], v[148:151], v[188:191], v[44:47]
	v_mfma_f32_16x16x32_bf16 v[40:43], v[156:159], v[188:191], v[40:43]
	v_mfma_f32_16x16x32_bf16 v[28:31], v[148:151], v[204:207], v[28:31]
	v_mfma_f32_16x16x32_bf16 v[24:27], v[156:159], v[204:207], v[24:27]
	v_mfma_f32_16x16x32_bf16 v[12:15], v[148:151], v[212:215], v[12:15]
	v_mfma_f32_16x16x32_bf16 v[8:11], v[156:159], v[212:215], v[8:11]
	v_mfma_f32_16x16x32_bf16 v[52:55], v[160:163], v[176:179], v[52:55]
	v_mfma_f32_16x16x32_bf16 v[48:51], v[168:171], v[176:179], v[48:51]
	v_mfma_f32_16x16x32_bf16 v[36:39], v[160:163], v[184:187], v[36:39]
	v_mfma_f32_16x16x32_bf16 v[32:35], v[168:171], v[184:187], v[32:35]
	v_mfma_f32_16x16x32_bf16 v[20:23], v[160:163], v[200:203], v[20:23]
	v_mfma_f32_16x16x32_bf16 v[16:19], v[168:171], v[200:203], v[16:19]
	v_mfma_f32_16x16x32_bf16 v[4:7], v[160:163], v[208:211], v[4:7]
	v_mfma_f32_16x16x32_bf16 v[0:3], v[168:171], v[208:211], v[0:3]
	v_mfma_f32_16x16x32_bf16 v[52:55], v[164:167], v[180:183], v[52:55]
	v_mfma_f32_16x16x32_bf16 v[48:51], v[172:175], v[180:183], v[48:51]
	v_mfma_f32_16x16x32_bf16 v[36:39], v[164:167], v[188:191], v[36:39]
	v_mfma_f32_16x16x32_bf16 v[32:35], v[172:175], v[188:191], v[32:35]
	v_mfma_f32_16x16x32_bf16 v[20:23], v[164:167], v[204:207], v[20:23]
	v_mfma_f32_16x16x32_bf16 v[16:19], v[172:175], v[204:207], v[16:19]
	v_mfma_f32_16x16x32_bf16 v[4:7], v[164:167], v[212:215], v[4:7]
	v_mfma_f32_16x16x32_bf16 v[0:3], v[172:175], v[212:215], v[0:3]
	s_setprio 0
	s_barrier
	s_add_u32 s86, s86, 0x100
	s_addc_u32 s87, s87, 0
	s_add_u32 s63, s63, 0x100
	s_addc_u32 s64, s64, 0
	s_cmp_ge_i32 s78, s16
	s_mov_b32 s69, s78
	s_cbranch_scc0 .LBB0_1626

; #define PG8_STAGE(bufoff, gbase, voff) do { _Pragma("unroll") for (int _i = 0; _i < 2; ++_i) \
;         __builtin_amdgcn_global_load_lds((const unsigned*)((const char*)(gbase) + (voff)[_i]), (PG8_LAS unsigned*)(lds + (bufoff) + ldsw + _i * 8192), 16, 0, 0); } while (0)
; #define PG8_LDA(dst, b, h) do { _Pragma("unroll") for (int m = 0; m < 4; ++m) _Pragma("unroll") for (int k = 0; k < 2; ++k) dst[m][k] = *(const PG8_LAS bf16x8*)(lds + PG8_SA(b, h) + aoff + m * 2048 + k * 1024); } while (0)
; #define PG8_LDB(dst, b, h) do { _Pragma("unroll") for (int n = 0; n < 2; ++n) _Pragma("unroll") for (int k = 0; k < 2; ++k) dst[n][k] = *(const PG8_LAS bf16x8*)(lds + PG8_SB(b, h) + boff + n * 2048 + k * 1024); } while (0)
; #define PG8_MMA(ai, bj, At, Bt) do { __builtin_amdgcn_s_setprio(1); _Pragma("unroll") for (int m = 0; m < 4; ++m) _Pragma("unroll") for (int n = 0; n < 2; ++n) _Pragma("unroll") for (int k = 0; k < 2; ++k) \
;         acc[ai][bj][m][n] = __builtin_amdgcn_mfma_f32_16x16x32_bf16(Bt[n][k], At[m][k], acc[ai][bj][m][n], 0, 0, 0); __builtin_amdgcn_s_setprio(0); } while (0)
; #define PG8_WAIT_V(n) asm volatile("s_waitcnt vmcnt(" #n ")" ::: "memory")
; #define PG8_WAIT_L(n) asm volatile("s_waitcnt lgkmcnt(" #n ")" ::: "memory")
; template <class Epi, class Sched, bool ALIGN_EPI = false, bool SP2 = false>
; __device__ __forceinline__ void gemm_phase(PG8_LAS unsigned char* lds, const Gemm g, const Sched& S, const Epi& E) {
;     ...
;             const bool last = (t == nt - 2);
;             const char* a1 = cA + (size_t)(t + 1) * kstep;
;             const char* a2 = last ? nA : cA + (size_t)(t + 2) * kstep; const char* b2 = last ? nB : cB + (size_t)(t + 2) * kstep;
;             const char* a3 = a2 + kstep; const char* b3 = b2 + kstep;
;             if (last && has_next) S.a_ready(nxt);
;             if constexpr (SP2) {
;             PG8_LDB(B0, 0, 0); PG8_LDB(B1, 0, 1); PG8_SCHED; PG8_LDA(At, 0, 0); PG8_STAGE(PG8_SA(1, 1), a1 + hstepA, voffA);
;             PG8_WAIT_V(8); PG8_WAIT_L(0); PG8_BAR; PG8_MMA(0, 0, At, B0); PG8_MMA(0, 1, At, B1); PG8_BAR; PG8_SCHED;
;             PG8_LDA(At, 0, 1); PG8_STAGE(PG8_SB(0, 0), b2, voffB); PG8_STAGE(PG8_SB(0, 1), b2 + hstepB, voffB); PG8_STAGE(PG8_SA(0, 0), a2, voffA);
;             PG8_WAIT_V(8); PG8_WAIT_L(0); PG8_BAR; PG8_MMA(1, 0, At, B0); PG8_MMA(1, 1, At, B1); PG8_BAR; PG8_SCHED;
.LBB0_1699:
	s_add_i32 s80, s68, 2
	s_add_u32 s69, s62, 0xfff00080
	s_addc_u32 s74, s63, -1
	s_add_i32 s75, 0, 0x10000
	s_cmp_eq_u32 s28, s68
	s_cselect_b32 s77, s45, s74
	s_cselect_b32 s76, s47, s69
	s_cselect_b32 s69, s59, s79
	s_cselect_b32 s68, s64, s78
	s_add_i32 s74, 0, 0x14000
	v_add_u32_e32 v150, s75, v168
	v_add_u32_e32 v170, s74, v168
	ds_read_b128 v[138:141], v150
	ds_read_b128 v[142:145], v150 offset:1024
	ds_read_b128 v[146:149], v150 offset:2048
	ds_read_b128 v[150:153], v150 offset:3072
	ds_read_b128 v[154:157], v170
	ds_read_b128 v[158:161], v170 offset:1024
	ds_read_b128 v[162:165], v170 offset:2048
	ds_read_b128 v[170:173], v170 offset:3072
	v_lshl_add_u64 v[212:213], s[62:63], 0, v[134:135]
	s_add_i32 m0, s3, 0xc000
	ds_read_b128 v[174:177], v169
	ds_read_b128 v[178:181], v169 offset:1024
	ds_read_b128 v[182:185], v169 offset:2048
	ds_read_b128 v[186:189], v169 offset:3072
	ds_read_b128 v[190:193], v169 offset:4096
	ds_read_b128 v[200:203], v169 offset:5120
	ds_read_b128 v[204:207], v169 offset:6144
	ds_read_b128 v[208:211], v169 offset:7168
	global_load_lds_dwordx4 v[212:213], off
	v_lshl_add_u64 v[212:213], s[62:63], 0, v[136:137]
	s_add_i32 m0, s3, 0xe000
	s_nop 0
	global_load_lds_dwordx4 v[212:213], off
	s_waitcnt vmcnt(8) lgkmcnt(0)
	s_barrier
	s_setprio 1
	v_mfma_f32_16x16x32_bf16 v[124:127], v[138:141], v[174:177], v[124:127]
	v_mfma_f32_16x16x32_bf16 v[120:123], v[146:149], v[174:177], v[120:123]
	v_mfma_f32_16x16x32_bf16 v[116:119], v[138:141], v[182:185], v[116:119]
	v_mfma_f32_16x16x32_bf16 v[112:115], v[146:149], v[182:185], v[112:115]
	v_mfma_f32_16x16x32_bf16 v[108:111], v[138:141], v[190:193], v[108:111]
	v_mfma_f32_16x16x32_bf16 v[104:107], v[146:149], v[190:193], v[104:107]
	v_mfma_f32_16x16x32_bf16 v[100:103], v[138:141], v[204:207], v[100:103]
	v_mfma_f32_16x16x32_bf16 v[96:99], v[146:149], v[204:207], v[96:99]
	v_mfma_f32_16x16x32_bf16 v[124:127], v[142:145], v[178:181], v[124:127]
	v_mfma_f32_16x16x32_bf16 v[120:123], v[150:153], v[178:181], v[120:123]
	v_mfma_f32_16x16x32_bf16 v[116:119], v[142:145], v[186:189], v[116:119]
	v_mfma_f32_16x16x32_bf16 v[112:115], v[150:153], v[186:189], v[112:115]
	v_mfma_f32_16x16x32_bf16 v[108:111], v[142:145], v[200:203], v[108:111]
	v_mfma_f32_16x16x32_bf16 v[104:107], v[150:153], v[200:203], v[104:107]
	v_mfma_f32_16x16x32_bf16 v[100:103], v[142:145], v[208:211], v[100:103]
	v_mfma_f32_16x16x32_bf16 v[96:99], v[150:153], v[208:211], v[96:99]
	v_mfma_f32_16x16x32_bf16 v[92:95], v[154:157], v[174:177], v[92:95]
	v_mfma_f32_16x16x32_bf16 v[84:87], v[162:165], v[174:177], v[84:87]
	v_mfma_f32_16x16x32_bf16 v[76:79], v[154:157], v[182:185], v[76:79]
	v_mfma_f32_16x16x32_bf16 v[68:71], v[162:165], v[182:185], v[68:71]
	v_mfma_f32_16x16x32_bf16 v[60:63], v[154:157], v[190:193], v[60:63]
	v_mfma_f32_16x16x32_bf16 v[52:55], v[162:165], v[190:193], v[52:55]
	v_mfma_f32_16x16x32_bf16 v[44:47], v[154:157], v[204:207], v[44:47]
	v_mfma_f32_16x16x32_bf16 v[36:39], v[162:165], v[204:207], v[36:39]
	v_mfma_f32_16x16x32_bf16 v[92:95], v[158:161], v[178:181], v[92:95]
	v_mfma_f32_16x16x32_bf16 v[84:87], v[170:173], v[178:181], v[84:87]
	v_mfma_f32_16x16x32_bf16 v[76:79], v[158:161], v[186:189], v[76:79]
	v_mfma_f32_16x16x32_bf16 v[68:71], v[170:173], v[186:189], v[68:71]
	v_mfma_f32_16x16x32_bf16 v[60:63], v[158:161], v[200:203], v[60:63]
	v_mfma_f32_16x16x32_bf16 v[52:55], v[170:173], v[200:203], v[52:55]
	v_mfma_f32_16x16x32_bf16 v[44:47], v[158:161], v[208:211], v[44:47]
	v_mfma_f32_16x16x32_bf16 v[36:39], v[170:173], v[208:211], v[36:39]
	s_setprio 0
	s_barrier
	s_add_i32 s75, s75, s2
	v_lshl_add_u64 v[212:213], s[68:69], 0, v[194:195]
	s_mov_b32 m0, s75
	ds_read_b128 v[174:177], v169 offset:16384
	ds_read_b128 v[178:181], v169 offset:17408
	ds_read_b128 v[182:185], v169 offset:18432
	ds_read_b128 v[186:189], v169 offset:19456
	ds_read_b128 v[190:193], v169 offset:20480
	ds_read_b128 v[200:203], v169 offset:21504
	ds_read_b128 v[204:207], v169 offset:22528
	ds_read_b128 v[208:211], v169 offset:23552
	global_load_lds_dwordx4 v[212:213], off
	s_add_i32 m0, s75, 0x2000
	s_add_u32 s82, s68, 0x100000
	v_lshl_add_u64 v[214:215], s[68:69], 0, v[128:129]
	s_addc_u32 s83, s69, 0
	s_add_i32 s74, s74, s2
	global_load_lds_dwordx4 v[214:215], off
	v_lshl_add_u64 v[228:229], s[82:83], 0, v[194:195]
	s_mov_b32 m0, s74
	v_lshl_add_u64 v[230:231], s[76:77], 0, v[130:131]
	global_load_lds_dwordx4 v[228:229], off
	v_lshl_add_u64 v[228:229], s[82:83], 0, v[128:129]
	s_add_i32 m0, s74, 0x2000
	s_nop 0
	global_load_lds_dwordx4 v[228:229], off
	v_lshl_add_u64 v[228:229], s[76:77], 0, v[132:133]
	s_mov_b32 m0, s3
	s_nop 0
	global_load_lds_dwordx4 v[228:229], off
	s_mov_b32 m0, s8
	s_nop 0
	global_load_lds_dwordx4 v[230:231], off
	s_waitcnt vmcnt(8) lgkmcnt(0)
	s_barrier
; #define PG8_STAGE(bufoff, gbase, voff) do { _Pragma("unroll") for (int _i = 0; _i < 2; ++_i) \
;         __builtin_amdgcn_global_load_lds((const unsigned*)((const char*)(gbase) + (voff)[_i]), (PG8_LAS unsigned*)(lds + (bufoff) + ldsw + _i * 8192), 16, 0, 0); } while (0)
; #define PG8_LDA(dst, b, h) do { _Pragma("unroll") for (int m = 0; m < 4; ++m) _Pragma("unroll") for (int k = 0; k < 2; ++k) dst[m][k] = *(const PG8_LAS bf16x8*)(lds + PG8_SA(b, h) + aoff + m * 2048 + k * 1024); } while (0)
; #define PG8_LDB(dst, b, h) do { _Pragma("unroll") for (int n = 0; n < 2; ++n) _Pragma("unroll") for (int k = 0; k < 2; ++k) dst[n][k] = *(const PG8_LAS bf16x8*)(lds + PG8_SB(b, h) + boff + n * 2048 + k * 1024); } while (0)
; #define PG8_MMA(ai, bj, At, Bt) do { __builtin_amdgcn_s_setprio(1); _Pragma("unroll") for (int m = 0; m < 4; ++m) _Pragma("unroll") for (int n = 0; n < 2; ++n) _Pragma("unroll") for (int k = 0; k < 2; ++k) \
;         acc[ai][bj][m][n] = __builtin_amdgcn_mfma_f32_16x16x32_bf16(Bt[n][k], At[m][k], acc[ai][bj][m][n], 0, 0, 0); __builtin_amdgcn_s_setprio(0); } while (0)
; #define PG8_WAIT_V(n) asm volatile("s_waitcnt vmcnt(" #n ")" ::: "memory")
; #define PG8_WAIT_L(n) asm volatile("s_waitcnt lgkmcnt(" #n ")" ::: "memory")
; #define PG8_BAR __builtin_amdgcn_s_barrier()
; #define PG8_SCHED __builtin_amdgcn_sched_barrier(0)
; template <class Epi, class Sched, bool ALIGN_EPI = false, bool SP2 = false>
; __device__ __forceinline__ void gemm_phase(PG8_LAS unsigned char* lds, const Gemm g, const Sched& S, const Epi& E) {
;     ...
;             PG8_WAIT_V(8); PG8_WAIT_L(0); PG8_BAR; PG8_MMA(1, 0, At, B0); PG8_MMA(1, 1, At, B1); PG8_BAR; PG8_SCHED;
;             PG8_LDB(B0, 1, 0); PG8_LDB(B1, 1, 1); PG8_SCHED; PG8_LDA(At, 1, 0); PG8_STAGE(PG8_SA(0, 1), a2 + hstepA, voffA);
;             PG8_WAIT_V(8); PG8_WAIT_L(0); PG8_BAR; PG8_MMA(0, 0, At, B0); PG8_MMA(0, 1, At, B1); PG8_BAR; PG8_SCHED;
	s_setprio 1
	v_mfma_f32_16x16x32_bf16 v[88:91], v[138:141], v[174:177], v[88:91]
	v_mfma_f32_16x16x32_bf16 v[80:83], v[146:149], v[174:177], v[80:83]
	v_mfma_f32_16x16x32_bf16 v[72:75], v[138:141], v[182:185], v[72:75]
	v_mfma_f32_16x16x32_bf16 v[64:67], v[146:149], v[182:185], v[64:67]
	v_mfma_f32_16x16x32_bf16 v[56:59], v[138:141], v[190:193], v[56:59]
	v_mfma_f32_16x16x32_bf16 v[48:51], v[146:149], v[190:193], v[48:51]
	v_mfma_f32_16x16x32_bf16 v[40:43], v[138:141], v[204:207], v[40:43]
	v_mfma_f32_16x16x32_bf16 v[32:35], v[146:149], v[204:207], v[32:35]
	v_mfma_f32_16x16x32_bf16 v[88:91], v[142:145], v[178:181], v[88:91]
	v_mfma_f32_16x16x32_bf16 v[80:83], v[150:153], v[178:181], v[80:83]
	v_mfma_f32_16x16x32_bf16 v[72:75], v[142:145], v[186:189], v[72:75]
	v_mfma_f32_16x16x32_bf16 v[64:67], v[150:153], v[186:189], v[64:67]
	v_mfma_f32_16x16x32_bf16 v[56:59], v[142:145], v[200:203], v[56:59]
	v_mfma_f32_16x16x32_bf16 v[48:51], v[150:153], v[200:203], v[48:51]
	v_mfma_f32_16x16x32_bf16 v[40:43], v[142:145], v[208:211], v[40:43]
	v_mfma_f32_16x16x32_bf16 v[32:35], v[150:153], v[208:211], v[32:35]
	v_mfma_f32_16x16x32_bf16 v[28:31], v[154:157], v[174:177], v[28:31]
	v_mfma_f32_16x16x32_bf16 v[24:27], v[162:165], v[174:177], v[24:27]
	v_mfma_f32_16x16x32_bf16 v[20:23], v[154:157], v[182:185], v[20:23]
	v_mfma_f32_16x16x32_bf16 v[16:19], v[162:165], v[182:185], v[16:19]
	v_mfma_f32_16x16x32_bf16 v[12:15], v[154:157], v[190:193], v[12:15]
	v_mfma_f32_16x16x32_bf16 v[8:11], v[162:165], v[190:193], v[8:11]
	v_mfma_f32_16x16x32_bf16 v[4:7], v[154:157], v[204:207], v[4:7]
	v_mfma_f32_16x16x32_bf16 v[0:3], v[162:165], v[204:207], v[0:3]
	v_mfma_f32_16x16x32_bf16 v[28:31], v[158:161], v[178:181], v[28:31]
	v_mfma_f32_16x16x32_bf16 v[24:27], v[170:173], v[178:181], v[24:27]
	v_mfma_f32_16x16x32_bf16 v[20:23], v[158:161], v[186:189], v[20:23]
	v_mfma_f32_16x16x32_bf16 v[16:19], v[170:173], v[186:189], v[16:19]
	v_mfma_f32_16x16x32_bf16 v[12:15], v[158:161], v[200:203], v[12:15]
	v_mfma_f32_16x16x32_bf16 v[8:11], v[170:173], v[200:203], v[8:11]
	v_mfma_f32_16x16x32_bf16 v[4:7], v[158:161], v[208:211], v[4:7]
	v_mfma_f32_16x16x32_bf16 v[0:3], v[170:173], v[208:211], v[0:3]
	s_setprio 0
	s_barrier
	s_add_i32 s74, 0, 0x18000
	s_add_i32 s75, 0, 0x1c000
	v_add_u32_e32 v150, s74, v168
	v_add_u32_e32 v170, s75, v168
	ds_read_b128 v[138:141], v150
	ds_read_b128 v[142:145], v150 offset:1024
	ds_read_b128 v[146:149], v150 offset:2048
	ds_read_b128 v[150:153], v150 offset:3072
	ds_read_b128 v[154:157], v170
	ds_read_b128 v[158:161], v170 offset:1024
	ds_read_b128 v[162:165], v170 offset:2048
	ds_read_b128 v[170:173], v170 offset:3072
	s_add_u32 s76, s76, 0x100000
	s_addc_u32 s77, s77, 0
	s_mov_b32 m0, s9
	v_lshl_add_u64 v[232:233], s[76:77], 0, v[132:133]
	ds_read_b128 v[174:177], v169 offset:32768
	ds_read_b128 v[178:181], v169 offset:33792
	ds_read_b128 v[182:185], v169 offset:34816
	ds_read_b128 v[186:189], v169 offset:35840
	ds_read_b128 v[190:193], v169 offset:36864
	ds_read_b128 v[200:203], v169 offset:37888
	ds_read_b128 v[204:207], v169 offset:38912
	ds_read_b128 v[208:211], v169 offset:39936
	global_load_lds_dwordx4 v[232:233], off
	v_lshl_add_u64 v[232:233], s[76:77], 0, v[130:131]
	s_mov_b32 m0, s10
	s_nop 0
	global_load_lds_dwordx4 v[232:233], off
	s_waitcnt vmcnt(8) lgkmcnt(0)
	s_barrier
	s_setprio 1
	v_mfma_f32_16x16x32_bf16 v[124:127], v[138:141], v[174:177], v[124:127]
	v_mfma_f32_16x16x32_bf16 v[120:123], v[146:149], v[174:177], v[120:123]
	v_mfma_f32_16x16x32_bf16 v[116:119], v[138:141], v[182:185], v[116:119]
	v_mfma_f32_16x16x32_bf16 v[112:115], v[146:149], v[182:185], v[112:115]
	v_mfma_f32_16x16x32_bf16 v[108:111], v[138:141], v[190:193], v[108:111]
	v_mfma_f32_16x16x32_bf16 v[104:107], v[146:149], v[190:193], v[104:107]
	v_mfma_f32_16x16x32_bf16 v[100:103], v[138:141], v[204:207], v[100:103]
	v_mfma_f32_16x16x32_bf16 v[96:99], v[146:149], v[204:207], v[96:99]
	v_mfma_f32_16x16x32_bf16 v[124:127], v[142:145], v[178:181], v[124:127]
	v_mfma_f32_16x16x32_bf16 v[120:123], v[150:153], v[178:181], v[120:123]
	v_mfma_f32_16x16x32_bf16 v[116:119], v[142:145], v[186:189], v[116:119]
	v_mfma_f32_16x16x32_bf16 v[112:115], v[150:153], v[186:189], v[112:115]
	v_mfma_f32_16x16x32_bf16 v[108:111], v[142:145], v[200:203], v[108:111]
	v_mfma_f32_16x16x32_bf16 v[104:107], v[150:153], v[200:203], v[104:107]
	v_mfma_f32_16x16x32_bf16 v[100:103], v[142:145], v[208:211], v[100:103]
	v_mfma_f32_16x16x32_bf16 v[96:99], v[150:153], v[208:211], v[96:99]
	v_mfma_f32_16x16x32_bf16 v[92:95], v[154:157], v[174:177], v[92:95]
	v_mfma_f32_16x16x32_bf16 v[84:87], v[162:165], v[174:177], v[84:87]
	v_mfma_f32_16x16x32_bf16 v[76:79], v[154:157], v[182:185], v[76:79]
	v_mfma_f32_16x16x32_bf16 v[68:71], v[162:165], v[182:185], v[68:71]
	v_mfma_f32_16x16x32_bf16 v[60:63], v[154:157], v[190:193], v[60:63]
	v_mfma_f32_16x16x32_bf16 v[52:55], v[162:165], v[190:193], v[52:55]
	v_mfma_f32_16x16x32_bf16 v[44:47], v[154:157], v[204:207], v[44:47]
	v_mfma_f32_16x16x32_bf16 v[36:39], v[162:165], v[204:207], v[36:39]
	v_mfma_f32_16x16x32_bf16 v[92:95], v[158:161], v[178:181], v[92:95]
	v_mfma_f32_16x16x32_bf16 v[84:87], v[170:173], v[178:181], v[84:87]
	v_mfma_f32_16x16x32_bf16 v[76:79], v[158:161], v[186:189], v[76:79]
	v_mfma_f32_16x16x32_bf16 v[68:71], v[170:173], v[186:189], v[68:71]
	v_mfma_f32_16x16x32_bf16 v[60:63], v[158:161], v[200:203], v[60:63]
	v_mfma_f32_16x16x32_bf16 v[52:55], v[170:173], v[200:203], v[52:55]
	v_mfma_f32_16x16x32_bf16 v[44:47], v[158:161], v[208:211], v[44:47]
	v_mfma_f32_16x16x32_bf16 v[36:39], v[170:173], v[208:211], v[36:39]
	s_setprio 0
	s_barrier
; #define PG8_STAGE(bufoff, gbase, voff) do { _Pragma("unroll") for (int _i = 0; _i < 2; ++_i) \
;         __builtin_amdgcn_global_load_lds((const unsigned*)((const char*)(gbase) + (voff)[_i]), (PG8_LAS unsigned*)(lds + (bufoff) + ldsw + _i * 8192), 16, 0, 0); } while (0)
; #define PG8_LDA(dst, b, h) do { _Pragma("unroll") for (int m = 0; m < 4; ++m) _Pragma("unroll") for (int k = 0; k < 2; ++k) dst[m][k] = *(const PG8_LAS bf16x8*)(lds + PG8_SA(b, h) + aoff + m * 2048 + k * 1024); } while (0)
; #define PG8_MMA(ai, bj, At, Bt) do { __builtin_amdgcn_s_setprio(1); _Pragma("unroll") for (int m = 0; m < 4; ++m) _Pragma("unroll") for (int n = 0; n < 2; ++n) _Pragma("unroll") for (int k = 0; k < 2; ++k) \
;         acc[ai][bj][m][n] = __builtin_amdgcn_mfma_f32_16x16x32_bf16(Bt[n][k], At[m][k], acc[ai][bj][m][n], 0, 0, 0); __builtin_amdgcn_s_setprio(0); } while (0)
; #define PG8_WAIT_V(n) asm volatile("s_waitcnt vmcnt(" #n ")" ::: "memory")
; #define PG8_WAIT_L(n) asm volatile("s_waitcnt lgkmcnt(" #n ")" ::: "memory")
; #define PG8_BAR __builtin_amdgcn_s_barrier()
; #define PG8_SCHED __builtin_amdgcn_sched_barrier(0)
; template <class Epi, class Sched, bool ALIGN_EPI = false, bool SP2 = false>
; __device__ __forceinline__ void gemm_phase(PG8_LAS unsigned char* lds, const Gemm g, const Sched& S, const Epi& E) {
;     ...
;             PG8_LDA(At, 1, 1); PG8_STAGE(PG8_SB(1, 0), b3, voffB); PG8_STAGE(PG8_SB(1, 1), b3 + hstepB, voffB); PG8_STAGE(PG8_SA(1, 0), a3, voffA);
;             PG8_WAIT_V(8); PG8_WAIT_L(0); PG8_BAR; PG8_MMA(1, 0, At, B0); PG8_MMA(1, 1, At, B1); PG8_BAR; PG8_SCHED;
;     __device__ __forceinline__ void operator()(AccRef acc, const pg8::Unit& u, int wr, int wc, int fr, int fq) const {
;     ...
;                     *(f32x4*)(op + off) = x0 + g0 * (acc[ai][bj][m][0] + b0);
;                     *(f32x4*)(op + off + 4) = x1 + g1 * (acc[ai][bj][m][1] + b1);
	s_add_i32 s74, s74, s2
	v_lshl_add_u64 v[212:213], v[212:213], 0, s[26:27]
	s_mov_b32 m0, s74
	ds_read_b128 v[174:177], v169 offset:49152
	ds_read_b128 v[178:181], v169 offset:50176
	ds_read_b128 v[182:185], v169 offset:51200
	ds_read_b128 v[186:189], v169 offset:52224
	ds_read_b128 v[190:193], v169 offset:53248
	ds_read_b128 v[200:203], v169 offset:54272
	ds_read_b128 v[204:207], v169 offset:55296
	ds_read_b128 v[208:211], v169 offset:56320
	global_load_lds_dwordx4 v[212:213], off
	s_add_i32 m0, s74, 0x2000
	s_add_u32 s68, s68, 0x100080
	v_lshl_add_u64 v[212:213], v[214:215], 0, s[26:27]
	s_addc_u32 s69, s69, 0
	s_add_i32 s74, s75, s2
	global_load_lds_dwordx4 v[212:213], off
	v_lshl_add_u64 v[212:213], s[68:69], 0, v[194:195]
	s_mov_b32 m0, s74
	s_nop 0
	global_load_lds_dwordx4 v[212:213], off
	v_lshl_add_u64 v[212:213], s[68:69], 0, v[128:129]
	s_add_i32 m0, s74, 0x2000
	s_nop 0
	global_load_lds_dwordx4 v[212:213], off
	v_lshl_add_u64 v[212:213], v[228:229], 0, s[26:27]
	s_mov_b32 m0, s16
	s_nop 0
	global_load_lds_dwordx4 v[212:213], off
	v_lshl_add_u64 v[212:213], v[230:231], 0, s[26:27]
	s_mov_b32 m0, s17
	s_nop 0
	global_load_lds_dwordx4 v[212:213], off
	s_waitcnt vmcnt(8) lgkmcnt(0)
	s_barrier
	s_setprio 1
	v_mfma_f32_16x16x32_bf16 v[88:91], v[138:141], v[174:177], v[88:91]
	v_mfma_f32_16x16x32_bf16 v[80:83], v[146:149], v[174:177], v[80:83]
	v_mfma_f32_16x16x32_bf16 v[72:75], v[138:141], v[182:185], v[72:75]
	v_mfma_f32_16x16x32_bf16 v[64:67], v[146:149], v[182:185], v[64:67]
	v_mfma_f32_16x16x32_bf16 v[56:59], v[138:141], v[190:193], v[56:59]
	v_mfma_f32_16x16x32_bf16 v[48:51], v[146:149], v[190:193], v[48:51]
	v_mfma_f32_16x16x32_bf16 v[40:43], v[138:141], v[204:207], v[40:43]
	v_mfma_f32_16x16x32_bf16 v[32:35], v[146:149], v[204:207], v[32:35]
	v_mfma_f32_16x16x32_bf16 v[88:91], v[142:145], v[178:181], v[88:91]
	v_mfma_f32_16x16x32_bf16 v[80:83], v[150:153], v[178:181], v[80:83]
	v_mfma_f32_16x16x32_bf16 v[72:75], v[142:145], v[186:189], v[72:75]
	v_mfma_f32_16x16x32_bf16 v[64:67], v[150:153], v[186:189], v[64:67]
	v_mfma_f32_16x16x32_bf16 v[56:59], v[142:145], v[200:203], v[56:59]
	v_mfma_f32_16x16x32_bf16 v[48:51], v[150:153], v[200:203], v[48:51]
	v_mfma_f32_16x16x32_bf16 v[40:43], v[142:145], v[208:211], v[40:43]
	v_mfma_f32_16x16x32_bf16 v[32:35], v[150:153], v[208:211], v[32:35]
	v_mfma_f32_16x16x32_bf16 v[28:31], v[154:157], v[174:177], v[28:31]
	v_mfma_f32_16x16x32_bf16 v[24:27], v[162:165], v[174:177], v[24:27]
	v_mfma_f32_16x16x32_bf16 v[20:23], v[154:157], v[182:185], v[20:23]
	v_mfma_f32_16x16x32_bf16 v[16:19], v[162:165], v[182:185], v[16:19]
	v_mfma_f32_16x16x32_bf16 v[12:15], v[154:157], v[190:193], v[12:15]
	v_mfma_f32_16x16x32_bf16 v[8:11], v[162:165], v[190:193], v[8:11]
	v_mfma_f32_16x16x32_bf16 v[4:7], v[154:157], v[204:207], v[4:7]
	v_mfma_f32_16x16x32_bf16 v[0:3], v[162:165], v[204:207], v[0:3]
	v_mfma_f32_16x16x32_bf16 v[28:31], v[158:161], v[178:181], v[28:31]
	v_mfma_f32_16x16x32_bf16 v[24:27], v[170:173], v[178:181], v[24:27]
	v_mfma_f32_16x16x32_bf16 v[20:23], v[158:161], v[186:189], v[20:23]
	v_mfma_f32_16x16x32_bf16 v[16:19], v[170:173], v[186:189], v[16:19]
	v_mfma_f32_16x16x32_bf16 v[12:15], v[158:161], v[200:203], v[12:15]
	v_mfma_f32_16x16x32_bf16 v[8:11], v[170:173], v[200:203], v[8:11]
	v_mfma_f32_16x16x32_bf16 v[4:7], v[158:161], v[208:211], v[4:7]
	v_mfma_f32_16x16x32_bf16 v[0:3], v[170:173], v[208:211], v[0:3]
	s_setprio 0
	s_barrier
	s_add_u32 s62, s62, 0x100
	s_addc_u32 s63, s63, 0
	s_add_u32 s78, s78, 0x100
	s_addc_u32 s79, s79, 0
	s_cmp_ge_i32 s80, s13
	s_mov_b32 s68, s80
	s_cbranch_scc0 .LBB0_1699
	v_pk_add_f32 v[158:159], v[126:127], 0 op_sel_hi:[1,0]
	v_pk_add_f32 v[160:161], v[124:125], 0 op_sel_hi:[1,0]
	v_pk_add_f32 v[162:163], v[122:123], 0 op_sel_hi:[1,0]
	v_pk_add_f32 v[164:165], v[120:121], 0 op_sel_hi:[1,0]
	v_pk_add_f32 v[150:151], v[118:119], 0 op_sel_hi:[1,0]
	v_pk_add_f32 v[152:153], v[116:117], 0 op_sel_hi:[1,0]
	v_pk_add_f32 v[154:155], v[114:115], 0 op_sel_hi:[1,0]
	v_pk_add_f32 v[156:157], v[112:113], 0 op_sel_hi:[1,0]
	v_pk_add_f32 v[142:143], v[110:111], 0 op_sel_hi:[1,0]
	v_pk_add_f32 v[144:145], v[108:109], 0 op_sel_hi:[1,0]
	v_pk_add_f32 v[146:147], v[106:107], 0 op_sel_hi:[1,0]
	v_pk_add_f32 v[148:149], v[104:105], 0 op_sel_hi:[1,0]
	v_pk_add_f32 v[124:125], v[102:103], 0 op_sel_hi:[1,0]
	v_pk_add_f32 v[126:127], v[100:101], 0 op_sel_hi:[1,0]
	v_pk_add_f32 v[138:139], v[98:99], 0 op_sel_hi:[1,0]
	v_pk_add_f32 v[140:141], v[96:97], 0 op_sel_hi:[1,0]
	v_pk_add_f32 v[116:117], v[90:91], 0 op_sel_hi:[1,0]
	v_pk_add_f32 v[118:119], v[88:89], 0 op_sel_hi:[1,0]
	v_pk_add_f32 v[120:121], v[82:83], 0 op_sel_hi:[1,0]
	v_pk_add_f32 v[122:123], v[80:81], 0 op_sel_hi:[1,0]
	v_pk_add_f32 v[108:109], v[74:75], 0 op_sel_hi:[1,0]
	v_pk_add_f32 v[110:111], v[72:73], 0 op_sel_hi:[1,0]
	v_pk_add_f32 v[112:113], v[66:67], 0 op_sel_hi:[1,0]
	v_pk_add_f32 v[114:115], v[64:65], 0 op_sel_hi:[1,0]
	v_pk_add_f32 v[100:101], v[58:59], 0 op_sel_hi:[1,0]
	v_pk_add_f32 v[102:103], v[56:57], 0 op_sel_hi:[1,0]
	v_pk_add_f32 v[104:105], v[50:51], 0 op_sel_hi:[1,0]
	v_pk_add_f32 v[106:107], v[48:49], 0 op_sel_hi:[1,0]
	v_pk_add_f32 v[88:89], v[42:43], 0 op_sel_hi:[1,0]
	v_pk_add_f32 v[90:91], v[40:41], 0 op_sel_hi:[1,0]
	v_pk_add_f32 v[96:97], v[34:35], 0 op_sel_hi:[1,0]
	v_pk_add_f32 v[98:99], v[32:33], 0 op_sel_hi:[1,0]
	v_pk_add_f32 v[72:73], v[94:95], 0 op_sel_hi:[1,0]
	v_pk_add_f32 v[74:75], v[92:93], 0 op_sel_hi:[1,0]
	v_pk_add_f32 v[80:81], v[86:87], 0 op_sel_hi:[1,0]
	v_pk_add_f32 v[82:83], v[84:85], 0 op_sel_hi:[1,0]
	v_pk_add_f32 v[56:57], v[78:79], 0 op_sel_hi:[1,0]
	v_pk_add_f32 v[58:59], v[76:77], 0 op_sel_hi:[1,0]
	v_pk_add_f32 v[64:65], v[70:71], 0 op_sel_hi:[1,0]
	v_pk_add_f32 v[66:67], v[68:69], 0 op_sel_hi:[1,0]
	v_pk_add_f32 v[48:49], v[62:63], 0 op_sel_hi:[1,0]
	v_pk_add_f32 v[50:51], v[60:61], 0 op_sel_hi:[1,0]
	v_pk_add_f32 v[54:55], v[54:55], 0 op_sel_hi:[1,0]
	v_pk_add_f32 v[52:53], v[52:53], 0 op_sel_hi:[1,0]
	v_pk_add_f32 v[40:41], v[46:47], 0 op_sel_hi:[1,0]
	v_pk_add_f32 v[42:43], v[44:45], 0 op_sel_hi:[1,0]
	v_pk_add_f32 v[44:45], v[38:39], 0 op_sel_hi:[1,0]
	v_pk_add_f32 v[46:47], v[36:37], 0 op_sel_hi:[1,0]
	v_pk_add_f32 v[32:33], v[30:31], 0 op_sel_hi:[1,0]
	v_pk_add_f32 v[34:35], v[28:29], 0 op_sel_hi:[1,0]
	v_pk_add_f32 v[36:37], v[26:27], 0 op_sel_hi:[1,0]
	v_pk_add_f32 v[38:39], v[24:25], 0 op_sel_hi:[1,0]
	v_pk_add_f32 v[24:25], v[22:23], 0 op_sel_hi:[1,0]
	v_pk_add_f32 v[26:27], v[20:21], 0 op_sel_hi:[1,0]
	v_pk_add_f32 v[28:29], v[18:19], 0 op_sel_hi:[1,0]
	v_pk_add_f32 v[30:31], v[16:17], 0 op_sel_hi:[1,0]
	v_pk_add_f32 v[20:21], v[14:15], 0 op_sel_hi:[1,0]
	v_pk_add_f32 v[22:23], v[12:13], 0 op_sel_hi:[1,0]
	v_pk_add_f32 v[10:11], v[10:11], 0 op_sel_hi:[1,0]
	v_pk_add_f32 v[8:9], v[8:9], 0 op_sel_hi:[1,0]
	v_pk_add_f32 v[18:19], v[6:7], 0 op_sel_hi:[1,0]
	v_pk_add_f32 v[16:17], v[4:5], 0 op_sel_hi:[1,0]
	v_pk_add_f32 v[14:15], v[2:3], 0 op_sel_hi:[1,0]
	v_pk_add_f32 v[12:13], v[0:1], 0 op_sel_hi:[1,0]

; #define PG8_STAGE(bufoff, gbase, voff) do { _Pragma("unroll") for (int _i = 0; _i < 2; ++_i) \
;         __builtin_amdgcn_global_load_lds((const unsigned*)((const char*)(gbase) + (voff)[_i]), (PG8_LAS unsigned*)(lds + (bufoff) + ldsw + _i * 8192), 16, 0, 0); } while (0)
; #define PG8_LDA(dst, b, h) do { _Pragma("unroll") for (int m = 0; m < 4; ++m) _Pragma("unroll") for (int k = 0; k < 2; ++k) dst[m][k] = *(const PG8_LAS bf16x8*)(lds + PG8_SA(b, h) + aoff + m * 2048 + k * 1024); } while (0)
; #define PG8_LDB(dst, b, h) do { _Pragma("unroll") for (int n = 0; n < 2; ++n) _Pragma("unroll") for (int k = 0; k < 2; ++k) dst[n][k] = *(const PG8_LAS bf16x8*)(lds + PG8_SB(b, h) + boff + n * 2048 + k * 1024); } while (0)
; #define PG8_MMA(ai, bj, At, Bt) do { __builtin_amdgcn_s_setprio(1); _Pragma("unroll") for (int m = 0; m < 4; ++m) _Pragma("unroll") for (int n = 0; n < 2; ++n) _Pragma("unroll") for (int k = 0; k < 2; ++k) \
;         acc[ai][bj][m][n] = __builtin_amdgcn_mfma_f32_16x16x32_bf16(Bt[n][k], At[m][k], acc[ai][bj][m][n], 0, 0, 0); __builtin_amdgcn_s_setprio(0); } while (0)
; #define PG8_WAIT_V(n) asm volatile("s_waitcnt vmcnt(" #n ")" ::: "memory")
; #define PG8_WAIT_L(n) asm volatile("s_waitcnt lgkmcnt(" #n ")" ::: "memory")
; template <class Epi, class Sched, bool ALIGN_EPI = false, bool SP2 = false>
; __device__ __forceinline__ void gemm_phase(PG8_LAS unsigned char* lds, const Gemm g, const Sched& S, const Epi& E) {
;     ...
;             const bool last = (t == nt - 2);
;             const char* a1 = cA + (size_t)(t + 1) * kstep;
;             const char* a2 = last ? nA : cA + (size_t)(t + 2) * kstep; const char* b2 = last ? nB : cB + (size_t)(t + 2) * kstep;
;             const char* a3 = a2 + kstep; const char* b3 = b2 + kstep;
;             if (last && has_next) S.a_ready(nxt);
;             if constexpr (SP2) {
;             PG8_LDB(B0, 0, 0); PG8_LDB(B1, 0, 1); PG8_SCHED; PG8_LDA(At, 0, 0); PG8_STAGE(PG8_SA(1, 1), a1 + hstepA, voffA);
;             PG8_WAIT_V(8); PG8_WAIT_L(0); PG8_BAR; PG8_MMA(0, 0, At, B0); PG8_MMA(0, 1, At, B1); PG8_BAR; PG8_SCHED;
;             PG8_LDA(At, 0, 1); PG8_STAGE(PG8_SB(0, 0), b2, voffB); PG8_STAGE(PG8_SB(0, 1), b2 + hstepB, voffB); PG8_STAGE(PG8_SA(0, 0), a2, voffA);
;             PG8_WAIT_V(8); PG8_WAIT_L(0); PG8_BAR; PG8_MMA(1, 0, At, B0); PG8_MMA(1, 1, At, B1); PG8_BAR; PG8_SCHED;
.LBB0_1726:
	s_add_i32 s64, s59, 2
	s_add_u32 s62, s52, 0xfff00080
	s_addc_u32 s63, s53, -1
	s_add_i32 s74, 0, 0x10000
	s_cmp_eq_u32 s16, s59
	s_cselect_b32 s69, s41, s63
	s_cselect_b32 s68, s40, s62
	s_cselect_b32 s63, s49, s58
	s_cselect_b32 s62, s48, s47
	s_add_i32 s59, 0, 0x14000
	v_add_u32_e32 v150, s74, v172
	v_add_u32_e32 v166, s59, v172
	ds_read_b128 v[138:141], v150
	ds_read_b128 v[142:145], v150 offset:1024
	ds_read_b128 v[146:149], v150 offset:2048
	ds_read_b128 v[150:153], v150 offset:3072
	ds_read_b128 v[154:157], v166
	ds_read_b128 v[158:161], v166 offset:1024
	ds_read_b128 v[162:165], v166 offset:2048
	ds_read_b128 v[166:169], v166 offset:3072
	v_lshl_add_u64 v[212:213], s[52:53], 0, v[134:135]
	s_add_i32 m0, s3, 0xc000
	ds_read_b128 v[174:177], v173
	ds_read_b128 v[178:181], v173 offset:1024
	ds_read_b128 v[182:185], v173 offset:2048
	ds_read_b128 v[186:189], v173 offset:3072
	ds_read_b128 v[190:193], v173 offset:4096
	ds_read_b128 v[200:203], v173 offset:5120
	ds_read_b128 v[204:207], v173 offset:6144
	ds_read_b128 v[208:211], v173 offset:7168
	global_load_lds_dwordx4 v[212:213], off
	v_lshl_add_u64 v[212:213], s[52:53], 0, v[136:137]
	s_add_i32 m0, s3, 0xe000
	s_nop 0
	global_load_lds_dwordx4 v[212:213], off
	s_waitcnt vmcnt(8) lgkmcnt(0)
	s_barrier
	s_setprio 1
	v_mfma_f32_16x16x32_bf16 v[124:127], v[138:141], v[174:177], v[124:127]
	v_mfma_f32_16x16x32_bf16 v[120:123], v[146:149], v[174:177], v[120:123]
	v_mfma_f32_16x16x32_bf16 v[116:119], v[138:141], v[182:185], v[116:119]
	v_mfma_f32_16x16x32_bf16 v[112:115], v[146:149], v[182:185], v[112:115]
	v_mfma_f32_16x16x32_bf16 v[108:111], v[138:141], v[190:193], v[108:111]
	v_mfma_f32_16x16x32_bf16 v[104:107], v[146:149], v[190:193], v[104:107]
	v_mfma_f32_16x16x32_bf16 v[100:103], v[138:141], v[204:207], v[100:103]
	v_mfma_f32_16x16x32_bf16 v[96:99], v[146:149], v[204:207], v[96:99]
	v_mfma_f32_16x16x32_bf16 v[124:127], v[142:145], v[178:181], v[124:127]
	v_mfma_f32_16x16x32_bf16 v[120:123], v[150:153], v[178:181], v[120:123]
	v_mfma_f32_16x16x32_bf16 v[116:119], v[142:145], v[186:189], v[116:119]
	v_mfma_f32_16x16x32_bf16 v[112:115], v[150:153], v[186:189], v[112:115]
	v_mfma_f32_16x16x32_bf16 v[108:111], v[142:145], v[200:203], v[108:111]
	v_mfma_f32_16x16x32_bf16 v[104:107], v[150:153], v[200:203], v[104:107]
	v_mfma_f32_16x16x32_bf16 v[100:103], v[142:145], v[208:211], v[100:103]
	v_mfma_f32_16x16x32_bf16 v[96:99], v[150:153], v[208:211], v[96:99]
	v_mfma_f32_16x16x32_bf16 v[92:95], v[154:157], v[174:177], v[92:95]
	v_mfma_f32_16x16x32_bf16 v[84:87], v[162:165], v[174:177], v[84:87]
	v_mfma_f32_16x16x32_bf16 v[76:79], v[154:157], v[182:185], v[76:79]
	v_mfma_f32_16x16x32_bf16 v[68:71], v[162:165], v[182:185], v[68:71]
	v_mfma_f32_16x16x32_bf16 v[60:63], v[154:157], v[190:193], v[60:63]
	v_mfma_f32_16x16x32_bf16 v[52:55], v[162:165], v[190:193], v[52:55]
	v_mfma_f32_16x16x32_bf16 v[44:47], v[154:157], v[204:207], v[44:47]
	v_mfma_f32_16x16x32_bf16 v[36:39], v[162:165], v[204:207], v[36:39]
	v_mfma_f32_16x16x32_bf16 v[92:95], v[158:161], v[178:181], v[92:95]
	v_mfma_f32_16x16x32_bf16 v[84:87], v[166:169], v[178:181], v[84:87]
	v_mfma_f32_16x16x32_bf16 v[76:79], v[158:161], v[186:189], v[76:79]
	v_mfma_f32_16x16x32_bf16 v[68:71], v[166:169], v[186:189], v[68:71]
	v_mfma_f32_16x16x32_bf16 v[60:63], v[158:161], v[200:203], v[60:63]
	v_mfma_f32_16x16x32_bf16 v[52:55], v[166:169], v[200:203], v[52:55]
	v_mfma_f32_16x16x32_bf16 v[44:47], v[158:161], v[208:211], v[44:47]
	v_mfma_f32_16x16x32_bf16 v[36:39], v[166:169], v[208:211], v[36:39]
	s_setprio 0
	s_barrier
	s_add_i32 s74, s74, s2
	v_lshl_add_u64 v[212:213], s[62:63], 0, v[194:195]
	s_mov_b32 m0, s74
	ds_read_b128 v[174:177], v173 offset:16384
	ds_read_b128 v[178:181], v173 offset:17408
	ds_read_b128 v[182:185], v173 offset:18432
	ds_read_b128 v[186:189], v173 offset:19456
	ds_read_b128 v[190:193], v173 offset:20480
	ds_read_b128 v[200:203], v173 offset:21504
	ds_read_b128 v[204:207], v173 offset:22528
	ds_read_b128 v[208:211], v173 offset:23552
	global_load_lds_dwordx4 v[212:213], off
	s_add_i32 m0, s74, 0x2000
	s_add_u32 s76, s62, 0x100000
	v_lshl_add_u64 v[214:215], s[62:63], 0, v[128:129]
	s_addc_u32 s77, s63, 0
	s_add_i32 s59, s59, s2
	global_load_lds_dwordx4 v[214:215], off
	v_lshl_add_u64 v[228:229], s[76:77], 0, v[194:195]
	s_mov_b32 m0, s59
	v_lshl_add_u64 v[230:231], s[68:69], 0, v[130:131]
	global_load_lds_dwordx4 v[228:229], off
	v_lshl_add_u64 v[228:229], s[76:77], 0, v[128:129]
	s_add_i32 m0, s59, 0x2000
	s_nop 0
	global_load_lds_dwordx4 v[228:229], off
	v_lshl_add_u64 v[228:229], s[68:69], 0, v[132:133]
	s_mov_b32 m0, s3
	s_nop 0
	global_load_lds_dwordx4 v[228:229], off
	s_mov_b32 m0, s8
	s_nop 0
	global_load_lds_dwordx4 v[230:231], off
	s_waitcnt vmcnt(8) lgkmcnt(0)
	s_barrier
; #define PG8_STAGE(bufoff, gbase, voff) do { _Pragma("unroll") for (int _i = 0; _i < 2; ++_i) \
;         __builtin_amdgcn_global_load_lds((const unsigned*)((const char*)(gbase) + (voff)[_i]), (PG8_LAS unsigned*)(lds + (bufoff) + ldsw + _i * 8192), 16, 0, 0); } while (0)
; #define PG8_LDA(dst, b, h) do { _Pragma("unroll") for (int m = 0; m < 4; ++m) _Pragma("unroll") for (int k = 0; k < 2; ++k) dst[m][k] = *(const PG8_LAS bf16x8*)(lds + PG8_SA(b, h) + aoff + m * 2048 + k * 1024); } while (0)
; #define PG8_LDB(dst, b, h) do { _Pragma("unroll") for (int n = 0; n < 2; ++n) _Pragma("unroll") for (int k = 0; k < 2; ++k) dst[n][k] = *(const PG8_LAS bf16x8*)(lds + PG8_SB(b, h) + boff + n * 2048 + k * 1024); } while (0)
; #define PG8_MMA(ai, bj, At, Bt) do { __builtin_amdgcn_s_setprio(1); _Pragma("unroll") for (int m = 0; m < 4; ++m) _Pragma("unroll") for (int n = 0; n < 2; ++n) _Pragma("unroll") for (int k = 0; k < 2; ++k) \
;         acc[ai][bj][m][n] = __builtin_amdgcn_mfma_f32_16x16x32_bf16(Bt[n][k], At[m][k], acc[ai][bj][m][n], 0, 0, 0); __builtin_amdgcn_s_setprio(0); } while (0)
; #define PG8_WAIT_V(n) asm volatile("s_waitcnt vmcnt(" #n ")" ::: "memory")
; #define PG8_WAIT_L(n) asm volatile("s_waitcnt lgkmcnt(" #n ")" ::: "memory")
; #define PG8_BAR __builtin_amdgcn_s_barrier()
; #define PG8_SCHED __builtin_amdgcn_sched_barrier(0)
; template <class Epi, class Sched, bool ALIGN_EPI = false, bool SP2 = false>
; __device__ __forceinline__ void gemm_phase(PG8_LAS unsigned char* lds, const Gemm g, const Sched& S, const Epi& E) {
;     ...
;             PG8_WAIT_V(8); PG8_WAIT_L(0); PG8_BAR; PG8_MMA(1, 0, At, B0); PG8_MMA(1, 1, At, B1); PG8_BAR; PG8_SCHED;
;             PG8_LDB(B0, 1, 0); PG8_LDB(B1, 1, 1); PG8_SCHED; PG8_LDA(At, 1, 0); PG8_STAGE(PG8_SA(0, 1), a2 + hstepA, voffA);
;             PG8_WAIT_V(8); PG8_WAIT_L(0); PG8_BAR; PG8_MMA(0, 0, At, B0); PG8_MMA(0, 1, At, B1); PG8_BAR; PG8_SCHED;
	s_setprio 1
	v_mfma_f32_16x16x32_bf16 v[88:91], v[138:141], v[174:177], v[88:91]
	v_mfma_f32_16x16x32_bf16 v[80:83], v[146:149], v[174:177], v[80:83]
	v_mfma_f32_16x16x32_bf16 v[72:75], v[138:141], v[182:185], v[72:75]
	v_mfma_f32_16x16x32_bf16 v[64:67], v[146:149], v[182:185], v[64:67]
	v_mfma_f32_16x16x32_bf16 v[56:59], v[138:141], v[190:193], v[56:59]
	v_mfma_f32_16x16x32_bf16 v[48:51], v[146:149], v[190:193], v[48:51]
	v_mfma_f32_16x16x32_bf16 v[40:43], v[138:141], v[204:207], v[40:43]
	v_mfma_f32_16x16x32_bf16 v[32:35], v[146:149], v[204:207], v[32:35]
	v_mfma_f32_16x16x32_bf16 v[88:91], v[142:145], v[178:181], v[88:91]
	v_mfma_f32_16x16x32_bf16 v[80:83], v[150:153], v[178:181], v[80:83]
	v_mfma_f32_16x16x32_bf16 v[72:75], v[142:145], v[186:189], v[72:75]
	v_mfma_f32_16x16x32_bf16 v[64:67], v[150:153], v[186:189], v[64:67]
	v_mfma_f32_16x16x32_bf16 v[56:59], v[142:145], v[200:203], v[56:59]
	v_mfma_f32_16x16x32_bf16 v[48:51], v[150:153], v[200:203], v[48:51]
	v_mfma_f32_16x16x32_bf16 v[40:43], v[142:145], v[208:211], v[40:43]
	v_mfma_f32_16x16x32_bf16 v[32:35], v[150:153], v[208:211], v[32:35]
	v_mfma_f32_16x16x32_bf16 v[28:31], v[154:157], v[174:177], v[28:31]
	v_mfma_f32_16x16x32_bf16 v[24:27], v[162:165], v[174:177], v[24:27]
	v_mfma_f32_16x16x32_bf16 v[20:23], v[154:157], v[182:185], v[20:23]
	v_mfma_f32_16x16x32_bf16 v[16:19], v[162:165], v[182:185], v[16:19]
	v_mfma_f32_16x16x32_bf16 v[12:15], v[154:157], v[190:193], v[12:15]
	v_mfma_f32_16x16x32_bf16 v[8:11], v[162:165], v[190:193], v[8:11]
	v_mfma_f32_16x16x32_bf16 v[4:7], v[154:157], v[204:207], v[4:7]
	v_mfma_f32_16x16x32_bf16 v[0:3], v[162:165], v[204:207], v[0:3]
	v_mfma_f32_16x16x32_bf16 v[28:31], v[158:161], v[178:181], v[28:31]
	v_mfma_f32_16x16x32_bf16 v[24:27], v[166:169], v[178:181], v[24:27]
	v_mfma_f32_16x16x32_bf16 v[20:23], v[158:161], v[186:189], v[20:23]
	v_mfma_f32_16x16x32_bf16 v[16:19], v[166:169], v[186:189], v[16:19]
	v_mfma_f32_16x16x32_bf16 v[12:15], v[158:161], v[200:203], v[12:15]
	v_mfma_f32_16x16x32_bf16 v[8:11], v[166:169], v[200:203], v[8:11]
	v_mfma_f32_16x16x32_bf16 v[4:7], v[158:161], v[208:211], v[4:7]
	v_mfma_f32_16x16x32_bf16 v[0:3], v[166:169], v[208:211], v[0:3]
	s_setprio 0
	s_barrier
	s_add_i32 s59, 0, 0x18000
	s_add_i32 s74, 0, 0x1c000
	v_add_u32_e32 v150, s59, v172
	v_add_u32_e32 v166, s74, v172
	ds_read_b128 v[138:141], v150
	ds_read_b128 v[142:145], v150 offset:1024
	ds_read_b128 v[146:149], v150 offset:2048
	ds_read_b128 v[150:153], v150 offset:3072
	ds_read_b128 v[154:157], v166
	ds_read_b128 v[158:161], v166 offset:1024
	ds_read_b128 v[162:165], v166 offset:2048
	ds_read_b128 v[166:169], v166 offset:3072
	s_add_u32 s68, s68, 0x100000
	s_addc_u32 s69, s69, 0
	s_mov_b32 m0, s9
	v_lshl_add_u64 v[232:233], s[68:69], 0, v[132:133]
	ds_read_b128 v[174:177], v173 offset:32768
	ds_read_b128 v[178:181], v173 offset:33792
	ds_read_b128 v[182:185], v173 offset:34816
	ds_read_b128 v[186:189], v173 offset:35840
	ds_read_b128 v[190:193], v173 offset:36864
	ds_read_b128 v[200:203], v173 offset:37888
	ds_read_b128 v[204:207], v173 offset:38912
	ds_read_b128 v[208:211], v173 offset:39936
	global_load_lds_dwordx4 v[232:233], off
	v_lshl_add_u64 v[232:233], s[68:69], 0, v[130:131]
	s_mov_b32 m0, s10
	s_nop 0
	global_load_lds_dwordx4 v[232:233], off
	s_waitcnt vmcnt(8) lgkmcnt(0)
	s_barrier
	s_setprio 1
	v_mfma_f32_16x16x32_bf16 v[124:127], v[138:141], v[174:177], v[124:127]
	v_mfma_f32_16x16x32_bf16 v[120:123], v[146:149], v[174:177], v[120:123]
	v_mfma_f32_16x16x32_bf16 v[116:119], v[138:141], v[182:185], v[116:119]
	v_mfma_f32_16x16x32_bf16 v[112:115], v[146:149], v[182:185], v[112:115]
	v_mfma_f32_16x16x32_bf16 v[108:111], v[138:141], v[190:193], v[108:111]
	v_mfma_f32_16x16x32_bf16 v[104:107], v[146:149], v[190:193], v[104:107]
	v_mfma_f32_16x16x32_bf16 v[100:103], v[138:141], v[204:207], v[100:103]
	v_mfma_f32_16x16x32_bf16 v[96:99], v[146:149], v[204:207], v[96:99]
	v_mfma_f32_16x16x32_bf16 v[124:127], v[142:145], v[178:181], v[124:127]
	v_mfma_f32_16x16x32_bf16 v[120:123], v[150:153], v[178:181], v[120:123]
	v_mfma_f32_16x16x32_bf16 v[116:119], v[142:145], v[186:189], v[116:119]
	v_mfma_f32_16x16x32_bf16 v[112:115], v[150:153], v[186:189], v[112:115]
	v_mfma_f32_16x16x32_bf16 v[108:111], v[142:145], v[200:203], v[108:111]
	v_mfma_f32_16x16x32_bf16 v[104:107], v[150:153], v[200:203], v[104:107]
	v_mfma_f32_16x16x32_bf16 v[100:103], v[142:145], v[208:211], v[100:103]
	v_mfma_f32_16x16x32_bf16 v[96:99], v[150:153], v[208:211], v[96:99]
	v_mfma_f32_16x16x32_bf16 v[92:95], v[154:157], v[174:177], v[92:95]
	v_mfma_f32_16x16x32_bf16 v[84:87], v[162:165], v[174:177], v[84:87]
	v_mfma_f32_16x16x32_bf16 v[76:79], v[154:157], v[182:185], v[76:79]
	v_mfma_f32_16x16x32_bf16 v[68:71], v[162:165], v[182:185], v[68:71]
	v_mfma_f32_16x16x32_bf16 v[60:63], v[154:157], v[190:193], v[60:63]
	v_mfma_f32_16x16x32_bf16 v[52:55], v[162:165], v[190:193], v[52:55]
	v_mfma_f32_16x16x32_bf16 v[44:47], v[154:157], v[204:207], v[44:47]
	v_mfma_f32_16x16x32_bf16 v[36:39], v[162:165], v[204:207], v[36:39]
	v_mfma_f32_16x16x32_bf16 v[92:95], v[158:161], v[178:181], v[92:95]
	v_mfma_f32_16x16x32_bf16 v[84:87], v[166:169], v[178:181], v[84:87]
	v_mfma_f32_16x16x32_bf16 v[76:79], v[158:161], v[186:189], v[76:79]
	v_mfma_f32_16x16x32_bf16 v[68:71], v[166:169], v[186:189], v[68:71]
	v_mfma_f32_16x16x32_bf16 v[60:63], v[158:161], v[200:203], v[60:63]
	v_mfma_f32_16x16x32_bf16 v[52:55], v[166:169], v[200:203], v[52:55]
	v_mfma_f32_16x16x32_bf16 v[44:47], v[158:161], v[208:211], v[44:47]
	v_mfma_f32_16x16x32_bf16 v[36:39], v[166:169], v[208:211], v[36:39]
	s_setprio 0
	s_barrier
; #define PG8_STAGE(bufoff, gbase, voff) do { _Pragma("unroll") for (int _i = 0; _i < 2; ++_i) \
;         __builtin_amdgcn_global_load_lds((const unsigned*)((const char*)(gbase) + (voff)[_i]), (PG8_LAS unsigned*)(lds + (bufoff) + ldsw + _i * 8192), 16, 0, 0); } while (0)
; #define PG8_LDA(dst, b, h) do { _Pragma("unroll") for (int m = 0; m < 4; ++m) _Pragma("unroll") for (int k = 0; k < 2; ++k) dst[m][k] = *(const PG8_LAS bf16x8*)(lds + PG8_SA(b, h) + aoff + m * 2048 + k * 1024); } while (0)
; #define PG8_MMA(ai, bj, At, Bt) do { __builtin_amdgcn_s_setprio(1); _Pragma("unroll") for (int m = 0; m < 4; ++m) _Pragma("unroll") for (int n = 0; n < 2; ++n) _Pragma("unroll") for (int k = 0; k < 2; ++k) \
;         acc[ai][bj][m][n] = __builtin_amdgcn_mfma_f32_16x16x32_bf16(Bt[n][k], At[m][k], acc[ai][bj][m][n], 0, 0, 0); __builtin_amdgcn_s_setprio(0); } while (0)
; #define PG8_WAIT_V(n) asm volatile("s_waitcnt vmcnt(" #n ")" ::: "memory")
; #define PG8_WAIT_L(n) asm volatile("s_waitcnt lgkmcnt(" #n ")" ::: "memory")
; #define PG8_BAR __builtin_amdgcn_s_barrier()
; #define PG8_SCHED __builtin_amdgcn_sched_barrier(0)
; template <class Epi, class Sched, bool ALIGN_EPI = false, bool SP2 = false>
; __device__ __forceinline__ void gemm_phase(PG8_LAS unsigned char* lds, const Gemm g, const Sched& S, const Epi& E) {
;     ...
;             PG8_LDA(At, 1, 1); PG8_STAGE(PG8_SB(1, 0), b3, voffB); PG8_STAGE(PG8_SB(1, 1), b3 + hstepB, voffB); PG8_STAGE(PG8_SA(1, 0), a3, voffA);
;             PG8_WAIT_V(8); PG8_WAIT_L(0); PG8_BAR; PG8_MMA(1, 0, At, B0); PG8_MMA(1, 1, At, B1); PG8_BAR; PG8_SCHED;
;     __device__ __forceinline__ void operator()(AccRef acc, const pg8::Unit& u, int wr, int wc, int fr, int fq) const {
;     ...
;                     *(f32x4*)(part + off) = g0 * (acc[ai][bj][m][0] + b0); *(f32x4*)(part + off + 4) = g1 * (acc[ai][bj][m][1] + b1);
	s_add_i32 s59, s59, s2
	v_lshl_add_u64 v[212:213], v[212:213], 0, s[26:27]
	s_mov_b32 m0, s59
	ds_read_b128 v[174:177], v173 offset:49152
	ds_read_b128 v[178:181], v173 offset:50176
	ds_read_b128 v[182:185], v173 offset:51200
	ds_read_b128 v[186:189], v173 offset:52224
	ds_read_b128 v[190:193], v173 offset:53248
	ds_read_b128 v[200:203], v173 offset:54272
	ds_read_b128 v[204:207], v173 offset:55296
	ds_read_b128 v[208:211], v173 offset:56320
	global_load_lds_dwordx4 v[212:213], off
	s_add_i32 m0, s59, 0x2000
	s_add_u32 s62, s62, 0x100080
	v_lshl_add_u64 v[212:213], v[214:215], 0, s[26:27]
	s_addc_u32 s63, s63, 0
	s_add_i32 s59, s74, s2
	global_load_lds_dwordx4 v[212:213], off
	v_lshl_add_u64 v[212:213], s[62:63], 0, v[194:195]
	s_mov_b32 m0, s59
	s_nop 0
	global_load_lds_dwordx4 v[212:213], off
	v_lshl_add_u64 v[212:213], s[62:63], 0, v[128:129]
	s_add_i32 m0, s59, 0x2000
	s_nop 0
	global_load_lds_dwordx4 v[212:213], off
	v_lshl_add_u64 v[212:213], v[228:229], 0, s[26:27]
	s_mov_b32 m0, s14
	s_nop 0
	global_load_lds_dwordx4 v[212:213], off
	v_lshl_add_u64 v[212:213], v[230:231], 0, s[26:27]
	s_mov_b32 m0, s15
	s_nop 0
	global_load_lds_dwordx4 v[212:213], off
	s_waitcnt vmcnt(8) lgkmcnt(0)
	s_barrier
	s_setprio 1
	v_mfma_f32_16x16x32_bf16 v[88:91], v[138:141], v[174:177], v[88:91]
	v_mfma_f32_16x16x32_bf16 v[80:83], v[146:149], v[174:177], v[80:83]
	v_mfma_f32_16x16x32_bf16 v[72:75], v[138:141], v[182:185], v[72:75]
	v_mfma_f32_16x16x32_bf16 v[64:67], v[146:149], v[182:185], v[64:67]
	v_mfma_f32_16x16x32_bf16 v[56:59], v[138:141], v[190:193], v[56:59]
	v_mfma_f32_16x16x32_bf16 v[48:51], v[146:149], v[190:193], v[48:51]
	v_mfma_f32_16x16x32_bf16 v[40:43], v[138:141], v[204:207], v[40:43]
	v_mfma_f32_16x16x32_bf16 v[32:35], v[146:149], v[204:207], v[32:35]
	v_mfma_f32_16x16x32_bf16 v[88:91], v[142:145], v[178:181], v[88:91]
	v_mfma_f32_16x16x32_bf16 v[80:83], v[150:153], v[178:181], v[80:83]
	v_mfma_f32_16x16x32_bf16 v[72:75], v[142:145], v[186:189], v[72:75]
	v_mfma_f32_16x16x32_bf16 v[64:67], v[150:153], v[186:189], v[64:67]
	v_mfma_f32_16x16x32_bf16 v[56:59], v[142:145], v[200:203], v[56:59]
	v_mfma_f32_16x16x32_bf16 v[48:51], v[150:153], v[200:203], v[48:51]
	v_mfma_f32_16x16x32_bf16 v[40:43], v[142:145], v[208:211], v[40:43]
	v_mfma_f32_16x16x32_bf16 v[32:35], v[150:153], v[208:211], v[32:35]
	v_mfma_f32_16x16x32_bf16 v[28:31], v[154:157], v[174:177], v[28:31]
	v_mfma_f32_16x16x32_bf16 v[24:27], v[162:165], v[174:177], v[24:27]
	v_mfma_f32_16x16x32_bf16 v[20:23], v[154:157], v[182:185], v[20:23]
	v_mfma_f32_16x16x32_bf16 v[16:19], v[162:165], v[182:185], v[16:19]
	v_mfma_f32_16x16x32_bf16 v[12:15], v[154:157], v[190:193], v[12:15]
	v_mfma_f32_16x16x32_bf16 v[8:11], v[162:165], v[190:193], v[8:11]
	v_mfma_f32_16x16x32_bf16 v[4:7], v[154:157], v[204:207], v[4:7]
	v_mfma_f32_16x16x32_bf16 v[0:3], v[162:165], v[204:207], v[0:3]
	v_mfma_f32_16x16x32_bf16 v[28:31], v[158:161], v[178:181], v[28:31]
	v_mfma_f32_16x16x32_bf16 v[24:27], v[166:169], v[178:181], v[24:27]
	v_mfma_f32_16x16x32_bf16 v[20:23], v[158:161], v[186:189], v[20:23]
	v_mfma_f32_16x16x32_bf16 v[16:19], v[166:169], v[186:189], v[16:19]
	v_mfma_f32_16x16x32_bf16 v[12:15], v[158:161], v[200:203], v[12:15]
	v_mfma_f32_16x16x32_bf16 v[8:11], v[166:169], v[200:203], v[8:11]
	v_mfma_f32_16x16x32_bf16 v[4:7], v[158:161], v[208:211], v[4:7]
	v_mfma_f32_16x16x32_bf16 v[0:3], v[166:169], v[208:211], v[0:3]
	s_setprio 0
	s_barrier
	s_add_u32 s52, s52, 0x100
	s_addc_u32 s53, s53, 0
	s_add_u32 s47, s47, 0x100
	s_addc_u32 s58, s58, 0
	s_cmp_ge_i32 s64, s11
	s_mov_b32 s59, s64
	s_cbranch_scc0 .LBB0_1726
	v_pk_add_f32 v[126:127], v[126:127], 0 op_sel_hi:[1,0]
	v_pk_add_f32 v[124:125], v[124:125], 0 op_sel_hi:[1,0]
	v_pk_add_f32 v[122:123], v[122:123], 0 op_sel_hi:[1,0]
	v_pk_add_f32 v[120:121], v[120:121], 0 op_sel_hi:[1,0]
	v_pk_add_f32 v[118:119], v[118:119], 0 op_sel_hi:[1,0]
	v_pk_add_f32 v[116:117], v[116:117], 0 op_sel_hi:[1,0]
	v_pk_add_f32 v[114:115], v[114:115], 0 op_sel_hi:[1,0]
	v_pk_add_f32 v[112:113], v[112:113], 0 op_sel_hi:[1,0]
	v_pk_add_f32 v[110:111], v[110:111], 0 op_sel_hi:[1,0]
	v_pk_add_f32 v[108:109], v[108:109], 0 op_sel_hi:[1,0]
	v_pk_add_f32 v[106:107], v[106:107], 0 op_sel_hi:[1,0]
	v_pk_add_f32 v[104:105], v[104:105], 0 op_sel_hi:[1,0]
	v_pk_add_f32 v[102:103], v[102:103], 0 op_sel_hi:[1,0]
	v_pk_add_f32 v[100:101], v[100:101], 0 op_sel_hi:[1,0]
	v_pk_add_f32 v[98:99], v[98:99], 0 op_sel_hi:[1,0]
	v_pk_add_f32 v[96:97], v[96:97], 0 op_sel_hi:[1,0]
	v_pk_add_f32 v[140:141], v[90:91], 0 op_sel_hi:[1,0]
	v_pk_add_f32 v[144:145], v[88:89], 0 op_sel_hi:[1,0]
	v_pk_add_f32 v[138:139], v[82:83], 0 op_sel_hi:[1,0]
	v_pk_add_f32 v[142:143], v[80:81], 0 op_sel_hi:[1,0]
	v_pk_add_f32 v[148:149], v[74:75], 0 op_sel_hi:[1,0]
	v_pk_add_f32 v[152:153], v[72:73], 0 op_sel_hi:[1,0]
	v_pk_add_f32 v[146:147], v[66:67], 0 op_sel_hi:[1,0]
	v_pk_add_f32 v[150:151], v[64:65], 0 op_sel_hi:[1,0]
	v_pk_add_f32 v[156:157], v[58:59], 0 op_sel_hi:[1,0]
	v_pk_add_f32 v[160:161], v[56:57], 0 op_sel_hi:[1,0]
	v_pk_add_f32 v[154:155], v[50:51], 0 op_sel_hi:[1,0]
	v_pk_add_f32 v[158:159], v[48:49], 0 op_sel_hi:[1,0]
	v_pk_add_f32 v[162:163], v[42:43], 0 op_sel_hi:[1,0]
	v_pk_add_f32 v[166:167], v[40:41], 0 op_sel_hi:[1,0]
	v_pk_add_f32 v[164:165], v[34:35], 0 op_sel_hi:[1,0]
	v_pk_add_f32 v[168:169], v[32:33], 0 op_sel_hi:[1,0]
	v_pk_add_f32 v[90:91], v[94:95], 0 op_sel_hi:[1,0]
	v_pk_add_f32 v[88:89], v[92:93], 0 op_sel_hi:[1,0]
	v_pk_add_f32 v[82:83], v[86:87], 0 op_sel_hi:[1,0]
	v_pk_add_f32 v[80:81], v[84:85], 0 op_sel_hi:[1,0]
	v_pk_add_f32 v[74:75], v[78:79], 0 op_sel_hi:[1,0]
	v_pk_add_f32 v[72:73], v[76:77], 0 op_sel_hi:[1,0]
	v_pk_add_f32 v[66:67], v[70:71], 0 op_sel_hi:[1,0]
	v_pk_add_f32 v[64:65], v[68:69], 0 op_sel_hi:[1,0]
	v_pk_add_f32 v[58:59], v[62:63], 0 op_sel_hi:[1,0]
	v_pk_add_f32 v[56:57], v[60:61], 0 op_sel_hi:[1,0]
	v_pk_add_f32 v[50:51], v[54:55], 0 op_sel_hi:[1,0]
	v_pk_add_f32 v[48:49], v[52:53], 0 op_sel_hi:[1,0]
	v_pk_add_f32 v[42:43], v[46:47], 0 op_sel_hi:[1,0]
	v_pk_add_f32 v[40:41], v[44:45], 0 op_sel_hi:[1,0]
	v_pk_add_f32 v[34:35], v[38:39], 0 op_sel_hi:[1,0]
	v_pk_add_f32 v[32:33], v[36:37], 0 op_sel_hi:[1,0]
	v_pk_add_f32 v[46:47], v[30:31], 0 op_sel_hi:[1,0]
	v_pk_add_f32 v[44:45], v[28:29], 0 op_sel_hi:[1,0]
	v_pk_add_f32 v[38:39], v[26:27], 0 op_sel_hi:[1,0]
	v_pk_add_f32 v[36:37], v[24:25], 0 op_sel_hi:[1,0]
	v_pk_add_f32 v[30:31], v[22:23], 0 op_sel_hi:[1,0]
	v_pk_add_f32 v[28:29], v[20:21], 0 op_sel_hi:[1,0]
	v_pk_add_f32 v[26:27], v[18:19], 0 op_sel_hi:[1,0]
	v_pk_add_f32 v[24:25], v[16:17], 0 op_sel_hi:[1,0]
	v_pk_add_f32 v[22:23], v[14:15], 0 op_sel_hi:[1,0]
	v_pk_add_f32 v[20:21], v[12:13], 0 op_sel_hi:[1,0]
	v_pk_add_f32 v[18:19], v[10:11], 0 op_sel_hi:[1,0]
	v_pk_add_f32 v[16:17], v[8:9], 0 op_sel_hi:[1,0]
	v_pk_add_f32 v[14:15], v[6:7], 0 op_sel_hi:[1,0]
	v_pk_add_f32 v[12:13], v[4:5], 0 op_sel_hi:[1,0]
	v_pk_add_f32 v[10:11], v[2:3], 0 op_sel_hi:[1,0]
	v_pk_add_f32 v[8:9], v[0:1], 0 op_sel_hi:[1,0]
